# in-proj and up-projection output stores also device-scope
# baseline (speedup 1.0000x reference)
; __device__ __forceinline__ unsigned short f2bf(float f) { return (unsigned short)(cvt_pk_bf16(f, f) & 0xffffu); }
; __device__ __forceinline__ void store4bf(bf16_t* p, f32x4 v) { u32x2 w; w.x = cvt_pk_bf16(v[0], v[1]); w.y = cvt_pk_bf16(v[2], v[3]); *(u32x2*)p = w; }
;   __device__ __forceinline__ void group(int row, int c32, int fq, f32x4 v0, f32x4 v1) const {
;     int b, e; const bool ok = row_be(row, b, e);
;     if (c32 < 512) {
;       if (c32 < 384) store8bf(cqkv + (size_t)row * 512 + c32 + fq * 8, v0, v1);
;       else { bf16_t* p = cqkv + (size_t)row * 512 + c32 + fq * 4; store4bf(p, v0); store4bf(p + 16, v1); }
;       if (c32 == 384 && ok) {
;         const float2* rp = rope + pos_of_e(e) * 16 + fq * 4; f32x4 o0, o1;
; #pragma unroll
;         for (int j = 0; j < 4; ++j) { const float2 cs = rp[j]; o0[j] = v0[j] * cs.x - v1[j] * cs.y; o1[j] = v1[j] * cs.x + v0[j] * cs.y; }
; #pragma unroll
;         for (int h = 0; h < 6; ++h) { bf16_t* q = ka + ((size_t)(b * 6 + h) * E + e) * 96 + 64 + fq * 4; store4bf(q, o0); store4bf(q + 16, o1); }
;       }
;       return;
;     }
;     if (!ok) return;
;     if (c32 < 768) { const int cc = c32 - 512, h = cc >> 6; store8bf(qd + ((size_t)(b * 4 + h) * E + e) * 64 + (cc & 63) + fq * 8, v0 * QSC_D, v1 * QSC_D); }
;     else if (c32 < 1024) { const int cc = c32 - 768, h = cc >> 6; store8bf(kd + ((size_t)(b * 4 + h) * E + e) * 64 + (cc & 63) + fq * 8, v0, v1); }
;     else if (c32 < 1280) { const int cc = c32 - 1024, h = cc >> 6; bf16_t* p = vtd + ((size_t)(b * 4 + h) * 64 + (cc & 63) + fq * 4) * E + e;
; #pragma unroll
;       for (int j = 0; j < 4; ++j) { p[(size_t)j * E] = f2bf(v0[j]); p[(size_t)(j + 16) * E] = f2bf(v1[j]); } }
;     else if (c32 < 1664) { const int cc = c32 - 1280, h = cc >> 6; store8bf(qs + ((size_t)(b * 6 + h) * E + e) * 64 + (cc & 63) + fq * 8, v0 * QSC_S, v1 * QSC_S); }
;     else if (c32 < 1792) { const int cc = c32 - 1664, g = cc >> 6; store8bf(ks + ((size_t)(b * 2 + g) * E + e) * 64 + (cc & 63) + fq * 8, v0, v1); }
;     else if (c32 < 1920) { const int cc = c32 - 1792, g = cc >> 6; bf16_t* p = vts + ((size_t)(b * 2 + g) * 64 + (cc & 63) + fq * 4) * E + e;
; #pragma unroll
;       for (int j = 0; j < 4; ++j) { p[(size_t)j * E] = f2bf(v0[j]); p[(size_t)(j + 16) * E] = f2bf(v1[j]); } }
.LBB0_313:
	v_bfe_u32 v143, v141, 4, 2
	v_lshlrev_b32_e32 v130, 5, v138
	s_cmp_eq_u32 s0, 4
	v_add_u32_e32 v144, s6, v139
	v_and_b32_e32 v137, 32, v130
	v_lshlrev_b32_e32 v138, 2, v143
	s_mov_b32 s6, 0x8000
	s_cselect_b64 s[20:21], -1, 0
	s_cmp_lg_u32 s0, 4
	v_cmp_gt_i32_e64 s[4:5], 4, v142
	v_or_b32_e32 v0, s90, v130
	s_mov_b32 s1, 2
	v_or_b32_e32 v140, v137, v138
	v_lshlrev_b32_e32 v139, 3, v143
	v_cmp_gt_i32_e64 s[6:7], s6, v144
	v_ashrrev_i32_e32 v145, 13, v144
	v_or_b32_e32 v132, v144, v136
	s_cselect_b64 s[12:13], -1, 0
	s_and_b64 vcc, exec, s[20:21]
	s_cbranch_vccnz .LBB0_393
	s_cmp_lg_u32 s0, 7
	s_mov_b64 s[10:11], -1
	s_cbranch_scc0 .LBB0_401
	s_cmp_gt_u32 s0, 1
	v_add_u32_e32 v130, 0xfffff900, v0
	s_cselect_b64 s[10:11], -1, 0
	s_cmp_gt_u32 s0, 2
	v_lshrrev_b32_e32 v150, 6, v130
	v_add_u32_e32 v130, 0xfffffb00, v0
	s_cselect_b64 s[24:25], -1, 0
	s_cmp_gt_u32 s0, 3
	v_lshrrev_b32_e32 v149, 6, v130
	v_add_u32_e32 v130, 0xfffffc00, v0
	s_cselect_b64 s[18:19], -1, 0
	s_cmp_gt_u32 s0, 4
	v_lshrrev_b32_e32 v148, 6, v130
	v_add_u32_e32 v130, 0xfffffd00, v0
	s_cselect_b64 s[16:17], -1, 0
	s_cmp_gt_u32 s0, 6
	v_lshrrev_b32_e32 v147, 6, v130
	v_add_u32_e32 v130, 0xfffffe00, v0
	s_cselect_b64 s[14:15], -1, 0
	v_lshrrev_b32_e32 v146, 6, v130
	s_mov_b64 s[8:9], -1
	s_and_b64 vcc, exec, s[10:11]
	s_cbranch_vccz .LBB0_334
	s_mov_b32 s1, 0x8000
	v_cmp_gt_i32_e32 vcc, s1, v132
	v_cmp_gt_u32_e64 s[8:9], s49, v144
	s_or_b64 s[22:23], vcc, s[8:9]
	s_and_saveexec_b64 s[8:9], s[22:23]
	s_cbranch_execz .LBB0_333
	v_and_b32_e32 v130, 0x1fcf, v132
	v_add_u32_e32 v130, 64, v130
	v_cndmask_b32_e32 v133, 0, v145, vcc
	v_cndmask_b32_e32 v130, v136, v130, vcc
	s_mov_b64 s[38:39], -1
	s_and_b64 vcc, exec, s[24:25]
	s_cbranch_vccz .LBB0_331
	s_and_b64 vcc, exec, s[18:19]
	s_cbranch_vccz .LBB0_328
	s_and_b64 vcc, exec, s[16:17]
	s_cbranch_vccz .LBB0_325
	s_and_b64 vcc, exec, s[14:15]
	s_cbranch_vccz .LBB0_322
	v_lshl_add_u32 v134, v133, 1, v150
	v_ashrrev_i32_e32 v135, 31, v134
	v_readlane_b32 s22, v254, 16
	v_lshlrev_b64 v[134:135], 6, v[134:135]
	v_readlane_b32 s23, v254, 17
	v_or_b32_e32 v131, v134, v140
	v_lshlrev_b32_e32 v134, 1, v130
	v_mov_b64_e32 v[152:153], s[22:23]
	v_mad_u64_u32 v[152:153], s[22:23], v131, s95, v[152:153]
	v_mad_i32_i24 v153, v135, s95, v153
	v_mov_b32_e32 v135, v1
	v_lshl_add_u64 v[134:135], v[152:153], 0, v[134:135]
	s_mov_b32 s1, 0x40000
	v_cvt_pk_bf16_f32 v131, v126, s0
	v_add_co_u32_e32 v152, vcc, s1, v134
	global_store_short v[134:135], v131, off sc1
	v_cvt_pk_bf16_f32 v131, v122, s0
	v_addc_co_u32_e32 v153, vcc, 0, v135, vcc
	s_movk_i32 s1, 0x4000
	global_store_short v[152:153], v131, off offset:2048 sc1
	v_add_co_u32_e32 v152, vcc, s1, v134
	v_cvt_pk_bf16_f32 v131, v127, s0
	s_nop 0
	v_addc_co_u32_e32 v153, vcc, 0, v135, vcc
	s_mov_b32 s1, 0x44000
	global_store_short v[152:153], v131, off offset:128 sc1
	v_add_co_u32_e32 v152, vcc, s1, v134
	v_cvt_pk_bf16_f32 v131, v123, s0
	s_nop 0
	v_addc_co_u32_e32 v153, vcc, 0, v135, vcc
	s_mov_b32 s1, 0x8000
	global_store_short v[152:153], v131, off offset:2176 sc1
	v_add_co_u32_e32 v152, vcc, s1, v134
	v_cvt_pk_bf16_f32 v131, v128, s0
	s_nop 0
	v_addc_co_u32_e32 v153, vcc, 0, v135, vcc
	s_mov_b32 s1, 0x48000
	global_store_short v[152:153], v131, off offset:256 sc1
	v_add_co_u32_e32 v152, vcc, s1, v134
	v_cvt_pk_bf16_f32 v131, v124, s0
	s_nop 0
	v_addc_co_u32_e32 v153, vcc, 0, v135, vcc
	global_store_short v[152:153], v131, off offset:2304 sc1
	v_add_co_u32_e32 v152, vcc, 0xc000, v134
	v_cvt_pk_bf16_f32 v131, v129, s0
	s_nop 0
	v_addc_co_u32_e32 v153, vcc, 0, v135, vcc
	v_add_co_u32_e32 v134, vcc, 0x4c000, v134
	global_store_short v[152:153], v131, off offset:384 sc1
	v_cvt_pk_bf16_f32 v131, v125, s0
	v_addc_co_u32_e32 v135, vcc, 0, v135, vcc
	global_store_short v[134:135], v131, off offset:2432 sc1
	s_mov_b64 s[38:39], 0
.LBB0_322:
	s_andn2_b64 vcc, exec, s[38:39]
	s_cbranch_vccnz .LBB0_324
	v_mad_i32_i24 v134, v133, 6, v149
	v_mov_b32_e32 v131, v1
	s_movk_i32 s1, 0x2040
	v_mad_i64_i32 v[134:135], s[22:23], v134, s1, v[130:131]
	v_readlane_b32 s22, v254, 12
	v_lshlrev_b64 v[134:135], 7, v[134:135]
	v_readlane_b32 s23, v254, 13
	v_lshlrev_b32_e32 v152, 1, v137
	v_mov_b32_e32 v153, v1
	v_lshl_add_u64 v[134:135], s[22:23], 0, v[134:135]
	v_lshl_add_u64 v[134:135], v[134:135], 0, v[152:153]
	v_lshlrev_b32_e32 v152, 1, v139
	s_mov_b32 s22, 0x3e38aa3b
	v_lshl_add_u64 v[134:135], v[134:135], 0, v[152:153]
	v_pk_mul_f32 v[152:153], v[128:129], s[22:23] op_sel_hi:[1,0]
	v_pk_mul_f32 v[158:159], v[126:127], s[22:23] op_sel_hi:[1,0]
	v_pk_mul_f32 v[160:161], v[124:125], s[22:23] op_sel_hi:[1,0]
	v_pk_mul_f32 v[162:163], v[122:123], s[22:23] op_sel_hi:[1,0]
	v_cvt_pk_bf16_f32 v166, v158, v159
	v_cvt_pk_bf16_f32 v167, v152, v153
	v_cvt_pk_bf16_f32 v168, v162, v163
	v_cvt_pk_bf16_f32 v169, v160, v161
	global_store_dwordx4 v[134:135], v[166:169], off sc1

; __device__ __forceinline__ unsigned short f2bf(float f) { return (unsigned short)(cvt_pk_bf16(f, f) & 0xffffu); }
;   __device__ __forceinline__ void group(int row, int c32, int fq, f32x4 v0, f32x4 v1) const {
;     ...
;     else if (c32 < 1280) { const int cc = c32 - 1024, h = cc >> 6; bf16_t* p = vtd + ((size_t)(b * 4 + h) * 64 + (cc & 63) + fq * 4) * E + e;
; #pragma unroll
;       for (int j = 0; j < 4; ++j) { p[(size_t)j * E] = f2bf(v0[j]); p[(size_t)(j + 16) * E] = f2bf(v1[j]); } }
.LBB0_325:
	s_andn2_b64 vcc, exec, s[38:39]
	s_cbranch_vccnz .LBB0_327
	v_lshl_add_u32 v134, v133, 2, v148
	v_ashrrev_i32_e32 v135, 31, v134
	v_readlane_b32 s22, v254, 10
	v_lshlrev_b64 v[134:135], 6, v[134:135]
	v_readlane_b32 s23, v254, 11
	v_or_b32_e32 v131, v134, v140
	v_lshlrev_b32_e32 v134, 1, v130
	v_mov_b64_e32 v[152:153], s[22:23]
	v_mad_u64_u32 v[152:153], s[22:23], v131, s95, v[152:153]
	v_mad_i32_i24 v153, v135, s95, v153
	v_mov_b32_e32 v135, v1
	v_lshl_add_u64 v[134:135], v[152:153], 0, v[134:135]
	s_mov_b32 s1, 0x40000
	v_cvt_pk_bf16_f32 v131, v126, s0
	v_add_co_u32_e32 v152, vcc, s1, v134
	global_store_short v[134:135], v131, off sc1
	v_cvt_pk_bf16_f32 v131, v122, s0
	v_addc_co_u32_e32 v153, vcc, 0, v135, vcc
	s_movk_i32 s1, 0x4000
	global_store_short v[152:153], v131, off offset:2048 sc1
	v_add_co_u32_e32 v152, vcc, s1, v134
	v_cvt_pk_bf16_f32 v131, v127, s0
	s_nop 0
	v_addc_co_u32_e32 v153, vcc, 0, v135, vcc
	s_mov_b32 s1, 0x44000
	global_store_short v[152:153], v131, off offset:128 sc1
	v_add_co_u32_e32 v152, vcc, s1, v134
	v_cvt_pk_bf16_f32 v131, v123, s0
	s_nop 0
	v_addc_co_u32_e32 v153, vcc, 0, v135, vcc
	s_mov_b32 s1, 0x8000
	global_store_short v[152:153], v131, off offset:2176 sc1
	v_add_co_u32_e32 v152, vcc, s1, v134
	v_cvt_pk_bf16_f32 v131, v128, s0
	s_nop 0
	v_addc_co_u32_e32 v153, vcc, 0, v135, vcc
	s_mov_b32 s1, 0x48000
	global_store_short v[152:153], v131, off offset:256 sc1
	v_add_co_u32_e32 v152, vcc, s1, v134
	v_cvt_pk_bf16_f32 v131, v124, s0
	s_nop 0
	v_addc_co_u32_e32 v153, vcc, 0, v135, vcc
	global_store_short v[152:153], v131, off offset:2304 sc1
	v_add_co_u32_e32 v152, vcc, 0xc000, v134
	v_cvt_pk_bf16_f32 v131, v129, s0
	s_nop 0
	v_addc_co_u32_e32 v153, vcc, 0, v135, vcc
	v_add_co_u32_e32 v134, vcc, 0x4c000, v134
	global_store_short v[152:153], v131, off offset:384 sc1
	v_cvt_pk_bf16_f32 v131, v125, s0
	v_addc_co_u32_e32 v135, vcc, 0, v135, vcc
	global_store_short v[134:135], v131, off offset:2432 sc1

; __device__ __forceinline__ void store8bf(bf16_t* p, f32x4 v0, f32x4 v1) { u32x4 w; w.x = cvt_pk_bf16(v0[0], v0[1]); w.y = cvt_pk_bf16(v0[2], v0[3]); w.z = cvt_pk_bf16(v1[0], v1[1]); w.w = cvt_pk_bf16(v1[2], v1[3]); *(u32x4*)p = w; }
;   __device__ __forceinline__ void group(int row, int c32, int fq, f32x4 v0, f32x4 v1) const {
;     ...
;     else if (c32 < 1024) { const int cc = c32 - 768, h = cc >> 6; store8bf(kd + ((size_t)(b * 4 + h) * E + e) * 64 + (cc & 63) + fq * 8, v0, v1); }
.LBB0_328:
	s_andn2_b64 vcc, exec, s[38:39]
	s_cbranch_vccnz .LBB0_330
	v_lshl_add_u32 v134, v133, 2, v147
	v_mov_b32_e32 v131, v1
	s_movk_i32 s1, 0x2040
	v_mad_i64_i32 v[134:135], s[22:23], v134, s1, v[130:131]
	v_readlane_b32 s22, v254, 8
	v_lshlrev_b64 v[134:135], 7, v[134:135]
	v_readlane_b32 s23, v254, 9
	v_lshlrev_b32_e32 v152, 1, v137
	v_mov_b32_e32 v153, v1
	v_lshl_add_u64 v[134:135], s[22:23], 0, v[134:135]
	v_lshl_add_u64 v[134:135], v[134:135], 0, v[152:153]
	v_lshlrev_b32_e32 v152, 1, v139
	v_lshl_add_u64 v[134:135], v[134:135], 0, v[152:153]
	v_cvt_pk_bf16_f32 v166, v126, v127
	v_cvt_pk_bf16_f32 v167, v128, v129
	v_cvt_pk_bf16_f32 v168, v122, v123
	v_cvt_pk_bf16_f32 v169, v124, v125
	global_store_dwordx4 v[134:135], v[166:169], off sc1

; __device__ __forceinline__ void store8bf(bf16_t* p, f32x4 v0, f32x4 v1) { u32x4 w; w.x = cvt_pk_bf16(v0[0], v0[1]); w.y = cvt_pk_bf16(v0[2], v0[3]); w.z = cvt_pk_bf16(v1[0], v1[1]); w.w = cvt_pk_bf16(v1[2], v1[3]); *(u32x4*)p = w; }
;   __device__ __forceinline__ void group(int row, int c32, int fq, f32x4 v0, f32x4 v1) const {
;     ...
;     if (c32 < 768) { const int cc = c32 - 512, h = cc >> 6; store8bf(qd + ((size_t)(b * 4 + h) * E + e) * 64 + (cc & 63) + fq * 8, v0 * QSC_D, v1 * QSC_D); }
.LBB0_331:
	s_andn2_b64 vcc, exec, s[38:39]
	s_cbranch_vccnz .LBB0_333
	v_lshl_add_u32 v133, v133, 2, v146
	v_mov_b32_e32 v131, v1
	s_movk_i32 s1, 0x2040
	v_mad_i64_i32 v[130:131], s[22:23], v133, s1, v[130:131]
	v_readlane_b32 s22, v254, 6
	v_lshlrev_b64 v[130:131], 7, v[130:131]
	v_readlane_b32 s23, v254, 7
	v_lshlrev_b32_e32 v134, 1, v137
	v_mov_b32_e32 v135, v1
	v_lshl_add_u64 v[130:131], s[22:23], 0, v[130:131]
	v_lshl_add_u64 v[130:131], v[130:131], 0, v[134:135]
	v_lshlrev_b32_e32 v134, 1, v139
	s_mov_b32 s22, 0x3e8293ee
	v_lshl_add_u64 v[130:131], v[130:131], 0, v[134:135]
	v_pk_mul_f32 v[134:135], v[128:129], s[22:23] op_sel_hi:[1,0]
	v_pk_mul_f32 v[152:153], v[126:127], s[22:23] op_sel_hi:[1,0]
	v_pk_mul_f32 v[158:159], v[124:125], s[22:23] op_sel_hi:[1,0]
	v_pk_mul_f32 v[160:161], v[122:123], s[22:23] op_sel_hi:[1,0]
	v_cvt_pk_bf16_f32 v166, v152, v153
	v_cvt_pk_bf16_f32 v167, v134, v135
	v_cvt_pk_bf16_f32 v168, v160, v161
	v_cvt_pk_bf16_f32 v169, v158, v159
	global_store_dwordx4 v[130:131], v[166:169], off sc1

; __device__ __forceinline__ unsigned short f2bf(float f) { return (unsigned short)(cvt_pk_bf16(f, f) & 0xffffu); }
;   __device__ __forceinline__ void group(int row, int c32, int fq, f32x4 v0, f32x4 v1) const { e->group(row, c32 + sh, fq, v0, v1); }
;     ...
;           for (int m = 0; m < 4; ++m) epi.group(row0 + m * 16 + fr, c32, fq, acc[ai][bj][m][0], acc[ai][bj][m][1]);
;   __device__ __forceinline__ void group(int row, int c32, int fq, f32x4 v0, f32x4 v1) const {
;     int b, e; const bool ok = row_be(row, b, e);
;     if (c32 < 512) {
;       if (c32 < 384) store8bf(cqkv + (size_t)row * 512 + c32 + fq * 8, v0, v1);
;       else { bf16_t* p = cqkv + (size_t)row * 512 + c32 + fq * 4; store4bf(p, v0); store4bf(p + 16, v1); }
;       if (c32 == 384 && ok) {
;         const float2* rp = rope + pos_of_e(e) * 16 + fq * 4; f32x4 o0, o1;
; #pragma unroll
;         for (int j = 0; j < 4; ++j) { const float2 cs = rp[j]; o0[j] = v0[j] * cs.x - v1[j] * cs.y; o1[j] = v1[j] * cs.x + v0[j] * cs.y; }
; #pragma unroll
;         for (int h = 0; h < 6; ++h) { bf16_t* q = ka + ((size_t)(b * 6 + h) * E + e) * 96 + 64 + fq * 4; store4bf(q, o0); store4bf(q + 16, o1); }
;       }
;       return;
;     }
;     if (!ok) return;
;     if (c32 < 768) { const int cc = c32 - 512, h = cc >> 6; store8bf(qd + ((size_t)(b * 4 + h) * E + e) * 64 + (cc & 63) + fq * 8, v0 * QSC_D, v1 * QSC_D); }
;     else if (c32 < 1024) { const int cc = c32 - 768, h = cc >> 6; store8bf(kd + ((size_t)(b * 4 + h) * E + e) * 64 + (cc & 63) + fq * 8, v0, v1); }
;     else if (c32 < 1280) { const int cc = c32 - 1024, h = cc >> 6; bf16_t* p = vtd + ((size_t)(b * 4 + h) * 64 + (cc & 63) + fq * 4) * E + e;
; #pragma unroll
;       for (int j = 0; j < 4; ++j) { p[(size_t)j * E] = f2bf(v0[j]); p[(size_t)(j + 16) * E] = f2bf(v1[j]); } }
;     else if (c32 < 1664) { const int cc = c32 - 1280, h = cc >> 6; store8bf(qs + ((size_t)(b * 6 + h) * E + e) * 64 + (cc & 63) + fq * 8, v0 * QSC_S, v1 * QSC_S); }
;     else if (c32 < 1792) { const int cc = c32 - 1664, g = cc >> 6; store8bf(ks + ((size_t)(b * 2 + g) * E + e) * 64 + (cc & 63) + fq * 8, v0, v1); }
;     else if (c32 < 1920) { const int cc = c32 - 1792, g = cc >> 6; bf16_t* p = vts + ((size_t)(b * 2 + g) * 64 + (cc & 63) + fq * 4) * E + e;
; #pragma unroll
;       for (int j = 0; j < 4; ++j) { p[(size_t)j * E] = f2bf(v0[j]); p[(size_t)(j + 16) * E] = f2bf(v1[j]); } }
.LBB0_334:
	s_andn2_b64 vcc, exec, s[8:9]
	s_cbranch_vccnz .LBB0_336
	v_ashrrev_i32_e32 v133, 31, v132
	v_readlane_b32 s8, v254, 0
	v_lshlrev_b64 v[130:131], 10, v[132:133]
	v_readlane_b32 s9, v254, 1
	v_lshlrev_b32_e32 v134, 1, v139
	v_mov_b32_e32 v135, v1
	v_lshl_add_u64 v[130:131], s[8:9], 0, v[130:131]
	v_lshl_add_u64 v[130:131], v[0:1], 1, v[130:131]
	v_cvt_pk_bf16_f32 v166, v126, v127
	v_cvt_pk_bf16_f32 v167, v128, v129
	v_lshl_add_u64 v[130:131], v[130:131], 0, v[134:135]
	v_cvt_pk_bf16_f32 v168, v122, v123
	v_cvt_pk_bf16_f32 v169, v124, v125
	global_store_dwordx4 v[130:131], v[166:169], off sc1
.LBB0_336:
	v_cndmask_b32_e64 v131, 0, 1, s[10:11]
	v_or_b32_e32 v130, 16, v132
	v_cmp_ne_u32_e64 s[8:9], 1, v131
	s_andn2_b64 vcc, exec, s[10:11]
	s_mov_b64 s[10:11], -1
	s_cbranch_vccnz .LBB0_394
	s_mov_b32 s1, 0x8000
	v_cmp_gt_i32_e32 vcc, s1, v130
	v_cmp_gt_u32_e64 s[10:11], s49, v144
	s_or_b64 s[22:23], vcc, s[10:11]
	s_and_saveexec_b64 s[10:11], s[22:23]
	s_cbranch_execz .LBB0_354
	v_and_b32_e32 v131, 0x1fdf, v130
	v_add_u32_e32 v133, 64, v131
	v_cndmask_b32_e32 v131, 1, v145, vcc
	v_cndmask_b32_e32 v134, v136, v133, vcc
	s_andn2_b64 vcc, exec, s[24:25]
	s_mov_b64 s[38:39], -1
	s_cbranch_vccnz .LBB0_352
	s_andn2_b64 vcc, exec, s[18:19]
	s_cbranch_vccnz .LBB0_349
	s_andn2_b64 vcc, exec, s[16:17]
	s_cbranch_vccnz .LBB0_346
	s_andn2_b64 vcc, exec, s[14:15]
	s_cbranch_vccnz .LBB0_343
	v_lshl_add_u32 v152, v131, 1, v150
	v_ashrrev_i32_e32 v153, 31, v152
	v_readlane_b32 s22, v254, 16
	v_lshlrev_b64 v[152:153], 6, v[152:153]
	v_readlane_b32 s23, v254, 17
	v_or_b32_e32 v133, v152, v140
	v_lshlrev_b32_e32 v152, 1, v134
	v_mov_b64_e32 v[158:159], s[22:23]
	v_mad_u64_u32 v[158:159], s[22:23], v133, s95, v[158:159]
	v_mad_i32_i24 v159, v153, s95, v159
	v_mov_b32_e32 v153, v1
	v_lshl_add_u64 v[152:153], v[158:159], 0, v[152:153]
	s_mov_b32 s1, 0x40000
	v_cvt_pk_bf16_f32 v133, v118, s0
	v_add_co_u32_e32 v158, vcc, s1, v152
	global_store_short v[152:153], v133, off sc1
	v_cvt_pk_bf16_f32 v133, v114, s0
	v_addc_co_u32_e32 v159, vcc, 0, v153, vcc
	s_movk_i32 s1, 0x4000
	global_store_short v[158:159], v133, off offset:2048 sc1
	v_add_co_u32_e32 v158, vcc, s1, v152
	v_cvt_pk_bf16_f32 v133, v119, s0
	s_nop 0
	v_addc_co_u32_e32 v159, vcc, 0, v153, vcc
	s_mov_b32 s1, 0x44000
	global_store_short v[158:159], v133, off offset:128 sc1
	v_add_co_u32_e32 v158, vcc, s1, v152
	v_cvt_pk_bf16_f32 v133, v115, s0
	s_nop 0
	v_addc_co_u32_e32 v159, vcc, 0, v153, vcc
	s_mov_b32 s1, 0x8000
	global_store_short v[158:159], v133, off offset:2176 sc1
	v_add_co_u32_e32 v158, vcc, s1, v152
	v_cvt_pk_bf16_f32 v133, v120, s0
	s_nop 0
	v_addc_co_u32_e32 v159, vcc, 0, v153, vcc
	s_mov_b32 s1, 0x48000
	global_store_short v[158:159], v133, off offset:256 sc1
	v_add_co_u32_e32 v158, vcc, s1, v152
	v_cvt_pk_bf16_f32 v133, v116, s0
	s_nop 0
	v_addc_co_u32_e32 v159, vcc, 0, v153, vcc
	global_store_short v[158:159], v133, off offset:2304 sc1
	v_add_co_u32_e32 v158, vcc, 0xc000, v152
	v_cvt_pk_bf16_f32 v133, v121, s0
	s_nop 0
	v_addc_co_u32_e32 v159, vcc, 0, v153, vcc
	v_add_co_u32_e32 v152, vcc, 0x4c000, v152
	global_store_short v[158:159], v133, off offset:384 sc1
	v_cvt_pk_bf16_f32 v133, v117, s0
	v_addc_co_u32_e32 v153, vcc, 0, v153, vcc
	s_mov_b64 s[38:39], 0
	global_store_short v[152:153], v133, off offset:2432 sc1
.LBB0_343:
	s_andn2_b64 vcc, exec, s[38:39]
	s_cbranch_vccnz .LBB0_345
	v_mad_i32_i24 v133, v131, 6, v149
	v_mov_b32_e32 v135, v1
	s_movk_i32 s1, 0x2040
	v_mad_i64_i32 v[152:153], s[22:23], v133, s1, v[134:135]
	v_readlane_b32 s22, v254, 12
	v_lshlrev_b64 v[152:153], 7, v[152:153]
	v_readlane_b32 s23, v254, 13
	v_lshlrev_b32_e32 v158, 1, v137
	v_mov_b32_e32 v159, v1
	v_lshl_add_u64 v[152:153], s[22:23], 0, v[152:153]
	v_lshl_add_u64 v[152:153], v[152:153], 0, v[158:159]
	v_lshlrev_b32_e32 v158, 1, v139
	s_mov_b32 s22, 0x3e38aa3b
	v_lshl_add_u64 v[152:153], v[152:153], 0, v[158:159]
	v_pk_mul_f32 v[158:159], v[120:121], s[22:23] op_sel_hi:[1,0]
	v_pk_mul_f32 v[160:161], v[118:119], s[22:23] op_sel_hi:[1,0]
	v_pk_mul_f32 v[162:163], v[116:117], s[22:23] op_sel_hi:[1,0]
	v_pk_mul_f32 v[164:165], v[114:115], s[22:23] op_sel_hi:[1,0]
	v_cvt_pk_bf16_f32 v166, v160, v161
	v_cvt_pk_bf16_f32 v167, v158, v159
	v_cvt_pk_bf16_f32 v168, v164, v165
	v_cvt_pk_bf16_f32 v169, v162, v163
	global_store_dwordx4 v[152:153], v[166:169], off sc1

; __device__ __forceinline__ unsigned short f2bf(float f) { return (unsigned short)(cvt_pk_bf16(f, f) & 0xffffu); }
;   __device__ __forceinline__ void group(int row, int c32, int fq, f32x4 v0, f32x4 v1) const {
;     ...
;     else if (c32 < 1280) { const int cc = c32 - 1024, h = cc >> 6; bf16_t* p = vtd + ((size_t)(b * 4 + h) * 64 + (cc & 63) + fq * 4) * E + e;
; #pragma unroll
;       for (int j = 0; j < 4; ++j) { p[(size_t)j * E] = f2bf(v0[j]); p[(size_t)(j + 16) * E] = f2bf(v1[j]); } }
.LBB0_346:
	s_andn2_b64 vcc, exec, s[38:39]
	s_cbranch_vccnz .LBB0_348
	v_lshl_add_u32 v152, v131, 2, v148
	v_ashrrev_i32_e32 v153, 31, v152
	v_readlane_b32 s22, v254, 10
	v_lshlrev_b64 v[152:153], 6, v[152:153]
	v_readlane_b32 s23, v254, 11
	v_or_b32_e32 v133, v152, v140
	v_lshlrev_b32_e32 v152, 1, v134
	v_mov_b64_e32 v[158:159], s[22:23]
	v_mad_u64_u32 v[158:159], s[22:23], v133, s95, v[158:159]
	v_mad_i32_i24 v159, v153, s95, v159
	v_mov_b32_e32 v153, v1
	v_lshl_add_u64 v[152:153], v[158:159], 0, v[152:153]
	s_mov_b32 s1, 0x40000
	v_cvt_pk_bf16_f32 v133, v118, s0
	v_add_co_u32_e32 v158, vcc, s1, v152
	global_store_short v[152:153], v133, off sc1
	v_cvt_pk_bf16_f32 v133, v114, s0
	v_addc_co_u32_e32 v159, vcc, 0, v153, vcc
	s_movk_i32 s1, 0x4000
	global_store_short v[158:159], v133, off offset:2048 sc1
	v_add_co_u32_e32 v158, vcc, s1, v152
	v_cvt_pk_bf16_f32 v133, v119, s0
	s_nop 0
	v_addc_co_u32_e32 v159, vcc, 0, v153, vcc
	s_mov_b32 s1, 0x44000
	global_store_short v[158:159], v133, off offset:128 sc1
	v_add_co_u32_e32 v158, vcc, s1, v152
	v_cvt_pk_bf16_f32 v133, v115, s0
	s_nop 0
	v_addc_co_u32_e32 v159, vcc, 0, v153, vcc
	s_mov_b32 s1, 0x8000
	global_store_short v[158:159], v133, off offset:2176 sc1
	v_add_co_u32_e32 v158, vcc, s1, v152
	v_cvt_pk_bf16_f32 v133, v120, s0
	s_nop 0
	v_addc_co_u32_e32 v159, vcc, 0, v153, vcc
	s_mov_b32 s1, 0x48000
	global_store_short v[158:159], v133, off offset:256 sc1
	v_add_co_u32_e32 v158, vcc, s1, v152
	v_cvt_pk_bf16_f32 v133, v116, s0
	s_nop 0
	v_addc_co_u32_e32 v159, vcc, 0, v153, vcc
	global_store_short v[158:159], v133, off offset:2304 sc1
	v_add_co_u32_e32 v158, vcc, 0xc000, v152
	v_cvt_pk_bf16_f32 v133, v121, s0
	s_nop 0
	v_addc_co_u32_e32 v159, vcc, 0, v153, vcc
	v_add_co_u32_e32 v152, vcc, 0x4c000, v152
	global_store_short v[158:159], v133, off offset:384 sc1
	v_cvt_pk_bf16_f32 v133, v117, s0
	v_addc_co_u32_e32 v153, vcc, 0, v153, vcc
	global_store_short v[152:153], v133, off offset:2432 sc1

; __device__ __forceinline__ void store8bf(bf16_t* p, f32x4 v0, f32x4 v1) { u32x4 w; w.x = cvt_pk_bf16(v0[0], v0[1]); w.y = cvt_pk_bf16(v0[2], v0[3]); w.z = cvt_pk_bf16(v1[0], v1[1]); w.w = cvt_pk_bf16(v1[2], v1[3]); *(u32x4*)p = w; }
;   __device__ __forceinline__ void group(int row, int c32, int fq, f32x4 v0, f32x4 v1) const {
;     ...
;     else if (c32 < 1024) { const int cc = c32 - 768, h = cc >> 6; store8bf(kd + ((size_t)(b * 4 + h) * E + e) * 64 + (cc & 63) + fq * 8, v0, v1); }
.LBB0_349:
	s_andn2_b64 vcc, exec, s[38:39]
	s_cbranch_vccnz .LBB0_351
	v_lshl_add_u32 v133, v131, 2, v147
	v_mov_b32_e32 v135, v1
	s_movk_i32 s1, 0x2040
	v_mad_i64_i32 v[152:153], s[22:23], v133, s1, v[134:135]
	v_readlane_b32 s22, v254, 8
	v_lshlrev_b64 v[152:153], 7, v[152:153]
	v_readlane_b32 s23, v254, 9
	v_lshlrev_b32_e32 v158, 1, v137
	v_mov_b32_e32 v159, v1
	v_lshl_add_u64 v[152:153], s[22:23], 0, v[152:153]
	v_lshl_add_u64 v[152:153], v[152:153], 0, v[158:159]
	v_lshlrev_b32_e32 v158, 1, v139
	v_lshl_add_u64 v[152:153], v[152:153], 0, v[158:159]
	v_cvt_pk_bf16_f32 v166, v118, v119
	v_cvt_pk_bf16_f32 v167, v120, v121
	v_cvt_pk_bf16_f32 v168, v114, v115
	v_cvt_pk_bf16_f32 v169, v116, v117
	global_store_dwordx4 v[152:153], v[166:169], off sc1

; __device__ __forceinline__ void store8bf(bf16_t* p, f32x4 v0, f32x4 v1) { u32x4 w; w.x = cvt_pk_bf16(v0[0], v0[1]); w.y = cvt_pk_bf16(v0[2], v0[3]); w.z = cvt_pk_bf16(v1[0], v1[1]); w.w = cvt_pk_bf16(v1[2], v1[3]); *(u32x4*)p = w; }
;   __device__ __forceinline__ void group(int row, int c32, int fq, f32x4 v0, f32x4 v1) const {
;     ...
;     if (c32 < 768) { const int cc = c32 - 512, h = cc >> 6; store8bf(qd + ((size_t)(b * 4 + h) * E + e) * 64 + (cc & 63) + fq * 8, v0 * QSC_D, v1 * QSC_D); }
.LBB0_352:
	s_andn2_b64 vcc, exec, s[38:39]
	s_cbranch_vccnz .LBB0_354
	v_lshl_add_u32 v131, v131, 2, v146
	v_mov_b32_e32 v135, v1
	s_movk_i32 s1, 0x2040
	v_mad_i64_i32 v[134:135], s[22:23], v131, s1, v[134:135]
	v_readlane_b32 s22, v254, 6
	v_lshlrev_b64 v[134:135], 7, v[134:135]
	v_readlane_b32 s23, v254, 7
	v_lshlrev_b32_e32 v152, 1, v137
	v_mov_b32_e32 v153, v1
	v_lshl_add_u64 v[134:135], s[22:23], 0, v[134:135]
	v_lshl_add_u64 v[134:135], v[134:135], 0, v[152:153]
	v_lshlrev_b32_e32 v152, 1, v139
	s_mov_b32 s22, 0x3e8293ee
	v_lshl_add_u64 v[134:135], v[134:135], 0, v[152:153]
	v_pk_mul_f32 v[152:153], v[120:121], s[22:23] op_sel_hi:[1,0]
	v_pk_mul_f32 v[158:159], v[118:119], s[22:23] op_sel_hi:[1,0]
	v_pk_mul_f32 v[160:161], v[116:117], s[22:23] op_sel_hi:[1,0]
	v_pk_mul_f32 v[162:163], v[114:115], s[22:23] op_sel_hi:[1,0]
	v_cvt_pk_bf16_f32 v166, v158, v159
	v_cvt_pk_bf16_f32 v167, v152, v153
	v_cvt_pk_bf16_f32 v168, v162, v163
	v_cvt_pk_bf16_f32 v169, v160, v161
	global_store_dwordx4 v[134:135], v[166:169], off sc1

; __device__ __forceinline__ unsigned short f2bf(float f) { return (unsigned short)(cvt_pk_bf16(f, f) & 0xffffu); }
;   __device__ __forceinline__ void group(int row, int c32, int fq, f32x4 v0, f32x4 v1) const { e->group(row, c32 + sh, fq, v0, v1); }
;     ...
;           for (int m = 0; m < 4; ++m) epi.group(row0 + m * 16 + fr, c32, fq, acc[ai][bj][m][0], acc[ai][bj][m][1]);
;   __device__ __forceinline__ void group(int row, int c32, int fq, f32x4 v0, f32x4 v1) const {
;     int b, e; const bool ok = row_be(row, b, e);
;     if (c32 < 512) {
;       if (c32 < 384) store8bf(cqkv + (size_t)row * 512 + c32 + fq * 8, v0, v1);
;       else { bf16_t* p = cqkv + (size_t)row * 512 + c32 + fq * 4; store4bf(p, v0); store4bf(p + 16, v1); }
;       if (c32 == 384 && ok) {
;         const float2* rp = rope + pos_of_e(e) * 16 + fq * 4; f32x4 o0, o1;
; #pragma unroll
;         for (int j = 0; j < 4; ++j) { const float2 cs = rp[j]; o0[j] = v0[j] * cs.x - v1[j] * cs.y; o1[j] = v1[j] * cs.x + v0[j] * cs.y; }
; #pragma unroll
;         for (int h = 0; h < 6; ++h) { bf16_t* q = ka + ((size_t)(b * 6 + h) * E + e) * 96 + 64 + fq * 4; store4bf(q, o0); store4bf(q + 16, o1); }
;       }
;       return;
;     }
;     if (!ok) return;
;     if (c32 < 768) { const int cc = c32 - 512, h = cc >> 6; store8bf(qd + ((size_t)(b * 4 + h) * E + e) * 64 + (cc & 63) + fq * 8, v0 * QSC_D, v1 * QSC_D); }
;     else if (c32 < 1024) { const int cc = c32 - 768, h = cc >> 6; store8bf(kd + ((size_t)(b * 4 + h) * E + e) * 64 + (cc & 63) + fq * 8, v0, v1); }
;     else if (c32 < 1280) { const int cc = c32 - 1024, h = cc >> 6; bf16_t* p = vtd + ((size_t)(b * 4 + h) * 64 + (cc & 63) + fq * 4) * E + e;
; #pragma unroll
;       for (int j = 0; j < 4; ++j) { p[(size_t)j * E] = f2bf(v0[j]); p[(size_t)(j + 16) * E] = f2bf(v1[j]); } }
;     else if (c32 < 1664) { const int cc = c32 - 1280, h = cc >> 6; store8bf(qs + ((size_t)(b * 6 + h) * E + e) * 64 + (cc & 63) + fq * 8, v0 * QSC_S, v1 * QSC_S); }
;     else if (c32 < 1792) { const int cc = c32 - 1664, g = cc >> 6; store8bf(ks + ((size_t)(b * 2 + g) * E + e) * 64 + (cc & 63) + fq * 8, v0, v1); }
;     else if (c32 < 1920) { const int cc = c32 - 1792, g = cc >> 6; bf16_t* p = vts + ((size_t)(b * 2 + g) * 64 + (cc & 63) + fq * 4) * E + e;
; #pragma unroll
;       for (int j = 0; j < 4; ++j) { p[(size_t)j * E] = f2bf(v0[j]); p[(size_t)(j + 16) * E] = f2bf(v1[j]); } }
.LBB0_356:
	s_mov_b32 s1, 0x8000
	v_cmp_gt_i32_e32 vcc, s1, v130
	v_cmp_gt_u32_e64 s[10:11], s49, v144
	s_or_b64 s[22:23], vcc, s[10:11]
	s_and_saveexec_b64 s[10:11], s[22:23]
	s_cbranch_execz .LBB0_373
	v_and_b32_e32 v131, 0x1fef, v130
	v_add_u32_e32 v133, 64, v131
	v_cndmask_b32_e32 v131, 2, v145, vcc
	v_cndmask_b32_e32 v134, v136, v133, vcc
	s_andn2_b64 vcc, exec, s[24:25]
	s_mov_b64 s[38:39], -1
	s_cbranch_vccnz .LBB0_371
	s_andn2_b64 vcc, exec, s[18:19]
	s_cbranch_vccnz .LBB0_368
	s_andn2_b64 vcc, exec, s[16:17]
	s_cbranch_vccnz .LBB0_365
	s_andn2_b64 vcc, exec, s[14:15]
	s_cbranch_vccnz .LBB0_362
	v_lshl_add_u32 v152, v131, 1, v150
	v_ashrrev_i32_e32 v153, 31, v152
	v_readlane_b32 s22, v254, 16
	v_lshlrev_b64 v[152:153], 6, v[152:153]
	v_readlane_b32 s23, v254, 17
	v_or_b32_e32 v133, v152, v140
	v_lshlrev_b32_e32 v152, 1, v134
	v_mov_b64_e32 v[158:159], s[22:23]
	v_mad_u64_u32 v[158:159], s[22:23], v133, s95, v[158:159]
	v_mad_i32_i24 v159, v153, s95, v159
	v_mov_b32_e32 v153, v1
	v_lshl_add_u64 v[152:153], v[158:159], 0, v[152:153]
	s_mov_b32 s1, 0x40000
	v_cvt_pk_bf16_f32 v133, v110, s0
	v_add_co_u32_e32 v158, vcc, s1, v152
	global_store_short v[152:153], v133, off sc1
	v_cvt_pk_bf16_f32 v133, v106, s0
	v_addc_co_u32_e32 v159, vcc, 0, v153, vcc
	s_movk_i32 s1, 0x4000
	global_store_short v[158:159], v133, off offset:2048 sc1
	v_add_co_u32_e32 v158, vcc, s1, v152
	v_cvt_pk_bf16_f32 v133, v111, s0
	s_nop 0
	v_addc_co_u32_e32 v159, vcc, 0, v153, vcc
	s_mov_b32 s1, 0x44000
	global_store_short v[158:159], v133, off offset:128 sc1
	v_add_co_u32_e32 v158, vcc, s1, v152
	v_cvt_pk_bf16_f32 v133, v107, s0
	s_nop 0
	v_addc_co_u32_e32 v159, vcc, 0, v153, vcc
	s_mov_b32 s1, 0x8000
	global_store_short v[158:159], v133, off offset:2176 sc1
	v_add_co_u32_e32 v158, vcc, s1, v152
	v_cvt_pk_bf16_f32 v133, v112, s0
	s_nop 0
	v_addc_co_u32_e32 v159, vcc, 0, v153, vcc
	s_mov_b32 s1, 0x48000
	global_store_short v[158:159], v133, off offset:256 sc1
	v_add_co_u32_e32 v158, vcc, s1, v152
	v_cvt_pk_bf16_f32 v133, v108, s0
	s_nop 0
	v_addc_co_u32_e32 v159, vcc, 0, v153, vcc
	global_store_short v[158:159], v133, off offset:2304 sc1
	v_add_co_u32_e32 v158, vcc, 0xc000, v152
	v_cvt_pk_bf16_f32 v133, v113, s0
	s_nop 0
	v_addc_co_u32_e32 v159, vcc, 0, v153, vcc
	v_add_co_u32_e32 v152, vcc, 0x4c000, v152
	global_store_short v[158:159], v133, off offset:384 sc1
	v_cvt_pk_bf16_f32 v133, v109, s0
	v_addc_co_u32_e32 v153, vcc, 0, v153, vcc
	s_mov_b64 s[38:39], 0
	global_store_short v[152:153], v133, off offset:2432 sc1
.LBB0_362:
	s_andn2_b64 vcc, exec, s[38:39]
	s_cbranch_vccnz .LBB0_364
	v_mad_i32_i24 v133, v131, 6, v149
	v_mov_b32_e32 v135, v1
	s_movk_i32 s1, 0x2040
	v_mad_i64_i32 v[152:153], s[22:23], v133, s1, v[134:135]
	v_readlane_b32 s22, v254, 12
	v_lshlrev_b64 v[152:153], 7, v[152:153]
	v_readlane_b32 s23, v254, 13
	v_lshlrev_b32_e32 v158, 1, v137
	v_mov_b32_e32 v159, v1
	v_lshl_add_u64 v[152:153], s[22:23], 0, v[152:153]
	v_lshl_add_u64 v[152:153], v[152:153], 0, v[158:159]
	v_lshlrev_b32_e32 v158, 1, v139
	s_mov_b32 s22, 0x3e38aa3b
	v_lshl_add_u64 v[152:153], v[152:153], 0, v[158:159]
	v_pk_mul_f32 v[158:159], v[112:113], s[22:23] op_sel_hi:[1,0]
	v_pk_mul_f32 v[160:161], v[110:111], s[22:23] op_sel_hi:[1,0]
	v_pk_mul_f32 v[162:163], v[108:109], s[22:23] op_sel_hi:[1,0]
	v_pk_mul_f32 v[164:165], v[106:107], s[22:23] op_sel_hi:[1,0]
	v_cvt_pk_bf16_f32 v166, v160, v161
	v_cvt_pk_bf16_f32 v167, v158, v159
	v_cvt_pk_bf16_f32 v168, v164, v165
	v_cvt_pk_bf16_f32 v169, v162, v163
	global_store_dwordx4 v[152:153], v[166:169], off sc1

; __device__ __forceinline__ unsigned short f2bf(float f) { return (unsigned short)(cvt_pk_bf16(f, f) & 0xffffu); }
;   __device__ __forceinline__ void group(int row, int c32, int fq, f32x4 v0, f32x4 v1) const {
;     ...
;     else if (c32 < 1280) { const int cc = c32 - 1024, h = cc >> 6; bf16_t* p = vtd + ((size_t)(b * 4 + h) * 64 + (cc & 63) + fq * 4) * E + e;
; #pragma unroll
;       for (int j = 0; j < 4; ++j) { p[(size_t)j * E] = f2bf(v0[j]); p[(size_t)(j + 16) * E] = f2bf(v1[j]); } }
.LBB0_365:
	s_andn2_b64 vcc, exec, s[38:39]
	s_cbranch_vccnz .LBB0_367
	v_lshl_add_u32 v152, v131, 2, v148
	v_ashrrev_i32_e32 v153, 31, v152
	v_readlane_b32 s22, v254, 10
	v_lshlrev_b64 v[152:153], 6, v[152:153]
	v_readlane_b32 s23, v254, 11
	v_or_b32_e32 v133, v152, v140
	v_lshlrev_b32_e32 v152, 1, v134
	v_mov_b64_e32 v[158:159], s[22:23]
	v_mad_u64_u32 v[158:159], s[22:23], v133, s95, v[158:159]
	v_mad_i32_i24 v159, v153, s95, v159
	v_mov_b32_e32 v153, v1
	v_lshl_add_u64 v[152:153], v[158:159], 0, v[152:153]
	s_mov_b32 s1, 0x40000
	v_cvt_pk_bf16_f32 v133, v110, s0
	v_add_co_u32_e32 v158, vcc, s1, v152
	global_store_short v[152:153], v133, off sc1
	v_cvt_pk_bf16_f32 v133, v106, s0
	v_addc_co_u32_e32 v159, vcc, 0, v153, vcc
	s_movk_i32 s1, 0x4000
	global_store_short v[158:159], v133, off offset:2048 sc1
	v_add_co_u32_e32 v158, vcc, s1, v152
	v_cvt_pk_bf16_f32 v133, v111, s0
	s_nop 0
	v_addc_co_u32_e32 v159, vcc, 0, v153, vcc
	s_mov_b32 s1, 0x44000
	global_store_short v[158:159], v133, off offset:128 sc1
	v_add_co_u32_e32 v158, vcc, s1, v152
	v_cvt_pk_bf16_f32 v133, v107, s0
	s_nop 0
	v_addc_co_u32_e32 v159, vcc, 0, v153, vcc
	s_mov_b32 s1, 0x8000
	global_store_short v[158:159], v133, off offset:2176 sc1
	v_add_co_u32_e32 v158, vcc, s1, v152
	v_cvt_pk_bf16_f32 v133, v112, s0
	s_nop 0
	v_addc_co_u32_e32 v159, vcc, 0, v153, vcc
	s_mov_b32 s1, 0x48000
	global_store_short v[158:159], v133, off offset:256 sc1
	v_add_co_u32_e32 v158, vcc, s1, v152
	v_cvt_pk_bf16_f32 v133, v108, s0
	s_nop 0
	v_addc_co_u32_e32 v159, vcc, 0, v153, vcc
	global_store_short v[158:159], v133, off offset:2304 sc1
	v_add_co_u32_e32 v158, vcc, 0xc000, v152
	v_cvt_pk_bf16_f32 v133, v113, s0
	s_nop 0
	v_addc_co_u32_e32 v159, vcc, 0, v153, vcc
	v_add_co_u32_e32 v152, vcc, 0x4c000, v152
	global_store_short v[158:159], v133, off offset:384 sc1
	v_cvt_pk_bf16_f32 v133, v109, s0
	v_addc_co_u32_e32 v153, vcc, 0, v153, vcc
	global_store_short v[152:153], v133, off offset:2432 sc1

; __device__ __forceinline__ void store8bf(bf16_t* p, f32x4 v0, f32x4 v1) { u32x4 w; w.x = cvt_pk_bf16(v0[0], v0[1]); w.y = cvt_pk_bf16(v0[2], v0[3]); w.z = cvt_pk_bf16(v1[0], v1[1]); w.w = cvt_pk_bf16(v1[2], v1[3]); *(u32x4*)p = w; }
;   __device__ __forceinline__ void group(int row, int c32, int fq, f32x4 v0, f32x4 v1) const {
;     ...
;     else if (c32 < 1024) { const int cc = c32 - 768, h = cc >> 6; store8bf(kd + ((size_t)(b * 4 + h) * E + e) * 64 + (cc & 63) + fq * 8, v0, v1); }
.LBB0_368:
	s_andn2_b64 vcc, exec, s[38:39]
	s_cbranch_vccnz .LBB0_370
	v_lshl_add_u32 v133, v131, 2, v147
	v_mov_b32_e32 v135, v1
	s_movk_i32 s1, 0x2040
	v_mad_i64_i32 v[152:153], s[22:23], v133, s1, v[134:135]
	v_readlane_b32 s22, v254, 8
	v_lshlrev_b64 v[152:153], 7, v[152:153]
	v_readlane_b32 s23, v254, 9
	v_lshlrev_b32_e32 v158, 1, v137
	v_mov_b32_e32 v159, v1
	v_lshl_add_u64 v[152:153], s[22:23], 0, v[152:153]
	v_lshl_add_u64 v[152:153], v[152:153], 0, v[158:159]
	v_lshlrev_b32_e32 v158, 1, v139
	v_lshl_add_u64 v[152:153], v[152:153], 0, v[158:159]
	v_cvt_pk_bf16_f32 v166, v110, v111
	v_cvt_pk_bf16_f32 v167, v112, v113
	v_cvt_pk_bf16_f32 v168, v106, v107
	v_cvt_pk_bf16_f32 v169, v108, v109
	global_store_dwordx4 v[152:153], v[166:169], off sc1

; __device__ __forceinline__ void store8bf(bf16_t* p, f32x4 v0, f32x4 v1) { u32x4 w; w.x = cvt_pk_bf16(v0[0], v0[1]); w.y = cvt_pk_bf16(v0[2], v0[3]); w.z = cvt_pk_bf16(v1[0], v1[1]); w.w = cvt_pk_bf16(v1[2], v1[3]); *(u32x4*)p = w; }
;   __device__ __forceinline__ void group(int row, int c32, int fq, f32x4 v0, f32x4 v1) const {
;     ...
;     if (c32 < 768) { const int cc = c32 - 512, h = cc >> 6; store8bf(qd + ((size_t)(b * 4 + h) * E + e) * 64 + (cc & 63) + fq * 8, v0 * QSC_D, v1 * QSC_D); }
.LBB0_371:
	s_andn2_b64 vcc, exec, s[38:39]
	s_cbranch_vccnz .LBB0_373
	v_lshl_add_u32 v131, v131, 2, v146
	v_mov_b32_e32 v135, v1
	s_movk_i32 s1, 0x2040
	v_mad_i64_i32 v[134:135], s[22:23], v131, s1, v[134:135]
	v_readlane_b32 s22, v254, 6
	v_lshlrev_b64 v[134:135], 7, v[134:135]
	v_readlane_b32 s23, v254, 7
	v_lshlrev_b32_e32 v152, 1, v137
	v_mov_b32_e32 v153, v1
	v_lshl_add_u64 v[134:135], s[22:23], 0, v[134:135]
	v_lshl_add_u64 v[134:135], v[134:135], 0, v[152:153]
	v_lshlrev_b32_e32 v152, 1, v139
	s_mov_b32 s22, 0x3e8293ee
	v_lshl_add_u64 v[134:135], v[134:135], 0, v[152:153]
	v_pk_mul_f32 v[152:153], v[112:113], s[22:23] op_sel_hi:[1,0]
	v_pk_mul_f32 v[158:159], v[110:111], s[22:23] op_sel_hi:[1,0]
	v_pk_mul_f32 v[160:161], v[108:109], s[22:23] op_sel_hi:[1,0]
	v_pk_mul_f32 v[162:163], v[106:107], s[22:23] op_sel_hi:[1,0]
	v_cvt_pk_bf16_f32 v166, v158, v159
	v_cvt_pk_bf16_f32 v167, v152, v153
	v_cvt_pk_bf16_f32 v168, v162, v163
	v_cvt_pk_bf16_f32 v169, v160, v161
	global_store_dwordx4 v[134:135], v[166:169], off sc1

; __device__ __forceinline__ unsigned short f2bf(float f) { return (unsigned short)(cvt_pk_bf16(f, f) & 0xffffu); }
;   __device__ __forceinline__ void group(int row, int c32, int fq, f32x4 v0, f32x4 v1) const { e->group(row, c32 + sh, fq, v0, v1); }
;     ...
;           for (int m = 0; m < 4; ++m) epi.group(row0 + m * 16 + fr, c32, fq, acc[ai][bj][m][0], acc[ai][bj][m][1]);
;   __device__ __forceinline__ void group(int row, int c32, int fq, f32x4 v0, f32x4 v1) const {
;     int b, e; const bool ok = row_be(row, b, e);
;     if (c32 < 512) {
;       if (c32 < 384) store8bf(cqkv + (size_t)row * 512 + c32 + fq * 8, v0, v1);
;       else { bf16_t* p = cqkv + (size_t)row * 512 + c32 + fq * 4; store4bf(p, v0); store4bf(p + 16, v1); }
;       if (c32 == 384 && ok) {
;         const float2* rp = rope + pos_of_e(e) * 16 + fq * 4; f32x4 o0, o1;
; #pragma unroll
;         for (int j = 0; j < 4; ++j) { const float2 cs = rp[j]; o0[j] = v0[j] * cs.x - v1[j] * cs.y; o1[j] = v1[j] * cs.x + v0[j] * cs.y; }
; #pragma unroll
;         for (int h = 0; h < 6; ++h) { bf16_t* q = ka + ((size_t)(b * 6 + h) * E + e) * 96 + 64 + fq * 4; store4bf(q, o0); store4bf(q + 16, o1); }
;       }
;       return;
;     }
;     if (!ok) return;
;     if (c32 < 768) { const int cc = c32 - 512, h = cc >> 6; store8bf(qd + ((size_t)(b * 4 + h) * E + e) * 64 + (cc & 63) + fq * 8, v0 * QSC_D, v1 * QSC_D); }
;     else if (c32 < 1024) { const int cc = c32 - 768, h = cc >> 6; store8bf(kd + ((size_t)(b * 4 + h) * E + e) * 64 + (cc & 63) + fq * 8, v0, v1); }
;     else if (c32 < 1280) { const int cc = c32 - 1024, h = cc >> 6; bf16_t* p = vtd + ((size_t)(b * 4 + h) * 64 + (cc & 63) + fq * 4) * E + e;
; #pragma unroll
;       for (int j = 0; j < 4; ++j) { p[(size_t)j * E] = f2bf(v0[j]); p[(size_t)(j + 16) * E] = f2bf(v1[j]); } }
;     else if (c32 < 1664) { const int cc = c32 - 1280, h = cc >> 6; store8bf(qs + ((size_t)(b * 6 + h) * E + e) * 64 + (cc & 63) + fq * 8, v0 * QSC_S, v1 * QSC_S); }
;     else if (c32 < 1792) { const int cc = c32 - 1664, g = cc >> 6; store8bf(ks + ((size_t)(b * 2 + g) * E + e) * 64 + (cc & 63) + fq * 8, v0, v1); }
;     else if (c32 < 1920) { const int cc = c32 - 1792, g = cc >> 6; bf16_t* p = vts + ((size_t)(b * 2 + g) * 64 + (cc & 63) + fq * 4) * E + e;
; #pragma unroll
;       for (int j = 0; j < 4; ++j) { p[(size_t)j * E] = f2bf(v0[j]); p[(size_t)(j + 16) * E] = f2bf(v1[j]); } }
.LBB0_375:
	s_mov_b32 s1, 0x8000
	v_cmp_gt_i32_e32 vcc, s1, v130
	v_cmp_gt_u32_e64 s[8:9], s49, v144
	s_or_b64 s[10:11], vcc, s[8:9]
	s_and_saveexec_b64 s[8:9], s[10:11]
	s_cbranch_execz .LBB0_392
	v_and_b32_e32 v131, 0x1fff, v130
	v_add_u32_e32 v133, 64, v131
	v_cndmask_b32_e32 v131, 3, v145, vcc
	v_cndmask_b32_e32 v134, v136, v133, vcc
	s_andn2_b64 vcc, exec, s[24:25]
	s_mov_b64 s[10:11], -1
	s_cbranch_vccnz .LBB0_390
	s_andn2_b64 vcc, exec, s[18:19]
	s_cbranch_vccnz .LBB0_387
	s_andn2_b64 vcc, exec, s[16:17]
	s_cbranch_vccnz .LBB0_384
	s_andn2_b64 vcc, exec, s[14:15]
	s_cbranch_vccnz .LBB0_381
	v_lshl_add_u32 v150, v131, 1, v150
	v_ashrrev_i32_e32 v151, 31, v150
	v_readlane_b32 s10, v254, 16
	v_lshlrev_b64 v[150:151], 6, v[150:151]
	v_readlane_b32 s11, v254, 17
	v_or_b32_e32 v133, v150, v140
	v_lshlrev_b32_e32 v150, 1, v134
	v_mov_b64_e32 v[152:153], s[10:11]
	v_mad_u64_u32 v[152:153], s[10:11], v133, s95, v[152:153]
	v_mad_i32_i24 v153, v151, s95, v153
	v_mov_b32_e32 v151, v1
	v_lshl_add_u64 v[150:151], v[152:153], 0, v[150:151]
	s_mov_b32 s1, 0x40000
	v_cvt_pk_bf16_f32 v133, v102, s0
	v_add_co_u32_e32 v152, vcc, s1, v150
	global_store_short v[150:151], v133, off sc1
	v_cvt_pk_bf16_f32 v133, v98, s0
	v_addc_co_u32_e32 v153, vcc, 0, v151, vcc
	s_movk_i32 s1, 0x4000
	global_store_short v[152:153], v133, off offset:2048 sc1
	v_add_co_u32_e32 v152, vcc, s1, v150
	v_cvt_pk_bf16_f32 v133, v103, s0
	s_nop 0
	v_addc_co_u32_e32 v153, vcc, 0, v151, vcc
	s_mov_b32 s1, 0x44000
	global_store_short v[152:153], v133, off offset:128 sc1
	v_add_co_u32_e32 v152, vcc, s1, v150
	v_cvt_pk_bf16_f32 v133, v99, s0
	s_nop 0
	v_addc_co_u32_e32 v153, vcc, 0, v151, vcc
	s_mov_b32 s1, 0x8000
	global_store_short v[152:153], v133, off offset:2176 sc1
	v_add_co_u32_e32 v152, vcc, s1, v150
	v_cvt_pk_bf16_f32 v133, v104, s0
	s_nop 0
	v_addc_co_u32_e32 v153, vcc, 0, v151, vcc
	s_mov_b32 s1, 0x48000
	global_store_short v[152:153], v133, off offset:256 sc1
	v_add_co_u32_e32 v152, vcc, s1, v150
	v_cvt_pk_bf16_f32 v133, v100, s0
	s_nop 0
	v_addc_co_u32_e32 v153, vcc, 0, v151, vcc
	global_store_short v[152:153], v133, off offset:2304 sc1
	v_add_co_u32_e32 v152, vcc, 0xc000, v150
	v_cvt_pk_bf16_f32 v133, v105, s0
	s_nop 0
	v_addc_co_u32_e32 v153, vcc, 0, v151, vcc
	v_add_co_u32_e32 v150, vcc, 0x4c000, v150
	global_store_short v[152:153], v133, off offset:384 sc1
	v_cvt_pk_bf16_f32 v133, v101, s0
	v_addc_co_u32_e32 v151, vcc, 0, v151, vcc
	s_mov_b64 s[10:11], 0
	global_store_short v[150:151], v133, off offset:2432 sc1
.LBB0_381:
	s_andn2_b64 vcc, exec, s[10:11]
	s_cbranch_vccnz .LBB0_383
	v_mad_i32_i24 v133, v131, 6, v149
	v_mov_b32_e32 v135, v1
	s_movk_i32 s1, 0x2040
	v_mad_i64_i32 v[150:151], s[10:11], v133, s1, v[134:135]
	v_readlane_b32 s10, v254, 12
	v_lshlrev_b64 v[150:151], 7, v[150:151]
	v_readlane_b32 s11, v254, 13
	v_lshlrev_b32_e32 v152, 1, v137
	v_mov_b32_e32 v153, v1
	v_lshl_add_u64 v[150:151], s[10:11], 0, v[150:151]
	v_lshl_add_u64 v[150:151], v[150:151], 0, v[152:153]
	v_lshlrev_b32_e32 v152, 1, v139
	s_mov_b32 s10, 0x3e38aa3b
	v_lshl_add_u64 v[158:159], v[150:151], 0, v[152:153]
	v_pk_mul_f32 v[152:153], v[104:105], s[10:11] op_sel_hi:[1,0]
	v_pk_mul_f32 v[150:151], v[102:103], s[10:11] op_sel_hi:[1,0]
	v_pk_mul_f32 v[160:161], v[100:101], s[10:11] op_sel_hi:[1,0]
	v_pk_mul_f32 v[162:163], v[98:99], s[10:11] op_sel_hi:[1,0]
	v_cvt_pk_bf16_f32 v150, v150, v151
	v_cvt_pk_bf16_f32 v151, v152, v153
	v_cvt_pk_bf16_f32 v152, v162, v163
	v_cvt_pk_bf16_f32 v153, v160, v161
	global_store_dwordx4 v[158:159], v[150:153], off sc1

; __device__ __forceinline__ unsigned short f2bf(float f) { return (unsigned short)(cvt_pk_bf16(f, f) & 0xffffu); }
;   __device__ __forceinline__ void group(int row, int c32, int fq, f32x4 v0, f32x4 v1) const {
;     ...
;     else if (c32 < 1280) { const int cc = c32 - 1024, h = cc >> 6; bf16_t* p = vtd + ((size_t)(b * 4 + h) * 64 + (cc & 63) + fq * 4) * E + e;
; #pragma unroll
;       for (int j = 0; j < 4; ++j) { p[(size_t)j * E] = f2bf(v0[j]); p[(size_t)(j + 16) * E] = f2bf(v1[j]); } }
.LBB0_384:
	s_andn2_b64 vcc, exec, s[10:11]
	s_cbranch_vccnz .LBB0_386
	v_lshl_add_u32 v148, v131, 2, v148
	v_ashrrev_i32_e32 v149, 31, v148
	v_readlane_b32 s10, v254, 10
	v_lshlrev_b64 v[148:149], 6, v[148:149]
	v_readlane_b32 s11, v254, 11
	v_or_b32_e32 v133, v148, v140
	v_lshlrev_b32_e32 v148, 1, v134
	v_mov_b64_e32 v[150:151], s[10:11]
	v_mad_u64_u32 v[150:151], s[10:11], v133, s95, v[150:151]
	v_mad_i32_i24 v151, v149, s95, v151
	v_mov_b32_e32 v149, v1
	v_lshl_add_u64 v[148:149], v[150:151], 0, v[148:149]
	s_mov_b32 s1, 0x40000
	v_cvt_pk_bf16_f32 v133, v102, s0
	v_add_co_u32_e32 v150, vcc, s1, v148
	global_store_short v[148:149], v133, off sc1
	v_cvt_pk_bf16_f32 v133, v98, s0
	v_addc_co_u32_e32 v151, vcc, 0, v149, vcc
	s_movk_i32 s1, 0x4000
	global_store_short v[150:151], v133, off offset:2048 sc1
	v_add_co_u32_e32 v150, vcc, s1, v148
	v_cvt_pk_bf16_f32 v133, v103, s0
	s_nop 0
	v_addc_co_u32_e32 v151, vcc, 0, v149, vcc
	s_mov_b32 s1, 0x44000
	global_store_short v[150:151], v133, off offset:128 sc1
	v_add_co_u32_e32 v150, vcc, s1, v148
	v_cvt_pk_bf16_f32 v133, v99, s0
	s_nop 0
	v_addc_co_u32_e32 v151, vcc, 0, v149, vcc
	s_mov_b32 s1, 0x8000
	global_store_short v[150:151], v133, off offset:2176 sc1
	v_add_co_u32_e32 v150, vcc, s1, v148
	v_cvt_pk_bf16_f32 v133, v104, s0
	s_nop 0
	v_addc_co_u32_e32 v151, vcc, 0, v149, vcc
	s_mov_b32 s1, 0x48000
	global_store_short v[150:151], v133, off offset:256 sc1
	v_add_co_u32_e32 v150, vcc, s1, v148
	v_cvt_pk_bf16_f32 v133, v100, s0
	s_nop 0
	v_addc_co_u32_e32 v151, vcc, 0, v149, vcc
	global_store_short v[150:151], v133, off offset:2304 sc1
	v_add_co_u32_e32 v150, vcc, 0xc000, v148
	v_cvt_pk_bf16_f32 v133, v105, s0
	s_nop 0
	v_addc_co_u32_e32 v151, vcc, 0, v149, vcc
	v_add_co_u32_e32 v148, vcc, 0x4c000, v148
	global_store_short v[150:151], v133, off offset:384 sc1
	v_cvt_pk_bf16_f32 v133, v101, s0
	v_addc_co_u32_e32 v149, vcc, 0, v149, vcc
	global_store_short v[148:149], v133, off offset:2432 sc1

; __device__ __forceinline__ void store8bf(bf16_t* p, f32x4 v0, f32x4 v1) { u32x4 w; w.x = cvt_pk_bf16(v0[0], v0[1]); w.y = cvt_pk_bf16(v0[2], v0[3]); w.z = cvt_pk_bf16(v1[0], v1[1]); w.w = cvt_pk_bf16(v1[2], v1[3]); *(u32x4*)p = w; }
;   __device__ __forceinline__ void group(int row, int c32, int fq, f32x4 v0, f32x4 v1) const {
;     ...
;     else if (c32 < 1024) { const int cc = c32 - 768, h = cc >> 6; store8bf(kd + ((size_t)(b * 4 + h) * E + e) * 64 + (cc & 63) + fq * 8, v0, v1); }
.LBB0_387:
	s_andn2_b64 vcc, exec, s[10:11]
	s_cbranch_vccnz .LBB0_389
	v_lshl_add_u32 v133, v131, 2, v147
	v_mov_b32_e32 v135, v1
	s_movk_i32 s1, 0x2040
	v_mad_i64_i32 v[148:149], s[10:11], v133, s1, v[134:135]
	v_readlane_b32 s10, v254, 8
	v_lshlrev_b64 v[148:149], 7, v[148:149]
	v_readlane_b32 s11, v254, 9
	v_lshlrev_b32_e32 v150, 1, v137
	v_mov_b32_e32 v151, v1
	v_lshl_add_u64 v[148:149], s[10:11], 0, v[148:149]
	v_lshl_add_u64 v[148:149], v[148:149], 0, v[150:151]
	v_lshlrev_b32_e32 v150, 1, v139
	v_lshl_add_u64 v[152:153], v[148:149], 0, v[150:151]
	v_cvt_pk_bf16_f32 v148, v102, v103
	v_cvt_pk_bf16_f32 v149, v104, v105
	v_cvt_pk_bf16_f32 v150, v98, v99
	v_cvt_pk_bf16_f32 v151, v100, v101
	global_store_dwordx4 v[152:153], v[148:151], off sc1

; __device__ __forceinline__ void store8bf(bf16_t* p, f32x4 v0, f32x4 v1) { u32x4 w; w.x = cvt_pk_bf16(v0[0], v0[1]); w.y = cvt_pk_bf16(v0[2], v0[3]); w.z = cvt_pk_bf16(v1[0], v1[1]); w.w = cvt_pk_bf16(v1[2], v1[3]); *(u32x4*)p = w; }
;   __device__ __forceinline__ void group(int row, int c32, int fq, f32x4 v0, f32x4 v1) const {
;     ...
;     if (c32 < 768) { const int cc = c32 - 512, h = cc >> 6; store8bf(qd + ((size_t)(b * 4 + h) * E + e) * 64 + (cc & 63) + fq * 8, v0 * QSC_D, v1 * QSC_D); }
.LBB0_390:
	s_andn2_b64 vcc, exec, s[10:11]
	s_cbranch_vccnz .LBB0_392
	v_lshl_add_u32 v131, v131, 2, v146
	v_mov_b32_e32 v135, v1
	s_movk_i32 s1, 0x2040
	v_mad_i64_i32 v[134:135], s[10:11], v131, s1, v[134:135]
	v_readlane_b32 s10, v254, 6
	v_lshlrev_b64 v[134:135], 7, v[134:135]
	v_readlane_b32 s11, v254, 7
	v_lshlrev_b32_e32 v146, 1, v137
	v_mov_b32_e32 v147, v1
	v_lshl_add_u64 v[134:135], s[10:11], 0, v[134:135]
	v_lshl_add_u64 v[134:135], v[134:135], 0, v[146:147]
	v_lshlrev_b32_e32 v146, 1, v139
	s_mov_b32 s10, 0x3e8293ee
	v_lshl_add_u64 v[134:135], v[134:135], 0, v[146:147]
	v_pk_mul_f32 v[148:149], v[104:105], s[10:11] op_sel_hi:[1,0]
	v_pk_mul_f32 v[146:147], v[102:103], s[10:11] op_sel_hi:[1,0]
	v_pk_mul_f32 v[150:151], v[100:101], s[10:11] op_sel_hi:[1,0]
	v_pk_mul_f32 v[152:153], v[98:99], s[10:11] op_sel_hi:[1,0]
	v_cvt_pk_bf16_f32 v146, v146, v147
	v_cvt_pk_bf16_f32 v147, v148, v149
	v_cvt_pk_bf16_f32 v148, v152, v153
	v_cvt_pk_bf16_f32 v149, v150, v151
	global_store_dwordx4 v[134:135], v[146:149], off sc1

; __device__ __forceinline__ void store8bf(bf16_t* p, f32x4 v0, f32x4 v1) { u32x4 w; w.x = cvt_pk_bf16(v0[0], v0[1]); w.y = cvt_pk_bf16(v0[2], v0[3]); w.z = cvt_pk_bf16(v1[0], v1[1]); w.w = cvt_pk_bf16(v1[2], v1[3]); *(u32x4*)p = w; }
;   __device__ __forceinline__ void group(int row, int c32, int fq, f32x4 v0, f32x4 v1) const { e->group(row, c32 + sh, fq, v0, v1); }
;     ...
;           for (int m = 0; m < 4; ++m) epi.group(row0 + m * 16 + fr, c32, fq, acc[ai][bj][m][0], acc[ai][bj][m][1]);
;   __device__ __forceinline__ void group(int row, int c32, int fq, f32x4 v0, f32x4 v1) const {
;     ...
;       if (c32 < 384) store8bf(cqkv + (size_t)row * 512 + c32 + fq * 8, v0, v1);
.LBB0_395:
	v_ashrrev_i32_e32 v131, 31, v130
	v_readlane_b32 s10, v254, 0
	v_lshlrev_b64 v[130:131], 10, v[130:131]
	v_readlane_b32 s11, v254, 1
	v_lshlrev_b32_e32 v134, 1, v139
	v_mov_b32_e32 v135, v1
	v_lshl_add_u64 v[130:131], s[10:11], 0, v[130:131]
	v_lshl_add_u64 v[130:131], v[0:1], 1, v[130:131]
	v_cvt_pk_bf16_f32 v166, v118, v119
	v_cvt_pk_bf16_f32 v167, v120, v121
	v_lshl_add_u64 v[130:131], v[130:131], 0, v[134:135]
	v_cvt_pk_bf16_f32 v168, v114, v115
	v_cvt_pk_bf16_f32 v169, v116, v117
	global_store_dwordx4 v[130:131], v[166:169], off sc1
	v_or_b32_e32 v130, 32, v132
	s_and_b64 vcc, exec, s[8:9]
	s_mov_b64 s[10:11], -1
	s_cbranch_vccz .LBB0_356

; __device__ __forceinline__ void store8bf(bf16_t* p, f32x4 v0, f32x4 v1) { u32x4 w; w.x = cvt_pk_bf16(v0[0], v0[1]); w.y = cvt_pk_bf16(v0[2], v0[3]); w.z = cvt_pk_bf16(v1[0], v1[1]); w.w = cvt_pk_bf16(v1[2], v1[3]); *(u32x4*)p = w; }
;   __device__ __forceinline__ void group(int row, int c32, int fq, f32x4 v0, f32x4 v1) const { e->group(row, c32 + sh, fq, v0, v1); }
;     ...
;           for (int m = 0; m < 4; ++m) epi.group(row0 + m * 16 + fr, c32, fq, acc[ai][bj][m][0], acc[ai][bj][m][1]);
;   __device__ __forceinline__ void group(int row, int c32, int fq, f32x4 v0, f32x4 v1) const {
;     ...
;       if (c32 < 384) store8bf(cqkv + (size_t)row * 512 + c32 + fq * 8, v0, v1);
.LBB0_397:
	v_ashrrev_i32_e32 v131, 31, v130
	v_readlane_b32 s10, v254, 0
	v_lshlrev_b64 v[130:131], 10, v[130:131]
	v_readlane_b32 s11, v254, 1
	v_lshlrev_b32_e32 v134, 1, v139
	v_mov_b32_e32 v135, v1
	v_lshl_add_u64 v[130:131], s[10:11], 0, v[130:131]
	v_lshl_add_u64 v[130:131], v[0:1], 1, v[130:131]
	v_cvt_pk_bf16_f32 v166, v110, v111
	v_cvt_pk_bf16_f32 v167, v112, v113
	v_lshl_add_u64 v[130:131], v[130:131], 0, v[134:135]
	v_cvt_pk_bf16_f32 v168, v106, v107
	v_cvt_pk_bf16_f32 v169, v108, v109
	global_store_dwordx4 v[130:131], v[166:169], off sc1
	v_or_b32_e32 v130, 48, v132
	s_and_b64 vcc, exec, s[8:9]
	s_mov_b64 s[8:9], -1
	s_cbranch_vccz .LBB0_375

; __device__ __forceinline__ void store8bf(bf16_t* p, f32x4 v0, f32x4 v1) { u32x4 w; w.x = cvt_pk_bf16(v0[0], v0[1]); w.y = cvt_pk_bf16(v0[2], v0[3]); w.z = cvt_pk_bf16(v1[0], v1[1]); w.w = cvt_pk_bf16(v1[2], v1[3]); *(u32x4*)p = w; }
;   __device__ __forceinline__ void group(int row, int c32, int fq, f32x4 v0, f32x4 v1) const {
;     ...
;       if (c32 < 384) store8bf(cqkv + (size_t)row * 512 + c32 + fq * 8, v0, v1);
.LBB0_399:
	v_ashrrev_i32_e32 v131, 31, v130
	v_readlane_b32 s8, v254, 0
	v_lshlrev_b64 v[130:131], 10, v[130:131]
	v_readlane_b32 s9, v254, 1
	v_lshlrev_b32_e32 v134, 1, v139
	v_mov_b32_e32 v135, v1
	v_lshl_add_u64 v[130:131], s[8:9], 0, v[130:131]
	v_lshl_add_u64 v[130:131], v[0:1], 1, v[130:131]
	v_cvt_pk_bf16_f32 v146, v102, v103
	v_cvt_pk_bf16_f32 v147, v104, v105
	v_lshl_add_u64 v[130:131], v[130:131], 0, v[134:135]
	v_cvt_pk_bf16_f32 v148, v98, v99
	v_cvt_pk_bf16_f32 v149, v100, v101
	global_store_dwordx4 v[130:131], v[146:149], off sc1

; #define LAS __attribute__((address_space(3)))
; __device__ __forceinline__ unsigned short f2bf(float f) { return (unsigned short)(cvt_pk_bf16(f, f) & 0xffffu); }
;   __device__ __forceinline__ bool vt_info(int c32, int b, bf16_t*& base) const { return e->vt_info(c32 + sh, b, base); }
;     ...
;         const int c32 = bcol + wc * 32 + bj * HALF, row0 = brow + ai * HALF + wr * 64;
;         int b0, e0; row_be(row0, b0, e0); bf16_t* vbase;
;         if (epi.vt_info(c32, b0, vbase)) {
; #pragma unroll
;           for (int m = 0; m < 4; ++m) { const float sc = epi.row_scale(row0 + m * 16 + fr);
; #pragma unroll
;             for (int n = 0; n < 2; ++n)
; #pragma unroll
;               for (int j = 0; j < 4; ++j) *(LAS bf16_t*)(T + (n * 16 + fq * 4 + j) * 144 + (m * 16 + fr) * 2) = f2bf(acc[ai][bj][m][n][j] * sc); }
;           asm volatile("s_waitcnt lgkmcnt(0)" ::: "memory");
; #pragma unroll
;           for (int q = 0; q < 4; ++q) { const int ch = lane + 64 * q, d = ch >> 3, ec = ch & 7;
;             *(u32x4*)(vbase + (size_t)d * E + e0 + ec * 8) = *(LAS const u32x4*)(T + d * 144 + ec * 16); }
;           asm volatile("s_waitcnt lgkmcnt(0)" ::: "memory");
.LBB0_402:
	s_movk_i32 s15, 0x1200
	v_mul_lo_u32 v131, v142, s15
	v_cndmask_b32_e64 v133, v213, v211, s[4:5]
	v_add3_u32 v131, 0, v131, v133
	v_and_b32_e32 v134, 7, v141
	v_lshl_add_u32 v133, v136, 1, v131
	v_lshl_add_u32 v131, v134, 4, v131
	v_lshlrev_b32_e32 v135, 3, v134
	v_and_b32_e32 v134, 0x1fc0, v144
	v_and_b32_e32 v130, 63, v141
	v_add_u32_e32 v134, 64, v134
	s_movk_i32 s4, 0x240
	v_cndmask_b32_e64 v134, 0, v134, s[6:7]
	v_mad_u32_u24 v143, v143, s4, v133
	v_lshrrev_b32_e32 v133, 3, v130
	v_cndmask_b32_e64 v146, 0, v145, s[6:7]
	s_and_b64 vcc, exec, s[10:11]
	v_lshlrev_b32_e32 v134, 1, v134
	v_lshlrev_b32_e32 v130, 1, v135
	v_mad_u32_u24 v141, v133, s54, v131
	v_mul_u32_u24_e32 v142, 0x2040, v133
	s_cbranch_vccz .LBB0_404
	v_readlane_b32 s24, v253, 16
	v_readlane_b32 s25, v253, 17
	v_readlane_b32 s26, v253, 18
	v_readlane_b32 s27, v253, 19
	v_readlane_b32 s28, v253, 20
	v_readlane_b32 s29, v253, 21
	v_add_u32_e32 v131, s14, v0
	v_readlane_b32 s30, v253, 22
	v_readlane_b32 s31, v253, 23
	s_mov_b64 s[24:25], s[28:29]
	v_lshrrev_b32_e32 v131, 6, v131
	s_mov_b64 s[26:27], s[30:31]
	v_lshl_add_u32 v148, v146, s1, v131
	s_add_u32 s4, s26, s8
	v_ashrrev_i32_e32 v149, 31, v148
	v_cvt_pk_bf16_f32 v126, v126, s0
	v_cvt_pk_bf16_f32 v122, v122, s0
	v_cvt_pk_bf16_f32 v118, v118, s0
	v_cvt_pk_bf16_f32 v114, v114, s0
	v_cvt_pk_bf16_f32 v110, v110, s0
	v_cvt_pk_bf16_f32 v106, v106, s0
	v_cvt_pk_bf16_f32 v102, v102, s0
	v_cvt_pk_bf16_f32 v98, v98, s0
	s_addc_u32 s5, s27, s9
	v_lshlrev_b64 v[148:149], 6, v[148:149]
	ds_write_b16 v143, v126
	v_cvt_pk_bf16_f32 v126, v127, s0
	ds_write_b16 v143, v122 offset:2304
	v_cvt_pk_bf16_f32 v122, v123, s0
	ds_write_b16 v143, v118 offset:32
	v_cvt_pk_bf16_f32 v118, v119, s0
	ds_write_b16 v143, v114 offset:2336
	v_cvt_pk_bf16_f32 v114, v115, s0
	ds_write_b16 v143, v110 offset:64
	v_cvt_pk_bf16_f32 v110, v111, s0
	ds_write_b16 v143, v106 offset:2368
	v_cvt_pk_bf16_f32 v106, v107, s0
	ds_write_b16 v143, v102 offset:96
	v_cvt_pk_bf16_f32 v102, v103, s0
	ds_write_b16 v143, v98 offset:2400
	v_cvt_pk_bf16_f32 v98, v99, s0
	v_or_b32_e32 v131, v148, v137
	v_mov_b64_e32 v[150:151], s[4:5]
	ds_write_b16 v143, v126 offset:144
	v_cvt_pk_bf16_f32 v126, v128, s0
	ds_write_b16 v143, v122 offset:2448
	v_cvt_pk_bf16_f32 v122, v124, s0
	ds_write_b16 v143, v118 offset:176
	v_cvt_pk_bf16_f32 v118, v120, s0
	ds_write_b16 v143, v114 offset:2480
	v_cvt_pk_bf16_f32 v114, v116, s0
	ds_write_b16 v143, v110 offset:208
	v_cvt_pk_bf16_f32 v110, v112, s0
	ds_write_b16 v143, v106 offset:2512
	v_cvt_pk_bf16_f32 v106, v108, s0
	ds_write_b16 v143, v102 offset:240
	v_cvt_pk_bf16_f32 v102, v104, s0
	ds_write_b16 v143, v98 offset:2544
	v_cvt_pk_bf16_f32 v98, v100, s0
	v_mad_u64_u32 v[150:151], s[4:5], v131, s95, v[150:151]
	ds_write_b16 v143, v126 offset:288
	v_cvt_pk_bf16_f32 v126, v129, s0
	ds_write_b16 v143, v122 offset:2592
	v_cvt_pk_bf16_f32 v122, v125, s0
	ds_write_b16 v143, v118 offset:320
	v_cvt_pk_bf16_f32 v118, v121, s0
	ds_write_b16 v143, v114 offset:2624
	v_cvt_pk_bf16_f32 v114, v117, s0
	ds_write_b16 v143, v110 offset:352
	v_cvt_pk_bf16_f32 v110, v113, s0
	ds_write_b16 v143, v106 offset:2656
	v_cvt_pk_bf16_f32 v106, v109, s0
	ds_write_b16 v143, v102 offset:384
	v_cvt_pk_bf16_f32 v102, v105, s0
	ds_write_b16 v143, v98 offset:2688
	v_cvt_pk_bf16_f32 v98, v101, s0
	v_mad_i32_i24 v151, v149, s95, v151
	ds_write_b16 v143, v126 offset:432
	ds_write_b16 v143, v122 offset:2736
	ds_write_b16 v143, v118 offset:464
	ds_write_b16 v143, v114 offset:2768
	ds_write_b16 v143, v110 offset:496
	ds_write_b16 v143, v106 offset:2800
	ds_write_b16 v143, v102 offset:528
	ds_write_b16 v143, v98 offset:2832
	v_mov_b32_e32 v135, v1
	s_waitcnt lgkmcnt(0)
	v_lshl_add_u64 v[98:99], v[150:151], 0, v[134:135]
	v_mov_b32_e32 v131, v1
	v_lshl_add_u64 v[102:103], v[98:99], 0, v[130:131]
	ds_read_b128 v[98:101], v141
	v_lshlrev_b32_e32 v104, 1, v142
	v_mov_b32_e32 v105, v1
	v_lshl_add_u64 v[106:107], v[102:103], 0, v[104:105]
	ds_read_b128 v[102:105], v141 offset:1152
	s_waitcnt lgkmcnt(0)
	global_store_dwordx4 v[106:107], v[98:101], off sc1
	s_nop 1
	v_add_co_u32_e32 v98, vcc, 0x20000, v106
	s_nop 1
	v_addc_co_u32_e32 v99, vcc, 0, v107, vcc
	global_store_dwordx4 v[98:99], v[102:105], off offset:1024 sc1
	ds_read_b128 v[98:101], v141 offset:2304
	ds_read_b128 v[102:105], v141 offset:3456
	v_add_co_u32_e32 v108, vcc, 0x40000, v106
	s_nop 1
	v_addc_co_u32_e32 v109, vcc, 0, v107, vcc
	s_waitcnt lgkmcnt(0)
	global_store_dwordx4 v[108:109], v[98:101], off offset:2048 sc1
	s_nop 1
	v_add_co_u32_e32 v98, vcc, 0x60000, v106
	s_nop 1
	v_addc_co_u32_e32 v99, vcc, 0, v107, vcc
	global_store_dwordx4 v[98:99], v[102:105], off offset:3072 sc1
	s_waitcnt lgkmcnt(0)
; __device__ __forceinline__ unsigned short f2bf(float f) { return (unsigned short)(cvt_pk_bf16(f, f) & 0xffffu); }
; __device__ __forceinline__ void store4bf(bf16_t* p, f32x4 v) { u32x2 w; w.x = cvt_pk_bf16(v[0], v[1]); w.y = cvt_pk_bf16(v[2], v[3]); *(u32x2*)p = w; }
;   __device__ __forceinline__ void group(int row, int c32, int fq, f32x4 v0, f32x4 v1) const {
;     int b, e; const bool ok = row_be(row, b, e);
;     if (c32 < 512) {
;       if (c32 < 384) store8bf(cqkv + (size_t)row * 512 + c32 + fq * 8, v0, v1);
;       else { bf16_t* p = cqkv + (size_t)row * 512 + c32 + fq * 4; store4bf(p, v0); store4bf(p + 16, v1); }
;       if (c32 == 384 && ok) {
;         const float2* rp = rope + pos_of_e(e) * 16 + fq * 4; f32x4 o0, o1;
; #pragma unroll
;         for (int j = 0; j < 4; ++j) { const float2 cs = rp[j]; o0[j] = v0[j] * cs.x - v1[j] * cs.y; o1[j] = v1[j] * cs.x + v0[j] * cs.y; }
; #pragma unroll
;         for (int h = 0; h < 6; ++h) { bf16_t* q = ka + ((size_t)(b * 6 + h) * E + e) * 96 + 64 + fq * 4; store4bf(q, o0); store4bf(q + 16, o1); }
;       }
;       return;
;     }
;     if (!ok) return;
;     if (c32 < 768) { const int cc = c32 - 512, h = cc >> 6; store8bf(qd + ((size_t)(b * 4 + h) * E + e) * 64 + (cc & 63) + fq * 8, v0 * QSC_D, v1 * QSC_D); }
;     else if (c32 < 1024) { const int cc = c32 - 768, h = cc >> 6; store8bf(kd + ((size_t)(b * 4 + h) * E + e) * 64 + (cc & 63) + fq * 8, v0, v1); }
;     else if (c32 < 1280) { const int cc = c32 - 1024, h = cc >> 6; bf16_t* p = vtd + ((size_t)(b * 4 + h) * 64 + (cc & 63) + fq * 4) * E + e;
; #pragma unroll
;       for (int j = 0; j < 4; ++j) { p[(size_t)j * E] = f2bf(v0[j]); p[(size_t)(j + 16) * E] = f2bf(v1[j]); } }
;     else if (c32 < 1664) { const int cc = c32 - 1280, h = cc >> 6; store8bf(qs + ((size_t)(b * 6 + h) * E + e) * 64 + (cc & 63) + fq * 8, v0 * QSC_S, v1 * QSC_S); }
;     else if (c32 < 1792) { const int cc = c32 - 1664, g = cc >> 6; store8bf(ks + ((size_t)(b * 2 + g) * E + e) * 64 + (cc & 63) + fq * 8, v0, v1); }
;     else if (c32 < 1920) { const int cc = c32 - 1792, g = cc >> 6; bf16_t* p = vts + ((size_t)(b * 2 + g) * 64 + (cc & 63) + fq * 4) * E + e;
; #pragma unroll
;       for (int j = 0; j < 4; ++j) { p[(size_t)j * E] = f2bf(v0[j]); p[(size_t)(j + 16) * E] = f2bf(v1[j]); } }
.LBB0_404:
	v_or_b32_e32 v112, 0x80, v0
	v_cndmask_b32_e64 v98, 0, 1, s[12:13]
	s_movk_i32 s1, 0x67f
	v_cmp_ne_u32_e64 s[4:5], 1, v98
	v_cmp_lt_u32_e64 s[10:11], s1, v112
	s_movk_i32 s1, 0x780
	v_add_u32_e32 v98, 0xfffff980, v0
	v_add_u32_e32 v99, 0xfffffa00, v0
	v_add_u32_e32 v100, 0xfffffb80, v0
	v_add_u32_e32 v101, 0xfffffc80, v0
	v_add_u32_e32 v102, 0xfffffd80, v0
	v_add_u32_e32 v103, 0xfffffe80, v0
	s_mov_b64 s[14:15], -1
	s_andn2_b64 vcc, exec, s[12:13]
	v_cmp_gt_u32_e64 s[8:9], s1, v112
	v_cmp_eq_u32_e64 s[6:7], s93, v0
	v_lshrrev_b32_e32 v110, 6, v98
	v_lshrrev_b32_e32 v109, 6, v99
	v_lshrrev_b32_e32 v111, 6, v100
	v_lshrrev_b32_e32 v106, 6, v101
	v_lshrrev_b32_e32 v108, 6, v102
	v_lshrrev_b32_e32 v107, 6, v103
	s_cbranch_vccnz .LBB0_530
	s_cmp_gt_u32 s0, 1
	s_cselect_b64 s[68:69], -1, 0
	s_cmp_gt_u32 s0, 2
	s_cselect_b64 s[44:45], -1, 0
	s_cmp_gt_u32 s0, 3
	s_cselect_b64 s[40:41], -1, 0
	s_cmp_gt_u32 s0, 4
	s_cselect_b64 s[38:39], -1, 0
	s_cmp_gt_u32 s0, 6
	v_and_b32_e32 v98, 0x1fcf, v132
	s_mov_b32 s1, 0x8000
	s_cselect_b64 s[26:27], -1, 0
	s_cmp_lg_u32 s0, 0
	v_add_u32_e32 v98, 64, v98
	v_cmp_gt_u32_e64 s[14:15], s49, v144
	v_cmp_gt_i32_e64 s[16:17], s1, v132
	s_cselect_b64 s[12:13], -1, 0
	s_or_b64 s[18:19], s[16:17], s[14:15]
	v_cndmask_b32_e64 v113, 0, v145, s[16:17]
	v_cndmask_b32_e64 v102, v136, v98, s[16:17]
	s_mov_b64 s[42:43], -1
	s_and_b64 vcc, exec, s[68:69]
	s_cbranch_vccz .LBB0_429
	s_and_saveexec_b64 s[70:71], s[18:19]
	s_cbranch_execz .LBB0_428
	s_andn2_b64 vcc, exec, s[44:45]
	s_cbranch_vccnz .LBB0_426
	s_andn2_b64 vcc, exec, s[40:41]
	s_cbranch_vccnz .LBB0_423
	s_andn2_b64 vcc, exec, s[38:39]
	s_cbranch_vccnz .LBB0_420
	s_and_saveexec_b64 s[22:23], s[10:11]
	s_xor_b64 s[24:25], exec, s[22:23]
	s_cbranch_execz .LBB0_417
	s_andn2_b64 vcc, exec, s[26:27]
	s_cbranch_vccnz .LBB0_415
	s_and_saveexec_b64 s[42:43], s[8:9]
	s_cbranch_execz .LBB0_414
	v_lshl_add_u32 v98, v113, 1, v110
	v_ashrrev_i32_e32 v99, 31, v98
	v_readlane_b32 s22, v254, 16
	v_lshlrev_b64 v[98:99], 6, v[98:99]
	v_readlane_b32 s23, v254, 17
	v_or_b32_e32 v98, v98, v140
	s_mov_b32 s1, 0x40000
	v_mov_b64_e32 v[100:101], s[22:23]
	v_mad_u64_u32 v[100:101], s[22:23], v98, s95, v[100:101]
	v_mad_i32_i24 v101, v99, s95, v101
	v_lshlrev_b32_e32 v98, 1, v102
	v_mov_b32_e32 v99, v1
	v_lshl_add_u64 v[98:99], v[100:101], 0, v[98:99]
	v_cvt_pk_bf16_f32 v100, v94, s0
	global_store_short v[98:99], v100, off sc1
	v_add_co_u32_e32 v100, vcc, s1, v98
	v_cvt_pk_bf16_f32 v103, v90, s0
	s_nop 0
	v_addc_co_u32_e32 v101, vcc, 0, v99, vcc
	s_movk_i32 s1, 0x4000
	global_store_short v[100:101], v103, off offset:2048 sc1
	v_add_co_u32_e32 v100, vcc, s1, v98
	v_cvt_pk_bf16_f32 v103, v95, s0
	s_nop 0
	v_addc_co_u32_e32 v101, vcc, 0, v99, vcc
	s_mov_b32 s1, 0x44000
	global_store_short v[100:101], v103, off offset:128 sc1
	v_add_co_u32_e32 v100, vcc, s1, v98
	v_cvt_pk_bf16_f32 v103, v91, s0
	s_nop 0
	v_addc_co_u32_e32 v101, vcc, 0, v99, vcc
	s_mov_b32 s1, 0x8000
	global_store_short v[100:101], v103, off offset:2176 sc1
	v_add_co_u32_e32 v100, vcc, s1, v98
	v_cvt_pk_bf16_f32 v103, v96, s0
	s_nop 0
	v_addc_co_u32_e32 v101, vcc, 0, v99, vcc
	s_mov_b32 s1, 0x48000
	global_store_short v[100:101], v103, off offset:256 sc1
	v_add_co_u32_e32 v100, vcc, s1, v98
	v_cvt_pk_bf16_f32 v103, v92, s0
	s_nop 0
	v_addc_co_u32_e32 v101, vcc, 0, v99, vcc
	global_store_short v[100:101], v103, off offset:2304 sc1
	v_add_co_u32_e32 v100, vcc, 0xc000, v98
	v_cvt_pk_bf16_f32 v103, v97, s0
	s_nop 0
	v_addc_co_u32_e32 v101, vcc, 0, v99, vcc
	v_add_co_u32_e32 v98, vcc, 0x4c000, v98
	global_store_short v[100:101], v103, off offset:384 sc1
	v_cvt_pk_bf16_f32 v100, v93, s0
	v_addc_co_u32_e32 v99, vcc, 0, v99, vcc
	global_store_short v[98:99], v100, off offset:2432 sc1

; __device__ __forceinline__ void store8bf(bf16_t* p, f32x4 v0, f32x4 v1) { u32x4 w; w.x = cvt_pk_bf16(v0[0], v0[1]); w.y = cvt_pk_bf16(v0[2], v0[3]); w.z = cvt_pk_bf16(v1[0], v1[1]); w.w = cvt_pk_bf16(v1[2], v1[3]); *(u32x4*)p = w; }
;   __device__ __forceinline__ void group(int row, int c32, int fq, f32x4 v0, f32x4 v1) const {
;     ...
;     else if (c32 < 1664) { const int cc = c32 - 1280, h = cc >> 6; store8bf(qs + ((size_t)(b * 6 + h) * E + e) * 64 + (cc & 63) + fq * 8, v0 * QSC_S, v1 * QSC_S); }
;     else if (c32 < 1792) { const int cc = c32 - 1664, g = cc >> 6; store8bf(ks + ((size_t)(b * 2 + g) * E + e) * 64 + (cc & 63) + fq * 8, v0, v1); }
.LBB0_415:
	s_andn2_b64 vcc, exec, s[42:43]
	s_cbranch_vccnz .LBB0_417
	v_lshl_add_u32 v98, v113, 1, v109
	v_mov_b32_e32 v103, v1
	s_movk_i32 s1, 0x2040
	v_mad_i64_i32 v[98:99], s[22:23], v98, s1, v[102:103]
	v_readlane_b32 s22, v254, 14
	v_lshlrev_b64 v[98:99], 7, v[98:99]
	v_readlane_b32 s23, v254, 15
	v_lshlrev_b32_e32 v100, 1, v137
	v_mov_b32_e32 v101, v1
	v_lshl_add_u64 v[98:99], s[22:23], 0, v[98:99]
	v_lshl_add_u64 v[98:99], v[98:99], 0, v[100:101]
	v_lshlrev_b32_e32 v100, 1, v139
	v_lshl_add_u64 v[104:105], v[98:99], 0, v[100:101]
	v_cvt_pk_bf16_f32 v98, v94, v95
	v_cvt_pk_bf16_f32 v99, v96, v97
	v_cvt_pk_bf16_f32 v100, v90, v91
	v_cvt_pk_bf16_f32 v101, v92, v93
	global_store_dwordx4 v[104:105], v[98:101], off sc1
.LBB0_417:
	s_andn2_saveexec_b64 s[42:43], s[24:25]
	s_cbranch_execz .LBB0_419
	v_mad_i32_i24 v98, v113, 6, v111
	v_mov_b32_e32 v103, v1
	s_movk_i32 s1, 0x2040
	v_mad_i64_i32 v[98:99], s[22:23], v98, s1, v[102:103]
	v_readlane_b32 s22, v254, 12
	v_lshlrev_b64 v[98:99], 7, v[98:99]
	v_readlane_b32 s23, v254, 13
	v_lshlrev_b32_e32 v100, 1, v137
	v_mov_b32_e32 v101, v1
	v_lshl_add_u64 v[98:99], s[22:23], 0, v[98:99]
	v_lshl_add_u64 v[98:99], v[98:99], 0, v[100:101]
	v_lshlrev_b32_e32 v100, 1, v139
	s_mov_b32 s22, 0x3e38aa3b
	v_lshl_add_u64 v[104:105], v[98:99], 0, v[100:101]
	v_pk_mul_f32 v[100:101], v[96:97], s[22:23] op_sel_hi:[1,0]
	v_pk_mul_f32 v[98:99], v[94:95], s[22:23] op_sel_hi:[1,0]
	v_pk_mul_f32 v[114:115], v[92:93], s[22:23] op_sel_hi:[1,0]
	v_pk_mul_f32 v[116:117], v[90:91], s[22:23] op_sel_hi:[1,0]
	v_cvt_pk_bf16_f32 v98, v98, v99
	v_cvt_pk_bf16_f32 v99, v100, v101
	v_cvt_pk_bf16_f32 v100, v116, v117
	v_cvt_pk_bf16_f32 v101, v114, v115
	global_store_dwordx4 v[104:105], v[98:101], off sc1

; __device__ __forceinline__ unsigned short f2bf(float f) { return (unsigned short)(cvt_pk_bf16(f, f) & 0xffffu); }
;   __device__ __forceinline__ void group(int row, int c32, int fq, f32x4 v0, f32x4 v1) const {
;     ...
;     else if (c32 < 1280) { const int cc = c32 - 1024, h = cc >> 6; bf16_t* p = vtd + ((size_t)(b * 4 + h) * 64 + (cc & 63) + fq * 4) * E + e;
; #pragma unroll
;       for (int j = 0; j < 4; ++j) { p[(size_t)j * E] = f2bf(v0[j]); p[(size_t)(j + 16) * E] = f2bf(v1[j]); } }
.LBB0_420:
	s_andn2_b64 vcc, exec, s[42:43]
	s_cbranch_vccnz .LBB0_422
	v_lshl_add_u32 v98, v113, 2, v106
	v_ashrrev_i32_e32 v99, 31, v98
	v_readlane_b32 s22, v254, 10
	v_lshlrev_b64 v[98:99], 6, v[98:99]
	v_readlane_b32 s23, v254, 11
	v_or_b32_e32 v98, v98, v140
	s_mov_b32 s1, 0x40000
	v_mov_b64_e32 v[100:101], s[22:23]
	v_mad_u64_u32 v[100:101], s[22:23], v98, s95, v[100:101]
	v_mad_i32_i24 v101, v99, s95, v101
	v_lshlrev_b32_e32 v98, 1, v102
	v_mov_b32_e32 v99, v1
	v_lshl_add_u64 v[98:99], v[100:101], 0, v[98:99]
	v_cvt_pk_bf16_f32 v100, v94, s0
	global_store_short v[98:99], v100, off sc1
	v_add_co_u32_e32 v100, vcc, s1, v98
	v_cvt_pk_bf16_f32 v103, v90, s0
	s_nop 0
	v_addc_co_u32_e32 v101, vcc, 0, v99, vcc
	s_movk_i32 s1, 0x4000
	global_store_short v[100:101], v103, off offset:2048 sc1
	v_add_co_u32_e32 v100, vcc, s1, v98
	v_cvt_pk_bf16_f32 v103, v95, s0
	s_nop 0
	v_addc_co_u32_e32 v101, vcc, 0, v99, vcc
	s_mov_b32 s1, 0x44000
	global_store_short v[100:101], v103, off offset:128 sc1
	v_add_co_u32_e32 v100, vcc, s1, v98
	v_cvt_pk_bf16_f32 v103, v91, s0
	s_nop 0
	v_addc_co_u32_e32 v101, vcc, 0, v99, vcc
	s_mov_b32 s1, 0x8000
	global_store_short v[100:101], v103, off offset:2176 sc1
	v_add_co_u32_e32 v100, vcc, s1, v98
	v_cvt_pk_bf16_f32 v103, v96, s0
	s_nop 0
	v_addc_co_u32_e32 v101, vcc, 0, v99, vcc
	s_mov_b32 s1, 0x48000
	global_store_short v[100:101], v103, off offset:256 sc1
	v_add_co_u32_e32 v100, vcc, s1, v98
	v_cvt_pk_bf16_f32 v103, v92, s0
	s_nop 0
	v_addc_co_u32_e32 v101, vcc, 0, v99, vcc
	global_store_short v[100:101], v103, off offset:2304 sc1
	v_add_co_u32_e32 v100, vcc, 0xc000, v98
	v_cvt_pk_bf16_f32 v103, v97, s0
	s_nop 0
	v_addc_co_u32_e32 v101, vcc, 0, v99, vcc
	v_add_co_u32_e32 v98, vcc, 0x4c000, v98
	global_store_short v[100:101], v103, off offset:384 sc1
	v_cvt_pk_bf16_f32 v100, v93, s0
	v_addc_co_u32_e32 v99, vcc, 0, v99, vcc
	global_store_short v[98:99], v100, off offset:2432 sc1

; __device__ __forceinline__ void store8bf(bf16_t* p, f32x4 v0, f32x4 v1) { u32x4 w; w.x = cvt_pk_bf16(v0[0], v0[1]); w.y = cvt_pk_bf16(v0[2], v0[3]); w.z = cvt_pk_bf16(v1[0], v1[1]); w.w = cvt_pk_bf16(v1[2], v1[3]); *(u32x4*)p = w; }
;   __device__ __forceinline__ void group(int row, int c32, int fq, f32x4 v0, f32x4 v1) const {
;     ...
;     else if (c32 < 1024) { const int cc = c32 - 768, h = cc >> 6; store8bf(kd + ((size_t)(b * 4 + h) * E + e) * 64 + (cc & 63) + fq * 8, v0, v1); }
.LBB0_423:
	s_andn2_b64 vcc, exec, s[42:43]
	s_cbranch_vccnz .LBB0_425
	v_lshl_add_u32 v98, v113, 2, v108
	v_mov_b32_e32 v103, v1
	s_movk_i32 s1, 0x2040
	v_mad_i64_i32 v[98:99], s[22:23], v98, s1, v[102:103]
	v_readlane_b32 s22, v254, 8
	v_lshlrev_b64 v[98:99], 7, v[98:99]
	v_readlane_b32 s23, v254, 9
	v_lshlrev_b32_e32 v100, 1, v137
	v_mov_b32_e32 v101, v1
	v_lshl_add_u64 v[98:99], s[22:23], 0, v[98:99]
	v_lshl_add_u64 v[98:99], v[98:99], 0, v[100:101]
	v_lshlrev_b32_e32 v100, 1, v139
	v_lshl_add_u64 v[104:105], v[98:99], 0, v[100:101]
	v_cvt_pk_bf16_f32 v98, v94, v95
	v_cvt_pk_bf16_f32 v99, v96, v97
	v_cvt_pk_bf16_f32 v100, v90, v91
	v_cvt_pk_bf16_f32 v101, v92, v93
	global_store_dwordx4 v[104:105], v[98:101], off sc1

; __device__ __forceinline__ void store8bf(bf16_t* p, f32x4 v0, f32x4 v1) { u32x4 w; w.x = cvt_pk_bf16(v0[0], v0[1]); w.y = cvt_pk_bf16(v0[2], v0[3]); w.z = cvt_pk_bf16(v1[0], v1[1]); w.w = cvt_pk_bf16(v1[2], v1[3]); *(u32x4*)p = w; }
;   __device__ __forceinline__ void group(int row, int c32, int fq, f32x4 v0, f32x4 v1) const {
;     ...
;     if (c32 < 768) { const int cc = c32 - 512, h = cc >> 6; store8bf(qd + ((size_t)(b * 4 + h) * E + e) * 64 + (cc & 63) + fq * 8, v0 * QSC_D, v1 * QSC_D); }
.LBB0_426:
	s_andn2_b64 vcc, exec, s[42:43]
	s_cbranch_vccnz .LBB0_428
	v_lshl_add_u32 v98, v113, 2, v107
	v_mov_b32_e32 v103, v1
	s_movk_i32 s1, 0x2040
	v_mad_i64_i32 v[98:99], s[22:23], v98, s1, v[102:103]
	v_readlane_b32 s22, v254, 6
	v_lshlrev_b64 v[98:99], 7, v[98:99]
	v_readlane_b32 s23, v254, 7
	v_lshlrev_b32_e32 v100, 1, v137
	v_mov_b32_e32 v101, v1
	v_lshl_add_u64 v[98:99], s[22:23], 0, v[98:99]
	v_lshl_add_u64 v[98:99], v[98:99], 0, v[100:101]
	v_lshlrev_b32_e32 v100, 1, v139
	s_mov_b32 s22, 0x3e8293ee
	v_lshl_add_u64 v[104:105], v[98:99], 0, v[100:101]
	v_pk_mul_f32 v[100:101], v[96:97], s[22:23] op_sel_hi:[1,0]
	v_pk_mul_f32 v[98:99], v[94:95], s[22:23] op_sel_hi:[1,0]
	v_pk_mul_f32 v[114:115], v[92:93], s[22:23] op_sel_hi:[1,0]
	v_pk_mul_f32 v[116:117], v[90:91], s[22:23] op_sel_hi:[1,0]
	v_cvt_pk_bf16_f32 v98, v98, v99
	v_cvt_pk_bf16_f32 v99, v100, v101
	v_cvt_pk_bf16_f32 v100, v116, v117
	v_cvt_pk_bf16_f32 v101, v114, v115
	global_store_dwordx4 v[104:105], v[98:101], off sc1

; __device__ __forceinline__ void store4bf(bf16_t* p, f32x4 v) { u32x2 w; w.x = cvt_pk_bf16(v[0], v[1]); w.y = cvt_pk_bf16(v[2], v[3]); *(u32x2*)p = w; }
; __device__ __forceinline__ void store8bf(bf16_t* p, f32x4 v0, f32x4 v1) { u32x4 w; w.x = cvt_pk_bf16(v0[0], v0[1]); w.y = cvt_pk_bf16(v0[2], v0[3]); w.z = cvt_pk_bf16(v1[0], v1[1]); w.w = cvt_pk_bf16(v1[2], v1[3]); *(u32x4*)p = w; }
;   __device__ __forceinline__ void group(int row, int c32, int fq, f32x4 v0, f32x4 v1) const {
;     ...
;     if (c32 < 512) {
;       if (c32 < 384) store8bf(cqkv + (size_t)row * 512 + c32 + fq * 8, v0, v1);
;       else { bf16_t* p = cqkv + (size_t)row * 512 + c32 + fq * 4; store4bf(p, v0); store4bf(p + 16, v1); }
;       if (c32 == 384 && ok) {
;         const float2* rp = rope + pos_of_e(e) * 16 + fq * 4; f32x4 o0, o1;
; #pragma unroll
;         for (int j = 0; j < 4; ++j) { const float2 cs = rp[j]; o0[j] = v0[j] * cs.x - v1[j] * cs.y; o1[j] = v1[j] * cs.x + v0[j] * cs.y; }
; #pragma unroll
;         for (int h = 0; h < 6; ++h) { bf16_t* q = ka + ((size_t)(b * 6 + h) * E + e) * 96 + 64 + fq * 4; store4bf(q, o0); store4bf(q + 16, o1); }
;       }
.LBB0_429:
	v_cndmask_b32_e64 v98, 0, 1, s[12:13]
	s_andn2_b64 vcc, exec, s[42:43]
	v_cmp_ne_u32_e64 s[12:13], 1, v98
	s_cbranch_vccnz .LBB0_436
	v_ashrrev_i32_e32 v133, 31, v132
	v_readlane_b32 s22, v254, 0
	v_lshlrev_b64 v[98:99], 10, v[132:133]
	v_readlane_b32 s23, v254, 1
	s_and_b64 vcc, exec, s[12:13]
	v_cvt_pk_bf16_f32 v100, v90, v91
	v_lshl_add_u64 v[104:105], s[22:23], 0, v[98:99]
	v_cvt_pk_bf16_f32 v98, v94, v95
	v_cvt_pk_bf16_f32 v99, v96, v97
	v_cvt_pk_bf16_f32 v101, v92, v93
	s_cbranch_vccnz .LBB0_761
	v_lshl_add_u64 v[114:115], v[0:1], 1, v[104:105]
	v_lshlrev_b32_e32 v116, 1, v138
	v_mov_b32_e32 v117, v1
	v_lshl_add_u64 v[114:115], v[114:115], 0, v[116:117]
	global_store_dwordx2 v[114:115], v[98:99], off offset:256 sc1
	global_store_dwordx2 v[114:115], v[100:101], off offset:288 sc1
	s_cbranch_execnz .LBB0_433
.LBB0_432:
	v_lshl_add_u64 v[104:105], v[0:1], 1, v[104:105]
	v_lshlrev_b32_e32 v114, 1, v139
	v_mov_b32_e32 v115, v1
	v_lshl_add_u64 v[104:105], v[104:105], 0, v[114:115]
	global_store_dwordx4 v[104:105], v[98:101], off offset:256 sc1
.LBB0_433:
	s_and_b64 s[22:23], s[6:7], s[18:19]
	s_and_saveexec_b64 s[18:19], s[22:23]
	s_cbranch_execz .LBB0_435
	v_lshlrev_b32_e32 v98, 4, v102
	v_add_u32_e32 v99, 0xfffffd00, v98
	v_cndmask_b32_e64 v98, v98, v99, s[16:17]
	v_readlane_b32 s16, v253, 40
	v_mov_b32_e32 v99, v1
	v_readlane_b32 s17, v253, 41
	v_lshlrev_b32_e32 v100, 3, v138
	v_mov_b32_e32 v101, v1
	v_lshl_add_u64 v[98:99], v[98:99], 3, s[16:17]
	v_lshl_add_u64 v[104:105], v[98:99], 0, v[100:101]
	global_load_dwordx4 v[98:101], v[104:105], off offset:16
	global_load_dwordx4 v[114:117], v[104:105], off
	v_mul_i32_i24_e32 v120, 6, v113
	v_mov_b32_e32 v103, v1
	s_movk_i32 s1, 0x2040
	s_waitcnt vmcnt(0)
	v_mov_b32_e32 v105, v116
	v_mov_b32_e32 v116, v115
	v_mov_b32_e32 v104, v114
	v_pk_mul_f32 v[114:115], v[94:95], v[116:117]
	v_pk_mul_f32 v[116:117], v[90:91], v[116:117]
	v_pk_fma_f32 v[114:115], v[90:91], v[104:105], v[114:115]
	v_pk_fma_f32 v[104:105], v[94:95], v[104:105], v[116:117] neg_lo:[0,0,1] neg_hi:[0,0,1]
	v_mov_b32_e32 v117, v100
	v_mov_b32_e32 v100, v99
	v_mov_b32_e32 v116, v98
	v_pk_mul_f32 v[98:99], v[96:97], v[100:101]
	s_nop 0
	v_pk_fma_f32 v[118:119], v[92:93], v[116:117], v[98:99]
	v_pk_mul_f32 v[98:99], v[92:93], v[100:101]
	s_nop 0
	v_pk_fma_f32 v[100:101], v[96:97], v[116:117], v[98:99] neg_lo:[0,0,1] neg_hi:[0,0,1]
	v_cvt_pk_bf16_f32 v98, v104, v105
	v_mad_i64_i32 v[104:105], s[16:17], v120, s1, v[102:103]
	v_readlane_b32 s16, v254, 4
	v_readlane_b32 s17, v254, 5
	v_cvt_pk_bf16_f32 v99, v100, v101
	v_cvt_pk_bf16_f32 v100, v114, v115
	v_mov_b64_e32 v[114:115], s[16:17]
	v_mad_u64_u32 v[116:117], s[16:17], v104, s47, v[114:115]
	v_mad_i32_i24 v117, v105, s47, v117
	v_lshlrev_b32_e32 v104, 1, v138
	v_mov_b32_e32 v105, v1
	v_lshl_add_u64 v[116:117], v[116:117], 0, v[104:105]
	v_cvt_pk_bf16_f32 v101, v118, v119
	global_store_dwordx2 v[116:117], v[98:99], off offset:128 sc1
	global_store_dwordx2 v[116:117], v[100:101], off offset:160 sc1
	v_or_b32_e32 v116, 1, v120
	v_mad_i64_i32 v[116:117], s[16:17], v116, s1, v[102:103]
	v_mad_u64_u32 v[118:119], s[16:17], v116, s47, v[114:115]
	v_mad_i32_i24 v119, v117, s47, v119
	v_lshl_add_u64 v[116:117], v[118:119], 0, v[104:105]
	global_store_dwordx2 v[116:117], v[98:99], off offset:128 sc1
	global_store_dwordx2 v[116:117], v[100:101], off offset:160 sc1
	v_mad_i32_i24 v116, v113, 6, 2
	v_mad_i64_i32 v[116:117], s[16:17], v116, s1, v[102:103]
	v_mad_u64_u32 v[118:119], s[16:17], v116, s47, v[114:115]
	v_mad_i32_i24 v119, v117, s47, v119
	v_lshl_add_u64 v[116:117], v[118:119], 0, v[104:105]
	global_store_dwordx2 v[116:117], v[98:99], off offset:128 sc1
	global_store_dwordx2 v[116:117], v[100:101], off offset:160 sc1
	v_mad_i32_i24 v116, v113, 6, 3
	v_mad_i64_i32 v[116:117], s[16:17], v116, s1, v[102:103]
	v_mad_u64_u32 v[118:119], s[16:17], v116, s47, v[114:115]
	v_mad_i32_i24 v119, v117, s47, v119
	v_lshl_add_u64 v[116:117], v[118:119], 0, v[104:105]
	global_store_dwordx2 v[116:117], v[98:99], off offset:128 sc1
	global_store_dwordx2 v[116:117], v[100:101], off offset:160 sc1
	v_mad_i32_i24 v116, v113, 6, 4
	v_mad_i32_i24 v113, v113, 6, 5
	v_mad_i64_i32 v[116:117], s[16:17], v116, s1, v[102:103]
	v_mad_i64_i32 v[102:103], s[16:17], v113, s1, v[102:103]
	v_mad_u64_u32 v[118:119], s[16:17], v116, s47, v[114:115]
	v_mad_u64_u32 v[114:115], s[16:17], v102, s47, v[114:115]
	v_mad_i32_i24 v119, v117, s47, v119
	v_mad_i32_i24 v115, v103, s47, v115
	v_lshl_add_u64 v[116:117], v[118:119], 0, v[104:105]
	v_lshl_add_u64 v[102:103], v[114:115], 0, v[104:105]
	global_store_dwordx2 v[116:117], v[98:99], off offset:128 sc1
	global_store_dwordx2 v[116:117], v[100:101], off offset:160 sc1
	global_store_dwordx2 v[102:103], v[98:99], off offset:128 sc1
	global_store_dwordx2 v[102:103], v[100:101], off offset:160 sc1

; __device__ __forceinline__ unsigned short f2bf(float f) { return (unsigned short)(cvt_pk_bf16(f, f) & 0xffffu); }
; __device__ __forceinline__ void store4bf(bf16_t* p, f32x4 v) { u32x2 w; w.x = cvt_pk_bf16(v[0], v[1]); w.y = cvt_pk_bf16(v[2], v[3]); *(u32x2*)p = w; }
;   __device__ __forceinline__ void group(int row, int c32, int fq, f32x4 v0, f32x4 v1) const {
;     int b, e; const bool ok = row_be(row, b, e);
;     if (c32 < 512) {
;       if (c32 < 384) store8bf(cqkv + (size_t)row * 512 + c32 + fq * 8, v0, v1);
;       else { bf16_t* p = cqkv + (size_t)row * 512 + c32 + fq * 4; store4bf(p, v0); store4bf(p + 16, v1); }
;       if (c32 == 384 && ok) {
;         const float2* rp = rope + pos_of_e(e) * 16 + fq * 4; f32x4 o0, o1;
; #pragma unroll
;         for (int j = 0; j < 4; ++j) { const float2 cs = rp[j]; o0[j] = v0[j] * cs.x - v1[j] * cs.y; o1[j] = v1[j] * cs.x + v0[j] * cs.y; }
; #pragma unroll
;         for (int h = 0; h < 6; ++h) { bf16_t* q = ka + ((size_t)(b * 6 + h) * E + e) * 96 + 64 + fq * 4; store4bf(q, o0); store4bf(q + 16, o1); }
;       }
;       return;
;     }
;     if (!ok) return;
;     if (c32 < 768) { const int cc = c32 - 512, h = cc >> 6; store8bf(qd + ((size_t)(b * 4 + h) * E + e) * 64 + (cc & 63) + fq * 8, v0 * QSC_D, v1 * QSC_D); }
;     else if (c32 < 1024) { const int cc = c32 - 768, h = cc >> 6; store8bf(kd + ((size_t)(b * 4 + h) * E + e) * 64 + (cc & 63) + fq * 8, v0, v1); }
;     else if (c32 < 1280) { const int cc = c32 - 1024, h = cc >> 6; bf16_t* p = vtd + ((size_t)(b * 4 + h) * 64 + (cc & 63) + fq * 4) * E + e;
; #pragma unroll
;       for (int j = 0; j < 4; ++j) { p[(size_t)j * E] = f2bf(v0[j]); p[(size_t)(j + 16) * E] = f2bf(v1[j]); } }
;     else if (c32 < 1664) { const int cc = c32 - 1280, h = cc >> 6; store8bf(qs + ((size_t)(b * 6 + h) * E + e) * 64 + (cc & 63) + fq * 8, v0 * QSC_S, v1 * QSC_S); }
;     else if (c32 < 1792) { const int cc = c32 - 1664, g = cc >> 6; store8bf(ks + ((size_t)(b * 2 + g) * E + e) * 64 + (cc & 63) + fq * 8, v0, v1); }
;     else if (c32 < 1920) { const int cc = c32 - 1792, g = cc >> 6; bf16_t* p = vts + ((size_t)(b * 2 + g) * 64 + (cc & 63) + fq * 4) * E + e;
; #pragma unroll
;       for (int j = 0; j < 4; ++j) { p[(size_t)j * E] = f2bf(v0[j]); p[(size_t)(j + 16) * E] = f2bf(v1[j]); } }
.LBB0_436:
	s_movk_i32 s1, 0x1fdf
	v_or_b32_e32 v98, 16, v132
	v_bitop3_b32 v99, v132, s1, 16 bitop3:0xc8
	s_mov_b32 s1, 0x8000
	v_add_u32_e32 v99, 64, v99
	v_cmp_gt_i32_e64 s[18:19], s1, v98
	s_or_b64 s[70:71], s[18:19], s[14:15]
	s_andn2_b64 vcc, exec, s[68:69]
	v_cndmask_b32_e64 v102, v136, v99, s[18:19]
	v_cndmask_b32_e64 v99, 0, 1, s[68:69]
	v_cndmask_b32_e64 v113, 1, v145, s[18:19]
	v_cmp_ne_u32_e64 s[16:17], 1, v99
	s_mov_b64 s[42:43], -1
	s_cbranch_vccnz .LBB0_460
	s_and_saveexec_b64 s[68:69], s[70:71]
	s_cbranch_execz .LBB0_459
	s_andn2_b64 vcc, exec, s[44:45]
	s_cbranch_vccnz .LBB0_457
	s_andn2_b64 vcc, exec, s[40:41]
	s_cbranch_vccnz .LBB0_454
	s_andn2_b64 vcc, exec, s[38:39]
	s_cbranch_vccnz .LBB0_451
	s_and_saveexec_b64 s[22:23], s[10:11]
	s_xor_b64 s[24:25], exec, s[22:23]
	s_cbranch_execz .LBB0_448
	s_andn2_b64 vcc, exec, s[26:27]
	s_cbranch_vccnz .LBB0_446
	s_and_saveexec_b64 s[42:43], s[8:9]
	s_cbranch_execz .LBB0_445
	v_lshl_add_u32 v100, v113, 1, v110
	v_ashrrev_i32_e32 v101, 31, v100
	v_readlane_b32 s22, v254, 16
	v_lshlrev_b64 v[100:101], 6, v[100:101]
	v_readlane_b32 s23, v254, 17
	v_or_b32_e32 v99, v100, v140
	v_lshlrev_b32_e32 v100, 1, v102
	v_mov_b64_e32 v[104:105], s[22:23]
	v_mad_u64_u32 v[104:105], s[22:23], v99, s95, v[104:105]
	v_mad_i32_i24 v105, v101, s95, v105
	v_mov_b32_e32 v101, v1
	v_lshl_add_u64 v[100:101], v[104:105], 0, v[100:101]
	s_mov_b32 s1, 0x40000
	v_cvt_pk_bf16_f32 v99, v86, s0
	v_add_co_u32_e32 v104, vcc, s1, v100
	global_store_short v[100:101], v99, off sc1
	v_cvt_pk_bf16_f32 v99, v82, s0
	v_addc_co_u32_e32 v105, vcc, 0, v101, vcc
	s_movk_i32 s1, 0x4000
	global_store_short v[104:105], v99, off offset:2048 sc1
	v_add_co_u32_e32 v104, vcc, s1, v100
	v_cvt_pk_bf16_f32 v99, v87, s0
	s_nop 0
	v_addc_co_u32_e32 v105, vcc, 0, v101, vcc
	s_mov_b32 s1, 0x44000
	global_store_short v[104:105], v99, off offset:128 sc1
	v_add_co_u32_e32 v104, vcc, s1, v100
	v_cvt_pk_bf16_f32 v99, v83, s0
	s_nop 0
	v_addc_co_u32_e32 v105, vcc, 0, v101, vcc
	s_mov_b32 s1, 0x8000
	global_store_short v[104:105], v99, off offset:2176 sc1
	v_add_co_u32_e32 v104, vcc, s1, v100
	v_cvt_pk_bf16_f32 v99, v88, s0
	s_nop 0
	v_addc_co_u32_e32 v105, vcc, 0, v101, vcc
	s_mov_b32 s1, 0x48000
	global_store_short v[104:105], v99, off offset:256 sc1
	v_add_co_u32_e32 v104, vcc, s1, v100
	v_cvt_pk_bf16_f32 v99, v84, s0
	s_nop 0
	v_addc_co_u32_e32 v105, vcc, 0, v101, vcc
	global_store_short v[104:105], v99, off offset:2304 sc1
	v_add_co_u32_e32 v104, vcc, 0xc000, v100
	v_cvt_pk_bf16_f32 v99, v89, s0
	s_nop 0
	v_addc_co_u32_e32 v105, vcc, 0, v101, vcc
	v_add_co_u32_e32 v100, vcc, 0x4c000, v100
	global_store_short v[104:105], v99, off offset:384 sc1
	v_cvt_pk_bf16_f32 v99, v85, s0
	v_addc_co_u32_e32 v101, vcc, 0, v101, vcc
	global_store_short v[100:101], v99, off offset:2432 sc1

; __device__ __forceinline__ void store8bf(bf16_t* p, f32x4 v0, f32x4 v1) { u32x4 w; w.x = cvt_pk_bf16(v0[0], v0[1]); w.y = cvt_pk_bf16(v0[2], v0[3]); w.z = cvt_pk_bf16(v1[0], v1[1]); w.w = cvt_pk_bf16(v1[2], v1[3]); *(u32x4*)p = w; }
;   __device__ __forceinline__ void group(int row, int c32, int fq, f32x4 v0, f32x4 v1) const {
;     ...
;     else if (c32 < 1664) { const int cc = c32 - 1280, h = cc >> 6; store8bf(qs + ((size_t)(b * 6 + h) * E + e) * 64 + (cc & 63) + fq * 8, v0 * QSC_S, v1 * QSC_S); }
;     else if (c32 < 1792) { const int cc = c32 - 1664, g = cc >> 6; store8bf(ks + ((size_t)(b * 2 + g) * E + e) * 64 + (cc & 63) + fq * 8, v0, v1); }
.LBB0_446:
	s_andn2_b64 vcc, exec, s[42:43]
	s_cbranch_vccnz .LBB0_448
	v_lshl_add_u32 v99, v113, 1, v109
	v_mov_b32_e32 v103, v1
	s_movk_i32 s1, 0x2040
	v_mad_i64_i32 v[100:101], s[22:23], v99, s1, v[102:103]
	v_readlane_b32 s22, v254, 14
	v_lshlrev_b64 v[100:101], 7, v[100:101]
	v_readlane_b32 s23, v254, 15
	v_lshlrev_b32_e32 v104, 1, v137
	v_mov_b32_e32 v105, v1
	v_lshl_add_u64 v[100:101], s[22:23], 0, v[100:101]
	v_lshl_add_u64 v[100:101], v[100:101], 0, v[104:105]
	v_lshlrev_b32_e32 v104, 1, v139
	v_lshl_add_u64 v[100:101], v[100:101], 0, v[104:105]
	v_cvt_pk_bf16_f32 v114, v86, v87
	v_cvt_pk_bf16_f32 v115, v88, v89
	v_cvt_pk_bf16_f32 v116, v82, v83
	v_cvt_pk_bf16_f32 v117, v84, v85
	global_store_dwordx4 v[100:101], v[114:117], off sc1
.LBB0_448:
	s_andn2_saveexec_b64 s[42:43], s[24:25]
	s_cbranch_execz .LBB0_450
	v_mad_i32_i24 v99, v113, 6, v111
	v_mov_b32_e32 v103, v1
	s_movk_i32 s1, 0x2040
	v_mad_i64_i32 v[100:101], s[22:23], v99, s1, v[102:103]
	v_readlane_b32 s22, v254, 12
	v_lshlrev_b64 v[100:101], 7, v[100:101]
	v_readlane_b32 s23, v254, 13
	v_lshlrev_b32_e32 v104, 1, v137
	v_mov_b32_e32 v105, v1
	v_lshl_add_u64 v[100:101], s[22:23], 0, v[100:101]
	v_lshl_add_u64 v[100:101], v[100:101], 0, v[104:105]
	v_lshlrev_b32_e32 v104, 1, v139
	s_mov_b32 s22, 0x3e38aa3b
	v_lshl_add_u64 v[100:101], v[100:101], 0, v[104:105]
	v_pk_mul_f32 v[104:105], v[88:89], s[22:23] op_sel_hi:[1,0]
	v_pk_mul_f32 v[114:115], v[86:87], s[22:23] op_sel_hi:[1,0]
	v_pk_mul_f32 v[118:119], v[84:85], s[22:23] op_sel_hi:[1,0]
	v_pk_mul_f32 v[116:117], v[82:83], s[22:23] op_sel_hi:[1,0]
	v_cvt_pk_bf16_f32 v114, v114, v115
	v_cvt_pk_bf16_f32 v115, v104, v105
	v_cvt_pk_bf16_f32 v116, v116, v117
	v_cvt_pk_bf16_f32 v117, v118, v119
	global_store_dwordx4 v[100:101], v[114:117], off sc1

; __device__ __forceinline__ unsigned short f2bf(float f) { return (unsigned short)(cvt_pk_bf16(f, f) & 0xffffu); }
;   __device__ __forceinline__ void group(int row, int c32, int fq, f32x4 v0, f32x4 v1) const {
;     ...
;     else if (c32 < 1280) { const int cc = c32 - 1024, h = cc >> 6; bf16_t* p = vtd + ((size_t)(b * 4 + h) * 64 + (cc & 63) + fq * 4) * E + e;
; #pragma unroll
;       for (int j = 0; j < 4; ++j) { p[(size_t)j * E] = f2bf(v0[j]); p[(size_t)(j + 16) * E] = f2bf(v1[j]); } }
.LBB0_451:
	s_andn2_b64 vcc, exec, s[42:43]
	s_cbranch_vccnz .LBB0_453
	v_lshl_add_u32 v100, v113, 2, v106
	v_ashrrev_i32_e32 v101, 31, v100
	v_readlane_b32 s22, v254, 10
	v_lshlrev_b64 v[100:101], 6, v[100:101]
	v_readlane_b32 s23, v254, 11
	v_or_b32_e32 v99, v100, v140
	v_lshlrev_b32_e32 v100, 1, v102
	v_mov_b64_e32 v[104:105], s[22:23]
	v_mad_u64_u32 v[104:105], s[22:23], v99, s95, v[104:105]
	v_mad_i32_i24 v105, v101, s95, v105
	v_mov_b32_e32 v101, v1
	v_lshl_add_u64 v[100:101], v[104:105], 0, v[100:101]
	s_mov_b32 s1, 0x40000
	v_cvt_pk_bf16_f32 v99, v86, s0
	v_add_co_u32_e32 v104, vcc, s1, v100
	global_store_short v[100:101], v99, off sc1
	v_cvt_pk_bf16_f32 v99, v82, s0
	v_addc_co_u32_e32 v105, vcc, 0, v101, vcc
	s_movk_i32 s1, 0x4000
	global_store_short v[104:105], v99, off offset:2048 sc1
	v_add_co_u32_e32 v104, vcc, s1, v100
	v_cvt_pk_bf16_f32 v99, v87, s0
	s_nop 0
	v_addc_co_u32_e32 v105, vcc, 0, v101, vcc
	s_mov_b32 s1, 0x44000
	global_store_short v[104:105], v99, off offset:128 sc1
	v_add_co_u32_e32 v104, vcc, s1, v100
	v_cvt_pk_bf16_f32 v99, v83, s0
	s_nop 0
	v_addc_co_u32_e32 v105, vcc, 0, v101, vcc
	s_mov_b32 s1, 0x8000
	global_store_short v[104:105], v99, off offset:2176 sc1
	v_add_co_u32_e32 v104, vcc, s1, v100
	v_cvt_pk_bf16_f32 v99, v88, s0
	s_nop 0
	v_addc_co_u32_e32 v105, vcc, 0, v101, vcc
	s_mov_b32 s1, 0x48000
	global_store_short v[104:105], v99, off offset:256 sc1
	v_add_co_u32_e32 v104, vcc, s1, v100
	v_cvt_pk_bf16_f32 v99, v84, s0
	s_nop 0
	v_addc_co_u32_e32 v105, vcc, 0, v101, vcc
	global_store_short v[104:105], v99, off offset:2304 sc1
	v_add_co_u32_e32 v104, vcc, 0xc000, v100
	v_cvt_pk_bf16_f32 v99, v89, s0
	s_nop 0
	v_addc_co_u32_e32 v105, vcc, 0, v101, vcc
	v_add_co_u32_e32 v100, vcc, 0x4c000, v100
	global_store_short v[104:105], v99, off offset:384 sc1
	v_cvt_pk_bf16_f32 v99, v85, s0
	v_addc_co_u32_e32 v101, vcc, 0, v101, vcc
	global_store_short v[100:101], v99, off offset:2432 sc1

; __device__ __forceinline__ void store8bf(bf16_t* p, f32x4 v0, f32x4 v1) { u32x4 w; w.x = cvt_pk_bf16(v0[0], v0[1]); w.y = cvt_pk_bf16(v0[2], v0[3]); w.z = cvt_pk_bf16(v1[0], v1[1]); w.w = cvt_pk_bf16(v1[2], v1[3]); *(u32x4*)p = w; }
;   __device__ __forceinline__ void group(int row, int c32, int fq, f32x4 v0, f32x4 v1) const {
;     ...
;     else if (c32 < 1024) { const int cc = c32 - 768, h = cc >> 6; store8bf(kd + ((size_t)(b * 4 + h) * E + e) * 64 + (cc & 63) + fq * 8, v0, v1); }
.LBB0_454:
	s_andn2_b64 vcc, exec, s[42:43]
	s_cbranch_vccnz .LBB0_456
	v_lshl_add_u32 v99, v113, 2, v108
	v_mov_b32_e32 v103, v1
	s_movk_i32 s1, 0x2040
	v_mad_i64_i32 v[100:101], s[22:23], v99, s1, v[102:103]
	v_readlane_b32 s22, v254, 8
	v_lshlrev_b64 v[100:101], 7, v[100:101]
	v_readlane_b32 s23, v254, 9
	v_lshlrev_b32_e32 v104, 1, v137
	v_mov_b32_e32 v105, v1
	v_lshl_add_u64 v[100:101], s[22:23], 0, v[100:101]
	v_lshl_add_u64 v[100:101], v[100:101], 0, v[104:105]
	v_lshlrev_b32_e32 v104, 1, v139
	v_lshl_add_u64 v[100:101], v[100:101], 0, v[104:105]
	v_cvt_pk_bf16_f32 v114, v86, v87
	v_cvt_pk_bf16_f32 v115, v88, v89
	v_cvt_pk_bf16_f32 v116, v82, v83
	v_cvt_pk_bf16_f32 v117, v84, v85
	global_store_dwordx4 v[100:101], v[114:117], off sc1

; __device__ __forceinline__ void store8bf(bf16_t* p, f32x4 v0, f32x4 v1) { u32x4 w; w.x = cvt_pk_bf16(v0[0], v0[1]); w.y = cvt_pk_bf16(v0[2], v0[3]); w.z = cvt_pk_bf16(v1[0], v1[1]); w.w = cvt_pk_bf16(v1[2], v1[3]); *(u32x4*)p = w; }
;   __device__ __forceinline__ void group(int row, int c32, int fq, f32x4 v0, f32x4 v1) const {
;     ...
;     if (c32 < 768) { const int cc = c32 - 512, h = cc >> 6; store8bf(qd + ((size_t)(b * 4 + h) * E + e) * 64 + (cc & 63) + fq * 8, v0 * QSC_D, v1 * QSC_D); }
.LBB0_457:
	s_andn2_b64 vcc, exec, s[42:43]
	s_cbranch_vccnz .LBB0_459
	v_lshl_add_u32 v99, v113, 2, v107
	v_mov_b32_e32 v103, v1
	s_movk_i32 s1, 0x2040
	v_mad_i64_i32 v[100:101], s[22:23], v99, s1, v[102:103]
	v_readlane_b32 s22, v254, 6
	v_lshlrev_b64 v[100:101], 7, v[100:101]
	v_readlane_b32 s23, v254, 7
	v_lshlrev_b32_e32 v104, 1, v137
	v_mov_b32_e32 v105, v1
	v_lshl_add_u64 v[100:101], s[22:23], 0, v[100:101]
	v_lshl_add_u64 v[100:101], v[100:101], 0, v[104:105]
	v_lshlrev_b32_e32 v104, 1, v139
	s_mov_b32 s22, 0x3e8293ee
	v_lshl_add_u64 v[100:101], v[100:101], 0, v[104:105]
	v_pk_mul_f32 v[104:105], v[88:89], s[22:23] op_sel_hi:[1,0]
	v_pk_mul_f32 v[114:115], v[86:87], s[22:23] op_sel_hi:[1,0]
	v_pk_mul_f32 v[118:119], v[84:85], s[22:23] op_sel_hi:[1,0]
	v_pk_mul_f32 v[116:117], v[82:83], s[22:23] op_sel_hi:[1,0]
	v_cvt_pk_bf16_f32 v114, v114, v115
	v_cvt_pk_bf16_f32 v115, v104, v105
	v_cvt_pk_bf16_f32 v116, v116, v117
	v_cvt_pk_bf16_f32 v117, v118, v119
	global_store_dwordx4 v[100:101], v[114:117], off sc1

; __device__ __forceinline__ void store4bf(bf16_t* p, f32x4 v) { u32x2 w; w.x = cvt_pk_bf16(v[0], v[1]); w.y = cvt_pk_bf16(v[2], v[3]); *(u32x2*)p = w; }
; __device__ __forceinline__ void store8bf(bf16_t* p, f32x4 v0, f32x4 v1) { u32x4 w; w.x = cvt_pk_bf16(v0[0], v0[1]); w.y = cvt_pk_bf16(v0[2], v0[3]); w.z = cvt_pk_bf16(v1[0], v1[1]); w.w = cvt_pk_bf16(v1[2], v1[3]); *(u32x4*)p = w; }
;   __device__ __forceinline__ void group(int row, int c32, int fq, f32x4 v0, f32x4 v1) const {
;     ...
;     if (c32 < 512) {
;       if (c32 < 384) store8bf(cqkv + (size_t)row * 512 + c32 + fq * 8, v0, v1);
;       else { bf16_t* p = cqkv + (size_t)row * 512 + c32 + fq * 4; store4bf(p, v0); store4bf(p + 16, v1); }
.LBB0_460:
	s_andn2_b64 vcc, exec, s[42:43]
	s_cbranch_vccnz .LBB0_467
	v_ashrrev_i32_e32 v99, 31, v98
	v_readlane_b32 s22, v254, 0
	v_lshlrev_b64 v[98:99], 10, v[98:99]
	v_readlane_b32 s23, v254, 1
	s_and_b64 vcc, exec, s[12:13]
	v_cvt_pk_bf16_f32 v100, v82, v83
	v_lshl_add_u64 v[104:105], s[22:23], 0, v[98:99]
	v_cvt_pk_bf16_f32 v98, v86, v87
	v_cvt_pk_bf16_f32 v99, v88, v89
	v_cvt_pk_bf16_f32 v101, v84, v85
	s_cbranch_vccnz .LBB0_762
	v_lshl_add_u64 v[114:115], v[0:1], 1, v[104:105]
	v_lshlrev_b32_e32 v116, 1, v138
	v_mov_b32_e32 v117, v1
	v_lshl_add_u64 v[114:115], v[114:115], 0, v[116:117]
	global_store_dwordx2 v[114:115], v[98:99], off offset:256 sc1
	global_store_dwordx2 v[114:115], v[100:101], off offset:288 sc1
	s_cbranch_execnz .LBB0_464

; __device__ __forceinline__ void store4bf(bf16_t* p, f32x4 v) { u32x2 w; w.x = cvt_pk_bf16(v[0], v[1]); w.y = cvt_pk_bf16(v[2], v[3]); *(u32x2*)p = w; }
;   __device__ __forceinline__ void group(int row, int c32, int fq, f32x4 v0, f32x4 v1) const {
;     ...
;       if (c32 == 384 && ok) {
;         const float2* rp = rope + pos_of_e(e) * 16 + fq * 4; f32x4 o0, o1;
; #pragma unroll
;         for (int j = 0; j < 4; ++j) { const float2 cs = rp[j]; o0[j] = v0[j] * cs.x - v1[j] * cs.y; o1[j] = v1[j] * cs.x + v0[j] * cs.y; }
; #pragma unroll
;         for (int h = 0; h < 6; ++h) { bf16_t* q = ka + ((size_t)(b * 6 + h) * E + e) * 96 + 64 + fq * 4; store4bf(q, o0); store4bf(q + 16, o1); }
;       }
.LBB0_464:
	s_and_b64 s[22:23], s[6:7], s[70:71]
	s_and_saveexec_b64 s[68:69], s[22:23]
	s_cbranch_execz .LBB0_466
	v_lshlrev_b32_e32 v98, 4, v102
	v_add_u32_e32 v99, 0xfffffd00, v98
	v_cndmask_b32_e64 v98, v98, v99, s[18:19]
	v_readlane_b32 s18, v253, 40
	v_mov_b32_e32 v99, v1
	v_readlane_b32 s19, v253, 41
	v_lshlrev_b32_e32 v100, 3, v138
	v_mov_b32_e32 v101, v1
	v_lshl_add_u64 v[98:99], v[98:99], 3, s[18:19]
	v_lshl_add_u64 v[104:105], v[98:99], 0, v[100:101]
	global_load_dwordx4 v[98:101], v[104:105], off offset:16
	global_load_dwordx4 v[114:117], v[104:105], off
	v_mul_i32_i24_e32 v120, 6, v113
	v_mov_b32_e32 v103, v1
	s_movk_i32 s1, 0x2040
	s_waitcnt vmcnt(0)
	v_mov_b32_e32 v105, v116
	v_mov_b32_e32 v116, v115
	v_mov_b32_e32 v104, v114
	v_pk_mul_f32 v[114:115], v[86:87], v[116:117]
	v_pk_mul_f32 v[116:117], v[82:83], v[116:117]
	v_pk_fma_f32 v[114:115], v[82:83], v[104:105], v[114:115]
	v_pk_fma_f32 v[104:105], v[86:87], v[104:105], v[116:117] neg_lo:[0,0,1] neg_hi:[0,0,1]
	v_mov_b32_e32 v117, v100
	v_mov_b32_e32 v100, v99
	v_mov_b32_e32 v116, v98
	v_pk_mul_f32 v[98:99], v[88:89], v[100:101]
	s_nop 0
	v_pk_fma_f32 v[118:119], v[84:85], v[116:117], v[98:99]
	v_pk_mul_f32 v[98:99], v[84:85], v[100:101]
	s_nop 0
	v_pk_fma_f32 v[100:101], v[88:89], v[116:117], v[98:99] neg_lo:[0,0,1] neg_hi:[0,0,1]
	v_cvt_pk_bf16_f32 v98, v104, v105
	v_mad_i64_i32 v[104:105], s[18:19], v120, s1, v[102:103]
	v_readlane_b32 s18, v254, 4
	v_readlane_b32 s19, v254, 5
	v_cvt_pk_bf16_f32 v99, v100, v101
	v_cvt_pk_bf16_f32 v100, v114, v115
	v_mov_b64_e32 v[114:115], s[18:19]
	v_mad_u64_u32 v[116:117], s[18:19], v104, s47, v[114:115]
	v_mad_i32_i24 v117, v105, s47, v117
	v_lshlrev_b32_e32 v104, 1, v138
	v_mov_b32_e32 v105, v1
	v_lshl_add_u64 v[116:117], v[116:117], 0, v[104:105]
	v_cvt_pk_bf16_f32 v101, v118, v119
	global_store_dwordx2 v[116:117], v[98:99], off offset:128 sc1
	global_store_dwordx2 v[116:117], v[100:101], off offset:160 sc1
	v_or_b32_e32 v116, 1, v120
	v_mad_i64_i32 v[116:117], s[18:19], v116, s1, v[102:103]
	v_mad_u64_u32 v[118:119], s[18:19], v116, s47, v[114:115]
	v_mad_i32_i24 v119, v117, s47, v119
	v_lshl_add_u64 v[116:117], v[118:119], 0, v[104:105]
	global_store_dwordx2 v[116:117], v[98:99], off offset:128 sc1
	global_store_dwordx2 v[116:117], v[100:101], off offset:160 sc1
	v_mad_i32_i24 v116, v113, 6, 2
	v_mad_i64_i32 v[116:117], s[18:19], v116, s1, v[102:103]
	v_mad_u64_u32 v[118:119], s[18:19], v116, s47, v[114:115]
	v_mad_i32_i24 v119, v117, s47, v119
	v_lshl_add_u64 v[116:117], v[118:119], 0, v[104:105]
	global_store_dwordx2 v[116:117], v[98:99], off offset:128 sc1
	global_store_dwordx2 v[116:117], v[100:101], off offset:160 sc1
	v_mad_i32_i24 v116, v113, 6, 3
	v_mad_i64_i32 v[116:117], s[18:19], v116, s1, v[102:103]
	v_mad_u64_u32 v[118:119], s[18:19], v116, s47, v[114:115]
	v_mad_i32_i24 v119, v117, s47, v119
	v_lshl_add_u64 v[116:117], v[118:119], 0, v[104:105]
	global_store_dwordx2 v[116:117], v[98:99], off offset:128 sc1
	global_store_dwordx2 v[116:117], v[100:101], off offset:160 sc1
	v_mad_i32_i24 v116, v113, 6, 4
	v_mad_i32_i24 v113, v113, 6, 5
	v_mad_i64_i32 v[116:117], s[18:19], v116, s1, v[102:103]
	v_mad_i64_i32 v[102:103], s[18:19], v113, s1, v[102:103]
	v_mad_u64_u32 v[118:119], s[18:19], v116, s47, v[114:115]
	v_mad_u64_u32 v[114:115], s[18:19], v102, s47, v[114:115]
	v_mad_i32_i24 v119, v117, s47, v119
	v_mad_i32_i24 v115, v103, s47, v115
	v_lshl_add_u64 v[116:117], v[118:119], 0, v[104:105]
	v_lshl_add_u64 v[102:103], v[114:115], 0, v[104:105]
	global_store_dwordx2 v[116:117], v[98:99], off offset:128 sc1
	global_store_dwordx2 v[116:117], v[100:101], off offset:160 sc1
	global_store_dwordx2 v[102:103], v[98:99], off offset:128 sc1
	global_store_dwordx2 v[102:103], v[100:101], off offset:160 sc1

; __device__ __forceinline__ unsigned short f2bf(float f) { return (unsigned short)(cvt_pk_bf16(f, f) & 0xffffu); }
; __device__ __forceinline__ void store4bf(bf16_t* p, f32x4 v) { u32x2 w; w.x = cvt_pk_bf16(v[0], v[1]); w.y = cvt_pk_bf16(v[2], v[3]); *(u32x2*)p = w; }
;   __device__ __forceinline__ void group(int row, int c32, int fq, f32x4 v0, f32x4 v1) const {
;     int b, e; const bool ok = row_be(row, b, e);
;     if (c32 < 512) {
;       if (c32 < 384) store8bf(cqkv + (size_t)row * 512 + c32 + fq * 8, v0, v1);
;       else { bf16_t* p = cqkv + (size_t)row * 512 + c32 + fq * 4; store4bf(p, v0); store4bf(p + 16, v1); }
;       if (c32 == 384 && ok) {
;         const float2* rp = rope + pos_of_e(e) * 16 + fq * 4; f32x4 o0, o1;
; #pragma unroll
;         for (int j = 0; j < 4; ++j) { const float2 cs = rp[j]; o0[j] = v0[j] * cs.x - v1[j] * cs.y; o1[j] = v1[j] * cs.x + v0[j] * cs.y; }
; #pragma unroll
;         for (int h = 0; h < 6; ++h) { bf16_t* q = ka + ((size_t)(b * 6 + h) * E + e) * 96 + 64 + fq * 4; store4bf(q, o0); store4bf(q + 16, o1); }
;       }
;       return;
;     }
;     if (!ok) return;
;     if (c32 < 768) { const int cc = c32 - 512, h = cc >> 6; store8bf(qd + ((size_t)(b * 4 + h) * E + e) * 64 + (cc & 63) + fq * 8, v0 * QSC_D, v1 * QSC_D); }
;     else if (c32 < 1024) { const int cc = c32 - 768, h = cc >> 6; store8bf(kd + ((size_t)(b * 4 + h) * E + e) * 64 + (cc & 63) + fq * 8, v0, v1); }
;     else if (c32 < 1280) { const int cc = c32 - 1024, h = cc >> 6; bf16_t* p = vtd + ((size_t)(b * 4 + h) * 64 + (cc & 63) + fq * 4) * E + e;
; #pragma unroll
;       for (int j = 0; j < 4; ++j) { p[(size_t)j * E] = f2bf(v0[j]); p[(size_t)(j + 16) * E] = f2bf(v1[j]); } }
;     else if (c32 < 1664) { const int cc = c32 - 1280, h = cc >> 6; store8bf(qs + ((size_t)(b * 6 + h) * E + e) * 64 + (cc & 63) + fq * 8, v0 * QSC_S, v1 * QSC_S); }
;     else if (c32 < 1792) { const int cc = c32 - 1664, g = cc >> 6; store8bf(ks + ((size_t)(b * 2 + g) * E + e) * 64 + (cc & 63) + fq * 8, v0, v1); }
;     else if (c32 < 1920) { const int cc = c32 - 1792, g = cc >> 6; bf16_t* p = vts + ((size_t)(b * 2 + g) * 64 + (cc & 63) + fq * 4) * E + e;
; #pragma unroll
;       for (int j = 0; j < 4; ++j) { p[(size_t)j * E] = f2bf(v0[j]); p[(size_t)(j + 16) * E] = f2bf(v1[j]); } }
.LBB0_467:
	s_movk_i32 s1, 0x1fef
	v_or_b32_e32 v98, 32, v132
	v_bitop3_b32 v99, v132, s1, 32 bitop3:0xc8
	s_mov_b32 s1, 0x8000
	v_add_u32_e32 v99, 64, v99
	v_cmp_gt_i32_e64 s[18:19], s1, v98
	s_or_b64 s[68:69], s[18:19], s[14:15]
	s_and_b64 vcc, exec, s[16:17]
	v_cndmask_b32_e64 v113, 2, v145, s[18:19]
	v_cndmask_b32_e64 v102, v136, v99, s[18:19]
	s_mov_b64 s[42:43], -1
	s_cbranch_vccnz .LBB0_491
	s_and_saveexec_b64 s[70:71], s[68:69]
	s_cbranch_execz .LBB0_490
	s_andn2_b64 vcc, exec, s[44:45]
	s_cbranch_vccnz .LBB0_488
	s_andn2_b64 vcc, exec, s[40:41]
	s_cbranch_vccnz .LBB0_485
	s_andn2_b64 vcc, exec, s[38:39]
	s_cbranch_vccnz .LBB0_482
	s_and_saveexec_b64 s[22:23], s[10:11]
	s_xor_b64 s[24:25], exec, s[22:23]
	s_cbranch_execz .LBB0_479
	s_andn2_b64 vcc, exec, s[26:27]
	s_cbranch_vccnz .LBB0_477
	s_and_saveexec_b64 s[42:43], s[8:9]
	s_cbranch_execz .LBB0_476
	v_lshl_add_u32 v100, v113, 1, v110
	v_ashrrev_i32_e32 v101, 31, v100
	v_readlane_b32 s22, v254, 16
	v_lshlrev_b64 v[100:101], 6, v[100:101]
	v_readlane_b32 s23, v254, 17
	v_or_b32_e32 v99, v100, v140
	v_lshlrev_b32_e32 v100, 1, v102
	v_mov_b64_e32 v[104:105], s[22:23]
	v_mad_u64_u32 v[104:105], s[22:23], v99, s95, v[104:105]
	v_mad_i32_i24 v105, v101, s95, v105
	v_mov_b32_e32 v101, v1
	v_lshl_add_u64 v[100:101], v[104:105], 0, v[100:101]
	s_mov_b32 s1, 0x40000
	v_cvt_pk_bf16_f32 v99, v78, s0
	v_add_co_u32_e32 v104, vcc, s1, v100
	global_store_short v[100:101], v99, off sc1
	v_cvt_pk_bf16_f32 v99, v74, s0
	v_addc_co_u32_e32 v105, vcc, 0, v101, vcc
	s_movk_i32 s1, 0x4000
	global_store_short v[104:105], v99, off offset:2048 sc1
	v_add_co_u32_e32 v104, vcc, s1, v100
	v_cvt_pk_bf16_f32 v99, v79, s0
	s_nop 0
	v_addc_co_u32_e32 v105, vcc, 0, v101, vcc
	s_mov_b32 s1, 0x44000
	global_store_short v[104:105], v99, off offset:128 sc1
	v_add_co_u32_e32 v104, vcc, s1, v100
	v_cvt_pk_bf16_f32 v99, v75, s0
	s_nop 0
	v_addc_co_u32_e32 v105, vcc, 0, v101, vcc
	s_mov_b32 s1, 0x8000
	global_store_short v[104:105], v99, off offset:2176 sc1
	v_add_co_u32_e32 v104, vcc, s1, v100
	v_cvt_pk_bf16_f32 v99, v80, s0
	s_nop 0
	v_addc_co_u32_e32 v105, vcc, 0, v101, vcc
	s_mov_b32 s1, 0x48000
	global_store_short v[104:105], v99, off offset:256 sc1
	v_add_co_u32_e32 v104, vcc, s1, v100
	v_cvt_pk_bf16_f32 v99, v76, s0
	s_nop 0
	v_addc_co_u32_e32 v105, vcc, 0, v101, vcc
	global_store_short v[104:105], v99, off offset:2304 sc1
	v_add_co_u32_e32 v104, vcc, 0xc000, v100
	v_cvt_pk_bf16_f32 v99, v81, s0
	s_nop 0
	v_addc_co_u32_e32 v105, vcc, 0, v101, vcc
	v_add_co_u32_e32 v100, vcc, 0x4c000, v100
	global_store_short v[104:105], v99, off offset:384 sc1
	v_cvt_pk_bf16_f32 v99, v77, s0
	v_addc_co_u32_e32 v101, vcc, 0, v101, vcc
	global_store_short v[100:101], v99, off offset:2432 sc1

; __device__ __forceinline__ void store8bf(bf16_t* p, f32x4 v0, f32x4 v1) { u32x4 w; w.x = cvt_pk_bf16(v0[0], v0[1]); w.y = cvt_pk_bf16(v0[2], v0[3]); w.z = cvt_pk_bf16(v1[0], v1[1]); w.w = cvt_pk_bf16(v1[2], v1[3]); *(u32x4*)p = w; }
;   __device__ __forceinline__ void group(int row, int c32, int fq, f32x4 v0, f32x4 v1) const {
;     ...
;     else if (c32 < 1664) { const int cc = c32 - 1280, h = cc >> 6; store8bf(qs + ((size_t)(b * 6 + h) * E + e) * 64 + (cc & 63) + fq * 8, v0 * QSC_S, v1 * QSC_S); }
;     else if (c32 < 1792) { const int cc = c32 - 1664, g = cc >> 6; store8bf(ks + ((size_t)(b * 2 + g) * E + e) * 64 + (cc & 63) + fq * 8, v0, v1); }
.LBB0_477:
	s_andn2_b64 vcc, exec, s[42:43]
	s_cbranch_vccnz .LBB0_479
	v_lshl_add_u32 v99, v113, 1, v109
	v_mov_b32_e32 v103, v1
	s_movk_i32 s1, 0x2040
	v_mad_i64_i32 v[100:101], s[22:23], v99, s1, v[102:103]
	v_readlane_b32 s22, v254, 14
	v_lshlrev_b64 v[100:101], 7, v[100:101]
	v_readlane_b32 s23, v254, 15
	v_lshlrev_b32_e32 v104, 1, v137
	v_mov_b32_e32 v105, v1
	v_lshl_add_u64 v[100:101], s[22:23], 0, v[100:101]
	v_lshl_add_u64 v[100:101], v[100:101], 0, v[104:105]
	v_lshlrev_b32_e32 v104, 1, v139
	v_lshl_add_u64 v[100:101], v[100:101], 0, v[104:105]
	v_cvt_pk_bf16_f32 v114, v78, v79
	v_cvt_pk_bf16_f32 v115, v80, v81
	v_cvt_pk_bf16_f32 v116, v74, v75
	v_cvt_pk_bf16_f32 v117, v76, v77
	global_store_dwordx4 v[100:101], v[114:117], off sc1
.LBB0_479:
	s_andn2_saveexec_b64 s[42:43], s[24:25]
	s_cbranch_execz .LBB0_481
	v_mad_i32_i24 v99, v113, 6, v111
	v_mov_b32_e32 v103, v1
	s_movk_i32 s1, 0x2040
	v_mad_i64_i32 v[100:101], s[22:23], v99, s1, v[102:103]
	v_readlane_b32 s22, v254, 12
	v_lshlrev_b64 v[100:101], 7, v[100:101]
	v_readlane_b32 s23, v254, 13
	v_lshlrev_b32_e32 v104, 1, v137
	v_mov_b32_e32 v105, v1
	v_lshl_add_u64 v[100:101], s[22:23], 0, v[100:101]
	v_lshl_add_u64 v[100:101], v[100:101], 0, v[104:105]
	v_lshlrev_b32_e32 v104, 1, v139
	s_mov_b32 s22, 0x3e38aa3b
	v_lshl_add_u64 v[100:101], v[100:101], 0, v[104:105]
	v_pk_mul_f32 v[104:105], v[80:81], s[22:23] op_sel_hi:[1,0]
	v_pk_mul_f32 v[114:115], v[78:79], s[22:23] op_sel_hi:[1,0]
	v_pk_mul_f32 v[118:119], v[76:77], s[22:23] op_sel_hi:[1,0]
	v_pk_mul_f32 v[116:117], v[74:75], s[22:23] op_sel_hi:[1,0]
	v_cvt_pk_bf16_f32 v114, v114, v115
	v_cvt_pk_bf16_f32 v115, v104, v105
	v_cvt_pk_bf16_f32 v116, v116, v117
	v_cvt_pk_bf16_f32 v117, v118, v119
	global_store_dwordx4 v[100:101], v[114:117], off sc1

; __device__ __forceinline__ unsigned short f2bf(float f) { return (unsigned short)(cvt_pk_bf16(f, f) & 0xffffu); }
;   __device__ __forceinline__ void group(int row, int c32, int fq, f32x4 v0, f32x4 v1) const {
;     ...
;     else if (c32 < 1280) { const int cc = c32 - 1024, h = cc >> 6; bf16_t* p = vtd + ((size_t)(b * 4 + h) * 64 + (cc & 63) + fq * 4) * E + e;
; #pragma unroll
;       for (int j = 0; j < 4; ++j) { p[(size_t)j * E] = f2bf(v0[j]); p[(size_t)(j + 16) * E] = f2bf(v1[j]); } }
.LBB0_482:
	s_andn2_b64 vcc, exec, s[42:43]
	s_cbranch_vccnz .LBB0_484
	v_lshl_add_u32 v100, v113, 2, v106
	v_ashrrev_i32_e32 v101, 31, v100
	v_readlane_b32 s22, v254, 10
	v_lshlrev_b64 v[100:101], 6, v[100:101]
	v_readlane_b32 s23, v254, 11
	v_or_b32_e32 v99, v100, v140
	v_lshlrev_b32_e32 v100, 1, v102
	v_mov_b64_e32 v[104:105], s[22:23]
	v_mad_u64_u32 v[104:105], s[22:23], v99, s95, v[104:105]
	v_mad_i32_i24 v105, v101, s95, v105
	v_mov_b32_e32 v101, v1
	v_lshl_add_u64 v[100:101], v[104:105], 0, v[100:101]
	s_mov_b32 s1, 0x40000
	v_cvt_pk_bf16_f32 v99, v78, s0
	v_add_co_u32_e32 v104, vcc, s1, v100
	global_store_short v[100:101], v99, off sc1
	v_cvt_pk_bf16_f32 v99, v74, s0
	v_addc_co_u32_e32 v105, vcc, 0, v101, vcc
	s_movk_i32 s1, 0x4000
	global_store_short v[104:105], v99, off offset:2048 sc1
	v_add_co_u32_e32 v104, vcc, s1, v100
	v_cvt_pk_bf16_f32 v99, v79, s0
	s_nop 0
	v_addc_co_u32_e32 v105, vcc, 0, v101, vcc
	s_mov_b32 s1, 0x44000
	global_store_short v[104:105], v99, off offset:128 sc1
	v_add_co_u32_e32 v104, vcc, s1, v100
	v_cvt_pk_bf16_f32 v99, v75, s0
	s_nop 0
	v_addc_co_u32_e32 v105, vcc, 0, v101, vcc
	s_mov_b32 s1, 0x8000
	global_store_short v[104:105], v99, off offset:2176 sc1
	v_add_co_u32_e32 v104, vcc, s1, v100
	v_cvt_pk_bf16_f32 v99, v80, s0
	s_nop 0
	v_addc_co_u32_e32 v105, vcc, 0, v101, vcc
	s_mov_b32 s1, 0x48000
	global_store_short v[104:105], v99, off offset:256 sc1
	v_add_co_u32_e32 v104, vcc, s1, v100
	v_cvt_pk_bf16_f32 v99, v76, s0
	s_nop 0
	v_addc_co_u32_e32 v105, vcc, 0, v101, vcc
	global_store_short v[104:105], v99, off offset:2304 sc1
	v_add_co_u32_e32 v104, vcc, 0xc000, v100
	v_cvt_pk_bf16_f32 v99, v81, s0
	s_nop 0
	v_addc_co_u32_e32 v105, vcc, 0, v101, vcc
	v_add_co_u32_e32 v100, vcc, 0x4c000, v100
	global_store_short v[104:105], v99, off offset:384 sc1
	v_cvt_pk_bf16_f32 v99, v77, s0
	v_addc_co_u32_e32 v101, vcc, 0, v101, vcc
	global_store_short v[100:101], v99, off offset:2432 sc1

; __device__ __forceinline__ void store8bf(bf16_t* p, f32x4 v0, f32x4 v1) { u32x4 w; w.x = cvt_pk_bf16(v0[0], v0[1]); w.y = cvt_pk_bf16(v0[2], v0[3]); w.z = cvt_pk_bf16(v1[0], v1[1]); w.w = cvt_pk_bf16(v1[2], v1[3]); *(u32x4*)p = w; }
;   __device__ __forceinline__ void group(int row, int c32, int fq, f32x4 v0, f32x4 v1) const {
;     ...
;     else if (c32 < 1024) { const int cc = c32 - 768, h = cc >> 6; store8bf(kd + ((size_t)(b * 4 + h) * E + e) * 64 + (cc & 63) + fq * 8, v0, v1); }
.LBB0_485:
	s_andn2_b64 vcc, exec, s[42:43]
	s_cbranch_vccnz .LBB0_487
	v_lshl_add_u32 v99, v113, 2, v108
	v_mov_b32_e32 v103, v1
	s_movk_i32 s1, 0x2040
	v_mad_i64_i32 v[100:101], s[22:23], v99, s1, v[102:103]
	v_readlane_b32 s22, v254, 8
	v_lshlrev_b64 v[100:101], 7, v[100:101]
	v_readlane_b32 s23, v254, 9
	v_lshlrev_b32_e32 v104, 1, v137
	v_mov_b32_e32 v105, v1
	v_lshl_add_u64 v[100:101], s[22:23], 0, v[100:101]
	v_lshl_add_u64 v[100:101], v[100:101], 0, v[104:105]
	v_lshlrev_b32_e32 v104, 1, v139
	v_lshl_add_u64 v[100:101], v[100:101], 0, v[104:105]
	v_cvt_pk_bf16_f32 v114, v78, v79
	v_cvt_pk_bf16_f32 v115, v80, v81
	v_cvt_pk_bf16_f32 v116, v74, v75
	v_cvt_pk_bf16_f32 v117, v76, v77
	global_store_dwordx4 v[100:101], v[114:117], off sc1

; __device__ __forceinline__ void store8bf(bf16_t* p, f32x4 v0, f32x4 v1) { u32x4 w; w.x = cvt_pk_bf16(v0[0], v0[1]); w.y = cvt_pk_bf16(v0[2], v0[3]); w.z = cvt_pk_bf16(v1[0], v1[1]); w.w = cvt_pk_bf16(v1[2], v1[3]); *(u32x4*)p = w; }
;   __device__ __forceinline__ void group(int row, int c32, int fq, f32x4 v0, f32x4 v1) const {
;     ...
;     if (c32 < 768) { const int cc = c32 - 512, h = cc >> 6; store8bf(qd + ((size_t)(b * 4 + h) * E + e) * 64 + (cc & 63) + fq * 8, v0 * QSC_D, v1 * QSC_D); }
.LBB0_488:
	s_andn2_b64 vcc, exec, s[42:43]
	s_cbranch_vccnz .LBB0_490
	v_lshl_add_u32 v99, v113, 2, v107
	v_mov_b32_e32 v103, v1
	s_movk_i32 s1, 0x2040
	v_mad_i64_i32 v[100:101], s[22:23], v99, s1, v[102:103]
	v_readlane_b32 s22, v254, 6
	v_lshlrev_b64 v[100:101], 7, v[100:101]
	v_readlane_b32 s23, v254, 7
	v_lshlrev_b32_e32 v104, 1, v137
	v_mov_b32_e32 v105, v1
	v_lshl_add_u64 v[100:101], s[22:23], 0, v[100:101]
	v_lshl_add_u64 v[100:101], v[100:101], 0, v[104:105]
	v_lshlrev_b32_e32 v104, 1, v139
	s_mov_b32 s22, 0x3e8293ee
	v_lshl_add_u64 v[100:101], v[100:101], 0, v[104:105]
	v_pk_mul_f32 v[104:105], v[80:81], s[22:23] op_sel_hi:[1,0]
	v_pk_mul_f32 v[114:115], v[78:79], s[22:23] op_sel_hi:[1,0]
	v_pk_mul_f32 v[118:119], v[76:77], s[22:23] op_sel_hi:[1,0]
	v_pk_mul_f32 v[116:117], v[74:75], s[22:23] op_sel_hi:[1,0]
	v_cvt_pk_bf16_f32 v114, v114, v115
	v_cvt_pk_bf16_f32 v115, v104, v105
	v_cvt_pk_bf16_f32 v116, v116, v117
	v_cvt_pk_bf16_f32 v117, v118, v119
	global_store_dwordx4 v[100:101], v[114:117], off sc1

; __device__ __forceinline__ void store4bf(bf16_t* p, f32x4 v) { u32x2 w; w.x = cvt_pk_bf16(v[0], v[1]); w.y = cvt_pk_bf16(v[2], v[3]); *(u32x2*)p = w; }
; __device__ __forceinline__ void store8bf(bf16_t* p, f32x4 v0, f32x4 v1) { u32x4 w; w.x = cvt_pk_bf16(v0[0], v0[1]); w.y = cvt_pk_bf16(v0[2], v0[3]); w.z = cvt_pk_bf16(v1[0], v1[1]); w.w = cvt_pk_bf16(v1[2], v1[3]); *(u32x4*)p = w; }
;   __device__ __forceinline__ void group(int row, int c32, int fq, f32x4 v0, f32x4 v1) const {
;     ...
;     if (c32 < 512) {
;       if (c32 < 384) store8bf(cqkv + (size_t)row * 512 + c32 + fq * 8, v0, v1);
;       else { bf16_t* p = cqkv + (size_t)row * 512 + c32 + fq * 4; store4bf(p, v0); store4bf(p + 16, v1); }
.LBB0_491:
	s_andn2_b64 vcc, exec, s[42:43]
	s_cbranch_vccnz .LBB0_498
	v_ashrrev_i32_e32 v99, 31, v98
	v_readlane_b32 s22, v254, 0
	v_lshlrev_b64 v[98:99], 10, v[98:99]
	v_readlane_b32 s23, v254, 1
	s_and_b64 vcc, exec, s[12:13]
	v_cvt_pk_bf16_f32 v100, v74, v75
	v_lshl_add_u64 v[104:105], s[22:23], 0, v[98:99]
	v_cvt_pk_bf16_f32 v98, v78, v79
	v_cvt_pk_bf16_f32 v99, v80, v81
	v_cvt_pk_bf16_f32 v101, v76, v77
	s_cbranch_vccnz .LBB0_763
	v_lshl_add_u64 v[114:115], v[0:1], 1, v[104:105]
	v_lshlrev_b32_e32 v116, 1, v138
	v_mov_b32_e32 v117, v1
	v_lshl_add_u64 v[114:115], v[114:115], 0, v[116:117]
	global_store_dwordx2 v[114:115], v[98:99], off offset:256 sc1
	global_store_dwordx2 v[114:115], v[100:101], off offset:288 sc1
	s_cbranch_execnz .LBB0_495

; __device__ __forceinline__ void store4bf(bf16_t* p, f32x4 v) { u32x2 w; w.x = cvt_pk_bf16(v[0], v[1]); w.y = cvt_pk_bf16(v[2], v[3]); *(u32x2*)p = w; }
;   __device__ __forceinline__ void group(int row, int c32, int fq, f32x4 v0, f32x4 v1) const {
;     ...
;       if (c32 == 384 && ok) {
;         const float2* rp = rope + pos_of_e(e) * 16 + fq * 4; f32x4 o0, o1;
; #pragma unroll
;         for (int j = 0; j < 4; ++j) { const float2 cs = rp[j]; o0[j] = v0[j] * cs.x - v1[j] * cs.y; o1[j] = v1[j] * cs.x + v0[j] * cs.y; }
; #pragma unroll
;         for (int h = 0; h < 6; ++h) { bf16_t* q = ka + ((size_t)(b * 6 + h) * E + e) * 96 + 64 + fq * 4; store4bf(q, o0); store4bf(q + 16, o1); }
;       }
.LBB0_495:
	s_and_b64 s[22:23], s[6:7], s[68:69]
	s_and_saveexec_b64 s[68:69], s[22:23]
	s_cbranch_execz .LBB0_497
	v_lshlrev_b32_e32 v98, 4, v102
	v_add_u32_e32 v99, 0xfffffd00, v98
	v_cndmask_b32_e64 v98, v98, v99, s[18:19]
	v_readlane_b32 s18, v253, 40
	v_mov_b32_e32 v99, v1
	v_readlane_b32 s19, v253, 41
	v_lshlrev_b32_e32 v100, 3, v138
	v_mov_b32_e32 v101, v1
	v_lshl_add_u64 v[98:99], v[98:99], 3, s[18:19]
	v_lshl_add_u64 v[104:105], v[98:99], 0, v[100:101]
	global_load_dwordx4 v[98:101], v[104:105], off offset:16
	global_load_dwordx4 v[114:117], v[104:105], off
	v_mul_i32_i24_e32 v120, 6, v113
	v_mov_b32_e32 v103, v1
	s_movk_i32 s1, 0x2040
	s_waitcnt vmcnt(0)
	v_mov_b32_e32 v105, v116
	v_mov_b32_e32 v116, v115
	v_mov_b32_e32 v104, v114
	v_pk_mul_f32 v[114:115], v[78:79], v[116:117]
	v_pk_mul_f32 v[116:117], v[74:75], v[116:117]
	v_pk_fma_f32 v[114:115], v[74:75], v[104:105], v[114:115]
	v_pk_fma_f32 v[104:105], v[78:79], v[104:105], v[116:117] neg_lo:[0,0,1] neg_hi:[0,0,1]
	v_mov_b32_e32 v117, v100
	v_mov_b32_e32 v100, v99
	v_mov_b32_e32 v116, v98
	v_pk_mul_f32 v[98:99], v[80:81], v[100:101]
	s_nop 0
	v_pk_fma_f32 v[118:119], v[76:77], v[116:117], v[98:99]
	v_pk_mul_f32 v[98:99], v[76:77], v[100:101]
	s_nop 0
	v_pk_fma_f32 v[100:101], v[80:81], v[116:117], v[98:99] neg_lo:[0,0,1] neg_hi:[0,0,1]
	v_cvt_pk_bf16_f32 v98, v104, v105
	v_mad_i64_i32 v[104:105], s[18:19], v120, s1, v[102:103]
	v_readlane_b32 s18, v254, 4
	v_readlane_b32 s19, v254, 5
	v_cvt_pk_bf16_f32 v99, v100, v101
	v_cvt_pk_bf16_f32 v100, v114, v115
	v_mov_b64_e32 v[114:115], s[18:19]
	v_mad_u64_u32 v[116:117], s[18:19], v104, s47, v[114:115]
	v_mad_i32_i24 v117, v105, s47, v117
	v_lshlrev_b32_e32 v104, 1, v138
	v_mov_b32_e32 v105, v1
	v_lshl_add_u64 v[116:117], v[116:117], 0, v[104:105]
	v_cvt_pk_bf16_f32 v101, v118, v119
	global_store_dwordx2 v[116:117], v[98:99], off offset:128 sc1
	global_store_dwordx2 v[116:117], v[100:101], off offset:160 sc1
	v_or_b32_e32 v116, 1, v120
	v_mad_i64_i32 v[116:117], s[18:19], v116, s1, v[102:103]
	v_mad_u64_u32 v[118:119], s[18:19], v116, s47, v[114:115]
	v_mad_i32_i24 v119, v117, s47, v119
	v_lshl_add_u64 v[116:117], v[118:119], 0, v[104:105]
	global_store_dwordx2 v[116:117], v[98:99], off offset:128 sc1
	global_store_dwordx2 v[116:117], v[100:101], off offset:160 sc1
	v_mad_i32_i24 v116, v113, 6, 2
	v_mad_i64_i32 v[116:117], s[18:19], v116, s1, v[102:103]
	v_mad_u64_u32 v[118:119], s[18:19], v116, s47, v[114:115]
	v_mad_i32_i24 v119, v117, s47, v119
	v_lshl_add_u64 v[116:117], v[118:119], 0, v[104:105]
	global_store_dwordx2 v[116:117], v[98:99], off offset:128 sc1
	global_store_dwordx2 v[116:117], v[100:101], off offset:160 sc1
	v_mad_i32_i24 v116, v113, 6, 3
	v_mad_i64_i32 v[116:117], s[18:19], v116, s1, v[102:103]
	v_mad_u64_u32 v[118:119], s[18:19], v116, s47, v[114:115]
	v_mad_i32_i24 v119, v117, s47, v119
	v_lshl_add_u64 v[116:117], v[118:119], 0, v[104:105]
	global_store_dwordx2 v[116:117], v[98:99], off offset:128 sc1
	global_store_dwordx2 v[116:117], v[100:101], off offset:160 sc1
	v_mad_i32_i24 v116, v113, 6, 4
	v_mad_i32_i24 v113, v113, 6, 5
	v_mad_i64_i32 v[116:117], s[18:19], v116, s1, v[102:103]
	v_mad_i64_i32 v[102:103], s[18:19], v113, s1, v[102:103]
	v_mad_u64_u32 v[118:119], s[18:19], v116, s47, v[114:115]
	v_mad_u64_u32 v[114:115], s[18:19], v102, s47, v[114:115]
	v_mad_i32_i24 v119, v117, s47, v119
	v_mad_i32_i24 v115, v103, s47, v115
	v_lshl_add_u64 v[116:117], v[118:119], 0, v[104:105]
	v_lshl_add_u64 v[102:103], v[114:115], 0, v[104:105]
	global_store_dwordx2 v[116:117], v[98:99], off offset:128 sc1
	global_store_dwordx2 v[116:117], v[100:101], off offset:160 sc1
	global_store_dwordx2 v[102:103], v[98:99], off offset:128 sc1
	global_store_dwordx2 v[102:103], v[100:101], off offset:160 sc1

; __device__ __forceinline__ unsigned short f2bf(float f) { return (unsigned short)(cvt_pk_bf16(f, f) & 0xffffu); }
; __device__ __forceinline__ void store4bf(bf16_t* p, f32x4 v) { u32x2 w; w.x = cvt_pk_bf16(v[0], v[1]); w.y = cvt_pk_bf16(v[2], v[3]); *(u32x2*)p = w; }
;   __device__ __forceinline__ void group(int row, int c32, int fq, f32x4 v0, f32x4 v1) const {
;     int b, e; const bool ok = row_be(row, b, e);
;     if (c32 < 512) {
;       if (c32 < 384) store8bf(cqkv + (size_t)row * 512 + c32 + fq * 8, v0, v1);
;       else { bf16_t* p = cqkv + (size_t)row * 512 + c32 + fq * 4; store4bf(p, v0); store4bf(p + 16, v1); }
;       if (c32 == 384 && ok) {
;         const float2* rp = rope + pos_of_e(e) * 16 + fq * 4; f32x4 o0, o1;
; #pragma unroll
;         for (int j = 0; j < 4; ++j) { const float2 cs = rp[j]; o0[j] = v0[j] * cs.x - v1[j] * cs.y; o1[j] = v1[j] * cs.x + v0[j] * cs.y; }
; #pragma unroll
;         for (int h = 0; h < 6; ++h) { bf16_t* q = ka + ((size_t)(b * 6 + h) * E + e) * 96 + 64 + fq * 4; store4bf(q, o0); store4bf(q + 16, o1); }
;       }
;       return;
;     }
;     if (!ok) return;
;     if (c32 < 768) { const int cc = c32 - 512, h = cc >> 6; store8bf(qd + ((size_t)(b * 4 + h) * E + e) * 64 + (cc & 63) + fq * 8, v0 * QSC_D, v1 * QSC_D); }
;     else if (c32 < 1024) { const int cc = c32 - 768, h = cc >> 6; store8bf(kd + ((size_t)(b * 4 + h) * E + e) * 64 + (cc & 63) + fq * 8, v0, v1); }
;     else if (c32 < 1280) { const int cc = c32 - 1024, h = cc >> 6; bf16_t* p = vtd + ((size_t)(b * 4 + h) * 64 + (cc & 63) + fq * 4) * E + e;
; #pragma unroll
;       for (int j = 0; j < 4; ++j) { p[(size_t)j * E] = f2bf(v0[j]); p[(size_t)(j + 16) * E] = f2bf(v1[j]); } }
;     else if (c32 < 1664) { const int cc = c32 - 1280, h = cc >> 6; store8bf(qs + ((size_t)(b * 6 + h) * E + e) * 64 + (cc & 63) + fq * 8, v0 * QSC_S, v1 * QSC_S); }
;     else if (c32 < 1792) { const int cc = c32 - 1664, g = cc >> 6; store8bf(ks + ((size_t)(b * 2 + g) * E + e) * 64 + (cc & 63) + fq * 8, v0, v1); }
;     else if (c32 < 1920) { const int cc = c32 - 1792, g = cc >> 6; bf16_t* p = vts + ((size_t)(b * 2 + g) * 64 + (cc & 63) + fq * 4) * E + e;
; #pragma unroll
;       for (int j = 0; j < 4; ++j) { p[(size_t)j * E] = f2bf(v0[j]); p[(size_t)(j + 16) * E] = f2bf(v1[j]); } }
.LBB0_498:
	s_movk_i32 s1, 0x1fff
	v_or_b32_e32 v98, 48, v132
	v_bitop3_b32 v99, v132, s1, 48 bitop3:0xc8
	s_mov_b32 s1, 0x8000
	v_add_u32_e32 v99, 64, v99
	v_cmp_gt_i32_e64 s[18:19], s1, v98
	s_or_b64 s[14:15], s[18:19], s[14:15]
	s_and_b64 vcc, exec, s[16:17]
	v_cndmask_b32_e64 v113, 3, v145, s[18:19]
	v_cndmask_b32_e64 v102, v136, v99, s[18:19]
	s_mov_b64 s[16:17], -1
	s_cbranch_vccnz .LBB0_522
	s_and_saveexec_b64 s[16:17], s[14:15]
	s_cbranch_execz .LBB0_521
	s_andn2_b64 vcc, exec, s[44:45]
	s_mov_b64 s[42:43], -1
	s_cbranch_vccnz .LBB0_519
	s_andn2_b64 vcc, exec, s[40:41]
	s_mov_b64 s[40:41], -1
	s_cbranch_vccnz .LBB0_516
	s_andn2_b64 vcc, exec, s[38:39]
	s_mov_b64 s[38:39], -1
	s_cbranch_vccnz .LBB0_513
	s_and_saveexec_b64 s[22:23], s[10:11]
	s_xor_b64 s[10:11], exec, s[22:23]
	s_cbranch_execz .LBB0_510
	s_andn2_b64 vcc, exec, s[26:27]
	s_mov_b64 s[24:25], -1
	s_cbranch_vccnz .LBB0_508
	s_and_saveexec_b64 s[24:25], s[8:9]
	s_cbranch_execz .LBB0_507
	v_lshl_add_u32 v100, v113, 1, v110
	v_ashrrev_i32_e32 v101, 31, v100
	v_readlane_b32 s8, v254, 16
	v_lshlrev_b64 v[100:101], 6, v[100:101]
	v_readlane_b32 s9, v254, 17
	v_or_b32_e32 v99, v100, v140
	v_lshlrev_b32_e32 v100, 1, v102
	v_mov_b64_e32 v[104:105], s[8:9]
	v_mad_u64_u32 v[104:105], s[8:9], v99, s95, v[104:105]
	v_mad_i32_i24 v105, v101, s95, v105
	v_mov_b32_e32 v101, v1
	v_lshl_add_u64 v[100:101], v[104:105], 0, v[100:101]
	s_mov_b32 s1, 0x40000
	v_cvt_pk_bf16_f32 v99, v70, s0
	v_add_co_u32_e32 v104, vcc, s1, v100
	global_store_short v[100:101], v99, off sc1
	v_cvt_pk_bf16_f32 v99, v66, s0
	v_addc_co_u32_e32 v105, vcc, 0, v101, vcc
	s_movk_i32 s1, 0x4000
	global_store_short v[104:105], v99, off offset:2048 sc1
	v_add_co_u32_e32 v104, vcc, s1, v100
	v_cvt_pk_bf16_f32 v99, v71, s0
	s_nop 0
	v_addc_co_u32_e32 v105, vcc, 0, v101, vcc
	s_mov_b32 s1, 0x44000
	global_store_short v[104:105], v99, off offset:128 sc1
	v_add_co_u32_e32 v104, vcc, s1, v100
	v_cvt_pk_bf16_f32 v99, v67, s0
	s_nop 0
	v_addc_co_u32_e32 v105, vcc, 0, v101, vcc
	s_mov_b32 s1, 0x8000
	global_store_short v[104:105], v99, off offset:2176 sc1
	v_add_co_u32_e32 v104, vcc, s1, v100
	v_cvt_pk_bf16_f32 v99, v72, s0
	s_nop 0
	v_addc_co_u32_e32 v105, vcc, 0, v101, vcc
	s_mov_b32 s1, 0x48000
	global_store_short v[104:105], v99, off offset:256 sc1
	v_add_co_u32_e32 v104, vcc, s1, v100
	v_cvt_pk_bf16_f32 v99, v68, s0
	s_nop 0
	v_addc_co_u32_e32 v105, vcc, 0, v101, vcc
	global_store_short v[104:105], v99, off offset:2304 sc1
	v_add_co_u32_e32 v104, vcc, 0xc000, v100
	v_cvt_pk_bf16_f32 v99, v73, s0
	s_nop 0
	v_addc_co_u32_e32 v105, vcc, 0, v101, vcc
	v_add_co_u32_e32 v100, vcc, 0x4c000, v100
	global_store_short v[104:105], v99, off offset:384 sc1
	v_cvt_pk_bf16_f32 v99, v69, s0
	v_addc_co_u32_e32 v101, vcc, 0, v101, vcc
	global_store_short v[100:101], v99, off offset:2432 sc1

; __device__ __forceinline__ void store8bf(bf16_t* p, f32x4 v0, f32x4 v1) { u32x4 w; w.x = cvt_pk_bf16(v0[0], v0[1]); w.y = cvt_pk_bf16(v0[2], v0[3]); w.z = cvt_pk_bf16(v1[0], v1[1]); w.w = cvt_pk_bf16(v1[2], v1[3]); *(u32x4*)p = w; }
;   __device__ __forceinline__ void group(int row, int c32, int fq, f32x4 v0, f32x4 v1) const {
;     ...
;     else if (c32 < 1664) { const int cc = c32 - 1280, h = cc >> 6; store8bf(qs + ((size_t)(b * 6 + h) * E + e) * 64 + (cc & 63) + fq * 8, v0 * QSC_S, v1 * QSC_S); }
;     else if (c32 < 1792) { const int cc = c32 - 1664, g = cc >> 6; store8bf(ks + ((size_t)(b * 2 + g) * E + e) * 64 + (cc & 63) + fq * 8, v0, v1); }
.LBB0_508:
	s_andn2_b64 vcc, exec, s[24:25]
	s_cbranch_vccnz .LBB0_510
	v_lshl_add_u32 v99, v113, 1, v109
	v_mov_b32_e32 v103, v1
	s_movk_i32 s1, 0x2040
	v_mad_i64_i32 v[100:101], s[8:9], v99, s1, v[102:103]
	v_readlane_b32 s8, v254, 14
	v_lshlrev_b64 v[100:101], 7, v[100:101]
	v_readlane_b32 s9, v254, 15
	v_lshlrev_b32_e32 v104, 1, v137
	v_mov_b32_e32 v105, v1
	v_lshl_add_u64 v[100:101], s[8:9], 0, v[100:101]
	v_lshl_add_u64 v[100:101], v[100:101], 0, v[104:105]
	v_lshlrev_b32_e32 v104, 1, v139
	v_lshl_add_u64 v[100:101], v[100:101], 0, v[104:105]
	v_cvt_pk_bf16_f32 v114, v70, v71
	v_cvt_pk_bf16_f32 v115, v72, v73
	v_cvt_pk_bf16_f32 v116, v66, v67
	v_cvt_pk_bf16_f32 v117, v68, v69
	global_store_dwordx4 v[100:101], v[114:117], off sc1
.LBB0_510:
	s_andn2_saveexec_b64 s[8:9], s[10:11]
	s_cbranch_execz .LBB0_512
	v_mad_i32_i24 v99, v113, 6, v111
	v_mov_b32_e32 v103, v1
	s_movk_i32 s1, 0x2040
	v_mad_i64_i32 v[100:101], s[10:11], v99, s1, v[102:103]
	v_readlane_b32 s10, v254, 12
	v_lshlrev_b64 v[100:101], 7, v[100:101]
	v_readlane_b32 s11, v254, 13
	v_lshlrev_b32_e32 v104, 1, v137
	v_mov_b32_e32 v105, v1
	v_lshl_add_u64 v[100:101], s[10:11], 0, v[100:101]
	v_lshl_add_u64 v[100:101], v[100:101], 0, v[104:105]
	v_lshlrev_b32_e32 v104, 1, v139
	s_mov_b32 s10, 0x3e38aa3b
	v_lshl_add_u64 v[100:101], v[100:101], 0, v[104:105]
	v_pk_mul_f32 v[104:105], v[72:73], s[10:11] op_sel_hi:[1,0]
	v_pk_mul_f32 v[114:115], v[70:71], s[10:11] op_sel_hi:[1,0]
	v_pk_mul_f32 v[118:119], v[68:69], s[10:11] op_sel_hi:[1,0]
	v_pk_mul_f32 v[116:117], v[66:67], s[10:11] op_sel_hi:[1,0]
	v_cvt_pk_bf16_f32 v114, v114, v115
	v_cvt_pk_bf16_f32 v115, v104, v105
	v_cvt_pk_bf16_f32 v116, v116, v117
	v_cvt_pk_bf16_f32 v117, v118, v119
	global_store_dwordx4 v[100:101], v[114:117], off sc1

; __device__ __forceinline__ unsigned short f2bf(float f) { return (unsigned short)(cvt_pk_bf16(f, f) & 0xffffu); }
;   __device__ __forceinline__ void group(int row, int c32, int fq, f32x4 v0, f32x4 v1) const {
;     ...
;     else if (c32 < 1280) { const int cc = c32 - 1024, h = cc >> 6; bf16_t* p = vtd + ((size_t)(b * 4 + h) * 64 + (cc & 63) + fq * 4) * E + e;
; #pragma unroll
;       for (int j = 0; j < 4; ++j) { p[(size_t)j * E] = f2bf(v0[j]); p[(size_t)(j + 16) * E] = f2bf(v1[j]); } }
.LBB0_513:
	s_andn2_b64 vcc, exec, s[38:39]
	s_cbranch_vccnz .LBB0_515
	v_lshl_add_u32 v100, v113, 2, v106
	v_ashrrev_i32_e32 v101, 31, v100
	v_readlane_b32 s8, v254, 10
	v_lshlrev_b64 v[100:101], 6, v[100:101]
	v_readlane_b32 s9, v254, 11
	v_or_b32_e32 v99, v100, v140
	v_lshlrev_b32_e32 v100, 1, v102
	v_mov_b64_e32 v[104:105], s[8:9]
	v_mad_u64_u32 v[104:105], s[8:9], v99, s95, v[104:105]
	v_mad_i32_i24 v105, v101, s95, v105
	v_mov_b32_e32 v101, v1
	v_lshl_add_u64 v[100:101], v[104:105], 0, v[100:101]
	s_mov_b32 s1, 0x40000
	v_cvt_pk_bf16_f32 v99, v70, s0
	v_add_co_u32_e32 v104, vcc, s1, v100
	global_store_short v[100:101], v99, off sc1
	v_cvt_pk_bf16_f32 v99, v66, s0
	v_addc_co_u32_e32 v105, vcc, 0, v101, vcc
	s_movk_i32 s1, 0x4000
	global_store_short v[104:105], v99, off offset:2048 sc1
	v_add_co_u32_e32 v104, vcc, s1, v100
	v_cvt_pk_bf16_f32 v99, v71, s0
	s_nop 0
	v_addc_co_u32_e32 v105, vcc, 0, v101, vcc
	s_mov_b32 s1, 0x44000
	global_store_short v[104:105], v99, off offset:128 sc1
	v_add_co_u32_e32 v104, vcc, s1, v100
	v_cvt_pk_bf16_f32 v99, v67, s0
	s_nop 0
	v_addc_co_u32_e32 v105, vcc, 0, v101, vcc
	s_mov_b32 s1, 0x8000
	global_store_short v[104:105], v99, off offset:2176 sc1
	v_add_co_u32_e32 v104, vcc, s1, v100
	v_cvt_pk_bf16_f32 v99, v72, s0
	s_nop 0
	v_addc_co_u32_e32 v105, vcc, 0, v101, vcc
	s_mov_b32 s1, 0x48000
	global_store_short v[104:105], v99, off offset:256 sc1
	v_add_co_u32_e32 v104, vcc, s1, v100
	v_cvt_pk_bf16_f32 v99, v68, s0
	s_nop 0
	v_addc_co_u32_e32 v105, vcc, 0, v101, vcc
	global_store_short v[104:105], v99, off offset:2304 sc1
	v_add_co_u32_e32 v104, vcc, 0xc000, v100
	v_cvt_pk_bf16_f32 v99, v73, s0
	s_nop 0
	v_addc_co_u32_e32 v105, vcc, 0, v101, vcc
	v_add_co_u32_e32 v100, vcc, 0x4c000, v100
	global_store_short v[104:105], v99, off offset:384 sc1
	v_cvt_pk_bf16_f32 v99, v69, s0
	v_addc_co_u32_e32 v101, vcc, 0, v101, vcc
	global_store_short v[100:101], v99, off offset:2432 sc1

; __device__ __forceinline__ void store8bf(bf16_t* p, f32x4 v0, f32x4 v1) { u32x4 w; w.x = cvt_pk_bf16(v0[0], v0[1]); w.y = cvt_pk_bf16(v0[2], v0[3]); w.z = cvt_pk_bf16(v1[0], v1[1]); w.w = cvt_pk_bf16(v1[2], v1[3]); *(u32x4*)p = w; }
;   __device__ __forceinline__ void group(int row, int c32, int fq, f32x4 v0, f32x4 v1) const {
;     ...
;     else if (c32 < 1024) { const int cc = c32 - 768, h = cc >> 6; store8bf(kd + ((size_t)(b * 4 + h) * E + e) * 64 + (cc & 63) + fq * 8, v0, v1); }
.LBB0_516:
	s_andn2_b64 vcc, exec, s[40:41]
	s_cbranch_vccnz .LBB0_518
	v_lshl_add_u32 v99, v113, 2, v108
	v_mov_b32_e32 v103, v1
	s_movk_i32 s1, 0x2040
	v_mad_i64_i32 v[100:101], s[8:9], v99, s1, v[102:103]
	v_readlane_b32 s8, v254, 8
	v_lshlrev_b64 v[100:101], 7, v[100:101]
	v_readlane_b32 s9, v254, 9
	v_lshlrev_b32_e32 v104, 1, v137
	v_mov_b32_e32 v105, v1
	v_lshl_add_u64 v[100:101], s[8:9], 0, v[100:101]
	v_lshl_add_u64 v[100:101], v[100:101], 0, v[104:105]
	v_lshlrev_b32_e32 v104, 1, v139
	v_lshl_add_u64 v[100:101], v[100:101], 0, v[104:105]
	v_cvt_pk_bf16_f32 v114, v70, v71
	v_cvt_pk_bf16_f32 v115, v72, v73
	v_cvt_pk_bf16_f32 v116, v66, v67
	v_cvt_pk_bf16_f32 v117, v68, v69
	global_store_dwordx4 v[100:101], v[114:117], off sc1

; __device__ __forceinline__ void store8bf(bf16_t* p, f32x4 v0, f32x4 v1) { u32x4 w; w.x = cvt_pk_bf16(v0[0], v0[1]); w.y = cvt_pk_bf16(v0[2], v0[3]); w.z = cvt_pk_bf16(v1[0], v1[1]); w.w = cvt_pk_bf16(v1[2], v1[3]); *(u32x4*)p = w; }
;   __device__ __forceinline__ void group(int row, int c32, int fq, f32x4 v0, f32x4 v1) const {
;     ...
;     if (c32 < 768) { const int cc = c32 - 512, h = cc >> 6; store8bf(qd + ((size_t)(b * 4 + h) * E + e) * 64 + (cc & 63) + fq * 8, v0 * QSC_D, v1 * QSC_D); }
.LBB0_519:
	s_andn2_b64 vcc, exec, s[42:43]
	s_cbranch_vccnz .LBB0_521
	v_lshl_add_u32 v99, v113, 2, v107
	v_mov_b32_e32 v103, v1
	s_movk_i32 s1, 0x2040
	v_mad_i64_i32 v[100:101], s[8:9], v99, s1, v[102:103]
	v_readlane_b32 s8, v254, 6
	v_lshlrev_b64 v[100:101], 7, v[100:101]
	v_readlane_b32 s9, v254, 7
	v_lshlrev_b32_e32 v104, 1, v137
	v_mov_b32_e32 v105, v1
	v_lshl_add_u64 v[100:101], s[8:9], 0, v[100:101]
	v_lshl_add_u64 v[100:101], v[100:101], 0, v[104:105]
	v_lshlrev_b32_e32 v104, 1, v139
	s_mov_b32 s8, 0x3e8293ee
	v_lshl_add_u64 v[100:101], v[100:101], 0, v[104:105]
	v_pk_mul_f32 v[104:105], v[72:73], s[8:9] op_sel_hi:[1,0]
	v_pk_mul_f32 v[114:115], v[70:71], s[8:9] op_sel_hi:[1,0]
	v_pk_mul_f32 v[118:119], v[68:69], s[8:9] op_sel_hi:[1,0]
	v_pk_mul_f32 v[116:117], v[66:67], s[8:9] op_sel_hi:[1,0]
	v_cvt_pk_bf16_f32 v114, v114, v115
	v_cvt_pk_bf16_f32 v115, v104, v105
	v_cvt_pk_bf16_f32 v116, v116, v117
	v_cvt_pk_bf16_f32 v117, v118, v119
	global_store_dwordx4 v[100:101], v[114:117], off sc1

; __device__ __forceinline__ void store4bf(bf16_t* p, f32x4 v) { u32x2 w; w.x = cvt_pk_bf16(v[0], v[1]); w.y = cvt_pk_bf16(v[2], v[3]); *(u32x2*)p = w; }
; __device__ __forceinline__ void store8bf(bf16_t* p, f32x4 v0, f32x4 v1) { u32x4 w; w.x = cvt_pk_bf16(v0[0], v0[1]); w.y = cvt_pk_bf16(v0[2], v0[3]); w.z = cvt_pk_bf16(v1[0], v1[1]); w.w = cvt_pk_bf16(v1[2], v1[3]); *(u32x4*)p = w; }
;   __device__ __forceinline__ void group(int row, int c32, int fq, f32x4 v0, f32x4 v1) const {
;     ...
;     if (c32 < 512) {
;       if (c32 < 384) store8bf(cqkv + (size_t)row * 512 + c32 + fq * 8, v0, v1);
;       else { bf16_t* p = cqkv + (size_t)row * 512 + c32 + fq * 4; store4bf(p, v0); store4bf(p + 16, v1); }
.LBB0_522:
	s_andn2_b64 vcc, exec, s[16:17]
	s_cbranch_vccnz .LBB0_529
	v_ashrrev_i32_e32 v99, 31, v98
	v_readlane_b32 s8, v254, 0
	v_lshlrev_b64 v[98:99], 10, v[98:99]
	v_readlane_b32 s9, v254, 1
	s_and_b64 vcc, exec, s[12:13]
	v_cvt_pk_bf16_f32 v100, v66, v67
	v_lshl_add_u64 v[104:105], s[8:9], 0, v[98:99]
	v_cvt_pk_bf16_f32 v98, v70, v71
	v_cvt_pk_bf16_f32 v99, v72, v73
	v_cvt_pk_bf16_f32 v101, v68, v69
	s_cbranch_vccnz .LBB0_764
	v_lshl_add_u64 v[114:115], v[0:1], 1, v[104:105]
	v_lshlrev_b32_e32 v116, 1, v138
	v_mov_b32_e32 v117, v1
	v_lshl_add_u64 v[114:115], v[114:115], 0, v[116:117]
	global_store_dwordx2 v[114:115], v[98:99], off offset:256 sc1
	global_store_dwordx2 v[114:115], v[100:101], off offset:288 sc1
	s_cbranch_execnz .LBB0_526

; __device__ __forceinline__ void store4bf(bf16_t* p, f32x4 v) { u32x2 w; w.x = cvt_pk_bf16(v[0], v[1]); w.y = cvt_pk_bf16(v[2], v[3]); *(u32x2*)p = w; }
;   __device__ __forceinline__ void group(int row, int c32, int fq, f32x4 v0, f32x4 v1) const {
;     ...
;       if (c32 == 384 && ok) {
;         const float2* rp = rope + pos_of_e(e) * 16 + fq * 4; f32x4 o0, o1;
; #pragma unroll
;         for (int j = 0; j < 4; ++j) { const float2 cs = rp[j]; o0[j] = v0[j] * cs.x - v1[j] * cs.y; o1[j] = v1[j] * cs.x + v0[j] * cs.y; }
; #pragma unroll
;         for (int h = 0; h < 6; ++h) { bf16_t* q = ka + ((size_t)(b * 6 + h) * E + e) * 96 + 64 + fq * 4; store4bf(q, o0); store4bf(q + 16, o1); }
;       }
.LBB0_526:
	s_and_b64 s[8:9], s[6:7], s[14:15]
	s_and_saveexec_b64 s[6:7], s[8:9]
	s_cbranch_execz .LBB0_528
	v_lshlrev_b32_e32 v98, 4, v102
	v_add_u32_e32 v99, 0xfffffd00, v98
	v_readlane_b32 s8, v253, 40
	v_cndmask_b32_e64 v98, v98, v99, s[18:19]
	v_mov_b32_e32 v99, v1
	v_readlane_b32 s9, v253, 41
	v_lshlrev_b32_e32 v100, 3, v138
	v_mov_b32_e32 v101, v1
	v_lshl_add_u64 v[98:99], v[98:99], 3, s[8:9]
	v_lshl_add_u64 v[104:105], v[98:99], 0, v[100:101]
	global_load_dwordx4 v[98:101], v[104:105], off offset:16
	global_load_dwordx4 v[114:117], v[104:105], off
	v_mul_i32_i24_e32 v120, 6, v113
	v_mov_b32_e32 v103, v1
	s_movk_i32 s1, 0x2040
	s_waitcnt vmcnt(0)
	v_mov_b32_e32 v105, v116
	v_mov_b32_e32 v116, v115
	v_mov_b32_e32 v104, v114
	v_pk_mul_f32 v[114:115], v[70:71], v[116:117]
	v_pk_mul_f32 v[116:117], v[66:67], v[116:117]
	v_pk_fma_f32 v[114:115], v[66:67], v[104:105], v[114:115]
	v_pk_fma_f32 v[104:105], v[70:71], v[104:105], v[116:117] neg_lo:[0,0,1] neg_hi:[0,0,1]
	v_mov_b32_e32 v117, v100
	v_mov_b32_e32 v100, v99
	v_mov_b32_e32 v116, v98
	v_pk_mul_f32 v[98:99], v[72:73], v[100:101]
	s_nop 0
	v_pk_fma_f32 v[118:119], v[68:69], v[116:117], v[98:99]
	v_pk_mul_f32 v[98:99], v[68:69], v[100:101]
	s_nop 0
	v_pk_fma_f32 v[100:101], v[72:73], v[116:117], v[98:99] neg_lo:[0,0,1] neg_hi:[0,0,1]
	v_cvt_pk_bf16_f32 v98, v104, v105
	v_mad_i64_i32 v[104:105], s[8:9], v120, s1, v[102:103]
	v_readlane_b32 s8, v254, 4
	v_readlane_b32 s9, v254, 5
	v_cvt_pk_bf16_f32 v99, v100, v101
	v_cvt_pk_bf16_f32 v100, v114, v115
	v_mov_b64_e32 v[114:115], s[8:9]
	v_mad_u64_u32 v[116:117], s[8:9], v104, s47, v[114:115]
	v_mad_i32_i24 v117, v105, s47, v117
	v_lshlrev_b32_e32 v104, 1, v138
	v_mov_b32_e32 v105, v1
	v_lshl_add_u64 v[116:117], v[116:117], 0, v[104:105]
	v_cvt_pk_bf16_f32 v101, v118, v119
	global_store_dwordx2 v[116:117], v[98:99], off offset:128 sc1
	global_store_dwordx2 v[116:117], v[100:101], off offset:160 sc1
	v_or_b32_e32 v116, 1, v120
	v_mad_i64_i32 v[116:117], s[8:9], v116, s1, v[102:103]
	v_mad_u64_u32 v[118:119], s[8:9], v116, s47, v[114:115]
	v_mad_i32_i24 v119, v117, s47, v119
	v_lshl_add_u64 v[116:117], v[118:119], 0, v[104:105]
	global_store_dwordx2 v[116:117], v[98:99], off offset:128 sc1
	global_store_dwordx2 v[116:117], v[100:101], off offset:160 sc1
	v_mad_i32_i24 v116, v113, 6, 2
	v_mad_i64_i32 v[116:117], s[8:9], v116, s1, v[102:103]
	v_mad_u64_u32 v[118:119], s[8:9], v116, s47, v[114:115]
	v_mad_i32_i24 v119, v117, s47, v119
	v_lshl_add_u64 v[116:117], v[118:119], 0, v[104:105]
	global_store_dwordx2 v[116:117], v[98:99], off offset:128 sc1
	global_store_dwordx2 v[116:117], v[100:101], off offset:160 sc1
	v_mad_i32_i24 v116, v113, 6, 3
	v_mad_i64_i32 v[116:117], s[8:9], v116, s1, v[102:103]
	v_mad_u64_u32 v[118:119], s[8:9], v116, s47, v[114:115]
	v_mad_i32_i24 v119, v117, s47, v119
	v_lshl_add_u64 v[116:117], v[118:119], 0, v[104:105]
	global_store_dwordx2 v[116:117], v[98:99], off offset:128 sc1
	global_store_dwordx2 v[116:117], v[100:101], off offset:160 sc1
	v_mad_i32_i24 v116, v113, 6, 4
	v_mad_i32_i24 v113, v113, 6, 5
	v_mad_i64_i32 v[116:117], s[8:9], v116, s1, v[102:103]
	v_mad_i64_i32 v[102:103], s[8:9], v113, s1, v[102:103]
	v_mad_u64_u32 v[118:119], s[8:9], v116, s47, v[114:115]
	v_mad_u64_u32 v[114:115], s[8:9], v102, s47, v[114:115]
	v_mad_i32_i24 v119, v117, s47, v119
	v_mad_i32_i24 v115, v103, s47, v115
	v_lshl_add_u64 v[116:117], v[118:119], 0, v[104:105]
	v_lshl_add_u64 v[102:103], v[114:115], 0, v[104:105]
	global_store_dwordx2 v[116:117], v[98:99], off offset:128 sc1
	global_store_dwordx2 v[116:117], v[100:101], off offset:160 sc1
	global_store_dwordx2 v[102:103], v[98:99], off offset:128 sc1
	global_store_dwordx2 v[102:103], v[100:101], off offset:160 sc1

; #define LAS __attribute__((address_space(3)))
; __device__ __forceinline__ unsigned short f2bf(float f) { return (unsigned short)(cvt_pk_bf16(f, f) & 0xffffu); }
;     ...
;           for (int m = 0; m < 4; ++m) { const float sc = epi.row_scale(row0 + m * 16 + fr);
; #pragma unroll
;             for (int n = 0; n < 2; ++n)
; #pragma unroll
;               for (int j = 0; j < 4; ++j) *(LAS bf16_t*)(T + (n * 16 + fq * 4 + j) * 144 + (m * 16 + fr) * 2) = f2bf(acc[ai][bj][m][n][j] * sc); }
;           asm volatile("s_waitcnt lgkmcnt(0)" ::: "memory");
; #pragma unroll
;           for (int q = 0; q < 4; ++q) { const int ch = lane + 64 * q, d = ch >> 3, ec = ch & 7;
;             *(u32x4*)(vbase + (size_t)d * E + e0 + ec * 8) = *(LAS const u32x4*)(T + d * 144 + ec * 16); }
;           asm volatile("s_waitcnt lgkmcnt(0)" ::: "memory");
.LBB0_530:
	s_and_b64 vcc, exec, s[14:15]
	s_cbranch_vccz .LBB0_532
	v_readlane_b32 s6, v254, 10
	v_cvt_pk_bf16_f32 v94, v94, s0
	v_cvt_pk_bf16_f32 v90, v90, s0
	v_cvt_pk_bf16_f32 v86, v86, s0
	v_cvt_pk_bf16_f32 v82, v82, s0
	v_cvt_pk_bf16_f32 v78, v78, s0
	v_cvt_pk_bf16_f32 v74, v74, s0
	v_cvt_pk_bf16_f32 v70, v70, s0
	v_cvt_pk_bf16_f32 v66, v66, s0
	v_lshl_or_b32 v98, v146, 2, v106
	v_readlane_b32 s7, v254, 11
	ds_write_b16 v143, v94
	v_cvt_pk_bf16_f32 v94, v95, s0
	ds_write_b16 v143, v90 offset:2304
	v_cvt_pk_bf16_f32 v90, v91, s0
	ds_write_b16 v143, v86 offset:32
	v_cvt_pk_bf16_f32 v86, v87, s0
	ds_write_b16 v143, v82 offset:2336
	v_cvt_pk_bf16_f32 v82, v83, s0
	ds_write_b16 v143, v78 offset:64
	v_cvt_pk_bf16_f32 v78, v79, s0
	ds_write_b16 v143, v74 offset:2368
	v_cvt_pk_bf16_f32 v74, v75, s0
	ds_write_b16 v143, v70 offset:96
	v_cvt_pk_bf16_f32 v70, v71, s0
	ds_write_b16 v143, v66 offset:2400
	v_cvt_pk_bf16_f32 v66, v67, s0
	v_ashrrev_i32_e32 v100, 31, v98
	v_lshl_or_b32 v101, v98, 6, v137
	v_mov_b64_e32 v[98:99], s[6:7]
	ds_write_b16 v143, v94 offset:144
	v_cvt_pk_bf16_f32 v94, v96, s0
	ds_write_b16 v143, v90 offset:2448
	v_cvt_pk_bf16_f32 v90, v92, s0
	ds_write_b16 v143, v86 offset:176
	v_cvt_pk_bf16_f32 v86, v88, s0
	ds_write_b16 v143, v82 offset:2480
	v_cvt_pk_bf16_f32 v82, v84, s0
	ds_write_b16 v143, v78 offset:208
	v_cvt_pk_bf16_f32 v78, v80, s0
	ds_write_b16 v143, v74 offset:2512
	v_cvt_pk_bf16_f32 v74, v76, s0
	ds_write_b16 v143, v70 offset:240
	v_cvt_pk_bf16_f32 v70, v72, s0
	ds_write_b16 v143, v66 offset:2544
	v_cvt_pk_bf16_f32 v66, v68, s0
	v_mad_u64_u32 v[98:99], s[6:7], v101, s95, v[98:99]
	ds_write_b16 v143, v94 offset:288
	v_cvt_pk_bf16_f32 v94, v97, s0
	ds_write_b16 v143, v90 offset:2592
	v_cvt_pk_bf16_f32 v90, v93, s0
	ds_write_b16 v143, v86 offset:320
	v_cvt_pk_bf16_f32 v86, v89, s0
	ds_write_b16 v143, v82 offset:2624
	v_cvt_pk_bf16_f32 v82, v85, s0
	ds_write_b16 v143, v78 offset:352
	v_cvt_pk_bf16_f32 v78, v81, s0
	ds_write_b16 v143, v74 offset:2656
	v_cvt_pk_bf16_f32 v74, v77, s0
	ds_write_b16 v143, v70 offset:384
	v_cvt_pk_bf16_f32 v70, v73, s0
	ds_write_b16 v143, v66 offset:2688
	v_cvt_pk_bf16_f32 v66, v69, s0
	v_mad_i32_i24 v99, v100, s95, v99
	ds_write_b16 v143, v94 offset:432
	ds_write_b16 v143, v90 offset:2736
	ds_write_b16 v143, v86 offset:464
	ds_write_b16 v143, v82 offset:2768
	ds_write_b16 v143, v78 offset:496
	ds_write_b16 v143, v74 offset:2800
	ds_write_b16 v143, v70 offset:528
	ds_write_b16 v143, v66 offset:2832
	v_mov_b32_e32 v135, v1
	s_waitcnt lgkmcnt(0)
	v_lshl_add_u64 v[66:67], v[98:99], 0, v[134:135]
	v_mov_b32_e32 v131, v1
	v_lshl_add_u64 v[70:71], v[66:67], 0, v[130:131]
	ds_read_b128 v[66:69], v141
	v_lshlrev_b32_e32 v72, 1, v142
	v_mov_b32_e32 v73, v1
	v_lshl_add_u64 v[74:75], v[70:71], 0, v[72:73]
	ds_read_b128 v[70:73], v141 offset:1152
	s_waitcnt lgkmcnt(0)
	global_store_dwordx4 v[74:75], v[66:69], off sc1
	s_nop 1
	v_add_co_u32_e32 v66, vcc, 0x20000, v74
	s_nop 1
	v_addc_co_u32_e32 v67, vcc, 0, v75, vcc
	global_store_dwordx4 v[66:67], v[70:73], off offset:1024 sc1
	ds_read_b128 v[66:69], v141 offset:2304
	ds_read_b128 v[70:73], v141 offset:3456
	v_add_co_u32_e32 v76, vcc, 0x40000, v74
	s_nop 1
	v_addc_co_u32_e32 v77, vcc, 0, v75, vcc
	s_waitcnt lgkmcnt(0)
	global_store_dwordx4 v[76:77], v[66:69], off offset:2048 sc1
	s_nop 1
	v_add_co_u32_e32 v66, vcc, 0x60000, v74
	s_nop 1
	v_addc_co_u32_e32 v67, vcc, 0, v75, vcc
	global_store_dwordx4 v[66:67], v[70:73], off offset:3072 sc1
	s_waitcnt lgkmcnt(0)
; __device__ __forceinline__ unsigned short f2bf(float f) { return (unsigned short)(cvt_pk_bf16(f, f) & 0xffffu); }
;     ...
;         const int c32 = bcol + wc * 32 + bj * HALF, row0 = brow + ai * HALF + wr * 64;
;         int b0, e0; row_be(row0, b0, e0); bf16_t* vbase;
;         if (epi.vt_info(c32, b0, vbase)) {
;   __device__ __forceinline__ void group(int row, int c32, int fq, f32x4 v0, f32x4 v1) const {
;     int b, e; const bool ok = row_be(row, b, e);
;     if (c32 < 512) {
;       if (c32 < 384) store8bf(cqkv + (size_t)row * 512 + c32 + fq * 8, v0, v1);
;       else { bf16_t* p = cqkv + (size_t)row * 512 + c32 + fq * 4; store4bf(p, v0); store4bf(p + 16, v1); }
;       if (c32 == 384 && ok) {
;         const float2* rp = rope + pos_of_e(e) * 16 + fq * 4; f32x4 o0, o1;
; #pragma unroll
;         for (int j = 0; j < 4; ++j) { const float2 cs = rp[j]; o0[j] = v0[j] * cs.x - v1[j] * cs.y; o1[j] = v1[j] * cs.x + v0[j] * cs.y; }
; #pragma unroll
;         for (int h = 0; h < 6; ++h) { bf16_t* q = ka + ((size_t)(b * 6 + h) * E + e) * 96 + 64 + fq * 4; store4bf(q, o0); store4bf(q + 16, o1); }
;       }
;       return;
;     }
;     if (!ok) return;
;     if (c32 < 768) { const int cc = c32 - 512, h = cc >> 6; store8bf(qd + ((size_t)(b * 4 + h) * E + e) * 64 + (cc & 63) + fq * 8, v0 * QSC_D, v1 * QSC_D); }
;     else if (c32 < 1024) { const int cc = c32 - 768, h = cc >> 6; store8bf(kd + ((size_t)(b * 4 + h) * E + e) * 64 + (cc & 63) + fq * 8, v0, v1); }
;     else if (c32 < 1280) { const int cc = c32 - 1024, h = cc >> 6; bf16_t* p = vtd + ((size_t)(b * 4 + h) * 64 + (cc & 63) + fq * 4) * E + e;
; #pragma unroll
;       for (int j = 0; j < 4; ++j) { p[(size_t)j * E] = f2bf(v0[j]); p[(size_t)(j + 16) * E] = f2bf(v1[j]); } }
;     else if (c32 < 1664) { const int cc = c32 - 1280, h = cc >> 6; store8bf(qs + ((size_t)(b * 6 + h) * E + e) * 64 + (cc & 63) + fq * 8, v0 * QSC_S, v1 * QSC_S); }
;     else if (c32 < 1792) { const int cc = c32 - 1664, g = cc >> 6; store8bf(ks + ((size_t)(b * 2 + g) * E + e) * 64 + (cc & 63) + fq * 8, v0, v1); }
;     else if (c32 < 1920) { const int cc = c32 - 1792, g = cc >> 6; bf16_t* p = vts + ((size_t)(b * 2 + g) * 64 + (cc & 63) + fq * 4) * E + e;
; #pragma unroll
;       for (int j = 0; j < 4; ++j) { p[(size_t)j * E] = f2bf(v0[j]); p[(size_t)(j + 16) * E] = f2bf(v1[j]); } }
.LBB0_532:
	s_nop 1
	v_add_u32_e32 v73, 0x80, v144
	s_movk_i32 s1, 0x7f80
	v_cmp_gt_i32_e64 s[6:7], s1, v144
	v_ashrrev_i32_e32 v72, 13, v73
	s_and_b64 vcc, exec, s[4:5]
	v_or_b32_e32 v66, v73, v136
	s_cbranch_vccnz .LBB0_620
	s_cmp_lg_u32 s0, 7
	s_mov_b64 s[20:21], -1
	s_cbranch_scc0 .LBB0_628
	s_cmp_gt_u32 s0, 1
	v_add_u32_e32 v67, 0xfffff900, v0
	s_cselect_b64 s[18:19], -1, 0
	s_cmp_gt_u32 s0, 2
	v_lshrrev_b32_e32 v78, 6, v67
	v_add_u32_e32 v67, 0xfffffb00, v0
	s_cselect_b64 s[16:17], -1, 0
	s_cmp_gt_u32 s0, 3
	v_lshrrev_b32_e32 v77, 6, v67
	v_add_u32_e32 v67, 0xfffffc00, v0
	s_cselect_b64 s[14:15], -1, 0
	s_cmp_gt_u32 s0, 4
	v_lshrrev_b32_e32 v76, 6, v67
	v_add_u32_e32 v67, 0xfffffd00, v0
	s_cselect_b64 s[12:13], -1, 0
	s_cmp_gt_u32 s0, 6
	v_lshrrev_b32_e32 v75, 6, v67
	v_add_u32_e32 v67, 0xfffffe00, v0
	s_cselect_b64 s[10:11], -1, 0
	s_cmp_lt_u32 s0, 2
	v_lshrrev_b32_e32 v74, 6, v67
	s_mov_b64 s[8:9], -1
	s_cbranch_scc1 .LBB0_553
	s_mov_b32 s1, 0x8000
	v_cmp_gt_i32_e32 vcc, s1, v66
	v_cmp_gt_u32_e64 s[8:9], s49, v73
	s_or_b64 s[20:21], vcc, s[8:9]
	s_and_saveexec_b64 s[8:9], s[20:21]
	s_cbranch_execz .LBB0_552
	v_and_b32_e32 v67, 0x1fcf, v66
	v_add_u32_e32 v68, 64, v67
	v_cndmask_b32_e32 v67, 0, v72, vcc
	v_cndmask_b32_e32 v68, v136, v68, vcc
	s_andn2_b64 vcc, exec, s[16:17]
	s_mov_b64 s[20:21], -1
	s_cbranch_vccnz .LBB0_550
	s_andn2_b64 vcc, exec, s[14:15]
	s_cbranch_vccnz .LBB0_547
	s_andn2_b64 vcc, exec, s[12:13]
	s_cbranch_vccnz .LBB0_544
	s_andn2_b64 vcc, exec, s[10:11]
	s_cbranch_vccnz .LBB0_541
	v_lshl_add_u32 v70, v67, 1, v78
	v_ashrrev_i32_e32 v71, 31, v70
	v_readlane_b32 s20, v254, 16
	v_lshlrev_b64 v[70:71], 6, v[70:71]
	v_readlane_b32 s21, v254, 17
	v_or_b32_e32 v69, v70, v140
	v_lshlrev_b32_e32 v70, 1, v68
	v_mov_b64_e32 v[80:81], s[20:21]
	v_mad_u64_u32 v[80:81], s[20:21], v69, s95, v[80:81]
	v_mad_i32_i24 v81, v71, s95, v81
	v_mov_b32_e32 v71, v1
	v_lshl_add_u64 v[70:71], v[80:81], 0, v[70:71]
	s_mov_b32 s1, 0x40000
	v_cvt_pk_bf16_f32 v69, v62, s0
	v_add_co_u32_e32 v80, vcc, s1, v70
	global_store_short v[70:71], v69, off sc1
	v_cvt_pk_bf16_f32 v69, v58, s0
	v_addc_co_u32_e32 v81, vcc, 0, v71, vcc
	s_movk_i32 s1, 0x4000
	global_store_short v[80:81], v69, off offset:2048 sc1
	v_add_co_u32_e32 v80, vcc, s1, v70
	v_cvt_pk_bf16_f32 v69, v63, s0
	s_nop 0
	v_addc_co_u32_e32 v81, vcc, 0, v71, vcc
	s_mov_b32 s1, 0x44000
	global_store_short v[80:81], v69, off offset:128 sc1
	v_add_co_u32_e32 v80, vcc, s1, v70
	v_cvt_pk_bf16_f32 v69, v59, s0
	s_nop 0
	v_addc_co_u32_e32 v81, vcc, 0, v71, vcc
	s_mov_b32 s1, 0x8000
	global_store_short v[80:81], v69, off offset:2176 sc1
	v_add_co_u32_e32 v80, vcc, s1, v70
	v_cvt_pk_bf16_f32 v69, v64, s0
	s_nop 0
	v_addc_co_u32_e32 v81, vcc, 0, v71, vcc
	s_mov_b32 s1, 0x48000
	global_store_short v[80:81], v69, off offset:256 sc1
	v_add_co_u32_e32 v80, vcc, s1, v70
	v_cvt_pk_bf16_f32 v69, v60, s0
	s_nop 0
	v_addc_co_u32_e32 v81, vcc, 0, v71, vcc
	global_store_short v[80:81], v69, off offset:2304 sc1
	v_add_co_u32_e32 v80, vcc, 0xc000, v70
	v_cvt_pk_bf16_f32 v69, v65, s0
	s_nop 0
	v_addc_co_u32_e32 v81, vcc, 0, v71, vcc
	v_add_co_u32_e32 v70, vcc, 0x4c000, v70
	global_store_short v[80:81], v69, off offset:384 sc1
	v_cvt_pk_bf16_f32 v69, v61, s0
	v_addc_co_u32_e32 v71, vcc, 0, v71, vcc
	s_mov_b64 s[20:21], 0
	global_store_short v[70:71], v69, off offset:2432 sc1
.LBB0_541:
	s_andn2_b64 vcc, exec, s[20:21]
	s_cbranch_vccnz .LBB0_543
	v_mad_i32_i24 v70, v67, 6, v77
	v_mov_b32_e32 v69, v1
	s_movk_i32 s1, 0x2040
	v_mad_i64_i32 v[70:71], s[20:21], v70, s1, v[68:69]
	v_readlane_b32 s20, v254, 12
	v_lshlrev_b64 v[70:71], 7, v[70:71]
	v_readlane_b32 s21, v254, 13
	v_lshlrev_b32_e32 v80, 1, v137
	v_mov_b32_e32 v81, v1
	v_lshl_add_u64 v[70:71], s[20:21], 0, v[70:71]
	v_lshl_add_u64 v[70:71], v[70:71], 0, v[80:81]
	v_lshlrev_b32_e32 v80, 1, v139
	s_mov_b32 s20, 0x3e38aa3b
	v_lshl_add_u64 v[70:71], v[70:71], 0, v[80:81]
	v_pk_mul_f32 v[82:83], v[64:65], s[20:21] op_sel_hi:[1,0]
	v_pk_mul_f32 v[80:81], v[62:63], s[20:21] op_sel_hi:[1,0]
	v_pk_mul_f32 v[84:85], v[60:61], s[20:21] op_sel_hi:[1,0]
	v_pk_mul_f32 v[86:87], v[58:59], s[20:21] op_sel_hi:[1,0]
	v_cvt_pk_bf16_f32 v80, v80, v81
	v_cvt_pk_bf16_f32 v81, v82, v83
	v_cvt_pk_bf16_f32 v82, v86, v87
	v_cvt_pk_bf16_f32 v83, v84, v85
	global_store_dwordx4 v[70:71], v[80:83], off sc1

; __device__ __forceinline__ unsigned short f2bf(float f) { return (unsigned short)(cvt_pk_bf16(f, f) & 0xffffu); }
;   __device__ __forceinline__ void group(int row, int c32, int fq, f32x4 v0, f32x4 v1) const {
;     ...
;     else if (c32 < 1280) { const int cc = c32 - 1024, h = cc >> 6; bf16_t* p = vtd + ((size_t)(b * 4 + h) * 64 + (cc & 63) + fq * 4) * E + e;
; #pragma unroll
;       for (int j = 0; j < 4; ++j) { p[(size_t)j * E] = f2bf(v0[j]); p[(size_t)(j + 16) * E] = f2bf(v1[j]); } }
.LBB0_544:
	s_andn2_b64 vcc, exec, s[20:21]
	s_cbranch_vccnz .LBB0_546
	v_lshl_add_u32 v70, v67, 2, v76
	v_ashrrev_i32_e32 v71, 31, v70
	v_readlane_b32 s20, v254, 10
	v_lshlrev_b64 v[70:71], 6, v[70:71]
	v_readlane_b32 s21, v254, 11
	v_or_b32_e32 v69, v70, v140
	v_lshlrev_b32_e32 v70, 1, v68
	v_mov_b64_e32 v[80:81], s[20:21]
	v_mad_u64_u32 v[80:81], s[20:21], v69, s95, v[80:81]
	v_mad_i32_i24 v81, v71, s95, v81
	v_mov_b32_e32 v71, v1
	v_lshl_add_u64 v[70:71], v[80:81], 0, v[70:71]
	s_mov_b32 s1, 0x40000
	v_cvt_pk_bf16_f32 v69, v62, s0
	v_add_co_u32_e32 v80, vcc, s1, v70
	global_store_short v[70:71], v69, off sc1
	v_cvt_pk_bf16_f32 v69, v58, s0
	v_addc_co_u32_e32 v81, vcc, 0, v71, vcc
	s_movk_i32 s1, 0x4000
	global_store_short v[80:81], v69, off offset:2048 sc1
	v_add_co_u32_e32 v80, vcc, s1, v70
	v_cvt_pk_bf16_f32 v69, v63, s0
	s_nop 0
	v_addc_co_u32_e32 v81, vcc, 0, v71, vcc
	s_mov_b32 s1, 0x44000
	global_store_short v[80:81], v69, off offset:128 sc1
	v_add_co_u32_e32 v80, vcc, s1, v70
	v_cvt_pk_bf16_f32 v69, v59, s0
	s_nop 0
	v_addc_co_u32_e32 v81, vcc, 0, v71, vcc
	s_mov_b32 s1, 0x8000
	global_store_short v[80:81], v69, off offset:2176 sc1
	v_add_co_u32_e32 v80, vcc, s1, v70
	v_cvt_pk_bf16_f32 v69, v64, s0
	s_nop 0
	v_addc_co_u32_e32 v81, vcc, 0, v71, vcc
	s_mov_b32 s1, 0x48000
	global_store_short v[80:81], v69, off offset:256 sc1
	v_add_co_u32_e32 v80, vcc, s1, v70
	v_cvt_pk_bf16_f32 v69, v60, s0
	s_nop 0
	v_addc_co_u32_e32 v81, vcc, 0, v71, vcc
	global_store_short v[80:81], v69, off offset:2304 sc1
	v_add_co_u32_e32 v80, vcc, 0xc000, v70
	v_cvt_pk_bf16_f32 v69, v65, s0
	s_nop 0
	v_addc_co_u32_e32 v81, vcc, 0, v71, vcc
	v_add_co_u32_e32 v70, vcc, 0x4c000, v70
	global_store_short v[80:81], v69, off offset:384 sc1
	v_cvt_pk_bf16_f32 v69, v61, s0
	v_addc_co_u32_e32 v71, vcc, 0, v71, vcc
	global_store_short v[70:71], v69, off offset:2432 sc1

; __device__ __forceinline__ void store8bf(bf16_t* p, f32x4 v0, f32x4 v1) { u32x4 w; w.x = cvt_pk_bf16(v0[0], v0[1]); w.y = cvt_pk_bf16(v0[2], v0[3]); w.z = cvt_pk_bf16(v1[0], v1[1]); w.w = cvt_pk_bf16(v1[2], v1[3]); *(u32x4*)p = w; }
;   __device__ __forceinline__ void group(int row, int c32, int fq, f32x4 v0, f32x4 v1) const {
;     ...
;     else if (c32 < 1024) { const int cc = c32 - 768, h = cc >> 6; store8bf(kd + ((size_t)(b * 4 + h) * E + e) * 64 + (cc & 63) + fq * 8, v0, v1); }
.LBB0_547:
	s_andn2_b64 vcc, exec, s[20:21]
	s_cbranch_vccnz .LBB0_549
	v_lshl_add_u32 v70, v67, 2, v75
	v_mov_b32_e32 v69, v1
	s_movk_i32 s1, 0x2040
	v_mad_i64_i32 v[70:71], s[20:21], v70, s1, v[68:69]
	v_readlane_b32 s20, v254, 8
	v_lshlrev_b64 v[70:71], 7, v[70:71]
	v_readlane_b32 s21, v254, 9
	v_lshlrev_b32_e32 v80, 1, v137
	v_mov_b32_e32 v81, v1
	v_lshl_add_u64 v[70:71], s[20:21], 0, v[70:71]
	v_lshl_add_u64 v[70:71], v[70:71], 0, v[80:81]
	v_lshlrev_b32_e32 v80, 1, v139
	v_lshl_add_u64 v[70:71], v[70:71], 0, v[80:81]
	v_cvt_pk_bf16_f32 v80, v62, v63
	v_cvt_pk_bf16_f32 v81, v64, v65
	v_cvt_pk_bf16_f32 v82, v58, v59
	v_cvt_pk_bf16_f32 v83, v60, v61
	global_store_dwordx4 v[70:71], v[80:83], off sc1

; __device__ __forceinline__ void store8bf(bf16_t* p, f32x4 v0, f32x4 v1) { u32x4 w; w.x = cvt_pk_bf16(v0[0], v0[1]); w.y = cvt_pk_bf16(v0[2], v0[3]); w.z = cvt_pk_bf16(v1[0], v1[1]); w.w = cvt_pk_bf16(v1[2], v1[3]); *(u32x4*)p = w; }
;   __device__ __forceinline__ void group(int row, int c32, int fq, f32x4 v0, f32x4 v1) const {
;     ...
;     if (c32 < 768) { const int cc = c32 - 512, h = cc >> 6; store8bf(qd + ((size_t)(b * 4 + h) * E + e) * 64 + (cc & 63) + fq * 8, v0 * QSC_D, v1 * QSC_D); }
.LBB0_550:
	s_andn2_b64 vcc, exec, s[20:21]
	s_cbranch_vccnz .LBB0_552
	v_lshl_add_u32 v67, v67, 2, v74
	v_mov_b32_e32 v69, v1
	s_movk_i32 s1, 0x2040
	v_mad_i64_i32 v[68:69], s[20:21], v67, s1, v[68:69]
	v_readlane_b32 s20, v254, 6
	v_lshlrev_b64 v[68:69], 7, v[68:69]
	v_readlane_b32 s21, v254, 7
	v_lshlrev_b32_e32 v70, 1, v137
	v_mov_b32_e32 v71, v1
	v_lshl_add_u64 v[68:69], s[20:21], 0, v[68:69]
	v_lshl_add_u64 v[68:69], v[68:69], 0, v[70:71]
	v_lshlrev_b32_e32 v70, 1, v139
	s_mov_b32 s20, 0x3e8293ee
	v_lshl_add_u64 v[80:81], v[68:69], 0, v[70:71]
	v_pk_mul_f32 v[70:71], v[64:65], s[20:21] op_sel_hi:[1,0]
	v_pk_mul_f32 v[68:69], v[62:63], s[20:21] op_sel_hi:[1,0]
	v_pk_mul_f32 v[82:83], v[60:61], s[20:21] op_sel_hi:[1,0]
	v_pk_mul_f32 v[84:85], v[58:59], s[20:21] op_sel_hi:[1,0]
	v_cvt_pk_bf16_f32 v68, v68, v69
	v_cvt_pk_bf16_f32 v69, v70, v71
	v_cvt_pk_bf16_f32 v70, v84, v85
	v_cvt_pk_bf16_f32 v71, v82, v83
	global_store_dwordx4 v[80:81], v[68:71], off sc1

; __device__ __forceinline__ unsigned short f2bf(float f) { return (unsigned short)(cvt_pk_bf16(f, f) & 0xffffu); }
; __device__ __forceinline__ void store4bf(bf16_t* p, f32x4 v) { u32x2 w; w.x = cvt_pk_bf16(v[0], v[1]); w.y = cvt_pk_bf16(v[2], v[3]); *(u32x2*)p = w; }
;   __device__ __forceinline__ void group(int row, int c32, int fq, f32x4 v0, f32x4 v1) const {
;     int b, e; const bool ok = row_be(row, b, e);
;     if (c32 < 512) {
;       if (c32 < 384) store8bf(cqkv + (size_t)row * 512 + c32 + fq * 8, v0, v1);
;       else { bf16_t* p = cqkv + (size_t)row * 512 + c32 + fq * 4; store4bf(p, v0); store4bf(p + 16, v1); }
;       if (c32 == 384 && ok) {
;         const float2* rp = rope + pos_of_e(e) * 16 + fq * 4; f32x4 o0, o1;
; #pragma unroll
;         for (int j = 0; j < 4; ++j) { const float2 cs = rp[j]; o0[j] = v0[j] * cs.x - v1[j] * cs.y; o1[j] = v1[j] * cs.x + v0[j] * cs.y; }
; #pragma unroll
;         for (int h = 0; h < 6; ++h) { bf16_t* q = ka + ((size_t)(b * 6 + h) * E + e) * 96 + 64 + fq * 4; store4bf(q, o0); store4bf(q + 16, o1); }
;       }
;       return;
;     }
;     if (!ok) return;
;     if (c32 < 768) { const int cc = c32 - 512, h = cc >> 6; store8bf(qd + ((size_t)(b * 4 + h) * E + e) * 64 + (cc & 63) + fq * 8, v0 * QSC_D, v1 * QSC_D); }
;     else if (c32 < 1024) { const int cc = c32 - 768, h = cc >> 6; store8bf(kd + ((size_t)(b * 4 + h) * E + e) * 64 + (cc & 63) + fq * 8, v0, v1); }
;     else if (c32 < 1280) { const int cc = c32 - 1024, h = cc >> 6; bf16_t* p = vtd + ((size_t)(b * 4 + h) * 64 + (cc & 63) + fq * 4) * E + e;
; #pragma unroll
;       for (int j = 0; j < 4; ++j) { p[(size_t)j * E] = f2bf(v0[j]); p[(size_t)(j + 16) * E] = f2bf(v1[j]); } }
;     else if (c32 < 1664) { const int cc = c32 - 1280, h = cc >> 6; store8bf(qs + ((size_t)(b * 6 + h) * E + e) * 64 + (cc & 63) + fq * 8, v0 * QSC_S, v1 * QSC_S); }
;     else if (c32 < 1792) { const int cc = c32 - 1664, g = cc >> 6; store8bf(ks + ((size_t)(b * 2 + g) * E + e) * 64 + (cc & 63) + fq * 8, v0, v1); }
;     else if (c32 < 1920) { const int cc = c32 - 1792, g = cc >> 6; bf16_t* p = vts + ((size_t)(b * 2 + g) * 64 + (cc & 63) + fq * 4) * E + e;
; #pragma unroll
;       for (int j = 0; j < 4; ++j) { p[(size_t)j * E] = f2bf(v0[j]); p[(size_t)(j + 16) * E] = f2bf(v1[j]); } }
.LBB0_553:
	s_andn2_b64 vcc, exec, s[8:9]
	s_cbranch_vccnz .LBB0_555
	v_ashrrev_i32_e32 v67, 31, v66
	v_readlane_b32 s8, v254, 0
	v_lshlrev_b64 v[68:69], 10, v[66:67]
	v_readlane_b32 s9, v254, 1
	v_lshlrev_b32_e32 v80, 1, v139
	v_mov_b32_e32 v81, v1
	v_lshl_add_u64 v[70:71], s[8:9], 0, v[68:69]
	v_lshl_add_u64 v[70:71], v[0:1], 1, v[70:71]
	v_cvt_pk_bf16_f32 v68, v62, v63
	v_cvt_pk_bf16_f32 v69, v64, v65
	v_lshl_add_u64 v[80:81], v[70:71], 0, v[80:81]
	v_cvt_pk_bf16_f32 v70, v58, v59
	v_cvt_pk_bf16_f32 v71, v60, v61
	global_store_dwordx4 v[80:81], v[68:71], off sc1
.LBB0_555:
	s_nop 1
	v_or_b32_e32 v68, 16, v66
	s_movk_i32 s1, 0x7fff
	v_cmp_lt_i32_e32 vcc, s1, v68
	s_and_saveexec_b64 s[8:9], vcc
	s_xor_b64 s[8:9], exec, s[8:9]
	v_bfe_u32 v67, v68, 4, 2
	v_cmp_gt_u32_e64 s[20:21], s49, v73
	s_or_saveexec_b64 s[8:9], s[8:9]
	v_mov_b32_e32 v70, v136
	s_xor_b64 exec, exec, s[8:9]
	v_and_b32_e32 v67, 0x1fdf, v68
	v_add_u32_e32 v70, 64, v67
	s_or_b64 s[20:21], s[20:21], exec
	v_mov_b32_e32 v67, v72
	s_or_b64 exec, exec, s[8:9]
	v_cndmask_b32_e64 v69, 0, 1, s[18:19]
	v_cmp_ne_u32_e64 s[8:9], 1, v69
	s_andn2_b64 vcc, exec, s[18:19]
	s_mov_b64 s[18:19], -1
	s_cbranch_vccnz .LBB0_578
	s_and_saveexec_b64 s[18:19], s[20:21]
	s_cbranch_execz .LBB0_577
	s_andn2_b64 vcc, exec, s[16:17]
	s_mov_b64 s[20:21], -1
	s_cbranch_vccnz .LBB0_575
	s_andn2_b64 vcc, exec, s[14:15]
	s_cbranch_vccnz .LBB0_572
	s_andn2_b64 vcc, exec, s[12:13]
	s_cbranch_vccnz .LBB0_569
	s_andn2_b64 vcc, exec, s[10:11]
	s_cbranch_vccnz .LBB0_566
	v_lshl_add_u32 v80, v67, 1, v78
	v_ashrrev_i32_e32 v81, 31, v80
	v_readlane_b32 s20, v254, 16
	v_lshlrev_b64 v[80:81], 6, v[80:81]
	v_readlane_b32 s21, v254, 17
	v_or_b32_e32 v69, v80, v140
	v_lshlrev_b32_e32 v80, 1, v70
	v_mov_b64_e32 v[82:83], s[20:21]
	v_mad_u64_u32 v[82:83], s[20:21], v69, s95, v[82:83]
	v_mad_i32_i24 v83, v81, s95, v83
	v_mov_b32_e32 v81, v1
	v_lshl_add_u64 v[80:81], v[82:83], 0, v[80:81]
	s_mov_b32 s1, 0x40000
	v_cvt_pk_bf16_f32 v69, v54, s0
	v_add_co_u32_e32 v82, vcc, s1, v80
	global_store_short v[80:81], v69, off sc1
	v_cvt_pk_bf16_f32 v69, v50, s0
	v_addc_co_u32_e32 v83, vcc, 0, v81, vcc
	s_movk_i32 s1, 0x4000
	global_store_short v[82:83], v69, off offset:2048 sc1
	v_add_co_u32_e32 v82, vcc, s1, v80
	v_cvt_pk_bf16_f32 v69, v55, s0
	s_nop 0
	v_addc_co_u32_e32 v83, vcc, 0, v81, vcc
	s_mov_b32 s1, 0x44000
	global_store_short v[82:83], v69, off offset:128 sc1
	v_add_co_u32_e32 v82, vcc, s1, v80
	v_cvt_pk_bf16_f32 v69, v51, s0
	s_nop 0
	v_addc_co_u32_e32 v83, vcc, 0, v81, vcc
	s_mov_b32 s1, 0x8000
	global_store_short v[82:83], v69, off offset:2176 sc1
	v_add_co_u32_e32 v82, vcc, s1, v80
	v_cvt_pk_bf16_f32 v69, v56, s0
	s_nop 0
	v_addc_co_u32_e32 v83, vcc, 0, v81, vcc
	s_mov_b32 s1, 0x48000
	global_store_short v[82:83], v69, off offset:256 sc1
	v_add_co_u32_e32 v82, vcc, s1, v80
	v_cvt_pk_bf16_f32 v69, v52, s0
	s_nop 0
	v_addc_co_u32_e32 v83, vcc, 0, v81, vcc
	global_store_short v[82:83], v69, off offset:2304 sc1
	v_add_co_u32_e32 v82, vcc, 0xc000, v80
	v_cvt_pk_bf16_f32 v69, v57, s0
	s_nop 0
	v_addc_co_u32_e32 v83, vcc, 0, v81, vcc
	v_add_co_u32_e32 v80, vcc, 0x4c000, v80
	global_store_short v[82:83], v69, off offset:384 sc1
	v_cvt_pk_bf16_f32 v69, v53, s0
	v_addc_co_u32_e32 v81, vcc, 0, v81, vcc
	s_mov_b64 s[20:21], 0
	global_store_short v[80:81], v69, off offset:2432 sc1
.LBB0_566:
	s_andn2_b64 vcc, exec, s[20:21]
	s_cbranch_vccnz .LBB0_568
	v_mad_i32_i24 v69, v67, 6, v77
	v_mov_b32_e32 v71, v1
	s_movk_i32 s1, 0x2040
	v_mad_i64_i32 v[80:81], s[20:21], v69, s1, v[70:71]
	v_readlane_b32 s20, v254, 12
	v_lshlrev_b64 v[80:81], 7, v[80:81]
	v_readlane_b32 s21, v254, 13
	v_lshlrev_b32_e32 v82, 1, v137
	v_mov_b32_e32 v83, v1
	v_lshl_add_u64 v[80:81], s[20:21], 0, v[80:81]
	v_lshl_add_u64 v[80:81], v[80:81], 0, v[82:83]
	v_lshlrev_b32_e32 v82, 1, v139
	s_mov_b32 s20, 0x3e38aa3b
	v_lshl_add_u64 v[84:85], v[80:81], 0, v[82:83]
	v_pk_mul_f32 v[82:83], v[56:57], s[20:21] op_sel_hi:[1,0]
	v_pk_mul_f32 v[80:81], v[54:55], s[20:21] op_sel_hi:[1,0]
	v_pk_mul_f32 v[86:87], v[52:53], s[20:21] op_sel_hi:[1,0]
	v_pk_mul_f32 v[88:89], v[50:51], s[20:21] op_sel_hi:[1,0]
	v_cvt_pk_bf16_f32 v80, v80, v81
	v_cvt_pk_bf16_f32 v81, v82, v83
	v_cvt_pk_bf16_f32 v82, v88, v89
	v_cvt_pk_bf16_f32 v83, v86, v87
	global_store_dwordx4 v[84:85], v[80:83], off sc1

; __device__ __forceinline__ unsigned short f2bf(float f) { return (unsigned short)(cvt_pk_bf16(f, f) & 0xffffu); }
;   __device__ __forceinline__ void group(int row, int c32, int fq, f32x4 v0, f32x4 v1) const {
;     ...
;     else if (c32 < 1280) { const int cc = c32 - 1024, h = cc >> 6; bf16_t* p = vtd + ((size_t)(b * 4 + h) * 64 + (cc & 63) + fq * 4) * E + e;
; #pragma unroll
;       for (int j = 0; j < 4; ++j) { p[(size_t)j * E] = f2bf(v0[j]); p[(size_t)(j + 16) * E] = f2bf(v1[j]); } }
.LBB0_569:
	s_andn2_b64 vcc, exec, s[20:21]
	s_cbranch_vccnz .LBB0_571
	v_lshl_add_u32 v80, v67, 2, v76
	v_ashrrev_i32_e32 v81, 31, v80
	v_readlane_b32 s20, v254, 10
	v_lshlrev_b64 v[80:81], 6, v[80:81]
	v_readlane_b32 s21, v254, 11
	v_or_b32_e32 v69, v80, v140
	v_lshlrev_b32_e32 v80, 1, v70
	v_mov_b64_e32 v[82:83], s[20:21]
	v_mad_u64_u32 v[82:83], s[20:21], v69, s95, v[82:83]
	v_mad_i32_i24 v83, v81, s95, v83
	v_mov_b32_e32 v81, v1
	v_lshl_add_u64 v[80:81], v[82:83], 0, v[80:81]
	s_mov_b32 s1, 0x40000
	v_cvt_pk_bf16_f32 v69, v54, s0
	v_add_co_u32_e32 v82, vcc, s1, v80
	global_store_short v[80:81], v69, off sc1
	v_cvt_pk_bf16_f32 v69, v50, s0
	v_addc_co_u32_e32 v83, vcc, 0, v81, vcc
	s_movk_i32 s1, 0x4000
	global_store_short v[82:83], v69, off offset:2048 sc1
	v_add_co_u32_e32 v82, vcc, s1, v80
	v_cvt_pk_bf16_f32 v69, v55, s0
	s_nop 0
	v_addc_co_u32_e32 v83, vcc, 0, v81, vcc
	s_mov_b32 s1, 0x44000
	global_store_short v[82:83], v69, off offset:128 sc1
	v_add_co_u32_e32 v82, vcc, s1, v80
	v_cvt_pk_bf16_f32 v69, v51, s0
	s_nop 0
	v_addc_co_u32_e32 v83, vcc, 0, v81, vcc
	s_mov_b32 s1, 0x8000
	global_store_short v[82:83], v69, off offset:2176 sc1
	v_add_co_u32_e32 v82, vcc, s1, v80
	v_cvt_pk_bf16_f32 v69, v56, s0
	s_nop 0
	v_addc_co_u32_e32 v83, vcc, 0, v81, vcc
	s_mov_b32 s1, 0x48000
	global_store_short v[82:83], v69, off offset:256 sc1
	v_add_co_u32_e32 v82, vcc, s1, v80
	v_cvt_pk_bf16_f32 v69, v52, s0
	s_nop 0
	v_addc_co_u32_e32 v83, vcc, 0, v81, vcc
	global_store_short v[82:83], v69, off offset:2304 sc1
	v_add_co_u32_e32 v82, vcc, 0xc000, v80
	v_cvt_pk_bf16_f32 v69, v57, s0
	s_nop 0
	v_addc_co_u32_e32 v83, vcc, 0, v81, vcc
	v_add_co_u32_e32 v80, vcc, 0x4c000, v80
	global_store_short v[82:83], v69, off offset:384 sc1
	v_cvt_pk_bf16_f32 v69, v53, s0
	v_addc_co_u32_e32 v81, vcc, 0, v81, vcc
	global_store_short v[80:81], v69, off offset:2432 sc1

; __device__ __forceinline__ void store8bf(bf16_t* p, f32x4 v0, f32x4 v1) { u32x4 w; w.x = cvt_pk_bf16(v0[0], v0[1]); w.y = cvt_pk_bf16(v0[2], v0[3]); w.z = cvt_pk_bf16(v1[0], v1[1]); w.w = cvt_pk_bf16(v1[2], v1[3]); *(u32x4*)p = w; }
;   __device__ __forceinline__ void group(int row, int c32, int fq, f32x4 v0, f32x4 v1) const {
;     ...
;     else if (c32 < 1024) { const int cc = c32 - 768, h = cc >> 6; store8bf(kd + ((size_t)(b * 4 + h) * E + e) * 64 + (cc & 63) + fq * 8, v0, v1); }
.LBB0_572:
	s_andn2_b64 vcc, exec, s[20:21]
	s_cbranch_vccnz .LBB0_574
	v_lshl_add_u32 v69, v67, 2, v75
	v_mov_b32_e32 v71, v1
	s_movk_i32 s1, 0x2040
	v_mad_i64_i32 v[80:81], s[20:21], v69, s1, v[70:71]
	v_readlane_b32 s20, v254, 8
	v_lshlrev_b64 v[80:81], 7, v[80:81]
	v_readlane_b32 s21, v254, 9
	v_lshlrev_b32_e32 v82, 1, v137
	v_mov_b32_e32 v83, v1
	v_lshl_add_u64 v[80:81], s[20:21], 0, v[80:81]
	v_lshl_add_u64 v[80:81], v[80:81], 0, v[82:83]
	v_lshlrev_b32_e32 v82, 1, v139
	v_lshl_add_u64 v[84:85], v[80:81], 0, v[82:83]
	v_cvt_pk_bf16_f32 v80, v54, v55
	v_cvt_pk_bf16_f32 v81, v56, v57
	v_cvt_pk_bf16_f32 v82, v50, v51
	v_cvt_pk_bf16_f32 v83, v52, v53
	global_store_dwordx4 v[84:85], v[80:83], off sc1

; __device__ __forceinline__ void store8bf(bf16_t* p, f32x4 v0, f32x4 v1) { u32x4 w; w.x = cvt_pk_bf16(v0[0], v0[1]); w.y = cvt_pk_bf16(v0[2], v0[3]); w.z = cvt_pk_bf16(v1[0], v1[1]); w.w = cvt_pk_bf16(v1[2], v1[3]); *(u32x4*)p = w; }
;   __device__ __forceinline__ void group(int row, int c32, int fq, f32x4 v0, f32x4 v1) const {
;     ...
;     if (c32 < 768) { const int cc = c32 - 512, h = cc >> 6; store8bf(qd + ((size_t)(b * 4 + h) * E + e) * 64 + (cc & 63) + fq * 8, v0 * QSC_D, v1 * QSC_D); }
.LBB0_575:
	s_andn2_b64 vcc, exec, s[20:21]
	s_cbranch_vccnz .LBB0_577
	v_lshl_add_u32 v67, v67, 2, v74
	v_mov_b32_e32 v71, v1
	s_movk_i32 s1, 0x2040
	v_mad_i64_i32 v[70:71], s[20:21], v67, s1, v[70:71]
	v_readlane_b32 s20, v254, 6
	v_lshlrev_b64 v[70:71], 7, v[70:71]
	v_readlane_b32 s21, v254, 7
	v_lshlrev_b32_e32 v80, 1, v137
	v_mov_b32_e32 v81, v1
	v_lshl_add_u64 v[70:71], s[20:21], 0, v[70:71]
	v_lshl_add_u64 v[70:71], v[70:71], 0, v[80:81]
	v_lshlrev_b32_e32 v80, 1, v139
	s_mov_b32 s20, 0x3e8293ee
	v_lshl_add_u64 v[70:71], v[70:71], 0, v[80:81]
	v_pk_mul_f32 v[82:83], v[56:57], s[20:21] op_sel_hi:[1,0]
	v_pk_mul_f32 v[80:81], v[54:55], s[20:21] op_sel_hi:[1,0]
	v_pk_mul_f32 v[84:85], v[52:53], s[20:21] op_sel_hi:[1,0]
	v_pk_mul_f32 v[86:87], v[50:51], s[20:21] op_sel_hi:[1,0]
	v_cvt_pk_bf16_f32 v80, v80, v81
	v_cvt_pk_bf16_f32 v81, v82, v83
	v_cvt_pk_bf16_f32 v82, v86, v87
	v_cvt_pk_bf16_f32 v83, v84, v85
	global_store_dwordx4 v[70:71], v[80:83], off sc1

; __device__ __forceinline__ void store8bf(bf16_t* p, f32x4 v0, f32x4 v1) { u32x4 w; w.x = cvt_pk_bf16(v0[0], v0[1]); w.y = cvt_pk_bf16(v0[2], v0[3]); w.z = cvt_pk_bf16(v1[0], v1[1]); w.w = cvt_pk_bf16(v1[2], v1[3]); *(u32x4*)p = w; }
;   __device__ __forceinline__ void group(int row, int c32, int fq, f32x4 v0, f32x4 v1) const {
;     ...
;       if (c32 < 384) store8bf(cqkv + (size_t)row * 512 + c32 + fq * 8, v0, v1);
.LBB0_578:
	s_andn2_b64 vcc, exec, s[18:19]
	s_cbranch_vccnz .LBB0_580
	v_ashrrev_i32_e32 v69, 31, v68
	v_readlane_b32 s18, v254, 0
	v_lshlrev_b64 v[68:69], 10, v[68:69]
	v_readlane_b32 s19, v254, 1
	v_lshlrev_b32_e32 v80, 1, v139
	v_mov_b32_e32 v81, v1
	v_lshl_add_u64 v[70:71], s[18:19], 0, v[68:69]
	v_lshl_add_u64 v[70:71], v[0:1], 1, v[70:71]
	v_cvt_pk_bf16_f32 v68, v54, v55
	v_cvt_pk_bf16_f32 v69, v56, v57
	v_lshl_add_u64 v[80:81], v[70:71], 0, v[80:81]
	v_cvt_pk_bf16_f32 v70, v50, v51
	v_cvt_pk_bf16_f32 v71, v52, v53
	global_store_dwordx4 v[80:81], v[68:71], off sc1

; __device__ __forceinline__ unsigned short f2bf(float f) { return (unsigned short)(cvt_pk_bf16(f, f) & 0xffffu); }
; __device__ __forceinline__ void store8bf(bf16_t* p, f32x4 v0, f32x4 v1) { u32x4 w; w.x = cvt_pk_bf16(v0[0], v0[1]); w.y = cvt_pk_bf16(v0[2], v0[3]); w.z = cvt_pk_bf16(v1[0], v1[1]); w.w = cvt_pk_bf16(v1[2], v1[3]); *(u32x4*)p = w; }
;   __device__ __forceinline__ void group(int row, int c32, int fq, f32x4 v0, f32x4 v1) const {
;     ...
;     else if (c32 < 1664) { const int cc = c32 - 1280, h = cc >> 6; store8bf(qs + ((size_t)(b * 6 + h) * E + e) * 64 + (cc & 63) + fq * 8, v0 * QSC_S, v1 * QSC_S); }
;     else if (c32 < 1792) { const int cc = c32 - 1664, g = cc >> 6; store8bf(ks + ((size_t)(b * 2 + g) * E + e) * 64 + (cc & 63) + fq * 8, v0, v1); }
;     else if (c32 < 1920) { const int cc = c32 - 1792, g = cc >> 6; bf16_t* p = vts + ((size_t)(b * 2 + g) * 64 + (cc & 63) + fq * 4) * E + e;
; #pragma unroll
;       for (int j = 0; j < 4; ++j) { p[(size_t)j * E] = f2bf(v0[j]); p[(size_t)(j + 16) * E] = f2bf(v1[j]); } }
.LBB0_583:
	s_and_saveexec_b64 s[18:19], s[20:21]
	s_cbranch_execz .LBB0_600
	s_andn2_b64 vcc, exec, s[16:17]
	s_mov_b64 s[20:21], -1
	s_cbranch_vccnz .LBB0_598
	s_andn2_b64 vcc, exec, s[14:15]
	s_cbranch_vccnz .LBB0_595
	s_andn2_b64 vcc, exec, s[12:13]
	s_cbranch_vccnz .LBB0_592
	s_andn2_b64 vcc, exec, s[10:11]
	s_cbranch_vccnz .LBB0_589
	v_lshl_add_u32 v80, v67, 1, v78
	v_ashrrev_i32_e32 v81, 31, v80
	v_readlane_b32 s20, v254, 16
	v_lshlrev_b64 v[80:81], 6, v[80:81]
	v_readlane_b32 s21, v254, 17
	v_or_b32_e32 v69, v80, v140
	v_lshlrev_b32_e32 v80, 1, v70
	v_mov_b64_e32 v[82:83], s[20:21]
	v_mad_u64_u32 v[82:83], s[20:21], v69, s95, v[82:83]
	v_mad_i32_i24 v83, v81, s95, v83
	v_mov_b32_e32 v81, v1
	v_lshl_add_u64 v[80:81], v[82:83], 0, v[80:81]
	s_mov_b32 s1, 0x40000
	v_cvt_pk_bf16_f32 v69, v46, s0
	v_add_co_u32_e32 v82, vcc, s1, v80
	global_store_short v[80:81], v69, off sc1
	v_cvt_pk_bf16_f32 v69, v42, s0
	v_addc_co_u32_e32 v83, vcc, 0, v81, vcc
	s_movk_i32 s1, 0x4000
	global_store_short v[82:83], v69, off offset:2048 sc1
	v_add_co_u32_e32 v82, vcc, s1, v80
	v_cvt_pk_bf16_f32 v69, v47, s0
	s_nop 0
	v_addc_co_u32_e32 v83, vcc, 0, v81, vcc
	s_mov_b32 s1, 0x44000
	global_store_short v[82:83], v69, off offset:128 sc1
	v_add_co_u32_e32 v82, vcc, s1, v80
	v_cvt_pk_bf16_f32 v69, v43, s0
	s_nop 0
	v_addc_co_u32_e32 v83, vcc, 0, v81, vcc
	s_mov_b32 s1, 0x8000
	global_store_short v[82:83], v69, off offset:2176 sc1
	v_add_co_u32_e32 v82, vcc, s1, v80
	v_cvt_pk_bf16_f32 v69, v48, s0
	s_nop 0
	v_addc_co_u32_e32 v83, vcc, 0, v81, vcc
	s_mov_b32 s1, 0x48000
	global_store_short v[82:83], v69, off offset:256 sc1
	v_add_co_u32_e32 v82, vcc, s1, v80
	v_cvt_pk_bf16_f32 v69, v44, s0
	s_nop 0
	v_addc_co_u32_e32 v83, vcc, 0, v81, vcc
	global_store_short v[82:83], v69, off offset:2304 sc1
	v_add_co_u32_e32 v82, vcc, 0xc000, v80
	v_cvt_pk_bf16_f32 v69, v49, s0
	s_nop 0
	v_addc_co_u32_e32 v83, vcc, 0, v81, vcc
	v_add_co_u32_e32 v80, vcc, 0x4c000, v80
	global_store_short v[82:83], v69, off offset:384 sc1
	v_cvt_pk_bf16_f32 v69, v45, s0
	v_addc_co_u32_e32 v81, vcc, 0, v81, vcc
	s_mov_b64 s[20:21], 0
	global_store_short v[80:81], v69, off offset:2432 sc1
.LBB0_589:
	s_andn2_b64 vcc, exec, s[20:21]
	s_cbranch_vccnz .LBB0_591
	v_mad_i32_i24 v69, v67, 6, v77
	v_mov_b32_e32 v71, v1
	s_movk_i32 s1, 0x2040
	v_mad_i64_i32 v[80:81], s[20:21], v69, s1, v[70:71]
	v_readlane_b32 s20, v254, 12
	v_lshlrev_b64 v[80:81], 7, v[80:81]
	v_readlane_b32 s21, v254, 13
	v_lshlrev_b32_e32 v82, 1, v137
	v_mov_b32_e32 v83, v1
	v_lshl_add_u64 v[80:81], s[20:21], 0, v[80:81]
	v_lshl_add_u64 v[80:81], v[80:81], 0, v[82:83]
	v_lshlrev_b32_e32 v82, 1, v139
	s_mov_b32 s20, 0x3e38aa3b
	v_lshl_add_u64 v[84:85], v[80:81], 0, v[82:83]
	v_pk_mul_f32 v[82:83], v[48:49], s[20:21] op_sel_hi:[1,0]
	v_pk_mul_f32 v[80:81], v[46:47], s[20:21] op_sel_hi:[1,0]
	v_pk_mul_f32 v[86:87], v[44:45], s[20:21] op_sel_hi:[1,0]
	v_pk_mul_f32 v[88:89], v[42:43], s[20:21] op_sel_hi:[1,0]
	v_cvt_pk_bf16_f32 v80, v80, v81
	v_cvt_pk_bf16_f32 v81, v82, v83
	v_cvt_pk_bf16_f32 v82, v88, v89
	v_cvt_pk_bf16_f32 v83, v86, v87
	global_store_dwordx4 v[84:85], v[80:83], off sc1

; __device__ __forceinline__ unsigned short f2bf(float f) { return (unsigned short)(cvt_pk_bf16(f, f) & 0xffffu); }
;   __device__ __forceinline__ void group(int row, int c32, int fq, f32x4 v0, f32x4 v1) const {
;     ...
;     else if (c32 < 1280) { const int cc = c32 - 1024, h = cc >> 6; bf16_t* p = vtd + ((size_t)(b * 4 + h) * 64 + (cc & 63) + fq * 4) * E + e;
; #pragma unroll
;       for (int j = 0; j < 4; ++j) { p[(size_t)j * E] = f2bf(v0[j]); p[(size_t)(j + 16) * E] = f2bf(v1[j]); } }
.LBB0_592:
	s_andn2_b64 vcc, exec, s[20:21]
	s_cbranch_vccnz .LBB0_594
	v_lshl_add_u32 v80, v67, 2, v76
	v_ashrrev_i32_e32 v81, 31, v80
	v_readlane_b32 s20, v254, 10
	v_lshlrev_b64 v[80:81], 6, v[80:81]
	v_readlane_b32 s21, v254, 11
	v_or_b32_e32 v69, v80, v140
	v_lshlrev_b32_e32 v80, 1, v70
	v_mov_b64_e32 v[82:83], s[20:21]
	v_mad_u64_u32 v[82:83], s[20:21], v69, s95, v[82:83]
	v_mad_i32_i24 v83, v81, s95, v83
	v_mov_b32_e32 v81, v1
	v_lshl_add_u64 v[80:81], v[82:83], 0, v[80:81]
	s_mov_b32 s1, 0x40000
	v_cvt_pk_bf16_f32 v69, v46, s0
	v_add_co_u32_e32 v82, vcc, s1, v80
	global_store_short v[80:81], v69, off sc1
	v_cvt_pk_bf16_f32 v69, v42, s0
	v_addc_co_u32_e32 v83, vcc, 0, v81, vcc
	s_movk_i32 s1, 0x4000
	global_store_short v[82:83], v69, off offset:2048 sc1
	v_add_co_u32_e32 v82, vcc, s1, v80
	v_cvt_pk_bf16_f32 v69, v47, s0
	s_nop 0
	v_addc_co_u32_e32 v83, vcc, 0, v81, vcc
	s_mov_b32 s1, 0x44000
	global_store_short v[82:83], v69, off offset:128 sc1
	v_add_co_u32_e32 v82, vcc, s1, v80
	v_cvt_pk_bf16_f32 v69, v43, s0
	s_nop 0
	v_addc_co_u32_e32 v83, vcc, 0, v81, vcc
	s_mov_b32 s1, 0x8000
	global_store_short v[82:83], v69, off offset:2176 sc1
	v_add_co_u32_e32 v82, vcc, s1, v80
	v_cvt_pk_bf16_f32 v69, v48, s0
	s_nop 0
	v_addc_co_u32_e32 v83, vcc, 0, v81, vcc
	s_mov_b32 s1, 0x48000
	global_store_short v[82:83], v69, off offset:256 sc1
	v_add_co_u32_e32 v82, vcc, s1, v80
	v_cvt_pk_bf16_f32 v69, v44, s0
	s_nop 0
	v_addc_co_u32_e32 v83, vcc, 0, v81, vcc
	global_store_short v[82:83], v69, off offset:2304 sc1
	v_add_co_u32_e32 v82, vcc, 0xc000, v80
	v_cvt_pk_bf16_f32 v69, v49, s0
	s_nop 0
	v_addc_co_u32_e32 v83, vcc, 0, v81, vcc
	v_add_co_u32_e32 v80, vcc, 0x4c000, v80
	global_store_short v[82:83], v69, off offset:384 sc1
	v_cvt_pk_bf16_f32 v69, v45, s0
	v_addc_co_u32_e32 v81, vcc, 0, v81, vcc
	global_store_short v[80:81], v69, off offset:2432 sc1

; __device__ __forceinline__ void store8bf(bf16_t* p, f32x4 v0, f32x4 v1) { u32x4 w; w.x = cvt_pk_bf16(v0[0], v0[1]); w.y = cvt_pk_bf16(v0[2], v0[3]); w.z = cvt_pk_bf16(v1[0], v1[1]); w.w = cvt_pk_bf16(v1[2], v1[3]); *(u32x4*)p = w; }
;   __device__ __forceinline__ void group(int row, int c32, int fq, f32x4 v0, f32x4 v1) const {
;     ...
;     else if (c32 < 1024) { const int cc = c32 - 768, h = cc >> 6; store8bf(kd + ((size_t)(b * 4 + h) * E + e) * 64 + (cc & 63) + fq * 8, v0, v1); }
.LBB0_595:
	s_andn2_b64 vcc, exec, s[20:21]
	s_cbranch_vccnz .LBB0_597
	v_lshl_add_u32 v69, v67, 2, v75
	v_mov_b32_e32 v71, v1
	s_movk_i32 s1, 0x2040
	v_mad_i64_i32 v[80:81], s[20:21], v69, s1, v[70:71]
	v_readlane_b32 s20, v254, 8
	v_lshlrev_b64 v[80:81], 7, v[80:81]
	v_readlane_b32 s21, v254, 9
	v_lshlrev_b32_e32 v82, 1, v137
	v_mov_b32_e32 v83, v1
	v_lshl_add_u64 v[80:81], s[20:21], 0, v[80:81]
	v_lshl_add_u64 v[80:81], v[80:81], 0, v[82:83]
	v_lshlrev_b32_e32 v82, 1, v139
	v_lshl_add_u64 v[84:85], v[80:81], 0, v[82:83]
	v_cvt_pk_bf16_f32 v80, v46, v47
	v_cvt_pk_bf16_f32 v81, v48, v49
	v_cvt_pk_bf16_f32 v82, v42, v43
	v_cvt_pk_bf16_f32 v83, v44, v45
	global_store_dwordx4 v[84:85], v[80:83], off sc1

; __device__ __forceinline__ void store8bf(bf16_t* p, f32x4 v0, f32x4 v1) { u32x4 w; w.x = cvt_pk_bf16(v0[0], v0[1]); w.y = cvt_pk_bf16(v0[2], v0[3]); w.z = cvt_pk_bf16(v1[0], v1[1]); w.w = cvt_pk_bf16(v1[2], v1[3]); *(u32x4*)p = w; }
;   __device__ __forceinline__ void group(int row, int c32, int fq, f32x4 v0, f32x4 v1) const {
;     ...
;     if (c32 < 768) { const int cc = c32 - 512, h = cc >> 6; store8bf(qd + ((size_t)(b * 4 + h) * E + e) * 64 + (cc & 63) + fq * 8, v0 * QSC_D, v1 * QSC_D); }
.LBB0_598:
	s_andn2_b64 vcc, exec, s[20:21]
	s_cbranch_vccnz .LBB0_600
	v_lshl_add_u32 v67, v67, 2, v74
	v_mov_b32_e32 v71, v1
	s_movk_i32 s1, 0x2040
	v_mad_i64_i32 v[70:71], s[20:21], v67, s1, v[70:71]
	v_readlane_b32 s20, v254, 6
	v_lshlrev_b64 v[70:71], 7, v[70:71]
	v_readlane_b32 s21, v254, 7
	v_lshlrev_b32_e32 v80, 1, v137
	v_mov_b32_e32 v81, v1
	v_lshl_add_u64 v[70:71], s[20:21], 0, v[70:71]
	v_lshl_add_u64 v[70:71], v[70:71], 0, v[80:81]
	v_lshlrev_b32_e32 v80, 1, v139
	s_mov_b32 s20, 0x3e8293ee
	v_lshl_add_u64 v[70:71], v[70:71], 0, v[80:81]
	v_pk_mul_f32 v[82:83], v[48:49], s[20:21] op_sel_hi:[1,0]
	v_pk_mul_f32 v[80:81], v[46:47], s[20:21] op_sel_hi:[1,0]
	v_pk_mul_f32 v[84:85], v[44:45], s[20:21] op_sel_hi:[1,0]
	v_pk_mul_f32 v[86:87], v[42:43], s[20:21] op_sel_hi:[1,0]
	v_cvt_pk_bf16_f32 v80, v80, v81
	v_cvt_pk_bf16_f32 v81, v82, v83
	v_cvt_pk_bf16_f32 v82, v86, v87
	v_cvt_pk_bf16_f32 v83, v84, v85
	global_store_dwordx4 v[70:71], v[80:83], off sc1

; __device__ __forceinline__ unsigned short f2bf(float f) { return (unsigned short)(cvt_pk_bf16(f, f) & 0xffffu); }
; __device__ __forceinline__ void store4bf(bf16_t* p, f32x4 v) { u32x2 w; w.x = cvt_pk_bf16(v[0], v[1]); w.y = cvt_pk_bf16(v[2], v[3]); *(u32x2*)p = w; }
;   __device__ __forceinline__ void group(int row, int c32, int fq, f32x4 v0, f32x4 v1) const {
;     int b, e; const bool ok = row_be(row, b, e);
;     if (c32 < 512) {
;       if (c32 < 384) store8bf(cqkv + (size_t)row * 512 + c32 + fq * 8, v0, v1);
;       else { bf16_t* p = cqkv + (size_t)row * 512 + c32 + fq * 4; store4bf(p, v0); store4bf(p + 16, v1); }
;       if (c32 == 384 && ok) {
;         const float2* rp = rope + pos_of_e(e) * 16 + fq * 4; f32x4 o0, o1;
; #pragma unroll
;         for (int j = 0; j < 4; ++j) { const float2 cs = rp[j]; o0[j] = v0[j] * cs.x - v1[j] * cs.y; o1[j] = v1[j] * cs.x + v0[j] * cs.y; }
; #pragma unroll
;         for (int h = 0; h < 6; ++h) { bf16_t* q = ka + ((size_t)(b * 6 + h) * E + e) * 96 + 64 + fq * 4; store4bf(q, o0); store4bf(q + 16, o1); }
;       }
;       return;
;     }
;     if (!ok) return;
;     if (c32 < 768) { const int cc = c32 - 512, h = cc >> 6; store8bf(qd + ((size_t)(b * 4 + h) * E + e) * 64 + (cc & 63) + fq * 8, v0 * QSC_D, v1 * QSC_D); }
;     else if (c32 < 1024) { const int cc = c32 - 768, h = cc >> 6; store8bf(kd + ((size_t)(b * 4 + h) * E + e) * 64 + (cc & 63) + fq * 8, v0, v1); }
;     else if (c32 < 1280) { const int cc = c32 - 1024, h = cc >> 6; bf16_t* p = vtd + ((size_t)(b * 4 + h) * 64 + (cc & 63) + fq * 4) * E + e;
; #pragma unroll
;       for (int j = 0; j < 4; ++j) { p[(size_t)j * E] = f2bf(v0[j]); p[(size_t)(j + 16) * E] = f2bf(v1[j]); } }
;     else if (c32 < 1664) { const int cc = c32 - 1280, h = cc >> 6; store8bf(qs + ((size_t)(b * 6 + h) * E + e) * 64 + (cc & 63) + fq * 8, v0 * QSC_S, v1 * QSC_S); }
;     else if (c32 < 1792) { const int cc = c32 - 1664, g = cc >> 6; store8bf(ks + ((size_t)(b * 2 + g) * E + e) * 64 + (cc & 63) + fq * 8, v0, v1); }
;     else if (c32 < 1920) { const int cc = c32 - 1792, g = cc >> 6; bf16_t* p = vts + ((size_t)(b * 2 + g) * 64 + (cc & 63) + fq * 4) * E + e;
; #pragma unroll
;       for (int j = 0; j < 4; ++j) { p[(size_t)j * E] = f2bf(v0[j]); p[(size_t)(j + 16) * E] = f2bf(v1[j]); } }
.LBB0_602:
	s_mov_b32 s1, 0x8000
	v_cmp_gt_i32_e32 vcc, s1, v68
	v_cmp_gt_u32_e64 s[8:9], s49, v73
	s_or_b64 s[18:19], vcc, s[8:9]
	s_and_saveexec_b64 s[8:9], s[18:19]
	s_cbranch_execz .LBB0_619
	v_and_b32_e32 v67, 0x1fff, v68
	v_add_u32_e32 v69, 64, v67
	v_cndmask_b32_e32 v67, 3, v72, vcc
	v_cndmask_b32_e32 v70, v136, v69, vcc
	s_andn2_b64 vcc, exec, s[16:17]
	s_mov_b64 s[16:17], -1
	s_cbranch_vccnz .LBB0_617
	s_andn2_b64 vcc, exec, s[14:15]
	s_mov_b64 s[14:15], -1
	s_cbranch_vccnz .LBB0_614
	s_andn2_b64 vcc, exec, s[12:13]
	s_mov_b64 s[12:13], -1
	s_cbranch_vccnz .LBB0_611
	s_andn2_b64 vcc, exec, s[10:11]
	s_mov_b64 s[10:11], -1
	s_cbranch_vccnz .LBB0_608
	v_lshl_add_u32 v78, v67, 1, v78
	v_ashrrev_i32_e32 v79, 31, v78
	v_readlane_b32 s10, v254, 16
	v_lshlrev_b64 v[78:79], 6, v[78:79]
	v_readlane_b32 s11, v254, 17
	v_or_b32_e32 v69, v78, v140
	v_lshlrev_b32_e32 v78, 1, v70
	v_mov_b64_e32 v[80:81], s[10:11]
	v_mad_u64_u32 v[80:81], s[10:11], v69, s95, v[80:81]
	v_mad_i32_i24 v81, v79, s95, v81
	v_mov_b32_e32 v79, v1
	v_lshl_add_u64 v[78:79], v[80:81], 0, v[78:79]
	s_mov_b32 s1, 0x40000
	v_cvt_pk_bf16_f32 v69, v38, s0
	v_add_co_u32_e32 v80, vcc, s1, v78
	global_store_short v[78:79], v69, off sc1
	v_cvt_pk_bf16_f32 v69, v34, s0
	v_addc_co_u32_e32 v81, vcc, 0, v79, vcc
	s_movk_i32 s1, 0x4000
	global_store_short v[80:81], v69, off offset:2048 sc1
	v_add_co_u32_e32 v80, vcc, s1, v78
	v_cvt_pk_bf16_f32 v69, v39, s0
	s_nop 0
	v_addc_co_u32_e32 v81, vcc, 0, v79, vcc
	s_mov_b32 s1, 0x44000
	global_store_short v[80:81], v69, off offset:128 sc1
	v_add_co_u32_e32 v80, vcc, s1, v78
	v_cvt_pk_bf16_f32 v69, v35, s0
	s_nop 0
	v_addc_co_u32_e32 v81, vcc, 0, v79, vcc
	s_mov_b32 s1, 0x8000
	global_store_short v[80:81], v69, off offset:2176 sc1
	v_add_co_u32_e32 v80, vcc, s1, v78
	v_cvt_pk_bf16_f32 v69, v40, s0
	s_nop 0
	v_addc_co_u32_e32 v81, vcc, 0, v79, vcc
	s_mov_b32 s1, 0x48000
	global_store_short v[80:81], v69, off offset:256 sc1
	v_add_co_u32_e32 v80, vcc, s1, v78
	v_cvt_pk_bf16_f32 v69, v36, s0
	s_nop 0
	v_addc_co_u32_e32 v81, vcc, 0, v79, vcc
	global_store_short v[80:81], v69, off offset:2304 sc1
	v_add_co_u32_e32 v80, vcc, 0xc000, v78
	v_cvt_pk_bf16_f32 v69, v41, s0
	s_nop 0
	v_addc_co_u32_e32 v81, vcc, 0, v79, vcc
	v_add_co_u32_e32 v78, vcc, 0x4c000, v78
	global_store_short v[80:81], v69, off offset:384 sc1
	v_cvt_pk_bf16_f32 v69, v37, s0
	v_addc_co_u32_e32 v79, vcc, 0, v79, vcc
	s_mov_b64 s[10:11], 0
	global_store_short v[78:79], v69, off offset:2432 sc1
.LBB0_608:
	s_andn2_b64 vcc, exec, s[10:11]
	s_cbranch_vccnz .LBB0_610
	v_mad_i32_i24 v69, v67, 6, v77
	v_mov_b32_e32 v71, v1
	s_movk_i32 s1, 0x2040
	v_mad_i64_i32 v[78:79], s[10:11], v69, s1, v[70:71]
	v_readlane_b32 s10, v254, 12
	v_lshlrev_b64 v[78:79], 7, v[78:79]
	v_readlane_b32 s11, v254, 13
	v_lshlrev_b32_e32 v80, 1, v137
	v_mov_b32_e32 v81, v1
	v_lshl_add_u64 v[78:79], s[10:11], 0, v[78:79]
	v_lshl_add_u64 v[78:79], v[78:79], 0, v[80:81]
	v_lshlrev_b32_e32 v80, 1, v139
	s_mov_b32 s10, 0x3e38aa3b
	v_lshl_add_u64 v[82:83], v[78:79], 0, v[80:81]
	v_pk_mul_f32 v[80:81], v[40:41], s[10:11] op_sel_hi:[1,0]
	v_pk_mul_f32 v[78:79], v[38:39], s[10:11] op_sel_hi:[1,0]
	v_pk_mul_f32 v[84:85], v[36:37], s[10:11] op_sel_hi:[1,0]
	v_pk_mul_f32 v[86:87], v[34:35], s[10:11] op_sel_hi:[1,0]
	v_cvt_pk_bf16_f32 v78, v78, v79
	v_cvt_pk_bf16_f32 v79, v80, v81
	v_cvt_pk_bf16_f32 v80, v86, v87
	v_cvt_pk_bf16_f32 v81, v84, v85
	global_store_dwordx4 v[82:83], v[78:81], off sc1

; __device__ __forceinline__ unsigned short f2bf(float f) { return (unsigned short)(cvt_pk_bf16(f, f) & 0xffffu); }
;   __device__ __forceinline__ void group(int row, int c32, int fq, f32x4 v0, f32x4 v1) const {
;     ...
;     else if (c32 < 1280) { const int cc = c32 - 1024, h = cc >> 6; bf16_t* p = vtd + ((size_t)(b * 4 + h) * 64 + (cc & 63) + fq * 4) * E + e;
; #pragma unroll
;       for (int j = 0; j < 4; ++j) { p[(size_t)j * E] = f2bf(v0[j]); p[(size_t)(j + 16) * E] = f2bf(v1[j]); } }
.LBB0_611:
	s_andn2_b64 vcc, exec, s[12:13]
	s_cbranch_vccnz .LBB0_613
	v_lshl_add_u32 v76, v67, 2, v76
	v_ashrrev_i32_e32 v77, 31, v76
	v_readlane_b32 s10, v254, 10
	v_lshlrev_b64 v[76:77], 6, v[76:77]
	v_readlane_b32 s11, v254, 11
	v_or_b32_e32 v69, v76, v140
	v_lshlrev_b32_e32 v76, 1, v70
	v_mov_b64_e32 v[78:79], s[10:11]
	v_mad_u64_u32 v[78:79], s[10:11], v69, s95, v[78:79]
	v_mad_i32_i24 v79, v77, s95, v79
	v_mov_b32_e32 v77, v1
	v_lshl_add_u64 v[76:77], v[78:79], 0, v[76:77]
	s_mov_b32 s1, 0x40000
	v_cvt_pk_bf16_f32 v69, v38, s0
	v_add_co_u32_e32 v78, vcc, s1, v76
	global_store_short v[76:77], v69, off sc1
	v_cvt_pk_bf16_f32 v69, v34, s0
	v_addc_co_u32_e32 v79, vcc, 0, v77, vcc
	s_movk_i32 s1, 0x4000
	global_store_short v[78:79], v69, off offset:2048 sc1
	v_add_co_u32_e32 v78, vcc, s1, v76
	v_cvt_pk_bf16_f32 v69, v39, s0
	s_nop 0
	v_addc_co_u32_e32 v79, vcc, 0, v77, vcc
	s_mov_b32 s1, 0x44000
	global_store_short v[78:79], v69, off offset:128 sc1
	v_add_co_u32_e32 v78, vcc, s1, v76
	v_cvt_pk_bf16_f32 v69, v35, s0
	s_nop 0
	v_addc_co_u32_e32 v79, vcc, 0, v77, vcc
	s_mov_b32 s1, 0x8000
	global_store_short v[78:79], v69, off offset:2176 sc1
	v_add_co_u32_e32 v78, vcc, s1, v76
	v_cvt_pk_bf16_f32 v69, v40, s0
	s_nop 0
	v_addc_co_u32_e32 v79, vcc, 0, v77, vcc
	s_mov_b32 s1, 0x48000
	global_store_short v[78:79], v69, off offset:256 sc1
	v_add_co_u32_e32 v78, vcc, s1, v76
	v_cvt_pk_bf16_f32 v69, v36, s0
	s_nop 0
	v_addc_co_u32_e32 v79, vcc, 0, v77, vcc
	global_store_short v[78:79], v69, off offset:2304 sc1
	v_add_co_u32_e32 v78, vcc, 0xc000, v76
	v_cvt_pk_bf16_f32 v69, v41, s0
	s_nop 0
	v_addc_co_u32_e32 v79, vcc, 0, v77, vcc
	v_add_co_u32_e32 v76, vcc, 0x4c000, v76
	global_store_short v[78:79], v69, off offset:384 sc1
	v_cvt_pk_bf16_f32 v69, v37, s0
	v_addc_co_u32_e32 v77, vcc, 0, v77, vcc
	global_store_short v[76:77], v69, off offset:2432 sc1

; __device__ __forceinline__ void store8bf(bf16_t* p, f32x4 v0, f32x4 v1) { u32x4 w; w.x = cvt_pk_bf16(v0[0], v0[1]); w.y = cvt_pk_bf16(v0[2], v0[3]); w.z = cvt_pk_bf16(v1[0], v1[1]); w.w = cvt_pk_bf16(v1[2], v1[3]); *(u32x4*)p = w; }
;   __device__ __forceinline__ void group(int row, int c32, int fq, f32x4 v0, f32x4 v1) const {
;     ...
;     else if (c32 < 1024) { const int cc = c32 - 768, h = cc >> 6; store8bf(kd + ((size_t)(b * 4 + h) * E + e) * 64 + (cc & 63) + fq * 8, v0, v1); }
.LBB0_614:
	s_andn2_b64 vcc, exec, s[14:15]
	s_cbranch_vccnz .LBB0_616
	v_lshl_add_u32 v69, v67, 2, v75
	v_mov_b32_e32 v71, v1
	s_movk_i32 s1, 0x2040
	v_mad_i64_i32 v[76:77], s[10:11], v69, s1, v[70:71]
	v_readlane_b32 s10, v254, 8
	v_lshlrev_b64 v[76:77], 7, v[76:77]
	v_readlane_b32 s11, v254, 9
	v_lshlrev_b32_e32 v78, 1, v137
	v_mov_b32_e32 v79, v1
	v_lshl_add_u64 v[76:77], s[10:11], 0, v[76:77]
	v_lshl_add_u64 v[76:77], v[76:77], 0, v[78:79]
	v_lshlrev_b32_e32 v78, 1, v139
	v_lshl_add_u64 v[80:81], v[76:77], 0, v[78:79]
	v_cvt_pk_bf16_f32 v76, v38, v39
	v_cvt_pk_bf16_f32 v77, v40, v41
	v_cvt_pk_bf16_f32 v78, v34, v35
	v_cvt_pk_bf16_f32 v79, v36, v37
	global_store_dwordx4 v[80:81], v[76:79], off sc1

; __device__ __forceinline__ void store8bf(bf16_t* p, f32x4 v0, f32x4 v1) { u32x4 w; w.x = cvt_pk_bf16(v0[0], v0[1]); w.y = cvt_pk_bf16(v0[2], v0[3]); w.z = cvt_pk_bf16(v1[0], v1[1]); w.w = cvt_pk_bf16(v1[2], v1[3]); *(u32x4*)p = w; }
;   __device__ __forceinline__ void group(int row, int c32, int fq, f32x4 v0, f32x4 v1) const {
;     ...
;     if (c32 < 768) { const int cc = c32 - 512, h = cc >> 6; store8bf(qd + ((size_t)(b * 4 + h) * E + e) * 64 + (cc & 63) + fq * 8, v0 * QSC_D, v1 * QSC_D); }
.LBB0_617:
	s_andn2_b64 vcc, exec, s[16:17]
	s_cbranch_vccnz .LBB0_619
	v_lshl_add_u32 v67, v67, 2, v74
	v_mov_b32_e32 v71, v1
	s_movk_i32 s1, 0x2040
	v_mad_i64_i32 v[70:71], s[10:11], v67, s1, v[70:71]
	v_readlane_b32 s10, v254, 6
	v_lshlrev_b64 v[70:71], 7, v[70:71]
	v_readlane_b32 s11, v254, 7
	v_lshlrev_b32_e32 v74, 1, v137
	v_mov_b32_e32 v75, v1
	v_lshl_add_u64 v[70:71], s[10:11], 0, v[70:71]
	v_lshl_add_u64 v[70:71], v[70:71], 0, v[74:75]
	v_lshlrev_b32_e32 v74, 1, v139
	s_mov_b32 s10, 0x3e8293ee
	v_lshl_add_u64 v[70:71], v[70:71], 0, v[74:75]
	v_pk_mul_f32 v[76:77], v[40:41], s[10:11] op_sel_hi:[1,0]
	v_pk_mul_f32 v[74:75], v[38:39], s[10:11] op_sel_hi:[1,0]
	v_pk_mul_f32 v[78:79], v[36:37], s[10:11] op_sel_hi:[1,0]
	v_pk_mul_f32 v[80:81], v[34:35], s[10:11] op_sel_hi:[1,0]
	v_cvt_pk_bf16_f32 v74, v74, v75
	v_cvt_pk_bf16_f32 v75, v76, v77
	v_cvt_pk_bf16_f32 v76, v80, v81
	v_cvt_pk_bf16_f32 v77, v78, v79
	global_store_dwordx4 v[70:71], v[74:77], off sc1

; __device__ __forceinline__ void store8bf(bf16_t* p, f32x4 v0, f32x4 v1) { u32x4 w; w.x = cvt_pk_bf16(v0[0], v0[1]); w.y = cvt_pk_bf16(v0[2], v0[3]); w.z = cvt_pk_bf16(v1[0], v1[1]); w.w = cvt_pk_bf16(v1[2], v1[3]); *(u32x4*)p = w; }
;   __device__ __forceinline__ void group(int row, int c32, int fq, f32x4 v0, f32x4 v1) const {
;     ...
;       if (c32 < 384) store8bf(cqkv + (size_t)row * 512 + c32 + fq * 8, v0, v1);
.LBB0_624:
	v_ashrrev_i32_e32 v69, 31, v68
	v_readlane_b32 s18, v254, 0
	v_lshlrev_b64 v[68:69], 10, v[68:69]
	v_readlane_b32 s19, v254, 1
	v_lshlrev_b32_e32 v80, 1, v139
	v_mov_b32_e32 v81, v1
	v_lshl_add_u64 v[70:71], s[18:19], 0, v[68:69]
	v_lshl_add_u64 v[70:71], v[0:1], 1, v[70:71]
	v_cvt_pk_bf16_f32 v68, v46, v47
	v_cvt_pk_bf16_f32 v69, v48, v49
	v_lshl_add_u64 v[80:81], v[70:71], 0, v[80:81]
	v_cvt_pk_bf16_f32 v70, v42, v43
	v_cvt_pk_bf16_f32 v71, v44, v45
	global_store_dwordx4 v[80:81], v[68:71], off sc1
	s_nop 1
	v_or_b32_e32 v68, 48, v66
	s_and_b64 vcc, exec, s[8:9]
	s_mov_b64 s[8:9], -1
	s_cbranch_vccz .LBB0_602

; __device__ __forceinline__ void store8bf(bf16_t* p, f32x4 v0, f32x4 v1) { u32x4 w; w.x = cvt_pk_bf16(v0[0], v0[1]); w.y = cvt_pk_bf16(v0[2], v0[3]); w.z = cvt_pk_bf16(v1[0], v1[1]); w.w = cvt_pk_bf16(v1[2], v1[3]); *(u32x4*)p = w; }
;   __device__ __forceinline__ void group(int row, int c32, int fq, f32x4 v0, f32x4 v1) const {
;     ...
;       if (c32 < 384) store8bf(cqkv + (size_t)row * 512 + c32 + fq * 8, v0, v1);
.LBB0_626:
	v_ashrrev_i32_e32 v69, 31, v68
	v_readlane_b32 s8, v254, 0
	v_lshlrev_b64 v[68:69], 10, v[68:69]
	v_readlane_b32 s9, v254, 1
	v_lshlrev_b32_e32 v74, 1, v139
	v_mov_b32_e32 v75, v1
	v_lshl_add_u64 v[70:71], s[8:9], 0, v[68:69]
	v_lshl_add_u64 v[70:71], v[0:1], 1, v[70:71]
	v_cvt_pk_bf16_f32 v68, v38, v39
	v_cvt_pk_bf16_f32 v69, v40, v41
	v_lshl_add_u64 v[74:75], v[70:71], 0, v[74:75]
	v_cvt_pk_bf16_f32 v70, v34, v35
	v_cvt_pk_bf16_f32 v71, v36, v37
	global_store_dwordx4 v[74:75], v[68:71], off sc1

; #define LAS __attribute__((address_space(3)))
; __device__ __forceinline__ unsigned short f2bf(float f) { return (unsigned short)(cvt_pk_bf16(f, f) & 0xffffu); }
;   __device__ __forceinline__ bool vt_info(int c32, int b, bf16_t*& base) const { return e->vt_info(c32 + sh, b, base); }
;     ...
;         const int c32 = bcol + wc * 32 + bj * HALF, row0 = brow + ai * HALF + wr * 64;
;         int b0, e0; row_be(row0, b0, e0); bf16_t* vbase;
;         if (epi.vt_info(c32, b0, vbase)) {
; #pragma unroll
;           for (int m = 0; m < 4; ++m) { const float sc = epi.row_scale(row0 + m * 16 + fr);
; #pragma unroll
;             for (int n = 0; n < 2; ++n)
; #pragma unroll
;               for (int j = 0; j < 4; ++j) *(LAS bf16_t*)(T + (n * 16 + fq * 4 + j) * 144 + (m * 16 + fr) * 2) = f2bf(acc[ai][bj][m][n][j] * sc); }
;           asm volatile("s_waitcnt lgkmcnt(0)" ::: "memory");
; #pragma unroll
;           for (int q = 0; q < 4; ++q) { const int ch = lane + 64 * q, d = ch >> 3, ec = ch & 7;
;             *(u32x4*)(vbase + (size_t)d * E + e0 + ec * 8) = *(LAS const u32x4*)(T + d * 144 + ec * 16); }
;           asm volatile("s_waitcnt lgkmcnt(0)" ::: "memory");
.LBB0_629:
	v_and_b32_e32 v67, 0x1fc0, v73
	v_add_u32_e32 v67, 64, v67
	v_cndmask_b32_e64 v67, 0, v67, s[6:7]
	v_cndmask_b32_e64 v70, 0, v72, s[6:7]
	s_and_b64 vcc, exec, s[20:21]
	v_lshlrev_b32_e32 v68, 1, v67
	s_cbranch_vccz .LBB0_633
	v_add_u32_e32 v67, s10, v0
	v_readlane_b32 s12, v253, 16
	v_lshrrev_b32_e32 v67, 6, v67
	v_readlane_b32 s18, v253, 22
	v_lshl_add_u32 v74, v70, s1, v67
	v_readlane_b32 s19, v253, 23
	s_add_u32 s6, s18, s8
	v_ashrrev_i32_e32 v75, 31, v74
	v_cvt_pk_bf16_f32 v62, v62, s0
	v_cvt_pk_bf16_f32 v58, v58, s0
	v_cvt_pk_bf16_f32 v54, v54, s0
	v_cvt_pk_bf16_f32 v50, v50, s0
	v_cvt_pk_bf16_f32 v46, v46, s0
	v_cvt_pk_bf16_f32 v42, v42, s0
	v_cvt_pk_bf16_f32 v38, v38, s0
	v_cvt_pk_bf16_f32 v34, v34, s0
	s_addc_u32 s7, s19, s9
	v_lshlrev_b64 v[74:75], 6, v[74:75]
	ds_write_b16 v143, v62
	v_cvt_pk_bf16_f32 v62, v63, s0
	ds_write_b16 v143, v58 offset:2304
	v_cvt_pk_bf16_f32 v58, v59, s0
	ds_write_b16 v143, v54 offset:32
	v_cvt_pk_bf16_f32 v54, v55, s0
	ds_write_b16 v143, v50 offset:2336
	v_cvt_pk_bf16_f32 v50, v51, s0
	ds_write_b16 v143, v46 offset:64
	v_cvt_pk_bf16_f32 v46, v47, s0
	ds_write_b16 v143, v42 offset:2368
	v_cvt_pk_bf16_f32 v42, v43, s0
	ds_write_b16 v143, v38 offset:96
	v_cvt_pk_bf16_f32 v38, v39, s0
	ds_write_b16 v143, v34 offset:2400
	v_cvt_pk_bf16_f32 v34, v35, s0
	v_or_b32_e32 v67, v74, v137
	v_mov_b64_e32 v[76:77], s[6:7]
	ds_write_b16 v143, v62 offset:144
	v_cvt_pk_bf16_f32 v62, v64, s0
	ds_write_b16 v143, v58 offset:2448
	v_cvt_pk_bf16_f32 v58, v60, s0
	ds_write_b16 v143, v54 offset:176
	v_cvt_pk_bf16_f32 v54, v56, s0
	ds_write_b16 v143, v50 offset:2480
	v_cvt_pk_bf16_f32 v50, v52, s0
	ds_write_b16 v143, v46 offset:208
	v_cvt_pk_bf16_f32 v46, v48, s0
	ds_write_b16 v143, v42 offset:2512
	v_cvt_pk_bf16_f32 v42, v44, s0
	ds_write_b16 v143, v38 offset:240
	v_cvt_pk_bf16_f32 v38, v40, s0
	ds_write_b16 v143, v34 offset:2544
	v_cvt_pk_bf16_f32 v34, v36, s0
	v_mad_u64_u32 v[76:77], s[6:7], v67, s95, v[76:77]
	ds_write_b16 v143, v62 offset:288
	v_cvt_pk_bf16_f32 v62, v65, s0
	ds_write_b16 v143, v58 offset:2592
	v_cvt_pk_bf16_f32 v58, v61, s0
	ds_write_b16 v143, v54 offset:320
	v_cvt_pk_bf16_f32 v54, v57, s0
	ds_write_b16 v143, v50 offset:2624
	v_cvt_pk_bf16_f32 v50, v53, s0
	ds_write_b16 v143, v46 offset:352
	v_cvt_pk_bf16_f32 v46, v49, s0
	ds_write_b16 v143, v42 offset:2656
	v_cvt_pk_bf16_f32 v42, v45, s0
	ds_write_b16 v143, v38 offset:384
	v_cvt_pk_bf16_f32 v38, v41, s0
	ds_write_b16 v143, v34 offset:2688
	v_cvt_pk_bf16_f32 v34, v37, s0
	v_mad_i32_i24 v77, v75, s95, v77
	ds_write_b16 v143, v62 offset:432
	ds_write_b16 v143, v58 offset:2736
	ds_write_b16 v143, v54 offset:464
	ds_write_b16 v143, v50 offset:2768
	ds_write_b16 v143, v46 offset:496
	ds_write_b16 v143, v42 offset:2800
	ds_write_b16 v143, v38 offset:528
	ds_write_b16 v143, v34 offset:2832
	v_mov_b32_e32 v69, v1
	s_waitcnt lgkmcnt(0)
	v_lshl_add_u64 v[34:35], v[76:77], 0, v[68:69]
	v_mov_b32_e32 v131, v1
	v_lshl_add_u64 v[38:39], v[34:35], 0, v[130:131]
	ds_read_b128 v[34:37], v141
	v_lshlrev_b32_e32 v40, 1, v142
	v_mov_b32_e32 v41, v1
	v_lshl_add_u64 v[42:43], v[38:39], 0, v[40:41]
	ds_read_b128 v[38:41], v141 offset:1152
	s_waitcnt lgkmcnt(0)
	global_store_dwordx4 v[42:43], v[34:37], off sc1
	v_readlane_b32 s13, v253, 17
	v_readlane_b32 s14, v253, 18
	v_add_co_u32_e32 v34, vcc, 0x20000, v42
	v_readlane_b32 s15, v253, 19
	s_nop 0
	v_addc_co_u32_e32 v35, vcc, 0, v43, vcc
	global_store_dwordx4 v[34:35], v[38:41], off offset:1024 sc1
	ds_read_b128 v[34:37], v141 offset:2304
	ds_read_b128 v[38:41], v141 offset:3456
	v_add_co_u32_e32 v44, vcc, 0x40000, v42
	v_readlane_b32 s16, v253, 20
	s_nop 0
	v_addc_co_u32_e32 v45, vcc, 0, v43, vcc
	s_waitcnt lgkmcnt(0)
	global_store_dwordx4 v[44:45], v[34:37], off offset:2048 sc1
	v_readlane_b32 s17, v253, 21
	s_nop 0
	v_add_co_u32_e32 v34, vcc, 0x60000, v42
	s_nop 1
	v_addc_co_u32_e32 v35, vcc, 0, v43, vcc
	global_store_dwordx4 v[34:35], v[38:41], off offset:3072 sc1
	s_waitcnt lgkmcnt(0)
	s_and_b64 vcc, exec, s[4:5]
	s_mov_b64 s[4:5], -1
	s_cbranch_vccz .LBB0_634
; #define LAS __attribute__((address_space(3)))
; __device__ __forceinline__ unsigned short f2bf(float f) { return (unsigned short)(cvt_pk_bf16(f, f) & 0xffffu); }
;     ...
;           for (int m = 0; m < 4; ++m) { const float sc = epi.row_scale(row0 + m * 16 + fr);
; #pragma unroll
;             for (int n = 0; n < 2; ++n)
; #pragma unroll
;               for (int j = 0; j < 4; ++j) *(LAS bf16_t*)(T + (n * 16 + fq * 4 + j) * 144 + (m * 16 + fr) * 2) = f2bf(acc[ai][bj][m][n][j] * sc); }
;           asm volatile("s_waitcnt lgkmcnt(0)" ::: "memory");
; #pragma unroll
;           for (int q = 0; q < 4; ++q) { const int ch = lane + 64 * q, d = ch >> 3, ec = ch & 7;
;             *(u32x4*)(vbase + (size_t)d * E + e0 + ec * 8) = *(LAS const u32x4*)(T + d * 144 + ec * 16); }
;           asm volatile("s_waitcnt lgkmcnt(0)" ::: "memory");
.LBB0_631:
	s_and_b64 vcc, exec, s[4:5]
	s_cbranch_vccz .LBB0_759
	v_readlane_b32 s0, v254, 10
	v_lshl_or_b32 v0, v70, 2, v106
	v_readlane_b32 s1, v254, 11
	v_ashrrev_i32_e32 v36, 31, v0
	v_lshl_or_b32 v0, v0, 6, v137
	v_mov_b64_e32 v[34:35], s[0:1]
	v_mad_u64_u32 v[34:35], s[0:1], v0, s95, v[34:35]
	v_mad_i32_i24 v35, v36, s95, v35
	s_nop 0
	v_cvt_pk_bf16_f32 v0, v30, s0
	ds_write_b16 v143, v0
	v_cvt_pk_bf16_f32 v0, v31, s0
	ds_write_b16 v143, v0 offset:144
	v_cvt_pk_bf16_f32 v0, v32, s0
	ds_write_b16 v143, v0 offset:288
	v_cvt_pk_bf16_f32 v0, v33, s0
	ds_write_b16 v143, v0 offset:432
	v_cvt_pk_bf16_f32 v0, v26, s0
	ds_write_b16 v143, v0 offset:2304
	v_cvt_pk_bf16_f32 v0, v27, s0
	ds_write_b16 v143, v0 offset:2448
	v_cvt_pk_bf16_f32 v0, v28, s0
	ds_write_b16 v143, v0 offset:2592
	v_cvt_pk_bf16_f32 v0, v29, s0
	ds_write_b16 v143, v0 offset:2736
	v_cvt_pk_bf16_f32 v0, v22, s0
	ds_write_b16 v143, v0 offset:32
	v_cvt_pk_bf16_f32 v0, v23, s0
	ds_write_b16 v143, v0 offset:176
	v_cvt_pk_bf16_f32 v0, v24, s0
	ds_write_b16 v143, v0 offset:320
	v_cvt_pk_bf16_f32 v0, v25, s0
	ds_write_b16 v143, v0 offset:464
	v_cvt_pk_bf16_f32 v0, v18, s0
	ds_write_b16 v143, v0 offset:2336
	v_cvt_pk_bf16_f32 v0, v19, s0
	ds_write_b16 v143, v0 offset:2480
	v_cvt_pk_bf16_f32 v0, v20, s0
	ds_write_b16 v143, v0 offset:2624
	v_cvt_pk_bf16_f32 v0, v21, s0
	ds_write_b16 v143, v0 offset:2768
	v_cvt_pk_bf16_f32 v0, v14, s0
	ds_write_b16 v143, v0 offset:64
	v_cvt_pk_bf16_f32 v0, v15, s0
	ds_write_b16 v143, v0 offset:208
	v_cvt_pk_bf16_f32 v0, v16, s0
	ds_write_b16 v143, v0 offset:352
	v_cvt_pk_bf16_f32 v0, v17, s0
	ds_write_b16 v143, v0 offset:496
	v_cvt_pk_bf16_f32 v0, v10, s0
	ds_write_b16 v143, v0 offset:2368
	v_cvt_pk_bf16_f32 v0, v11, s0
	ds_write_b16 v143, v0 offset:2512
	v_cvt_pk_bf16_f32 v0, v12, s0
	ds_write_b16 v143, v0 offset:2656
	v_cvt_pk_bf16_f32 v0, v13, s0
	ds_write_b16 v143, v0 offset:2800
	v_cvt_pk_bf16_f32 v0, v6, s0
	ds_write_b16 v143, v0 offset:96
	v_cvt_pk_bf16_f32 v0, v7, s0
	ds_write_b16 v143, v0 offset:240
	v_cvt_pk_bf16_f32 v0, v8, s0
	ds_write_b16 v143, v0 offset:384
	v_cvt_pk_bf16_f32 v0, v9, s0
	ds_write_b16 v143, v0 offset:528
	v_cvt_pk_bf16_f32 v0, v2, s0
	ds_write_b16 v143, v0 offset:2400
	v_cvt_pk_bf16_f32 v0, v3, s0
	ds_write_b16 v143, v0 offset:2544
	v_cvt_pk_bf16_f32 v0, v4, s0
	ds_write_b16 v143, v0 offset:2688
	v_cvt_pk_bf16_f32 v0, v5, s0
	ds_write_b16 v143, v0 offset:2832
	s_waitcnt lgkmcnt(0)
	v_mov_b32_e32 v69, v1
	v_lshl_add_u64 v[6:7], v[34:35], 0, v[68:69]
	v_mov_b32_e32 v131, v1
	ds_read_b128 v[2:5], v141
	v_lshl_add_u64 v[6:7], v[6:7], 0, v[130:131]
	v_lshlrev_b32_e32 v0, 1, v142
	v_lshl_add_u64 v[10:11], v[6:7], 0, v[0:1]
	ds_read_b128 v[6:9], v141 offset:1152
	s_waitcnt lgkmcnt(0)
	global_store_dwordx4 v[10:11], v[2:5], off sc1
	s_nop 1
	v_add_co_u32_e32 v2, vcc, 0x20000, v10
	s_nop 1
	v_addc_co_u32_e32 v3, vcc, 0, v11, vcc
	global_store_dwordx4 v[2:3], v[6:9], off offset:1024 sc1
	ds_read_b128 v[2:5], v141 offset:2304
	ds_read_b128 v[6:9], v141 offset:3456
	v_add_co_u32_e32 v12, vcc, 0x40000, v10
	s_nop 1
	v_addc_co_u32_e32 v13, vcc, 0, v11, vcc
	s_waitcnt lgkmcnt(0)
	global_store_dwordx4 v[12:13], v[2:5], off offset:2048 sc1
	s_nop 1
	v_add_co_u32_e32 v2, vcc, 0x60000, v10
	s_nop 1
	v_addc_co_u32_e32 v3, vcc, 0, v11, vcc
	global_store_dwordx4 v[2:3], v[6:9], off offset:3072 sc1
	s_waitcnt lgkmcnt(0)
	v_cndmask_b32_e64 v0, 0, 1, s[2:3]
	v_cmp_ne_u32_e64 s[4:5], 1, v0
	s_andn2_b64 vcc, exec, s[2:3]
	s_cbranch_vccnz .LBB0_300
	s_branch .LBB0_760

; __device__ __forceinline__ unsigned short f2bf(float f) { return (unsigned short)(cvt_pk_bf16(f, f) & 0xffffu); }
; __device__ __forceinline__ void store4bf(bf16_t* p, f32x4 v) { u32x2 w; w.x = cvt_pk_bf16(v[0], v[1]); w.y = cvt_pk_bf16(v[2], v[3]); *(u32x2*)p = w; }
;   __device__ __forceinline__ void group(int row, int c32, int fq, f32x4 v0, f32x4 v1) const {
;     int b, e; const bool ok = row_be(row, b, e);
;     if (c32 < 512) {
;       if (c32 < 384) store8bf(cqkv + (size_t)row * 512 + c32 + fq * 8, v0, v1);
;       else { bf16_t* p = cqkv + (size_t)row * 512 + c32 + fq * 4; store4bf(p, v0); store4bf(p + 16, v1); }
;       if (c32 == 384 && ok) {
;         const float2* rp = rope + pos_of_e(e) * 16 + fq * 4; f32x4 o0, o1;
; #pragma unroll
;         for (int j = 0; j < 4; ++j) { const float2 cs = rp[j]; o0[j] = v0[j] * cs.x - v1[j] * cs.y; o1[j] = v1[j] * cs.x + v0[j] * cs.y; }
; #pragma unroll
;         for (int h = 0; h < 6; ++h) { bf16_t* q = ka + ((size_t)(b * 6 + h) * E + e) * 96 + 64 + fq * 4; store4bf(q, o0); store4bf(q + 16, o1); }
;       }
;       return;
;     }
;     if (!ok) return;
;     if (c32 < 768) { const int cc = c32 - 512, h = cc >> 6; store8bf(qd + ((size_t)(b * 4 + h) * E + e) * 64 + (cc & 63) + fq * 8, v0 * QSC_D, v1 * QSC_D); }
;     else if (c32 < 1024) { const int cc = c32 - 768, h = cc >> 6; store8bf(kd + ((size_t)(b * 4 + h) * E + e) * 64 + (cc & 63) + fq * 8, v0, v1); }
;     else if (c32 < 1280) { const int cc = c32 - 1024, h = cc >> 6; bf16_t* p = vtd + ((size_t)(b * 4 + h) * 64 + (cc & 63) + fq * 4) * E + e;
; #pragma unroll
;       for (int j = 0; j < 4; ++j) { p[(size_t)j * E] = f2bf(v0[j]); p[(size_t)(j + 16) * E] = f2bf(v1[j]); } }
;     else if (c32 < 1664) { const int cc = c32 - 1280, h = cc >> 6; store8bf(qs + ((size_t)(b * 6 + h) * E + e) * 64 + (cc & 63) + fq * 8, v0 * QSC_S, v1 * QSC_S); }
;     else if (c32 < 1792) { const int cc = c32 - 1664, g = cc >> 6; store8bf(ks + ((size_t)(b * 2 + g) * E + e) * 64 + (cc & 63) + fq * 8, v0, v1); }
;     else if (c32 < 1920) { const int cc = c32 - 1792, g = cc >> 6; bf16_t* p = vts + ((size_t)(b * 2 + g) * 64 + (cc & 63) + fq * 4) * E + e;
; #pragma unroll
;       for (int j = 0; j < 4; ++j) { p[(size_t)j * E] = f2bf(v0[j]); p[(size_t)(j + 16) * E] = f2bf(v1[j]); } }
.LBB0_634:
	s_cmp_gt_u32 s0, 1
	s_cselect_b64 s[40:41], -1, 0
	s_cmp_gt_u32 s0, 2
	s_cselect_b64 s[38:39], -1, 0
	s_cmp_gt_u32 s0, 3
	s_cselect_b64 s[24:25], -1, 0
	s_cmp_gt_u32 s0, 4
	s_cselect_b64 s[20:21], -1, 0
	s_cmp_gt_u32 s0, 6
	s_movk_i32 s1, 0x67f
	s_cselect_b64 s[18:19], -1, 0
	s_cmp_lg_u32 s0, 0
	v_and_b32_e32 v34, 0x1fcf, v66
	s_mov_b32 s0, 0x8000
	v_cmp_lt_u32_e64 s[8:9], s1, v112
	s_movk_i32 s1, 0x780
	v_add_u32_e32 v34, 64, v34
	v_cmp_gt_u32_e64 s[12:13], s49, v73
	v_cmp_gt_i32_e64 s[14:15], s0, v66
	v_cmp_gt_u32_e64 s[6:7], s1, v112
	s_cselect_b64 s[10:11], -1, 0
	v_cmp_eq_u32_e64 s[4:5], s93, v0
	v_cndmask_b32_e64 v42, 0, v72, s[14:15]
	v_cndmask_b32_e64 v38, v136, v34, s[14:15]
	s_or_b64 s[16:17], s[14:15], s[12:13]
	s_mov_b64 s[42:43], -1
	s_and_b64 vcc, exec, s[40:41]
	s_cbranch_vccz .LBB0_658
	s_and_saveexec_b64 s[44:45], s[16:17]
	s_cbranch_execz .LBB0_657
	s_andn2_b64 vcc, exec, s[38:39]
	s_cbranch_vccnz .LBB0_655
	s_andn2_b64 vcc, exec, s[24:25]
	s_cbranch_vccnz .LBB0_652
	s_andn2_b64 vcc, exec, s[20:21]
	s_cbranch_vccnz .LBB0_649
	s_and_saveexec_b64 s[0:1], s[8:9]
	s_xor_b64 s[68:69], exec, s[0:1]
	s_cbranch_execz .LBB0_646
	s_andn2_b64 vcc, exec, s[18:19]
	s_cbranch_vccnz .LBB0_644
	s_and_saveexec_b64 s[42:43], s[6:7]
	s_cbranch_execz .LBB0_643
	v_lshl_add_u32 v34, v42, 1, v110
	v_ashrrev_i32_e32 v35, 31, v34
	v_readlane_b32 s0, v254, 16
	v_lshlrev_b64 v[34:35], 6, v[34:35]
	v_readlane_b32 s1, v254, 17
	v_or_b32_e32 v34, v34, v140
	s_nop 0
	v_mov_b64_e32 v[36:37], s[0:1]
	v_mad_u64_u32 v[36:37], s[0:1], v34, s95, v[36:37]
	v_mad_i32_i24 v37, v35, s95, v37
	v_lshlrev_b32_e32 v34, 1, v38
	v_mov_b32_e32 v35, v1
	v_lshl_add_u64 v[34:35], v[36:37], 0, v[34:35]
	v_cvt_pk_bf16_f32 v36, v30, s0
	v_cvt_pk_bf16_f32 v39, v26, s0
	s_mov_b32 s0, 0x40000
	global_store_short v[34:35], v36, off sc1
	v_add_co_u32_e32 v36, vcc, s0, v34
	s_nop 1
	v_addc_co_u32_e32 v37, vcc, 0, v35, vcc
	global_store_short v[36:37], v39, off offset:2048 sc1
	v_cvt_pk_bf16_f32 v39, v31, s0
	s_movk_i32 s0, 0x4000
	v_add_co_u32_e32 v36, vcc, s0, v34
	s_nop 1
	v_addc_co_u32_e32 v37, vcc, 0, v35, vcc
	global_store_short v[36:37], v39, off offset:128 sc1
	v_cvt_pk_bf16_f32 v39, v27, s0
	s_mov_b32 s0, 0x44000
	v_add_co_u32_e32 v36, vcc, s0, v34
	s_nop 1
	v_addc_co_u32_e32 v37, vcc, 0, v35, vcc
	global_store_short v[36:37], v39, off offset:2176 sc1
	v_cvt_pk_bf16_f32 v39, v32, s0
	s_mov_b32 s0, 0x8000
	v_add_co_u32_e32 v36, vcc, s0, v34
	s_nop 1
	v_addc_co_u32_e32 v37, vcc, 0, v35, vcc
	global_store_short v[36:37], v39, off offset:256 sc1
	v_cvt_pk_bf16_f32 v39, v28, s0
	s_mov_b32 s0, 0x48000
	v_add_co_u32_e32 v36, vcc, s0, v34
	s_nop 1
	v_addc_co_u32_e32 v37, vcc, 0, v35, vcc
	global_store_short v[36:37], v39, off offset:2304 sc1
	v_add_co_u32_e32 v36, vcc, 0xc000, v34
	v_cvt_pk_bf16_f32 v39, v33, s0
	s_nop 0
	v_addc_co_u32_e32 v37, vcc, 0, v35, vcc
	v_add_co_u32_e32 v34, vcc, 0x4c000, v34
	global_store_short v[36:37], v39, off offset:384 sc1
	v_cvt_pk_bf16_f32 v36, v29, s0
	v_addc_co_u32_e32 v35, vcc, 0, v35, vcc
	global_store_short v[34:35], v36, off offset:2432 sc1

; __device__ __forceinline__ void store8bf(bf16_t* p, f32x4 v0, f32x4 v1) { u32x4 w; w.x = cvt_pk_bf16(v0[0], v0[1]); w.y = cvt_pk_bf16(v0[2], v0[3]); w.z = cvt_pk_bf16(v1[0], v1[1]); w.w = cvt_pk_bf16(v1[2], v1[3]); *(u32x4*)p = w; }
;   __device__ __forceinline__ void group(int row, int c32, int fq, f32x4 v0, f32x4 v1) const {
;     ...
;     else if (c32 < 1664) { const int cc = c32 - 1280, h = cc >> 6; store8bf(qs + ((size_t)(b * 6 + h) * E + e) * 64 + (cc & 63) + fq * 8, v0 * QSC_S, v1 * QSC_S); }
;     else if (c32 < 1792) { const int cc = c32 - 1664, g = cc >> 6; store8bf(ks + ((size_t)(b * 2 + g) * E + e) * 64 + (cc & 63) + fq * 8, v0, v1); }
.LBB0_644:
	s_andn2_b64 vcc, exec, s[42:43]
	s_cbranch_vccnz .LBB0_646
	v_lshl_add_u32 v34, v42, 1, v109
	v_mov_b32_e32 v39, v1
	s_movk_i32 s0, 0x2040
	v_mad_i64_i32 v[34:35], s[0:1], v34, s0, v[38:39]
	v_readlane_b32 s0, v254, 14
	v_lshlrev_b64 v[34:35], 7, v[34:35]
	v_readlane_b32 s1, v254, 15
	v_lshlrev_b32_e32 v36, 1, v137
	v_mov_b32_e32 v37, v1
	v_lshl_add_u64 v[34:35], s[0:1], 0, v[34:35]
	v_lshl_add_u64 v[34:35], v[34:35], 0, v[36:37]
	v_lshlrev_b32_e32 v36, 1, v139
	v_lshl_add_u64 v[40:41], v[34:35], 0, v[36:37]
	v_cvt_pk_bf16_f32 v34, v30, v31
	v_cvt_pk_bf16_f32 v35, v32, v33
	v_cvt_pk_bf16_f32 v36, v26, v27
	v_cvt_pk_bf16_f32 v37, v28, v29
	global_store_dwordx4 v[40:41], v[34:37], off sc1
.LBB0_646:
	s_andn2_saveexec_b64 s[42:43], s[68:69]
	s_cbranch_execz .LBB0_648
	v_mad_i32_i24 v34, v42, 6, v111
	v_mov_b32_e32 v39, v1
	s_movk_i32 s0, 0x2040
	v_mad_i64_i32 v[34:35], s[0:1], v34, s0, v[38:39]
	v_readlane_b32 s0, v254, 12
	v_lshlrev_b64 v[34:35], 7, v[34:35]
	v_readlane_b32 s1, v254, 13
	v_lshlrev_b32_e32 v36, 1, v137
	v_mov_b32_e32 v37, v1
	v_lshl_add_u64 v[34:35], s[0:1], 0, v[34:35]
	v_lshl_add_u64 v[34:35], v[34:35], 0, v[36:37]
	v_lshlrev_b32_e32 v36, 1, v139
	s_mov_b32 s0, 0x3e38aa3b
	v_lshl_add_u64 v[40:41], v[34:35], 0, v[36:37]
	v_pk_mul_f32 v[36:37], v[32:33], s[0:1] op_sel_hi:[1,0]
	v_pk_mul_f32 v[34:35], v[30:31], s[0:1] op_sel_hi:[1,0]
	v_pk_mul_f32 v[44:45], v[28:29], s[0:1] op_sel_hi:[1,0]
	v_pk_mul_f32 v[46:47], v[26:27], s[0:1] op_sel_hi:[1,0]
	v_cvt_pk_bf16_f32 v34, v34, v35
	v_cvt_pk_bf16_f32 v35, v36, v37
	v_cvt_pk_bf16_f32 v36, v46, v47
	v_cvt_pk_bf16_f32 v37, v44, v45
	global_store_dwordx4 v[40:41], v[34:37], off sc1

; __device__ __forceinline__ unsigned short f2bf(float f) { return (unsigned short)(cvt_pk_bf16(f, f) & 0xffffu); }
;   __device__ __forceinline__ void group(int row, int c32, int fq, f32x4 v0, f32x4 v1) const {
;     ...
;     else if (c32 < 1280) { const int cc = c32 - 1024, h = cc >> 6; bf16_t* p = vtd + ((size_t)(b * 4 + h) * 64 + (cc & 63) + fq * 4) * E + e;
; #pragma unroll
;       for (int j = 0; j < 4; ++j) { p[(size_t)j * E] = f2bf(v0[j]); p[(size_t)(j + 16) * E] = f2bf(v1[j]); } }
.LBB0_649:
	s_andn2_b64 vcc, exec, s[42:43]
	s_cbranch_vccnz .LBB0_651
	v_lshl_add_u32 v34, v42, 2, v106
	v_ashrrev_i32_e32 v35, 31, v34
	v_readlane_b32 s0, v254, 10
	v_lshlrev_b64 v[34:35], 6, v[34:35]
	v_readlane_b32 s1, v254, 11
	v_or_b32_e32 v34, v34, v140
	s_nop 0
	v_mov_b64_e32 v[36:37], s[0:1]
	v_mad_u64_u32 v[36:37], s[0:1], v34, s95, v[36:37]
	v_mad_i32_i24 v37, v35, s95, v37
	v_lshlrev_b32_e32 v34, 1, v38
	v_mov_b32_e32 v35, v1
	v_lshl_add_u64 v[34:35], v[36:37], 0, v[34:35]
	v_cvt_pk_bf16_f32 v36, v30, s0
	v_cvt_pk_bf16_f32 v39, v26, s0
	s_mov_b32 s0, 0x40000
	global_store_short v[34:35], v36, off sc1
	v_add_co_u32_e32 v36, vcc, s0, v34
	s_nop 1
	v_addc_co_u32_e32 v37, vcc, 0, v35, vcc
	global_store_short v[36:37], v39, off offset:2048 sc1
	v_cvt_pk_bf16_f32 v39, v31, s0
	s_movk_i32 s0, 0x4000
	v_add_co_u32_e32 v36, vcc, s0, v34
	s_nop 1
	v_addc_co_u32_e32 v37, vcc, 0, v35, vcc
	global_store_short v[36:37], v39, off offset:128 sc1
	v_cvt_pk_bf16_f32 v39, v27, s0
	s_mov_b32 s0, 0x44000
	v_add_co_u32_e32 v36, vcc, s0, v34
	s_nop 1
	v_addc_co_u32_e32 v37, vcc, 0, v35, vcc
	global_store_short v[36:37], v39, off offset:2176 sc1
	v_cvt_pk_bf16_f32 v39, v32, s0
	s_mov_b32 s0, 0x8000
	v_add_co_u32_e32 v36, vcc, s0, v34
	s_nop 1
	v_addc_co_u32_e32 v37, vcc, 0, v35, vcc
	global_store_short v[36:37], v39, off offset:256 sc1
	v_cvt_pk_bf16_f32 v39, v28, s0
	s_mov_b32 s0, 0x48000
	v_add_co_u32_e32 v36, vcc, s0, v34
	s_nop 1
	v_addc_co_u32_e32 v37, vcc, 0, v35, vcc
	global_store_short v[36:37], v39, off offset:2304 sc1
	v_add_co_u32_e32 v36, vcc, 0xc000, v34
	v_cvt_pk_bf16_f32 v39, v33, s0
	s_nop 0
	v_addc_co_u32_e32 v37, vcc, 0, v35, vcc
	v_add_co_u32_e32 v34, vcc, 0x4c000, v34
	global_store_short v[36:37], v39, off offset:384 sc1
	v_cvt_pk_bf16_f32 v36, v29, s0
	v_addc_co_u32_e32 v35, vcc, 0, v35, vcc
	global_store_short v[34:35], v36, off offset:2432 sc1

; __device__ __forceinline__ void store8bf(bf16_t* p, f32x4 v0, f32x4 v1) { u32x4 w; w.x = cvt_pk_bf16(v0[0], v0[1]); w.y = cvt_pk_bf16(v0[2], v0[3]); w.z = cvt_pk_bf16(v1[0], v1[1]); w.w = cvt_pk_bf16(v1[2], v1[3]); *(u32x4*)p = w; }
;   __device__ __forceinline__ void group(int row, int c32, int fq, f32x4 v0, f32x4 v1) const {
;     ...
;     else if (c32 < 1024) { const int cc = c32 - 768, h = cc >> 6; store8bf(kd + ((size_t)(b * 4 + h) * E + e) * 64 + (cc & 63) + fq * 8, v0, v1); }
.LBB0_652:
	s_andn2_b64 vcc, exec, s[42:43]
	s_cbranch_vccnz .LBB0_654
	v_lshl_add_u32 v34, v42, 2, v108
	v_mov_b32_e32 v39, v1
	s_movk_i32 s0, 0x2040
	v_mad_i64_i32 v[34:35], s[0:1], v34, s0, v[38:39]
	v_readlane_b32 s0, v254, 8
	v_lshlrev_b64 v[34:35], 7, v[34:35]
	v_readlane_b32 s1, v254, 9
	v_lshlrev_b32_e32 v36, 1, v137
	v_mov_b32_e32 v37, v1
	v_lshl_add_u64 v[34:35], s[0:1], 0, v[34:35]
	v_lshl_add_u64 v[34:35], v[34:35], 0, v[36:37]
	v_lshlrev_b32_e32 v36, 1, v139
	v_lshl_add_u64 v[40:41], v[34:35], 0, v[36:37]
	v_cvt_pk_bf16_f32 v34, v30, v31
	v_cvt_pk_bf16_f32 v35, v32, v33
	v_cvt_pk_bf16_f32 v36, v26, v27
	v_cvt_pk_bf16_f32 v37, v28, v29
	global_store_dwordx4 v[40:41], v[34:37], off sc1

; __device__ __forceinline__ void store8bf(bf16_t* p, f32x4 v0, f32x4 v1) { u32x4 w; w.x = cvt_pk_bf16(v0[0], v0[1]); w.y = cvt_pk_bf16(v0[2], v0[3]); w.z = cvt_pk_bf16(v1[0], v1[1]); w.w = cvt_pk_bf16(v1[2], v1[3]); *(u32x4*)p = w; }
;   __device__ __forceinline__ void group(int row, int c32, int fq, f32x4 v0, f32x4 v1) const {
;     ...
;     if (c32 < 768) { const int cc = c32 - 512, h = cc >> 6; store8bf(qd + ((size_t)(b * 4 + h) * E + e) * 64 + (cc & 63) + fq * 8, v0 * QSC_D, v1 * QSC_D); }
.LBB0_655:
	s_andn2_b64 vcc, exec, s[42:43]
	s_cbranch_vccnz .LBB0_657
	v_lshl_add_u32 v34, v42, 2, v107
	v_mov_b32_e32 v39, v1
	s_movk_i32 s0, 0x2040
	v_mad_i64_i32 v[34:35], s[0:1], v34, s0, v[38:39]
	v_readlane_b32 s0, v254, 6
	v_lshlrev_b64 v[34:35], 7, v[34:35]
	v_readlane_b32 s1, v254, 7
	v_lshlrev_b32_e32 v36, 1, v137
	v_mov_b32_e32 v37, v1
	v_lshl_add_u64 v[34:35], s[0:1], 0, v[34:35]
	v_lshl_add_u64 v[34:35], v[34:35], 0, v[36:37]
	v_lshlrev_b32_e32 v36, 1, v139
	s_mov_b32 s0, 0x3e8293ee
	v_lshl_add_u64 v[40:41], v[34:35], 0, v[36:37]
	v_pk_mul_f32 v[36:37], v[32:33], s[0:1] op_sel_hi:[1,0]
	v_pk_mul_f32 v[34:35], v[30:31], s[0:1] op_sel_hi:[1,0]
	v_pk_mul_f32 v[44:45], v[28:29], s[0:1] op_sel_hi:[1,0]
	v_pk_mul_f32 v[46:47], v[26:27], s[0:1] op_sel_hi:[1,0]
	v_cvt_pk_bf16_f32 v34, v34, v35
	v_cvt_pk_bf16_f32 v35, v36, v37
	v_cvt_pk_bf16_f32 v36, v46, v47
	v_cvt_pk_bf16_f32 v37, v44, v45
	global_store_dwordx4 v[40:41], v[34:37], off sc1

; __device__ __forceinline__ void store4bf(bf16_t* p, f32x4 v) { u32x2 w; w.x = cvt_pk_bf16(v[0], v[1]); w.y = cvt_pk_bf16(v[2], v[3]); *(u32x2*)p = w; }
; __device__ __forceinline__ void store8bf(bf16_t* p, f32x4 v0, f32x4 v1) { u32x4 w; w.x = cvt_pk_bf16(v0[0], v0[1]); w.y = cvt_pk_bf16(v0[2], v0[3]); w.z = cvt_pk_bf16(v1[0], v1[1]); w.w = cvt_pk_bf16(v1[2], v1[3]); *(u32x4*)p = w; }
;   __device__ __forceinline__ void group(int row, int c32, int fq, f32x4 v0, f32x4 v1) const {
;     ...
;     if (c32 < 512) {
;       if (c32 < 384) store8bf(cqkv + (size_t)row * 512 + c32 + fq * 8, v0, v1);
;       else { bf16_t* p = cqkv + (size_t)row * 512 + c32 + fq * 4; store4bf(p, v0); store4bf(p + 16, v1); }
;       if (c32 == 384 && ok) {
;         const float2* rp = rope + pos_of_e(e) * 16 + fq * 4; f32x4 o0, o1;
; #pragma unroll
;         for (int j = 0; j < 4; ++j) { const float2 cs = rp[j]; o0[j] = v0[j] * cs.x - v1[j] * cs.y; o1[j] = v1[j] * cs.x + v0[j] * cs.y; }
; #pragma unroll
;         for (int h = 0; h < 6; ++h) { bf16_t* q = ka + ((size_t)(b * 6 + h) * E + e) * 96 + 64 + fq * 4; store4bf(q, o0); store4bf(q + 16, o1); }
;       }
.LBB0_658:
	v_cndmask_b32_e64 v34, 0, 1, s[10:11]
	s_andn2_b64 vcc, exec, s[42:43]
	v_cmp_ne_u32_e64 s[10:11], 1, v34
	s_cbranch_vccnz .LBB0_665
	v_ashrrev_i32_e32 v67, 31, v66
	v_readlane_b32 s0, v254, 0
	v_lshlrev_b64 v[34:35], 10, v[66:67]
	v_readlane_b32 s1, v254, 1
	s_and_b64 vcc, exec, s[10:11]
	v_cvt_pk_bf16_f32 v36, v26, v27
	v_lshl_add_u64 v[40:41], s[0:1], 0, v[34:35]
	v_cvt_pk_bf16_f32 v34, v30, v31
	v_cvt_pk_bf16_f32 v35, v32, v33
	v_cvt_pk_bf16_f32 v37, v28, v29
	s_cbranch_vccnz .LBB0_765
	v_lshl_add_u64 v[44:45], v[0:1], 1, v[40:41]
	v_lshlrev_b32_e32 v46, 1, v138
	v_mov_b32_e32 v47, v1
	v_lshl_add_u64 v[44:45], v[44:45], 0, v[46:47]
	global_store_dwordx2 v[44:45], v[34:35], off offset:256 sc1
	global_store_dwordx2 v[44:45], v[36:37], off offset:288 sc1
	s_cbranch_execnz .LBB0_662
.LBB0_661:
	v_lshl_add_u64 v[40:41], v[0:1], 1, v[40:41]
	v_lshlrev_b32_e32 v44, 1, v139
	v_mov_b32_e32 v45, v1
	v_lshl_add_u64 v[40:41], v[40:41], 0, v[44:45]
	global_store_dwordx4 v[40:41], v[34:37], off offset:256 sc1
.LBB0_662:
	s_and_b64 s[0:1], s[4:5], s[16:17]
	s_and_saveexec_b64 s[16:17], s[0:1]
	s_cbranch_execz .LBB0_664
	v_lshlrev_b32_e32 v34, 4, v38
	v_add_u32_e32 v35, 0xfffffd00, v34
	v_readlane_b32 s0, v253, 40
	v_cndmask_b32_e64 v34, v34, v35, s[14:15]
	v_mov_b32_e32 v35, v1
	v_readlane_b32 s1, v253, 41
	v_lshlrev_b32_e32 v36, 3, v138
	v_mov_b32_e32 v37, v1
	v_lshl_add_u64 v[34:35], v[34:35], 3, s[0:1]
	v_lshl_add_u64 v[40:41], v[34:35], 0, v[36:37]
	global_load_dwordx4 v[34:37], v[40:41], off offset:16
	global_load_dwordx4 v[44:47], v[40:41], off
	v_mul_i32_i24_e32 v43, 6, v42
	v_mov_b32_e32 v39, v1
	s_movk_i32 s14, 0x2040
	s_waitcnt vmcnt(0)
	v_mov_b32_e32 v41, v46
	v_mov_b32_e32 v46, v45
	v_mov_b32_e32 v40, v44
	v_pk_mul_f32 v[44:45], v[30:31], v[46:47]
	v_pk_mul_f32 v[46:47], v[26:27], v[46:47]
	v_pk_fma_f32 v[44:45], v[26:27], v[40:41], v[44:45]
	v_pk_fma_f32 v[40:41], v[30:31], v[40:41], v[46:47] neg_lo:[0,0,1] neg_hi:[0,0,1]
	v_mov_b32_e32 v47, v36
	v_mov_b32_e32 v36, v35
	v_mov_b32_e32 v46, v34
	v_pk_mul_f32 v[34:35], v[32:33], v[36:37]
	s_nop 0
	v_pk_fma_f32 v[48:49], v[28:29], v[46:47], v[34:35]
	v_pk_mul_f32 v[34:35], v[28:29], v[36:37]
	s_nop 0
	v_pk_fma_f32 v[36:37], v[32:33], v[46:47], v[34:35] neg_lo:[0,0,1] neg_hi:[0,0,1]
	v_cvt_pk_bf16_f32 v34, v40, v41
	v_mad_i64_i32 v[40:41], s[0:1], v43, s14, v[38:39]
	v_readlane_b32 s0, v254, 4
	v_readlane_b32 s1, v254, 5
	v_cvt_pk_bf16_f32 v35, v36, v37
	v_cvt_pk_bf16_f32 v36, v44, v45
	v_mov_b64_e32 v[44:45], s[0:1]
	v_mad_u64_u32 v[46:47], s[0:1], v40, s47, v[44:45]
	v_mad_i32_i24 v47, v41, s47, v47
	v_lshlrev_b32_e32 v40, 1, v138
	v_mov_b32_e32 v41, v1
	v_lshl_add_u64 v[46:47], v[46:47], 0, v[40:41]
	v_or_b32_e32 v43, 1, v43
	v_cvt_pk_bf16_f32 v37, v48, v49
	global_store_dwordx2 v[46:47], v[34:35], off offset:128 sc1
	global_store_dwordx2 v[46:47], v[36:37], off offset:160 sc1
	v_mad_i64_i32 v[46:47], s[0:1], v43, s14, v[38:39]
	v_mad_u64_u32 v[48:49], s[0:1], v46, s47, v[44:45]
	v_mad_i32_i24 v49, v47, s47, v49
	v_lshl_add_u64 v[46:47], v[48:49], 0, v[40:41]
	v_mad_i32_i24 v43, v42, 6, 2
	global_store_dwordx2 v[46:47], v[34:35], off offset:128 sc1
	global_store_dwordx2 v[46:47], v[36:37], off offset:160 sc1
	v_mad_i64_i32 v[46:47], s[0:1], v43, s14, v[38:39]
	v_mad_u64_u32 v[48:49], s[0:1], v46, s47, v[44:45]
	v_mad_i32_i24 v49, v47, s47, v49
	v_lshl_add_u64 v[46:47], v[48:49], 0, v[40:41]
	v_mad_i32_i24 v43, v42, 6, 3
	global_store_dwordx2 v[46:47], v[34:35], off offset:128 sc1
	global_store_dwordx2 v[46:47], v[36:37], off offset:160 sc1
	v_mad_i64_i32 v[46:47], s[0:1], v43, s14, v[38:39]
	v_mad_u64_u32 v[48:49], s[0:1], v46, s47, v[44:45]
	v_mad_i32_i24 v49, v47, s47, v49
	v_lshl_add_u64 v[46:47], v[48:49], 0, v[40:41]
	v_mad_i32_i24 v43, v42, 6, 4
	v_mad_i32_i24 v42, v42, 6, 5
	global_store_dwordx2 v[46:47], v[34:35], off offset:128 sc1
	global_store_dwordx2 v[46:47], v[36:37], off offset:160 sc1
	v_mad_i64_i32 v[46:47], s[0:1], v43, s14, v[38:39]
	v_mad_i64_i32 v[38:39], s[0:1], v42, s14, v[38:39]
	v_mad_u64_u32 v[48:49], s[0:1], v46, s47, v[44:45]
	v_mad_u64_u32 v[42:43], s[0:1], v38, s47, v[44:45]
	v_mad_i32_i24 v49, v47, s47, v49
	v_mad_i32_i24 v43, v39, s47, v43
	v_lshl_add_u64 v[46:47], v[48:49], 0, v[40:41]
	v_lshl_add_u64 v[38:39], v[42:43], 0, v[40:41]
	global_store_dwordx2 v[46:47], v[34:35], off offset:128 sc1
	global_store_dwordx2 v[46:47], v[36:37], off offset:160 sc1
	global_store_dwordx2 v[38:39], v[34:35], off offset:128 sc1
	global_store_dwordx2 v[38:39], v[36:37], off offset:160 sc1

; __device__ __forceinline__ unsigned short f2bf(float f) { return (unsigned short)(cvt_pk_bf16(f, f) & 0xffffu); }
; __device__ __forceinline__ void store4bf(bf16_t* p, f32x4 v) { u32x2 w; w.x = cvt_pk_bf16(v[0], v[1]); w.y = cvt_pk_bf16(v[2], v[3]); *(u32x2*)p = w; }
;   __device__ __forceinline__ void group(int row, int c32, int fq, f32x4 v0, f32x4 v1) const {
;     int b, e; const bool ok = row_be(row, b, e);
;     if (c32 < 512) {
;       if (c32 < 384) store8bf(cqkv + (size_t)row * 512 + c32 + fq * 8, v0, v1);
;       else { bf16_t* p = cqkv + (size_t)row * 512 + c32 + fq * 4; store4bf(p, v0); store4bf(p + 16, v1); }
;       if (c32 == 384 && ok) {
;         const float2* rp = rope + pos_of_e(e) * 16 + fq * 4; f32x4 o0, o1;
; #pragma unroll
;         for (int j = 0; j < 4; ++j) { const float2 cs = rp[j]; o0[j] = v0[j] * cs.x - v1[j] * cs.y; o1[j] = v1[j] * cs.x + v0[j] * cs.y; }
; #pragma unroll
;         for (int h = 0; h < 6; ++h) { bf16_t* q = ka + ((size_t)(b * 6 + h) * E + e) * 96 + 64 + fq * 4; store4bf(q, o0); store4bf(q + 16, o1); }
;       }
;       return;
;     }
;     if (!ok) return;
;     if (c32 < 768) { const int cc = c32 - 512, h = cc >> 6; store8bf(qd + ((size_t)(b * 4 + h) * E + e) * 64 + (cc & 63) + fq * 8, v0 * QSC_D, v1 * QSC_D); }
;     else if (c32 < 1024) { const int cc = c32 - 768, h = cc >> 6; store8bf(kd + ((size_t)(b * 4 + h) * E + e) * 64 + (cc & 63) + fq * 8, v0, v1); }
;     else if (c32 < 1280) { const int cc = c32 - 1024, h = cc >> 6; bf16_t* p = vtd + ((size_t)(b * 4 + h) * 64 + (cc & 63) + fq * 4) * E + e;
; #pragma unroll
;       for (int j = 0; j < 4; ++j) { p[(size_t)j * E] = f2bf(v0[j]); p[(size_t)(j + 16) * E] = f2bf(v1[j]); } }
;     else if (c32 < 1664) { const int cc = c32 - 1280, h = cc >> 6; store8bf(qs + ((size_t)(b * 6 + h) * E + e) * 64 + (cc & 63) + fq * 8, v0 * QSC_S, v1 * QSC_S); }
;     else if (c32 < 1792) { const int cc = c32 - 1664, g = cc >> 6; store8bf(ks + ((size_t)(b * 2 + g) * E + e) * 64 + (cc & 63) + fq * 8, v0, v1); }
;     else if (c32 < 1920) { const int cc = c32 - 1792, g = cc >> 6; bf16_t* p = vts + ((size_t)(b * 2 + g) * 64 + (cc & 63) + fq * 4) * E + e;
; #pragma unroll
;       for (int j = 0; j < 4; ++j) { p[(size_t)j * E] = f2bf(v0[j]); p[(size_t)(j + 16) * E] = f2bf(v1[j]); } }
.LBB0_665:
	s_movk_i32 s0, 0x1fdf
	v_or_b32_e32 v34, 16, v66
	v_bitop3_b32 v35, v66, s0, 16 bitop3:0xc8
	s_mov_b32 s0, 0x8000
	v_add_u32_e32 v35, 64, v35
	v_cmp_gt_i32_e64 s[16:17], s0, v34
	v_bfe_u32 v36, v34, 4, 2
	s_or_b64 s[44:45], s[16:17], s[12:13]
	v_cndmask_b32_e64 v38, v136, v35, s[16:17]
	v_cndmask_b32_e64 v35, 0, 1, s[40:41]
	v_cndmask_b32_e64 v42, v36, v72, s[16:17]
	v_cmp_ne_u32_e64 s[14:15], 1, v35
	s_andn2_b64 vcc, exec, s[40:41]
	s_mov_b64 s[40:41], -1
	s_cbranch_vccnz .LBB0_689
	s_and_saveexec_b64 s[40:41], s[44:45]
	s_cbranch_execz .LBB0_688
	s_andn2_b64 vcc, exec, s[38:39]
	s_mov_b64 s[42:43], -1
	s_cbranch_vccnz .LBB0_686
	s_andn2_b64 vcc, exec, s[24:25]
	s_cbranch_vccnz .LBB0_683
	s_andn2_b64 vcc, exec, s[20:21]
	s_cbranch_vccnz .LBB0_680
	s_and_saveexec_b64 s[0:1], s[8:9]
	s_xor_b64 s[68:69], exec, s[0:1]
	s_cbranch_execz .LBB0_677
	s_andn2_b64 vcc, exec, s[18:19]
	s_cbranch_vccnz .LBB0_675
	s_and_saveexec_b64 s[42:43], s[6:7]
	s_cbranch_execz .LBB0_674
	v_lshl_add_u32 v36, v42, 1, v110
	v_ashrrev_i32_e32 v37, 31, v36
	v_readlane_b32 s0, v254, 16
	v_lshlrev_b64 v[36:37], 6, v[36:37]
	v_readlane_b32 s1, v254, 17
	v_or_b32_e32 v35, v36, v140
	v_lshlrev_b32_e32 v36, 1, v38
	v_mov_b64_e32 v[40:41], s[0:1]
	v_mad_u64_u32 v[40:41], s[0:1], v35, s95, v[40:41]
	v_mad_i32_i24 v41, v37, s95, v41
	v_mov_b32_e32 v37, v1
	v_lshl_add_u64 v[36:37], v[40:41], 0, v[36:37]
	v_cvt_pk_bf16_f32 v35, v22, s0
	global_store_short v[36:37], v35, off sc1
	v_cvt_pk_bf16_f32 v35, v18, s0
	s_mov_b32 s0, 0x40000
	v_add_co_u32_e32 v40, vcc, s0, v36
	s_nop 1
	v_addc_co_u32_e32 v41, vcc, 0, v37, vcc
	global_store_short v[40:41], v35, off offset:2048 sc1
	v_cvt_pk_bf16_f32 v35, v23, s0
	s_movk_i32 s0, 0x4000
	v_add_co_u32_e32 v40, vcc, s0, v36
	s_nop 1
	v_addc_co_u32_e32 v41, vcc, 0, v37, vcc
	global_store_short v[40:41], v35, off offset:128 sc1
	v_cvt_pk_bf16_f32 v35, v19, s0
	s_mov_b32 s0, 0x44000
	v_add_co_u32_e32 v40, vcc, s0, v36
	s_nop 1
	v_addc_co_u32_e32 v41, vcc, 0, v37, vcc
	global_store_short v[40:41], v35, off offset:2176 sc1
	v_cvt_pk_bf16_f32 v35, v24, s0
	s_mov_b32 s0, 0x8000
	v_add_co_u32_e32 v40, vcc, s0, v36
	s_nop 1
	v_addc_co_u32_e32 v41, vcc, 0, v37, vcc
	global_store_short v[40:41], v35, off offset:256 sc1
	v_cvt_pk_bf16_f32 v35, v20, s0
	s_mov_b32 s0, 0x48000
	v_add_co_u32_e32 v40, vcc, s0, v36
	s_nop 1
	v_addc_co_u32_e32 v41, vcc, 0, v37, vcc
	global_store_short v[40:41], v35, off offset:2304 sc1
	v_add_co_u32_e32 v40, vcc, 0xc000, v36
	v_cvt_pk_bf16_f32 v35, v25, s0
	s_nop 0
	v_addc_co_u32_e32 v41, vcc, 0, v37, vcc
	v_add_co_u32_e32 v36, vcc, 0x4c000, v36
	global_store_short v[40:41], v35, off offset:384 sc1
	v_cvt_pk_bf16_f32 v35, v21, s0
	v_addc_co_u32_e32 v37, vcc, 0, v37, vcc
	global_store_short v[36:37], v35, off offset:2432 sc1

; __device__ __forceinline__ void store8bf(bf16_t* p, f32x4 v0, f32x4 v1) { u32x4 w; w.x = cvt_pk_bf16(v0[0], v0[1]); w.y = cvt_pk_bf16(v0[2], v0[3]); w.z = cvt_pk_bf16(v1[0], v1[1]); w.w = cvt_pk_bf16(v1[2], v1[3]); *(u32x4*)p = w; }
;   __device__ __forceinline__ void group(int row, int c32, int fq, f32x4 v0, f32x4 v1) const {
;     ...
;     else if (c32 < 1664) { const int cc = c32 - 1280, h = cc >> 6; store8bf(qs + ((size_t)(b * 6 + h) * E + e) * 64 + (cc & 63) + fq * 8, v0 * QSC_S, v1 * QSC_S); }
;     else if (c32 < 1792) { const int cc = c32 - 1664, g = cc >> 6; store8bf(ks + ((size_t)(b * 2 + g) * E + e) * 64 + (cc & 63) + fq * 8, v0, v1); }
.LBB0_675:
	s_andn2_b64 vcc, exec, s[42:43]
	s_cbranch_vccnz .LBB0_677
	v_lshl_add_u32 v35, v42, 1, v109
	v_mov_b32_e32 v39, v1
	s_movk_i32 s0, 0x2040
	v_mad_i64_i32 v[36:37], s[0:1], v35, s0, v[38:39]
	v_readlane_b32 s0, v254, 14
	v_lshlrev_b64 v[36:37], 7, v[36:37]
	v_readlane_b32 s1, v254, 15
	v_lshlrev_b32_e32 v40, 1, v137
	v_mov_b32_e32 v41, v1
	v_lshl_add_u64 v[36:37], s[0:1], 0, v[36:37]
	v_lshl_add_u64 v[36:37], v[36:37], 0, v[40:41]
	v_lshlrev_b32_e32 v40, 1, v139
	v_lshl_add_u64 v[36:37], v[36:37], 0, v[40:41]
	v_cvt_pk_bf16_f32 v44, v22, v23
	v_cvt_pk_bf16_f32 v45, v24, v25
	v_cvt_pk_bf16_f32 v46, v18, v19
	v_cvt_pk_bf16_f32 v47, v20, v21
	global_store_dwordx4 v[36:37], v[44:47], off sc1
.LBB0_677:
	s_andn2_saveexec_b64 s[42:43], s[68:69]
	s_cbranch_execz .LBB0_679
	v_mad_i32_i24 v35, v42, 6, v111
	v_mov_b32_e32 v39, v1
	s_movk_i32 s0, 0x2040
	v_mad_i64_i32 v[36:37], s[0:1], v35, s0, v[38:39]
	v_readlane_b32 s0, v254, 12
	v_lshlrev_b64 v[36:37], 7, v[36:37]
	v_readlane_b32 s1, v254, 13
	v_lshlrev_b32_e32 v40, 1, v137
	v_mov_b32_e32 v41, v1
	v_lshl_add_u64 v[36:37], s[0:1], 0, v[36:37]
	v_lshl_add_u64 v[36:37], v[36:37], 0, v[40:41]
	v_lshlrev_b32_e32 v40, 1, v139
	s_mov_b32 s0, 0x3e38aa3b
	v_lshl_add_u64 v[36:37], v[36:37], 0, v[40:41]
	v_pk_mul_f32 v[40:41], v[24:25], s[0:1] op_sel_hi:[1,0]
	v_pk_mul_f32 v[44:45], v[22:23], s[0:1] op_sel_hi:[1,0]
	v_pk_mul_f32 v[48:49], v[20:21], s[0:1] op_sel_hi:[1,0]
	v_pk_mul_f32 v[46:47], v[18:19], s[0:1] op_sel_hi:[1,0]
	v_cvt_pk_bf16_f32 v44, v44, v45
	v_cvt_pk_bf16_f32 v45, v40, v41
	v_cvt_pk_bf16_f32 v46, v46, v47
	v_cvt_pk_bf16_f32 v47, v48, v49
	global_store_dwordx4 v[36:37], v[44:47], off sc1

; __device__ __forceinline__ unsigned short f2bf(float f) { return (unsigned short)(cvt_pk_bf16(f, f) & 0xffffu); }
;   __device__ __forceinline__ void group(int row, int c32, int fq, f32x4 v0, f32x4 v1) const {
;     ...
;     else if (c32 < 1280) { const int cc = c32 - 1024, h = cc >> 6; bf16_t* p = vtd + ((size_t)(b * 4 + h) * 64 + (cc & 63) + fq * 4) * E + e;
; #pragma unroll
;       for (int j = 0; j < 4; ++j) { p[(size_t)j * E] = f2bf(v0[j]); p[(size_t)(j + 16) * E] = f2bf(v1[j]); } }
.LBB0_680:
	s_andn2_b64 vcc, exec, s[42:43]
	s_cbranch_vccnz .LBB0_682
	v_lshl_add_u32 v36, v42, 2, v106
	v_ashrrev_i32_e32 v37, 31, v36
	v_readlane_b32 s0, v254, 10
	v_lshlrev_b64 v[36:37], 6, v[36:37]
	v_readlane_b32 s1, v254, 11
	v_or_b32_e32 v35, v36, v140
	v_lshlrev_b32_e32 v36, 1, v38
	v_mov_b64_e32 v[40:41], s[0:1]
	v_mad_u64_u32 v[40:41], s[0:1], v35, s95, v[40:41]
	v_mad_i32_i24 v41, v37, s95, v41
	v_mov_b32_e32 v37, v1
	v_lshl_add_u64 v[36:37], v[40:41], 0, v[36:37]
	v_cvt_pk_bf16_f32 v35, v22, s0
	global_store_short v[36:37], v35, off sc1
	v_cvt_pk_bf16_f32 v35, v18, s0
	s_mov_b32 s0, 0x40000
	v_add_co_u32_e32 v40, vcc, s0, v36
	s_nop 1
	v_addc_co_u32_e32 v41, vcc, 0, v37, vcc
	global_store_short v[40:41], v35, off offset:2048 sc1
	v_cvt_pk_bf16_f32 v35, v23, s0
	s_movk_i32 s0, 0x4000
	v_add_co_u32_e32 v40, vcc, s0, v36
	s_nop 1
	v_addc_co_u32_e32 v41, vcc, 0, v37, vcc
	global_store_short v[40:41], v35, off offset:128 sc1
	v_cvt_pk_bf16_f32 v35, v19, s0
	s_mov_b32 s0, 0x44000
	v_add_co_u32_e32 v40, vcc, s0, v36
	s_nop 1
	v_addc_co_u32_e32 v41, vcc, 0, v37, vcc
	global_store_short v[40:41], v35, off offset:2176 sc1
	v_cvt_pk_bf16_f32 v35, v24, s0
	s_mov_b32 s0, 0x8000
	v_add_co_u32_e32 v40, vcc, s0, v36
	s_nop 1
	v_addc_co_u32_e32 v41, vcc, 0, v37, vcc
	global_store_short v[40:41], v35, off offset:256 sc1
	v_cvt_pk_bf16_f32 v35, v20, s0
	s_mov_b32 s0, 0x48000
	v_add_co_u32_e32 v40, vcc, s0, v36
	s_nop 1
	v_addc_co_u32_e32 v41, vcc, 0, v37, vcc
	global_store_short v[40:41], v35, off offset:2304 sc1
	v_add_co_u32_e32 v40, vcc, 0xc000, v36
	v_cvt_pk_bf16_f32 v35, v25, s0
	s_nop 0
	v_addc_co_u32_e32 v41, vcc, 0, v37, vcc
	v_add_co_u32_e32 v36, vcc, 0x4c000, v36
	global_store_short v[40:41], v35, off offset:384 sc1
	v_cvt_pk_bf16_f32 v35, v21, s0
	v_addc_co_u32_e32 v37, vcc, 0, v37, vcc
	global_store_short v[36:37], v35, off offset:2432 sc1

; __device__ __forceinline__ void store8bf(bf16_t* p, f32x4 v0, f32x4 v1) { u32x4 w; w.x = cvt_pk_bf16(v0[0], v0[1]); w.y = cvt_pk_bf16(v0[2], v0[3]); w.z = cvt_pk_bf16(v1[0], v1[1]); w.w = cvt_pk_bf16(v1[2], v1[3]); *(u32x4*)p = w; }
;   __device__ __forceinline__ void group(int row, int c32, int fq, f32x4 v0, f32x4 v1) const {
;     ...
;     else if (c32 < 1024) { const int cc = c32 - 768, h = cc >> 6; store8bf(kd + ((size_t)(b * 4 + h) * E + e) * 64 + (cc & 63) + fq * 8, v0, v1); }
.LBB0_683:
	s_andn2_b64 vcc, exec, s[42:43]
	s_cbranch_vccnz .LBB0_685
	v_lshl_add_u32 v35, v42, 2, v108
	v_mov_b32_e32 v39, v1
	s_movk_i32 s0, 0x2040
	v_mad_i64_i32 v[36:37], s[0:1], v35, s0, v[38:39]
	v_readlane_b32 s0, v254, 8
	v_lshlrev_b64 v[36:37], 7, v[36:37]
	v_readlane_b32 s1, v254, 9
	v_lshlrev_b32_e32 v40, 1, v137
	v_mov_b32_e32 v41, v1
	v_lshl_add_u64 v[36:37], s[0:1], 0, v[36:37]
	v_lshl_add_u64 v[36:37], v[36:37], 0, v[40:41]
	v_lshlrev_b32_e32 v40, 1, v139
	v_lshl_add_u64 v[36:37], v[36:37], 0, v[40:41]
	v_cvt_pk_bf16_f32 v44, v22, v23
	v_cvt_pk_bf16_f32 v45, v24, v25
	v_cvt_pk_bf16_f32 v46, v18, v19
	v_cvt_pk_bf16_f32 v47, v20, v21
	global_store_dwordx4 v[36:37], v[44:47], off sc1

; __device__ __forceinline__ void store8bf(bf16_t* p, f32x4 v0, f32x4 v1) { u32x4 w; w.x = cvt_pk_bf16(v0[0], v0[1]); w.y = cvt_pk_bf16(v0[2], v0[3]); w.z = cvt_pk_bf16(v1[0], v1[1]); w.w = cvt_pk_bf16(v1[2], v1[3]); *(u32x4*)p = w; }
;   __device__ __forceinline__ void group(int row, int c32, int fq, f32x4 v0, f32x4 v1) const {
;     ...
;     if (c32 < 768) { const int cc = c32 - 512, h = cc >> 6; store8bf(qd + ((size_t)(b * 4 + h) * E + e) * 64 + (cc & 63) + fq * 8, v0 * QSC_D, v1 * QSC_D); }
.LBB0_686:
	s_andn2_b64 vcc, exec, s[42:43]
	s_cbranch_vccnz .LBB0_688
	v_lshl_add_u32 v35, v42, 2, v107
	v_mov_b32_e32 v39, v1
	s_movk_i32 s0, 0x2040
	v_mad_i64_i32 v[36:37], s[0:1], v35, s0, v[38:39]
	v_readlane_b32 s0, v254, 6
	v_lshlrev_b64 v[36:37], 7, v[36:37]
	v_readlane_b32 s1, v254, 7
	v_lshlrev_b32_e32 v40, 1, v137
	v_mov_b32_e32 v41, v1
	v_lshl_add_u64 v[36:37], s[0:1], 0, v[36:37]
	v_lshl_add_u64 v[36:37], v[36:37], 0, v[40:41]
	v_lshlrev_b32_e32 v40, 1, v139
	s_mov_b32 s0, 0x3e8293ee
	v_lshl_add_u64 v[36:37], v[36:37], 0, v[40:41]
	v_pk_mul_f32 v[40:41], v[24:25], s[0:1] op_sel_hi:[1,0]
	v_pk_mul_f32 v[44:45], v[22:23], s[0:1] op_sel_hi:[1,0]
	v_pk_mul_f32 v[48:49], v[20:21], s[0:1] op_sel_hi:[1,0]
	v_pk_mul_f32 v[46:47], v[18:19], s[0:1] op_sel_hi:[1,0]
	v_cvt_pk_bf16_f32 v44, v44, v45
	v_cvt_pk_bf16_f32 v45, v40, v41
	v_cvt_pk_bf16_f32 v46, v46, v47
	v_cvt_pk_bf16_f32 v47, v48, v49
	global_store_dwordx4 v[36:37], v[44:47], off sc1

; __device__ __forceinline__ void store4bf(bf16_t* p, f32x4 v) { u32x2 w; w.x = cvt_pk_bf16(v[0], v[1]); w.y = cvt_pk_bf16(v[2], v[3]); *(u32x2*)p = w; }
; __device__ __forceinline__ void store8bf(bf16_t* p, f32x4 v0, f32x4 v1) { u32x4 w; w.x = cvt_pk_bf16(v0[0], v0[1]); w.y = cvt_pk_bf16(v0[2], v0[3]); w.z = cvt_pk_bf16(v1[0], v1[1]); w.w = cvt_pk_bf16(v1[2], v1[3]); *(u32x4*)p = w; }
;   __device__ __forceinline__ void group(int row, int c32, int fq, f32x4 v0, f32x4 v1) const {
;     ...
;     if (c32 < 512) {
;       if (c32 < 384) store8bf(cqkv + (size_t)row * 512 + c32 + fq * 8, v0, v1);
;       else { bf16_t* p = cqkv + (size_t)row * 512 + c32 + fq * 4; store4bf(p, v0); store4bf(p + 16, v1); }
;       if (c32 == 384 && ok) {
;         const float2* rp = rope + pos_of_e(e) * 16 + fq * 4; f32x4 o0, o1;
; #pragma unroll
;         for (int j = 0; j < 4; ++j) { const float2 cs = rp[j]; o0[j] = v0[j] * cs.x - v1[j] * cs.y; o1[j] = v1[j] * cs.x + v0[j] * cs.y; }
; #pragma unroll
;         for (int h = 0; h < 6; ++h) { bf16_t* q = ka + ((size_t)(b * 6 + h) * E + e) * 96 + 64 + fq * 4; store4bf(q, o0); store4bf(q + 16, o1); }
;       }
;       return;
.LBB0_689:
	s_andn2_b64 vcc, exec, s[40:41]
	s_cbranch_vccnz .LBB0_696
	v_ashrrev_i32_e32 v35, 31, v34
	v_readlane_b32 s0, v254, 0
	v_lshlrev_b64 v[34:35], 10, v[34:35]
	v_readlane_b32 s1, v254, 1
	s_and_b64 vcc, exec, s[10:11]
	v_cvt_pk_bf16_f32 v36, v18, v19
	v_lshl_add_u64 v[40:41], s[0:1], 0, v[34:35]
	v_cvt_pk_bf16_f32 v34, v22, v23
	v_cvt_pk_bf16_f32 v35, v24, v25
	v_cvt_pk_bf16_f32 v37, v20, v21
	s_cbranch_vccnz .LBB0_766
	v_lshl_add_u64 v[44:45], v[0:1], 1, v[40:41]
	v_lshlrev_b32_e32 v46, 1, v138
	v_mov_b32_e32 v47, v1
	v_lshl_add_u64 v[44:45], v[44:45], 0, v[46:47]
	global_store_dwordx2 v[44:45], v[34:35], off offset:256 sc1
	global_store_dwordx2 v[44:45], v[36:37], off offset:288 sc1
	s_cbranch_execnz .LBB0_693
.LBB0_692:
	v_mov_b32_e32 v44, v0
	v_mov_b32_e32 v45, v1
	v_lshl_add_u64 v[40:41], v[44:45], 1, v[40:41]
	v_lshlrev_b32_e32 v44, 1, v139
	v_lshl_add_u64 v[40:41], v[40:41], 0, v[44:45]
	global_store_dwordx4 v[40:41], v[34:37], off offset:256 sc1
.LBB0_693:
	s_and_b64 s[0:1], s[4:5], s[44:45]
	s_and_saveexec_b64 s[40:41], s[0:1]
	s_cbranch_execz .LBB0_695
	v_lshlrev_b32_e32 v34, 4, v38
	v_add_u32_e32 v35, 0xfffffd00, v34
	v_readlane_b32 s0, v253, 40
	v_cndmask_b32_e64 v34, v34, v35, s[16:17]
	v_mov_b32_e32 v35, v1
	v_readlane_b32 s1, v253, 41
	v_lshlrev_b32_e32 v36, 3, v138
	v_mov_b32_e32 v37, v1
	v_lshl_add_u64 v[34:35], v[34:35], 3, s[0:1]
	v_lshl_add_u64 v[40:41], v[34:35], 0, v[36:37]
	global_load_dwordx4 v[34:37], v[40:41], off offset:16
	global_load_dwordx4 v[44:47], v[40:41], off
	v_mul_i32_i24_e32 v43, 6, v42
	v_mov_b32_e32 v39, v1
	s_movk_i32 s16, 0x2040
	s_waitcnt vmcnt(0)
	v_mov_b32_e32 v41, v46
	v_mov_b32_e32 v46, v45
	v_mov_b32_e32 v40, v44
	v_pk_mul_f32 v[44:45], v[22:23], v[46:47]
	v_pk_mul_f32 v[46:47], v[18:19], v[46:47]
	v_pk_fma_f32 v[44:45], v[18:19], v[40:41], v[44:45]
	v_pk_fma_f32 v[40:41], v[22:23], v[40:41], v[46:47] neg_lo:[0,0,1] neg_hi:[0,0,1]
	v_mov_b32_e32 v47, v36
	v_mov_b32_e32 v36, v35
	v_mov_b32_e32 v46, v34
	v_pk_mul_f32 v[34:35], v[24:25], v[36:37]
	s_nop 0
	v_pk_fma_f32 v[48:49], v[20:21], v[46:47], v[34:35]
	v_pk_mul_f32 v[34:35], v[20:21], v[36:37]
	s_nop 0
	v_pk_fma_f32 v[36:37], v[24:25], v[46:47], v[34:35] neg_lo:[0,0,1] neg_hi:[0,0,1]
	v_cvt_pk_bf16_f32 v34, v40, v41
	v_mad_i64_i32 v[40:41], s[0:1], v43, s16, v[38:39]
	v_readlane_b32 s0, v254, 4
	v_readlane_b32 s1, v254, 5
	v_cvt_pk_bf16_f32 v35, v36, v37
	v_cvt_pk_bf16_f32 v36, v44, v45
	v_mov_b64_e32 v[44:45], s[0:1]
	v_mad_u64_u32 v[46:47], s[0:1], v40, s47, v[44:45]
	v_mad_i32_i24 v47, v41, s47, v47
	v_lshlrev_b32_e32 v40, 1, v138
	v_mov_b32_e32 v41, v1
	v_lshl_add_u64 v[46:47], v[46:47], 0, v[40:41]
	v_or_b32_e32 v43, 1, v43
	v_cvt_pk_bf16_f32 v37, v48, v49
	global_store_dwordx2 v[46:47], v[34:35], off offset:128 sc1
	global_store_dwordx2 v[46:47], v[36:37], off offset:160 sc1
	v_mad_i64_i32 v[46:47], s[0:1], v43, s16, v[38:39]
	v_mad_u64_u32 v[48:49], s[0:1], v46, s47, v[44:45]
	v_mad_i32_i24 v49, v47, s47, v49
	v_lshl_add_u64 v[46:47], v[48:49], 0, v[40:41]
	v_mad_i32_i24 v43, v42, 6, 2
	global_store_dwordx2 v[46:47], v[34:35], off offset:128 sc1
	global_store_dwordx2 v[46:47], v[36:37], off offset:160 sc1
	v_mad_i64_i32 v[46:47], s[0:1], v43, s16, v[38:39]
	v_mad_u64_u32 v[48:49], s[0:1], v46, s47, v[44:45]
	v_mad_i32_i24 v49, v47, s47, v49
	v_lshl_add_u64 v[46:47], v[48:49], 0, v[40:41]
	v_mad_i32_i24 v43, v42, 6, 3
	global_store_dwordx2 v[46:47], v[34:35], off offset:128 sc1
	global_store_dwordx2 v[46:47], v[36:37], off offset:160 sc1
	v_mad_i64_i32 v[46:47], s[0:1], v43, s16, v[38:39]
	v_mad_u64_u32 v[48:49], s[0:1], v46, s47, v[44:45]
	v_mad_i32_i24 v49, v47, s47, v49
	v_lshl_add_u64 v[46:47], v[48:49], 0, v[40:41]
	v_mad_i32_i24 v43, v42, 6, 4
	v_mad_i32_i24 v42, v42, 6, 5
	global_store_dwordx2 v[46:47], v[34:35], off offset:128 sc1
	global_store_dwordx2 v[46:47], v[36:37], off offset:160 sc1
	v_mad_i64_i32 v[46:47], s[0:1], v43, s16, v[38:39]
	v_mad_i64_i32 v[38:39], s[0:1], v42, s16, v[38:39]
	v_mad_u64_u32 v[48:49], s[0:1], v46, s47, v[44:45]
	v_mad_u64_u32 v[42:43], s[0:1], v38, s47, v[44:45]
	v_mad_i32_i24 v49, v47, s47, v49
	v_mad_i32_i24 v43, v39, s47, v43
	v_lshl_add_u64 v[46:47], v[48:49], 0, v[40:41]
	v_lshl_add_u64 v[38:39], v[42:43], 0, v[40:41]
	global_store_dwordx2 v[46:47], v[34:35], off offset:128 sc1
	global_store_dwordx2 v[46:47], v[36:37], off offset:160 sc1
	global_store_dwordx2 v[38:39], v[34:35], off offset:128 sc1
	global_store_dwordx2 v[38:39], v[36:37], off offset:160 sc1

; __device__ __forceinline__ unsigned short f2bf(float f) { return (unsigned short)(cvt_pk_bf16(f, f) & 0xffffu); }
; __device__ __forceinline__ void store4bf(bf16_t* p, f32x4 v) { u32x2 w; w.x = cvt_pk_bf16(v[0], v[1]); w.y = cvt_pk_bf16(v[2], v[3]); *(u32x2*)p = w; }
;   __device__ __forceinline__ void group(int row, int c32, int fq, f32x4 v0, f32x4 v1) const {
;     int b, e; const bool ok = row_be(row, b, e);
;     if (c32 < 512) {
;       if (c32 < 384) store8bf(cqkv + (size_t)row * 512 + c32 + fq * 8, v0, v1);
;       else { bf16_t* p = cqkv + (size_t)row * 512 + c32 + fq * 4; store4bf(p, v0); store4bf(p + 16, v1); }
;       if (c32 == 384 && ok) {
;         const float2* rp = rope + pos_of_e(e) * 16 + fq * 4; f32x4 o0, o1;
; #pragma unroll
;         for (int j = 0; j < 4; ++j) { const float2 cs = rp[j]; o0[j] = v0[j] * cs.x - v1[j] * cs.y; o1[j] = v1[j] * cs.x + v0[j] * cs.y; }
; #pragma unroll
;         for (int h = 0; h < 6; ++h) { bf16_t* q = ka + ((size_t)(b * 6 + h) * E + e) * 96 + 64 + fq * 4; store4bf(q, o0); store4bf(q + 16, o1); }
;       }
;       return;
;     }
;     if (!ok) return;
;     if (c32 < 768) { const int cc = c32 - 512, h = cc >> 6; store8bf(qd + ((size_t)(b * 4 + h) * E + e) * 64 + (cc & 63) + fq * 8, v0 * QSC_D, v1 * QSC_D); }
;     else if (c32 < 1024) { const int cc = c32 - 768, h = cc >> 6; store8bf(kd + ((size_t)(b * 4 + h) * E + e) * 64 + (cc & 63) + fq * 8, v0, v1); }
;     else if (c32 < 1280) { const int cc = c32 - 1024, h = cc >> 6; bf16_t* p = vtd + ((size_t)(b * 4 + h) * 64 + (cc & 63) + fq * 4) * E + e;
; #pragma unroll
;       for (int j = 0; j < 4; ++j) { p[(size_t)j * E] = f2bf(v0[j]); p[(size_t)(j + 16) * E] = f2bf(v1[j]); } }
;     else if (c32 < 1664) { const int cc = c32 - 1280, h = cc >> 6; store8bf(qs + ((size_t)(b * 6 + h) * E + e) * 64 + (cc & 63) + fq * 8, v0 * QSC_S, v1 * QSC_S); }
;     else if (c32 < 1792) { const int cc = c32 - 1664, g = cc >> 6; store8bf(ks + ((size_t)(b * 2 + g) * E + e) * 64 + (cc & 63) + fq * 8, v0, v1); }
;     else if (c32 < 1920) { const int cc = c32 - 1792, g = cc >> 6; bf16_t* p = vts + ((size_t)(b * 2 + g) * 64 + (cc & 63) + fq * 4) * E + e;
; #pragma unroll
;       for (int j = 0; j < 4; ++j) { p[(size_t)j * E] = f2bf(v0[j]); p[(size_t)(j + 16) * E] = f2bf(v1[j]); } }
.LBB0_696:
	s_movk_i32 s0, 0x1fef
	v_or_b32_e32 v34, 32, v66
	v_bitop3_b32 v35, v66, s0, 32 bitop3:0xc8
	s_mov_b32 s0, 0x8000
	v_add_u32_e32 v35, 64, v35
	v_bfe_u32 v36, v34, 4, 2
	v_cmp_gt_i32_e64 s[16:17], s0, v34
	s_or_b64 s[40:41], s[16:17], s[12:13]
	s_and_b64 vcc, exec, s[14:15]
	v_cndmask_b32_e64 v42, v36, v72, s[16:17]
	v_cndmask_b32_e64 v38, v136, v35, s[16:17]
	s_mov_b64 s[42:43], -1
	s_cbranch_vccnz .LBB0_720
	s_and_saveexec_b64 s[44:45], s[40:41]
	s_cbranch_execz .LBB0_719
	s_andn2_b64 vcc, exec, s[38:39]
	s_cbranch_vccnz .LBB0_717
	s_andn2_b64 vcc, exec, s[24:25]
	s_cbranch_vccnz .LBB0_714
	s_andn2_b64 vcc, exec, s[20:21]
	s_cbranch_vccnz .LBB0_711
	s_and_saveexec_b64 s[0:1], s[8:9]
	s_xor_b64 s[68:69], exec, s[0:1]
	s_cbranch_execz .LBB0_708
	s_andn2_b64 vcc, exec, s[18:19]
	s_cbranch_vccnz .LBB0_706
	s_and_saveexec_b64 s[42:43], s[6:7]
	s_cbranch_execz .LBB0_705
	v_lshl_add_u32 v36, v42, 1, v110
	v_ashrrev_i32_e32 v37, 31, v36
	v_readlane_b32 s0, v254, 16
	v_lshlrev_b64 v[36:37], 6, v[36:37]
	v_readlane_b32 s1, v254, 17
	v_or_b32_e32 v35, v36, v140
	v_lshlrev_b32_e32 v36, 1, v38
	v_mov_b64_e32 v[40:41], s[0:1]
	v_mad_u64_u32 v[40:41], s[0:1], v35, s95, v[40:41]
	v_mad_i32_i24 v41, v37, s95, v41
	v_mov_b32_e32 v37, v1
	v_lshl_add_u64 v[36:37], v[40:41], 0, v[36:37]
	v_cvt_pk_bf16_f32 v35, v14, s0
	global_store_short v[36:37], v35, off sc1
	v_cvt_pk_bf16_f32 v35, v10, s0
	s_mov_b32 s0, 0x40000
	v_add_co_u32_e32 v40, vcc, s0, v36
	s_nop 1
	v_addc_co_u32_e32 v41, vcc, 0, v37, vcc
	global_store_short v[40:41], v35, off offset:2048 sc1
	v_cvt_pk_bf16_f32 v35, v15, s0
	s_movk_i32 s0, 0x4000
	v_add_co_u32_e32 v40, vcc, s0, v36
	s_nop 1
	v_addc_co_u32_e32 v41, vcc, 0, v37, vcc
	global_store_short v[40:41], v35, off offset:128 sc1
	v_cvt_pk_bf16_f32 v35, v11, s0
	s_mov_b32 s0, 0x44000
	v_add_co_u32_e32 v40, vcc, s0, v36
	s_nop 1
	v_addc_co_u32_e32 v41, vcc, 0, v37, vcc
	global_store_short v[40:41], v35, off offset:2176 sc1
	v_cvt_pk_bf16_f32 v35, v16, s0
	s_mov_b32 s0, 0x8000
	v_add_co_u32_e32 v40, vcc, s0, v36
	s_nop 1
	v_addc_co_u32_e32 v41, vcc, 0, v37, vcc
	global_store_short v[40:41], v35, off offset:256 sc1
	v_cvt_pk_bf16_f32 v35, v12, s0
	s_mov_b32 s0, 0x48000
	v_add_co_u32_e32 v40, vcc, s0, v36
	s_nop 1
	v_addc_co_u32_e32 v41, vcc, 0, v37, vcc
	global_store_short v[40:41], v35, off offset:2304 sc1
	v_add_co_u32_e32 v40, vcc, 0xc000, v36
	v_cvt_pk_bf16_f32 v35, v17, s0
	s_nop 0
	v_addc_co_u32_e32 v41, vcc, 0, v37, vcc
	v_add_co_u32_e32 v36, vcc, 0x4c000, v36
	global_store_short v[40:41], v35, off offset:384 sc1
	v_cvt_pk_bf16_f32 v35, v13, s0
	v_addc_co_u32_e32 v37, vcc, 0, v37, vcc
	global_store_short v[36:37], v35, off offset:2432 sc1

; __device__ __forceinline__ void store8bf(bf16_t* p, f32x4 v0, f32x4 v1) { u32x4 w; w.x = cvt_pk_bf16(v0[0], v0[1]); w.y = cvt_pk_bf16(v0[2], v0[3]); w.z = cvt_pk_bf16(v1[0], v1[1]); w.w = cvt_pk_bf16(v1[2], v1[3]); *(u32x4*)p = w; }
;   __device__ __forceinline__ void group(int row, int c32, int fq, f32x4 v0, f32x4 v1) const {
;     ...
;     else if (c32 < 1664) { const int cc = c32 - 1280, h = cc >> 6; store8bf(qs + ((size_t)(b * 6 + h) * E + e) * 64 + (cc & 63) + fq * 8, v0 * QSC_S, v1 * QSC_S); }
;     else if (c32 < 1792) { const int cc = c32 - 1664, g = cc >> 6; store8bf(ks + ((size_t)(b * 2 + g) * E + e) * 64 + (cc & 63) + fq * 8, v0, v1); }
.LBB0_706:
	s_andn2_b64 vcc, exec, s[42:43]
	s_cbranch_vccnz .LBB0_708
	v_lshl_add_u32 v35, v42, 1, v109
	v_mov_b32_e32 v39, v1
	s_movk_i32 s0, 0x2040
	v_mad_i64_i32 v[36:37], s[0:1], v35, s0, v[38:39]
	v_readlane_b32 s0, v254, 14
	v_lshlrev_b64 v[36:37], 7, v[36:37]
	v_readlane_b32 s1, v254, 15
	v_lshlrev_b32_e32 v40, 1, v137
	v_mov_b32_e32 v41, v1
	v_lshl_add_u64 v[36:37], s[0:1], 0, v[36:37]
	v_lshl_add_u64 v[36:37], v[36:37], 0, v[40:41]
	v_lshlrev_b32_e32 v40, 1, v139
	v_lshl_add_u64 v[36:37], v[36:37], 0, v[40:41]
	v_cvt_pk_bf16_f32 v44, v14, v15
	v_cvt_pk_bf16_f32 v45, v16, v17
	v_cvt_pk_bf16_f32 v46, v10, v11
	v_cvt_pk_bf16_f32 v47, v12, v13
	global_store_dwordx4 v[36:37], v[44:47], off sc1
.LBB0_708:
	s_andn2_saveexec_b64 s[42:43], s[68:69]
	s_cbranch_execz .LBB0_710
	v_mad_i32_i24 v35, v42, 6, v111
	v_mov_b32_e32 v39, v1
	s_movk_i32 s0, 0x2040
	v_mad_i64_i32 v[36:37], s[0:1], v35, s0, v[38:39]
	v_readlane_b32 s0, v254, 12
	v_lshlrev_b64 v[36:37], 7, v[36:37]
	v_readlane_b32 s1, v254, 13
	v_lshlrev_b32_e32 v40, 1, v137
	v_mov_b32_e32 v41, v1
	v_lshl_add_u64 v[36:37], s[0:1], 0, v[36:37]
	v_lshl_add_u64 v[36:37], v[36:37], 0, v[40:41]
	v_lshlrev_b32_e32 v40, 1, v139
	s_mov_b32 s0, 0x3e38aa3b
	v_lshl_add_u64 v[36:37], v[36:37], 0, v[40:41]
	v_pk_mul_f32 v[40:41], v[16:17], s[0:1] op_sel_hi:[1,0]
	v_pk_mul_f32 v[44:45], v[14:15], s[0:1] op_sel_hi:[1,0]
	v_pk_mul_f32 v[48:49], v[12:13], s[0:1] op_sel_hi:[1,0]
	v_pk_mul_f32 v[46:47], v[10:11], s[0:1] op_sel_hi:[1,0]
	v_cvt_pk_bf16_f32 v44, v44, v45
	v_cvt_pk_bf16_f32 v45, v40, v41
	v_cvt_pk_bf16_f32 v46, v46, v47
	v_cvt_pk_bf16_f32 v47, v48, v49
	global_store_dwordx4 v[36:37], v[44:47], off sc1

; __device__ __forceinline__ unsigned short f2bf(float f) { return (unsigned short)(cvt_pk_bf16(f, f) & 0xffffu); }
;   __device__ __forceinline__ void group(int row, int c32, int fq, f32x4 v0, f32x4 v1) const {
;     ...
;     else if (c32 < 1280) { const int cc = c32 - 1024, h = cc >> 6; bf16_t* p = vtd + ((size_t)(b * 4 + h) * 64 + (cc & 63) + fq * 4) * E + e;
; #pragma unroll
;       for (int j = 0; j < 4; ++j) { p[(size_t)j * E] = f2bf(v0[j]); p[(size_t)(j + 16) * E] = f2bf(v1[j]); } }
.LBB0_711:
	s_andn2_b64 vcc, exec, s[42:43]
	s_cbranch_vccnz .LBB0_713
	v_lshl_add_u32 v36, v42, 2, v106
	v_ashrrev_i32_e32 v37, 31, v36
	v_readlane_b32 s0, v254, 10
	v_lshlrev_b64 v[36:37], 6, v[36:37]
	v_readlane_b32 s1, v254, 11
	v_or_b32_e32 v35, v36, v140
	v_lshlrev_b32_e32 v36, 1, v38
	v_mov_b64_e32 v[40:41], s[0:1]
	v_mad_u64_u32 v[40:41], s[0:1], v35, s95, v[40:41]
	v_mad_i32_i24 v41, v37, s95, v41
	v_mov_b32_e32 v37, v1
	v_lshl_add_u64 v[36:37], v[40:41], 0, v[36:37]
	v_cvt_pk_bf16_f32 v35, v14, s0
	global_store_short v[36:37], v35, off sc1
	v_cvt_pk_bf16_f32 v35, v10, s0
	s_mov_b32 s0, 0x40000
	v_add_co_u32_e32 v40, vcc, s0, v36
	s_nop 1
	v_addc_co_u32_e32 v41, vcc, 0, v37, vcc
	global_store_short v[40:41], v35, off offset:2048 sc1
	v_cvt_pk_bf16_f32 v35, v15, s0
	s_movk_i32 s0, 0x4000
	v_add_co_u32_e32 v40, vcc, s0, v36
	s_nop 1
	v_addc_co_u32_e32 v41, vcc, 0, v37, vcc
	global_store_short v[40:41], v35, off offset:128 sc1
	v_cvt_pk_bf16_f32 v35, v11, s0
	s_mov_b32 s0, 0x44000
	v_add_co_u32_e32 v40, vcc, s0, v36
	s_nop 1
	v_addc_co_u32_e32 v41, vcc, 0, v37, vcc
	global_store_short v[40:41], v35, off offset:2176 sc1
	v_cvt_pk_bf16_f32 v35, v16, s0
	s_mov_b32 s0, 0x8000
	v_add_co_u32_e32 v40, vcc, s0, v36
	s_nop 1
	v_addc_co_u32_e32 v41, vcc, 0, v37, vcc
	global_store_short v[40:41], v35, off offset:256 sc1
	v_cvt_pk_bf16_f32 v35, v12, s0
	s_mov_b32 s0, 0x48000
	v_add_co_u32_e32 v40, vcc, s0, v36
	s_nop 1
	v_addc_co_u32_e32 v41, vcc, 0, v37, vcc
	global_store_short v[40:41], v35, off offset:2304 sc1
	v_add_co_u32_e32 v40, vcc, 0xc000, v36
	v_cvt_pk_bf16_f32 v35, v17, s0
	s_nop 0
	v_addc_co_u32_e32 v41, vcc, 0, v37, vcc
	v_add_co_u32_e32 v36, vcc, 0x4c000, v36
	global_store_short v[40:41], v35, off offset:384 sc1
	v_cvt_pk_bf16_f32 v35, v13, s0
	v_addc_co_u32_e32 v37, vcc, 0, v37, vcc
	global_store_short v[36:37], v35, off offset:2432 sc1

; __device__ __forceinline__ void store8bf(bf16_t* p, f32x4 v0, f32x4 v1) { u32x4 w; w.x = cvt_pk_bf16(v0[0], v0[1]); w.y = cvt_pk_bf16(v0[2], v0[3]); w.z = cvt_pk_bf16(v1[0], v1[1]); w.w = cvt_pk_bf16(v1[2], v1[3]); *(u32x4*)p = w; }
;   __device__ __forceinline__ void group(int row, int c32, int fq, f32x4 v0, f32x4 v1) const {
;     ...
;     else if (c32 < 1024) { const int cc = c32 - 768, h = cc >> 6; store8bf(kd + ((size_t)(b * 4 + h) * E + e) * 64 + (cc & 63) + fq * 8, v0, v1); }
.LBB0_714:
	s_andn2_b64 vcc, exec, s[42:43]
	s_cbranch_vccnz .LBB0_716
	v_lshl_add_u32 v35, v42, 2, v108
	v_mov_b32_e32 v39, v1
	s_movk_i32 s0, 0x2040
	v_mad_i64_i32 v[36:37], s[0:1], v35, s0, v[38:39]
	v_readlane_b32 s0, v254, 8
	v_lshlrev_b64 v[36:37], 7, v[36:37]
	v_readlane_b32 s1, v254, 9
	v_lshlrev_b32_e32 v40, 1, v137
	v_mov_b32_e32 v41, v1
	v_lshl_add_u64 v[36:37], s[0:1], 0, v[36:37]
	v_lshl_add_u64 v[36:37], v[36:37], 0, v[40:41]
	v_lshlrev_b32_e32 v40, 1, v139
	v_lshl_add_u64 v[36:37], v[36:37], 0, v[40:41]
	v_cvt_pk_bf16_f32 v44, v14, v15
	v_cvt_pk_bf16_f32 v45, v16, v17
	v_cvt_pk_bf16_f32 v46, v10, v11
	v_cvt_pk_bf16_f32 v47, v12, v13
	global_store_dwordx4 v[36:37], v[44:47], off sc1

; __device__ __forceinline__ void store8bf(bf16_t* p, f32x4 v0, f32x4 v1) { u32x4 w; w.x = cvt_pk_bf16(v0[0], v0[1]); w.y = cvt_pk_bf16(v0[2], v0[3]); w.z = cvt_pk_bf16(v1[0], v1[1]); w.w = cvt_pk_bf16(v1[2], v1[3]); *(u32x4*)p = w; }
;   __device__ __forceinline__ void group(int row, int c32, int fq, f32x4 v0, f32x4 v1) const {
;     ...
;     if (c32 < 768) { const int cc = c32 - 512, h = cc >> 6; store8bf(qd + ((size_t)(b * 4 + h) * E + e) * 64 + (cc & 63) + fq * 8, v0 * QSC_D, v1 * QSC_D); }
.LBB0_717:
	s_andn2_b64 vcc, exec, s[42:43]
	s_cbranch_vccnz .LBB0_719
	v_lshl_add_u32 v35, v42, 2, v107
	v_mov_b32_e32 v39, v1
	s_movk_i32 s0, 0x2040
	v_mad_i64_i32 v[36:37], s[0:1], v35, s0, v[38:39]
	v_readlane_b32 s0, v254, 6
	v_lshlrev_b64 v[36:37], 7, v[36:37]
	v_readlane_b32 s1, v254, 7
	v_lshlrev_b32_e32 v40, 1, v137
	v_mov_b32_e32 v41, v1
	v_lshl_add_u64 v[36:37], s[0:1], 0, v[36:37]
	v_lshl_add_u64 v[36:37], v[36:37], 0, v[40:41]
	v_lshlrev_b32_e32 v40, 1, v139
	s_mov_b32 s0, 0x3e8293ee
	v_lshl_add_u64 v[36:37], v[36:37], 0, v[40:41]
	v_pk_mul_f32 v[40:41], v[16:17], s[0:1] op_sel_hi:[1,0]
	v_pk_mul_f32 v[44:45], v[14:15], s[0:1] op_sel_hi:[1,0]
	v_pk_mul_f32 v[48:49], v[12:13], s[0:1] op_sel_hi:[1,0]
	v_pk_mul_f32 v[46:47], v[10:11], s[0:1] op_sel_hi:[1,0]
	v_cvt_pk_bf16_f32 v44, v44, v45
	v_cvt_pk_bf16_f32 v45, v40, v41
	v_cvt_pk_bf16_f32 v46, v46, v47
	v_cvt_pk_bf16_f32 v47, v48, v49
	global_store_dwordx4 v[36:37], v[44:47], off sc1

; __device__ __forceinline__ void store4bf(bf16_t* p, f32x4 v) { u32x2 w; w.x = cvt_pk_bf16(v[0], v[1]); w.y = cvt_pk_bf16(v[2], v[3]); *(u32x2*)p = w; }
; __device__ __forceinline__ void store8bf(bf16_t* p, f32x4 v0, f32x4 v1) { u32x4 w; w.x = cvt_pk_bf16(v0[0], v0[1]); w.y = cvt_pk_bf16(v0[2], v0[3]); w.z = cvt_pk_bf16(v1[0], v1[1]); w.w = cvt_pk_bf16(v1[2], v1[3]); *(u32x4*)p = w; }
;   __device__ __forceinline__ void group(int row, int c32, int fq, f32x4 v0, f32x4 v1) const {
;     ...
;     if (c32 < 512) {
;       if (c32 < 384) store8bf(cqkv + (size_t)row * 512 + c32 + fq * 8, v0, v1);
;       else { bf16_t* p = cqkv + (size_t)row * 512 + c32 + fq * 4; store4bf(p, v0); store4bf(p + 16, v1); }
.LBB0_720:
	s_andn2_b64 vcc, exec, s[42:43]
	s_cbranch_vccnz .LBB0_727
	v_ashrrev_i32_e32 v35, 31, v34
	v_readlane_b32 s0, v254, 0
	v_lshlrev_b64 v[34:35], 10, v[34:35]
	v_readlane_b32 s1, v254, 1
	s_and_b64 vcc, exec, s[10:11]
	v_cvt_pk_bf16_f32 v36, v10, v11
	v_lshl_add_u64 v[40:41], s[0:1], 0, v[34:35]
	v_cvt_pk_bf16_f32 v34, v14, v15
	v_cvt_pk_bf16_f32 v35, v16, v17
	v_cvt_pk_bf16_f32 v37, v12, v13
	s_cbranch_vccnz .LBB0_767
	v_mov_b32_e32 v44, v0
	v_mov_b32_e32 v45, v1
	v_lshl_add_u64 v[44:45], v[44:45], 1, v[40:41]
	v_lshlrev_b32_e32 v46, 1, v138
	v_mov_b32_e32 v47, v1
	v_lshl_add_u64 v[44:45], v[44:45], 0, v[46:47]
	global_store_dwordx2 v[44:45], v[34:35], off offset:256 sc1
	global_store_dwordx2 v[44:45], v[36:37], off offset:288 sc1
	s_cbranch_execnz .LBB0_724

; __device__ __forceinline__ void store4bf(bf16_t* p, f32x4 v) { u32x2 w; w.x = cvt_pk_bf16(v[0], v[1]); w.y = cvt_pk_bf16(v[2], v[3]); *(u32x2*)p = w; }
;   __device__ __forceinline__ void group(int row, int c32, int fq, f32x4 v0, f32x4 v1) const {
;     ...
;       if (c32 == 384 && ok) {
;         const float2* rp = rope + pos_of_e(e) * 16 + fq * 4; f32x4 o0, o1;
; #pragma unroll
;         for (int j = 0; j < 4; ++j) { const float2 cs = rp[j]; o0[j] = v0[j] * cs.x - v1[j] * cs.y; o1[j] = v1[j] * cs.x + v0[j] * cs.y; }
; #pragma unroll
;         for (int h = 0; h < 6; ++h) { bf16_t* q = ka + ((size_t)(b * 6 + h) * E + e) * 96 + 64 + fq * 4; store4bf(q, o0); store4bf(q + 16, o1); }
;       }
.LBB0_724:
	s_and_b64 s[0:1], s[4:5], s[40:41]
	s_and_saveexec_b64 s[40:41], s[0:1]
	s_cbranch_execz .LBB0_726
	v_lshlrev_b32_e32 v34, 4, v38
	v_add_u32_e32 v35, 0xfffffd00, v34
	v_readlane_b32 s0, v253, 40
	v_cndmask_b32_e64 v34, v34, v35, s[16:17]
	v_mov_b32_e32 v35, v1
	v_readlane_b32 s1, v253, 41
	v_lshlrev_b32_e32 v36, 3, v138
	v_mov_b32_e32 v37, v1
	v_lshl_add_u64 v[34:35], v[34:35], 3, s[0:1]
	v_lshl_add_u64 v[40:41], v[34:35], 0, v[36:37]
	global_load_dwordx4 v[34:37], v[40:41], off offset:16
	global_load_dwordx4 v[44:47], v[40:41], off
	v_mul_i32_i24_e32 v43, 6, v42
	v_mov_b32_e32 v39, v1
	s_movk_i32 s16, 0x2040
	s_waitcnt vmcnt(0)
	v_mov_b32_e32 v41, v46
	v_mov_b32_e32 v46, v45
	v_mov_b32_e32 v40, v44
	v_pk_mul_f32 v[44:45], v[14:15], v[46:47]
	v_pk_mul_f32 v[46:47], v[10:11], v[46:47]
	v_pk_fma_f32 v[44:45], v[10:11], v[40:41], v[44:45]
	v_pk_fma_f32 v[40:41], v[14:15], v[40:41], v[46:47] neg_lo:[0,0,1] neg_hi:[0,0,1]
	v_mov_b32_e32 v47, v36
	v_mov_b32_e32 v36, v35
	v_mov_b32_e32 v46, v34
	v_pk_mul_f32 v[34:35], v[16:17], v[36:37]
	s_nop 0
	v_pk_fma_f32 v[48:49], v[12:13], v[46:47], v[34:35]
	v_pk_mul_f32 v[34:35], v[12:13], v[36:37]
	s_nop 0
	v_pk_fma_f32 v[36:37], v[16:17], v[46:47], v[34:35] neg_lo:[0,0,1] neg_hi:[0,0,1]
	v_cvt_pk_bf16_f32 v34, v40, v41
	v_mad_i64_i32 v[40:41], s[0:1], v43, s16, v[38:39]
	v_readlane_b32 s0, v254, 4
	v_readlane_b32 s1, v254, 5
	v_cvt_pk_bf16_f32 v35, v36, v37
	v_cvt_pk_bf16_f32 v36, v44, v45
	v_mov_b64_e32 v[44:45], s[0:1]
	v_mad_u64_u32 v[46:47], s[0:1], v40, s47, v[44:45]
	v_mad_i32_i24 v47, v41, s47, v47
	v_lshlrev_b32_e32 v40, 1, v138
	v_mov_b32_e32 v41, v1
	v_lshl_add_u64 v[46:47], v[46:47], 0, v[40:41]
	v_or_b32_e32 v43, 1, v43
	v_cvt_pk_bf16_f32 v37, v48, v49
	global_store_dwordx2 v[46:47], v[34:35], off offset:128 sc1
	global_store_dwordx2 v[46:47], v[36:37], off offset:160 sc1
	v_mad_i64_i32 v[46:47], s[0:1], v43, s16, v[38:39]
	v_mad_u64_u32 v[48:49], s[0:1], v46, s47, v[44:45]
	v_mad_i32_i24 v49, v47, s47, v49
	v_lshl_add_u64 v[46:47], v[48:49], 0, v[40:41]
	v_mad_i32_i24 v43, v42, 6, 2
	global_store_dwordx2 v[46:47], v[34:35], off offset:128 sc1
	global_store_dwordx2 v[46:47], v[36:37], off offset:160 sc1
	v_mad_i64_i32 v[46:47], s[0:1], v43, s16, v[38:39]
	v_mad_u64_u32 v[48:49], s[0:1], v46, s47, v[44:45]
	v_mad_i32_i24 v49, v47, s47, v49
	v_lshl_add_u64 v[46:47], v[48:49], 0, v[40:41]
	v_mad_i32_i24 v43, v42, 6, 3
	global_store_dwordx2 v[46:47], v[34:35], off offset:128 sc1
	global_store_dwordx2 v[46:47], v[36:37], off offset:160 sc1
	v_mad_i64_i32 v[46:47], s[0:1], v43, s16, v[38:39]
	v_mad_u64_u32 v[48:49], s[0:1], v46, s47, v[44:45]
	v_mad_i32_i24 v49, v47, s47, v49
	v_lshl_add_u64 v[46:47], v[48:49], 0, v[40:41]
	v_mad_i32_i24 v43, v42, 6, 4
	v_mad_i32_i24 v42, v42, 6, 5
	global_store_dwordx2 v[46:47], v[34:35], off offset:128 sc1
	global_store_dwordx2 v[46:47], v[36:37], off offset:160 sc1
	v_mad_i64_i32 v[46:47], s[0:1], v43, s16, v[38:39]
	v_mad_i64_i32 v[38:39], s[0:1], v42, s16, v[38:39]
	v_mad_u64_u32 v[48:49], s[0:1], v46, s47, v[44:45]
	v_mad_u64_u32 v[42:43], s[0:1], v38, s47, v[44:45]
	v_mad_i32_i24 v49, v47, s47, v49
	v_mad_i32_i24 v43, v39, s47, v43
	v_lshl_add_u64 v[46:47], v[48:49], 0, v[40:41]
	v_lshl_add_u64 v[38:39], v[42:43], 0, v[40:41]
	global_store_dwordx2 v[46:47], v[34:35], off offset:128 sc1
	global_store_dwordx2 v[46:47], v[36:37], off offset:160 sc1
	global_store_dwordx2 v[38:39], v[34:35], off offset:128 sc1
	global_store_dwordx2 v[38:39], v[36:37], off offset:160 sc1

; __device__ __forceinline__ unsigned short f2bf(float f) { return (unsigned short)(cvt_pk_bf16(f, f) & 0xffffu); }
; __device__ __forceinline__ void store4bf(bf16_t* p, f32x4 v) { u32x2 w; w.x = cvt_pk_bf16(v[0], v[1]); w.y = cvt_pk_bf16(v[2], v[3]); *(u32x2*)p = w; }
;   __device__ __forceinline__ void group(int row, int c32, int fq, f32x4 v0, f32x4 v1) const {
;     int b, e; const bool ok = row_be(row, b, e);
;     if (c32 < 512) {
;       if (c32 < 384) store8bf(cqkv + (size_t)row * 512 + c32 + fq * 8, v0, v1);
;       else { bf16_t* p = cqkv + (size_t)row * 512 + c32 + fq * 4; store4bf(p, v0); store4bf(p + 16, v1); }
;       if (c32 == 384 && ok) {
;         const float2* rp = rope + pos_of_e(e) * 16 + fq * 4; f32x4 o0, o1;
; #pragma unroll
;         for (int j = 0; j < 4; ++j) { const float2 cs = rp[j]; o0[j] = v0[j] * cs.x - v1[j] * cs.y; o1[j] = v1[j] * cs.x + v0[j] * cs.y; }
; #pragma unroll
;         for (int h = 0; h < 6; ++h) { bf16_t* q = ka + ((size_t)(b * 6 + h) * E + e) * 96 + 64 + fq * 4; store4bf(q, o0); store4bf(q + 16, o1); }
;       }
;       return;
;     }
;     if (!ok) return;
;     if (c32 < 768) { const int cc = c32 - 512, h = cc >> 6; store8bf(qd + ((size_t)(b * 4 + h) * E + e) * 64 + (cc & 63) + fq * 8, v0 * QSC_D, v1 * QSC_D); }
;     else if (c32 < 1024) { const int cc = c32 - 768, h = cc >> 6; store8bf(kd + ((size_t)(b * 4 + h) * E + e) * 64 + (cc & 63) + fq * 8, v0, v1); }
;     else if (c32 < 1280) { const int cc = c32 - 1024, h = cc >> 6; bf16_t* p = vtd + ((size_t)(b * 4 + h) * 64 + (cc & 63) + fq * 4) * E + e;
; #pragma unroll
;       for (int j = 0; j < 4; ++j) { p[(size_t)j * E] = f2bf(v0[j]); p[(size_t)(j + 16) * E] = f2bf(v1[j]); } }
;     else if (c32 < 1664) { const int cc = c32 - 1280, h = cc >> 6; store8bf(qs + ((size_t)(b * 6 + h) * E + e) * 64 + (cc & 63) + fq * 8, v0 * QSC_S, v1 * QSC_S); }
;     else if (c32 < 1792) { const int cc = c32 - 1664, g = cc >> 6; store8bf(ks + ((size_t)(b * 2 + g) * E + e) * 64 + (cc & 63) + fq * 8, v0, v1); }
;     else if (c32 < 1920) { const int cc = c32 - 1792, g = cc >> 6; bf16_t* p = vts + ((size_t)(b * 2 + g) * 64 + (cc & 63) + fq * 4) * E + e;
; #pragma unroll
;       for (int j = 0; j < 4; ++j) { p[(size_t)j * E] = f2bf(v0[j]); p[(size_t)(j + 16) * E] = f2bf(v1[j]); } }
.LBB0_727:
	s_movk_i32 s0, 0x1fff
	v_or_b32_e32 v34, 48, v66
	v_bitop3_b32 v35, v66, s0, 48 bitop3:0xc8
	s_mov_b32 s0, 0x8000
	v_add_u32_e32 v35, 64, v35
	v_cmp_gt_i32_e64 s[16:17], s0, v34
	s_or_b64 s[12:13], s[16:17], s[12:13]
	s_and_b64 vcc, exec, s[14:15]
	v_cndmask_b32_e64 v44, 3, v72, s[16:17]
	v_cndmask_b32_e64 v38, v136, v35, s[16:17]
	s_mov_b64 s[14:15], -1
	s_cbranch_vccnz .LBB0_751
	s_and_saveexec_b64 s[14:15], s[12:13]
	s_cbranch_execz .LBB0_750
	s_andn2_b64 vcc, exec, s[38:39]
	s_mov_b64 s[38:39], -1
	s_cbranch_vccnz .LBB0_748
	s_andn2_b64 vcc, exec, s[24:25]
	s_mov_b64 s[24:25], -1
	s_cbranch_vccnz .LBB0_745
	s_andn2_b64 vcc, exec, s[20:21]
	s_mov_b64 s[20:21], -1
	s_cbranch_vccnz .LBB0_742
	s_and_saveexec_b64 s[0:1], s[8:9]
	s_xor_b64 s[8:9], exec, s[0:1]
	s_cbranch_execz .LBB0_739
	s_andn2_b64 vcc, exec, s[18:19]
	s_mov_b64 s[18:19], -1
	s_cbranch_vccnz .LBB0_737
	s_and_saveexec_b64 s[18:19], s[6:7]
	s_cbranch_execz .LBB0_736
	v_lshl_add_u32 v36, v44, 1, v110
	v_ashrrev_i32_e32 v37, 31, v36
	v_readlane_b32 s0, v254, 16
	v_lshlrev_b64 v[36:37], 6, v[36:37]
	v_readlane_b32 s1, v254, 17
	v_or_b32_e32 v35, v36, v140
	v_lshlrev_b32_e32 v36, 1, v38
	v_mov_b64_e32 v[40:41], s[0:1]
	v_mad_u64_u32 v[40:41], s[0:1], v35, s95, v[40:41]
	v_mad_i32_i24 v41, v37, s95, v41
	v_mov_b32_e32 v37, v1
	v_lshl_add_u64 v[36:37], v[40:41], 0, v[36:37]
	v_cvt_pk_bf16_f32 v35, v6, s0
	global_store_short v[36:37], v35, off sc1
	v_cvt_pk_bf16_f32 v35, v2, s0
	s_mov_b32 s0, 0x40000
	v_add_co_u32_e32 v40, vcc, s0, v36
	s_nop 1
	v_addc_co_u32_e32 v41, vcc, 0, v37, vcc
	global_store_short v[40:41], v35, off offset:2048 sc1
	v_cvt_pk_bf16_f32 v35, v7, s0
	s_movk_i32 s0, 0x4000
	v_add_co_u32_e32 v40, vcc, s0, v36
	s_nop 1
	v_addc_co_u32_e32 v41, vcc, 0, v37, vcc
	global_store_short v[40:41], v35, off offset:128 sc1
	v_cvt_pk_bf16_f32 v35, v3, s0
	s_mov_b32 s0, 0x44000
	v_add_co_u32_e32 v40, vcc, s0, v36
	s_nop 1
	v_addc_co_u32_e32 v41, vcc, 0, v37, vcc
	global_store_short v[40:41], v35, off offset:2176 sc1
	v_cvt_pk_bf16_f32 v35, v8, s0
	s_mov_b32 s0, 0x8000
	v_add_co_u32_e32 v40, vcc, s0, v36
	s_nop 1
	v_addc_co_u32_e32 v41, vcc, 0, v37, vcc
	global_store_short v[40:41], v35, off offset:256 sc1
	v_cvt_pk_bf16_f32 v35, v4, s0
	s_mov_b32 s0, 0x48000
	v_add_co_u32_e32 v40, vcc, s0, v36
	s_nop 1
	v_addc_co_u32_e32 v41, vcc, 0, v37, vcc
	global_store_short v[40:41], v35, off offset:2304 sc1
	v_add_co_u32_e32 v40, vcc, 0xc000, v36
	v_cvt_pk_bf16_f32 v35, v9, s0
	s_nop 0
	v_addc_co_u32_e32 v41, vcc, 0, v37, vcc
	v_add_co_u32_e32 v36, vcc, 0x4c000, v36
	global_store_short v[40:41], v35, off offset:384 sc1
	v_cvt_pk_bf16_f32 v35, v5, s0
	v_addc_co_u32_e32 v37, vcc, 0, v37, vcc
	global_store_short v[36:37], v35, off offset:2432 sc1

; __device__ __forceinline__ void store8bf(bf16_t* p, f32x4 v0, f32x4 v1) { u32x4 w; w.x = cvt_pk_bf16(v0[0], v0[1]); w.y = cvt_pk_bf16(v0[2], v0[3]); w.z = cvt_pk_bf16(v1[0], v1[1]); w.w = cvt_pk_bf16(v1[2], v1[3]); *(u32x4*)p = w; }
;   __device__ __forceinline__ void group(int row, int c32, int fq, f32x4 v0, f32x4 v1) const {
;     ...
;     else if (c32 < 1664) { const int cc = c32 - 1280, h = cc >> 6; store8bf(qs + ((size_t)(b * 6 + h) * E + e) * 64 + (cc & 63) + fq * 8, v0 * QSC_S, v1 * QSC_S); }
;     else if (c32 < 1792) { const int cc = c32 - 1664, g = cc >> 6; store8bf(ks + ((size_t)(b * 2 + g) * E + e) * 64 + (cc & 63) + fq * 8, v0, v1); }
.LBB0_737:
	s_andn2_b64 vcc, exec, s[18:19]
	s_cbranch_vccnz .LBB0_739
	v_lshl_add_u32 v35, v44, 1, v109
	v_mov_b32_e32 v39, v1
	s_movk_i32 s0, 0x2040
	v_mad_i64_i32 v[36:37], s[0:1], v35, s0, v[38:39]
	v_readlane_b32 s0, v254, 14
	v_lshlrev_b64 v[36:37], 7, v[36:37]
	v_readlane_b32 s1, v254, 15
	v_lshlrev_b32_e32 v40, 1, v137
	v_mov_b32_e32 v41, v1
	v_lshl_add_u64 v[36:37], s[0:1], 0, v[36:37]
	v_lshl_add_u64 v[36:37], v[36:37], 0, v[40:41]
	v_lshlrev_b32_e32 v40, 1, v139
	v_lshl_add_u64 v[36:37], v[36:37], 0, v[40:41]
	v_cvt_pk_bf16_f32 v40, v6, v7
	v_cvt_pk_bf16_f32 v41, v8, v9
	v_cvt_pk_bf16_f32 v42, v2, v3
	v_cvt_pk_bf16_f32 v43, v4, v5
	global_store_dwordx4 v[36:37], v[40:43], off sc1
.LBB0_739:
	s_andn2_saveexec_b64 s[6:7], s[8:9]
	s_cbranch_execz .LBB0_741
	v_mad_i32_i24 v35, v44, 6, v111
	v_mov_b32_e32 v39, v1
	s_movk_i32 s0, 0x2040
	v_mad_i64_i32 v[36:37], s[0:1], v35, s0, v[38:39]
	v_readlane_b32 s0, v254, 12
	v_lshlrev_b64 v[36:37], 7, v[36:37]
	v_readlane_b32 s1, v254, 13
	v_lshlrev_b32_e32 v40, 1, v137
	v_mov_b32_e32 v41, v1
	v_lshl_add_u64 v[36:37], s[0:1], 0, v[36:37]
	v_lshl_add_u64 v[36:37], v[36:37], 0, v[40:41]
	v_lshlrev_b32_e32 v40, 1, v139
	s_mov_b32 s0, 0x3e38aa3b
	v_lshl_add_u64 v[36:37], v[36:37], 0, v[40:41]
	v_pk_mul_f32 v[42:43], v[8:9], s[0:1] op_sel_hi:[1,0]
	v_pk_mul_f32 v[40:41], v[6:7], s[0:1] op_sel_hi:[1,0]
	v_pk_mul_f32 v[46:47], v[4:5], s[0:1] op_sel_hi:[1,0]
	v_pk_mul_f32 v[48:49], v[2:3], s[0:1] op_sel_hi:[1,0]
	v_cvt_pk_bf16_f32 v40, v40, v41
	v_cvt_pk_bf16_f32 v41, v42, v43
	v_cvt_pk_bf16_f32 v42, v48, v49
	v_cvt_pk_bf16_f32 v43, v46, v47
	global_store_dwordx4 v[36:37], v[40:43], off sc1

; __device__ __forceinline__ unsigned short f2bf(float f) { return (unsigned short)(cvt_pk_bf16(f, f) & 0xffffu); }
;   __device__ __forceinline__ void group(int row, int c32, int fq, f32x4 v0, f32x4 v1) const {
;     ...
;     else if (c32 < 1280) { const int cc = c32 - 1024, h = cc >> 6; bf16_t* p = vtd + ((size_t)(b * 4 + h) * 64 + (cc & 63) + fq * 4) * E + e;
; #pragma unroll
;       for (int j = 0; j < 4; ++j) { p[(size_t)j * E] = f2bf(v0[j]); p[(size_t)(j + 16) * E] = f2bf(v1[j]); } }
.LBB0_742:
	s_andn2_b64 vcc, exec, s[20:21]
	s_cbranch_vccnz .LBB0_744
	v_lshl_add_u32 v36, v44, 2, v106
	v_ashrrev_i32_e32 v37, 31, v36
	v_readlane_b32 s0, v254, 10
	v_lshlrev_b64 v[36:37], 6, v[36:37]
	v_readlane_b32 s1, v254, 11
	v_or_b32_e32 v35, v36, v140
	v_lshlrev_b32_e32 v36, 1, v38
	v_mov_b64_e32 v[40:41], s[0:1]
	v_mad_u64_u32 v[40:41], s[0:1], v35, s95, v[40:41]
	v_mad_i32_i24 v41, v37, s95, v41
	v_mov_b32_e32 v37, v1
	v_lshl_add_u64 v[36:37], v[40:41], 0, v[36:37]
	v_cvt_pk_bf16_f32 v35, v6, s0
	global_store_short v[36:37], v35, off sc1
	v_cvt_pk_bf16_f32 v35, v2, s0
	s_mov_b32 s0, 0x40000
	v_add_co_u32_e32 v40, vcc, s0, v36
	s_nop 1
	v_addc_co_u32_e32 v41, vcc, 0, v37, vcc
	global_store_short v[40:41], v35, off offset:2048 sc1
	v_cvt_pk_bf16_f32 v35, v7, s0
	s_movk_i32 s0, 0x4000
	v_add_co_u32_e32 v40, vcc, s0, v36
	s_nop 1
	v_addc_co_u32_e32 v41, vcc, 0, v37, vcc
	global_store_short v[40:41], v35, off offset:128 sc1
	v_cvt_pk_bf16_f32 v35, v3, s0
	s_mov_b32 s0, 0x44000
	v_add_co_u32_e32 v40, vcc, s0, v36
	s_nop 1
	v_addc_co_u32_e32 v41, vcc, 0, v37, vcc
	global_store_short v[40:41], v35, off offset:2176 sc1
	v_cvt_pk_bf16_f32 v35, v8, s0
	s_mov_b32 s0, 0x8000
	v_add_co_u32_e32 v40, vcc, s0, v36
	s_nop 1
	v_addc_co_u32_e32 v41, vcc, 0, v37, vcc
	global_store_short v[40:41], v35, off offset:256 sc1
	v_cvt_pk_bf16_f32 v35, v4, s0
	s_mov_b32 s0, 0x48000
	v_add_co_u32_e32 v40, vcc, s0, v36
	s_nop 1
	v_addc_co_u32_e32 v41, vcc, 0, v37, vcc
	global_store_short v[40:41], v35, off offset:2304 sc1
	v_add_co_u32_e32 v40, vcc, 0xc000, v36
	v_cvt_pk_bf16_f32 v35, v9, s0
	s_nop 0
	v_addc_co_u32_e32 v41, vcc, 0, v37, vcc
	v_add_co_u32_e32 v36, vcc, 0x4c000, v36
	global_store_short v[40:41], v35, off offset:384 sc1
	v_cvt_pk_bf16_f32 v35, v5, s0
	v_addc_co_u32_e32 v37, vcc, 0, v37, vcc
	global_store_short v[36:37], v35, off offset:2432 sc1

; __device__ __forceinline__ void store8bf(bf16_t* p, f32x4 v0, f32x4 v1) { u32x4 w; w.x = cvt_pk_bf16(v0[0], v0[1]); w.y = cvt_pk_bf16(v0[2], v0[3]); w.z = cvt_pk_bf16(v1[0], v1[1]); w.w = cvt_pk_bf16(v1[2], v1[3]); *(u32x4*)p = w; }
;   __device__ __forceinline__ void group(int row, int c32, int fq, f32x4 v0, f32x4 v1) const {
;     ...
;     else if (c32 < 1024) { const int cc = c32 - 768, h = cc >> 6; store8bf(kd + ((size_t)(b * 4 + h) * E + e) * 64 + (cc & 63) + fq * 8, v0, v1); }
.LBB0_745:
	s_andn2_b64 vcc, exec, s[24:25]
	s_cbranch_vccnz .LBB0_747
	v_lshl_add_u32 v35, v44, 2, v108
	v_mov_b32_e32 v39, v1
	s_movk_i32 s0, 0x2040
	v_mad_i64_i32 v[36:37], s[0:1], v35, s0, v[38:39]
	v_readlane_b32 s0, v254, 8
	v_lshlrev_b64 v[36:37], 7, v[36:37]
	v_readlane_b32 s1, v254, 9
	v_lshlrev_b32_e32 v40, 1, v137
	v_mov_b32_e32 v41, v1
	v_lshl_add_u64 v[36:37], s[0:1], 0, v[36:37]
	v_lshl_add_u64 v[36:37], v[36:37], 0, v[40:41]
	v_lshlrev_b32_e32 v40, 1, v139
	v_lshl_add_u64 v[36:37], v[36:37], 0, v[40:41]
	v_cvt_pk_bf16_f32 v40, v6, v7
	v_cvt_pk_bf16_f32 v41, v8, v9
	v_cvt_pk_bf16_f32 v42, v2, v3
	v_cvt_pk_bf16_f32 v43, v4, v5
	global_store_dwordx4 v[36:37], v[40:43], off sc1

; __device__ __forceinline__ void store8bf(bf16_t* p, f32x4 v0, f32x4 v1) { u32x4 w; w.x = cvt_pk_bf16(v0[0], v0[1]); w.y = cvt_pk_bf16(v0[2], v0[3]); w.z = cvt_pk_bf16(v1[0], v1[1]); w.w = cvt_pk_bf16(v1[2], v1[3]); *(u32x4*)p = w; }
;   __device__ __forceinline__ void group(int row, int c32, int fq, f32x4 v0, f32x4 v1) const {
;     ...
;     if (c32 < 768) { const int cc = c32 - 512, h = cc >> 6; store8bf(qd + ((size_t)(b * 4 + h) * E + e) * 64 + (cc & 63) + fq * 8, v0 * QSC_D, v1 * QSC_D); }
.LBB0_748:
	s_andn2_b64 vcc, exec, s[38:39]
	s_cbranch_vccnz .LBB0_750
	v_lshl_add_u32 v35, v44, 2, v107
	v_mov_b32_e32 v39, v1
	s_movk_i32 s0, 0x2040
	v_mad_i64_i32 v[36:37], s[0:1], v35, s0, v[38:39]
	v_readlane_b32 s0, v254, 6
	v_lshlrev_b64 v[36:37], 7, v[36:37]
	v_readlane_b32 s1, v254, 7
	v_lshlrev_b32_e32 v40, 1, v137
	v_mov_b32_e32 v41, v1
	v_lshl_add_u64 v[36:37], s[0:1], 0, v[36:37]
	v_lshl_add_u64 v[36:37], v[36:37], 0, v[40:41]
	v_lshlrev_b32_e32 v40, 1, v139
	s_mov_b32 s0, 0x3e8293ee
	v_lshl_add_u64 v[36:37], v[36:37], 0, v[40:41]
	v_pk_mul_f32 v[42:43], v[8:9], s[0:1] op_sel_hi:[1,0]
	v_pk_mul_f32 v[40:41], v[6:7], s[0:1] op_sel_hi:[1,0]
	v_pk_mul_f32 v[46:47], v[4:5], s[0:1] op_sel_hi:[1,0]
	v_pk_mul_f32 v[48:49], v[2:3], s[0:1] op_sel_hi:[1,0]
	v_cvt_pk_bf16_f32 v40, v40, v41
	v_cvt_pk_bf16_f32 v41, v42, v43
	v_cvt_pk_bf16_f32 v42, v48, v49
	v_cvt_pk_bf16_f32 v43, v46, v47
	global_store_dwordx4 v[36:37], v[40:43], off sc1

; __device__ __forceinline__ void store4bf(bf16_t* p, f32x4 v) { u32x2 w; w.x = cvt_pk_bf16(v[0], v[1]); w.y = cvt_pk_bf16(v[2], v[3]); *(u32x2*)p = w; }
; __device__ __forceinline__ void store8bf(bf16_t* p, f32x4 v0, f32x4 v1) { u32x4 w; w.x = cvt_pk_bf16(v0[0], v0[1]); w.y = cvt_pk_bf16(v0[2], v0[3]); w.z = cvt_pk_bf16(v1[0], v1[1]); w.w = cvt_pk_bf16(v1[2], v1[3]); *(u32x4*)p = w; }
;   __device__ __forceinline__ void group(int row, int c32, int fq, f32x4 v0, f32x4 v1) const {
;     ...
;     if (c32 < 512) {
;       if (c32 < 384) store8bf(cqkv + (size_t)row * 512 + c32 + fq * 8, v0, v1);
;       else { bf16_t* p = cqkv + (size_t)row * 512 + c32 + fq * 4; store4bf(p, v0); store4bf(p + 16, v1); }
;       if (c32 == 384 && ok) {
;         const float2* rp = rope + pos_of_e(e) * 16 + fq * 4; f32x4 o0, o1;
; #pragma unroll
;         for (int j = 0; j < 4; ++j) { const float2 cs = rp[j]; o0[j] = v0[j] * cs.x - v1[j] * cs.y; o1[j] = v1[j] * cs.x + v0[j] * cs.y; }
; #pragma unroll
;         for (int h = 0; h < 6; ++h) { bf16_t* q = ka + ((size_t)(b * 6 + h) * E + e) * 96 + 64 + fq * 4; store4bf(q, o0); store4bf(q + 16, o1); }
;       }
.LBB0_751:
	s_andn2_b64 vcc, exec, s[14:15]
	s_cbranch_vccnz .LBB0_758
	v_ashrrev_i32_e32 v35, 31, v34
	v_readlane_b32 s0, v254, 0
	v_lshlrev_b64 v[34:35], 10, v[34:35]
	v_readlane_b32 s1, v254, 1
	s_and_b64 vcc, exec, s[10:11]
	v_lshlrev_b32_e32 v40, 1, v138
	v_lshl_add_u64 v[42:43], s[0:1], 0, v[34:35]
	v_cvt_pk_bf16_f32 v34, v6, v7
	v_cvt_pk_bf16_f32 v35, v8, v9
	v_cvt_pk_bf16_f32 v36, v2, v3
	v_cvt_pk_bf16_f32 v37, v4, v5
	s_cbranch_vccnz .LBB0_768
	v_mov_b32_e32 v46, v0
	v_mov_b32_e32 v47, v1
	v_lshl_add_u64 v[46:47], v[46:47], 1, v[42:43]
	v_mov_b32_e32 v41, v1
	v_lshl_add_u64 v[46:47], v[46:47], 0, v[40:41]
	global_store_dwordx2 v[46:47], v[34:35], off offset:256 sc1
	global_store_dwordx2 v[46:47], v[36:37], off offset:288 sc1
	s_cbranch_execnz .LBB0_755
.LBB0_754:
	v_mov_b32_e32 v46, v0
	v_mov_b32_e32 v47, v1
	v_lshl_add_u64 v[42:43], v[46:47], 1, v[42:43]
	v_lshlrev_b32_e32 v46, 1, v139
	v_lshl_add_u64 v[42:43], v[42:43], 0, v[46:47]
	global_store_dwordx4 v[42:43], v[34:37], off offset:256 sc1
.LBB0_755:
	s_and_b64 s[0:1], s[4:5], s[12:13]
	s_and_saveexec_b64 s[4:5], s[0:1]
	s_cbranch_execz .LBB0_757
	v_lshlrev_b32_e32 v0, 4, v38
	v_add_u32_e32 v34, 0xfffffd00, v0
	v_readlane_b32 s0, v253, 40
	v_cndmask_b32_e64 v34, v0, v34, s[16:17]
	v_mov_b32_e32 v35, v1
	v_readlane_b32 s1, v253, 41
	v_lshlrev_b32_e32 v36, 3, v138
	v_mov_b32_e32 v37, v1
	v_lshl_add_u64 v[34:35], v[34:35], 3, s[0:1]
	v_lshl_add_u64 v[42:43], v[34:35], 0, v[36:37]
	global_load_dwordx4 v[34:37], v[42:43], off offset:16
	global_load_dwordx4 v[46:49], v[42:43], off
	v_mul_i32_i24_e32 v0, 6, v44
	v_mov_b32_e32 v39, v1
	s_movk_i32 s6, 0x2040
	v_mov_b32_e32 v41, v1
	s_waitcnt vmcnt(0)
	v_mov_b32_e32 v43, v48
	v_mov_b32_e32 v48, v47
	v_mov_b32_e32 v42, v46
	v_pk_mul_f32 v[46:47], v[6:7], v[48:49]
	v_pk_mul_f32 v[48:49], v[2:3], v[48:49]
	v_pk_fma_f32 v[46:47], v[2:3], v[42:43], v[46:47]
	v_pk_fma_f32 v[42:43], v[6:7], v[42:43], v[48:49] neg_lo:[0,0,1] neg_hi:[0,0,1]
	v_mov_b32_e32 v49, v36
	v_mov_b32_e32 v36, v35
	v_mov_b32_e32 v48, v34
	v_pk_mul_f32 v[34:35], v[8:9], v[36:37]
	s_nop 0
	v_pk_fma_f32 v[50:51], v[4:5], v[48:49], v[34:35]
	v_pk_mul_f32 v[34:35], v[4:5], v[36:37]
	s_nop 0
	v_pk_fma_f32 v[36:37], v[8:9], v[48:49], v[34:35] neg_lo:[0,0,1] neg_hi:[0,0,1]
	v_cvt_pk_bf16_f32 v34, v42, v43
	v_mad_i64_i32 v[42:43], s[0:1], v0, s6, v[38:39]
	v_readlane_b32 s0, v254, 4
	v_readlane_b32 s1, v254, 5
	v_cvt_pk_bf16_f32 v35, v36, v37
	v_cvt_pk_bf16_f32 v36, v46, v47
	v_mov_b64_e32 v[46:47], s[0:1]
	v_mad_u64_u32 v[48:49], s[0:1], v42, s47, v[46:47]
	v_mad_i32_i24 v49, v43, s47, v49
	v_lshl_add_u64 v[42:43], v[48:49], 0, v[40:41]
	v_or_b32_e32 v0, 1, v0
	v_cvt_pk_bf16_f32 v37, v50, v51
	global_store_dwordx2 v[42:43], v[34:35], off offset:128 sc1
	global_store_dwordx2 v[42:43], v[36:37], off offset:160 sc1
	v_mad_i64_i32 v[42:43], s[0:1], v0, s6, v[38:39]
	v_mad_u64_u32 v[48:49], s[0:1], v42, s47, v[46:47]
	v_mad_i32_i24 v49, v43, s47, v49
	v_lshl_add_u64 v[42:43], v[48:49], 0, v[40:41]
	v_mad_i32_i24 v0, v44, 6, 2
	global_store_dwordx2 v[42:43], v[34:35], off offset:128 sc1
	global_store_dwordx2 v[42:43], v[36:37], off offset:160 sc1
	v_mad_i64_i32 v[42:43], s[0:1], v0, s6, v[38:39]
	v_mad_u64_u32 v[48:49], s[0:1], v42, s47, v[46:47]
	v_mad_i32_i24 v49, v43, s47, v49
	v_lshl_add_u64 v[42:43], v[48:49], 0, v[40:41]
	v_mad_i32_i24 v0, v44, 6, 3
	global_store_dwordx2 v[42:43], v[34:35], off offset:128 sc1
	global_store_dwordx2 v[42:43], v[36:37], off offset:160 sc1
	v_mad_i64_i32 v[42:43], s[0:1], v0, s6, v[38:39]
	v_mad_u64_u32 v[48:49], s[0:1], v42, s47, v[46:47]
	v_mad_i32_i24 v49, v43, s47, v49
	v_lshl_add_u64 v[42:43], v[48:49], 0, v[40:41]
	v_mad_i32_i24 v0, v44, 6, 4
	global_store_dwordx2 v[42:43], v[34:35], off offset:128 sc1
	global_store_dwordx2 v[42:43], v[36:37], off offset:160 sc1
	v_mad_i64_i32 v[42:43], s[0:1], v0, s6, v[38:39]
	v_mad_u64_u32 v[48:49], s[0:1], v42, s47, v[46:47]
	v_mad_i32_i24 v49, v43, s47, v49
	v_mad_i32_i24 v0, v44, 6, 5
	v_lshl_add_u64 v[42:43], v[48:49], 0, v[40:41]
	v_mad_i64_i32 v[38:39], s[0:1], v0, s6, v[38:39]
	global_store_dwordx2 v[42:43], v[34:35], off offset:128 sc1
	global_store_dwordx2 v[42:43], v[36:37], off offset:160 sc1
	v_mad_u64_u32 v[42:43], s[0:1], v38, s47, v[46:47]
	v_mad_i32_i24 v43, v39, s47, v43
	v_lshl_add_u64 v[38:39], v[42:43], 0, v[40:41]
	global_store_dwordx2 v[38:39], v[34:35], off offset:128 sc1
	global_store_dwordx2 v[38:39], v[36:37], off offset:160 sc1

; template <class Epi, class Pre>
; __device__ __forceinline__ void meta_gemm(const bf16_t* __restrict__ A, int lda, const bf16_t* __restrict__ Bt, int ldb, int N, int K, Epi& epi, Pre pre) {
;     ...
;     const bf16_t* ap = A + (size_t)(NREAL + fr) * lda + wid * ks + fq * 8;
;     const bf16_t* bp = Bt + (size_t)(cb + fr) * ldb + wid * ks + fq * 8;
; #pragma unroll 4
;     for (int k0 = 0; k0 < ks; k0 += 32) {
;       const bf16x8 a = *(const bf16x8*)(ap + k0);
; #pragma unroll
;       for (int bj = 0; bj < 2; ++bj)
; #pragma unroll
;         for (int n = 0; n < 2; ++n) { const bf16x8 b = *(const bf16x8*)(bp + (size_t)(bj * 128 + n * 16) * ldb + k0); acc[bj][n] = __builtin_amdgcn_mfma_f32_16x16x32_bf16(b, a, acc[bj][n], 0, 0, 0); }
;     }
; #pragma unroll
;     for (int bj = 0; bj < 2; ++bj)
; #pragma unroll
;       for (int n = 0; n < 2; ++n)
; #pragma unroll
;         for (int j = 0; j < 4; ++j) part[(wid * 16 + (bj * 2 + n) * 4 + j) * 64 + lane] = acc[bj][n][j];
;     __syncthreads();
;     if (wid < 4) {
;       f32x4 v[2][2];
; #pragma unroll
;       for (int bj = 0; bj < 2; ++bj)
; #pragma unroll
;         for (int n = 0; n < 2; ++n)
; #pragma unroll
;           for (int j = 0; j < 4; ++j) { float s = 0.f;
; #pragma unroll
;             for (int w = 0; w < 8; ++w) s += part[(w * 16 + (bj * 2 + n) * 4 + j) * 64 + lane];
.LBB0_782:
	s_and_b32 s8, s1, 0x60
	s_and_b32 s14, s0, 0xffffff00
	s_or_b32 s13, s14, s8
	v_or_b32_e32 v6, s13, v110
	v_ashrrev_i32_e32 v7, 31, v6
	v_lshlrev_b64 v[6:7], 9, v[6:7]
	v_lshl_add_u64 v[18:19], v[22:23], 0, v[6:7]
	v_add_co_u32_e32 v10, vcc, 0x2000, v18
	s_mov_b32 s8, 0x10000
	s_nop 0
	v_addc_co_u32_e32 v11, vcc, 0, v19, vcc
	global_load_dwordx4 v[6:9], v[18:19], off
	v_add_co_u32_e32 v14, vcc, s8, v18
	global_load_dwordx4 v[10:13], v[10:11], off
	s_nop 0
	v_addc_co_u32_e32 v15, vcc, 0, v19, vcc
	v_add_co_u32_e32 v18, vcc, 0x12000, v18
	global_load_dwordx4 v[14:17], v[14:15], off
	s_nop 0
	v_addc_co_u32_e32 v19, vcc, 0, v19, vcc
	global_load_dwordx4 v[18:21], v[18:19], off
	s_waitcnt vmcnt(3)
	v_mfma_f32_16x16x32_bf16 v[6:9], v[6:9], v[2:5], 0
	s_waitcnt vmcnt(2)
	v_mfma_f32_16x16x32_bf16 v[10:13], v[10:13], v[2:5], 0
	s_waitcnt vmcnt(1)
	v_mfma_f32_16x16x32_bf16 v[14:17], v[14:17], v[2:5], 0
	s_waitcnt vmcnt(0)
	v_mfma_f32_16x16x32_bf16 v[18:21], v[18:21], v[2:5], 0
	s_nop 1
	ds_write2st64_b32 v113, v6, v7 offset1:1
	ds_write2st64_b32 v113, v8, v9 offset0:2 offset1:3
	ds_write2st64_b32 v113, v10, v11 offset0:4 offset1:5
	ds_write2st64_b32 v113, v12, v13 offset0:6 offset1:7
	ds_write2st64_b32 v113, v14, v15 offset0:8 offset1:9
	ds_write2st64_b32 v113, v16, v17 offset0:10 offset1:11
	ds_write2st64_b32 v113, v18, v19 offset0:12 offset1:13
	ds_write2st64_b32 v113, v20, v21 offset0:14 offset1:15
	s_waitcnt lgkmcnt(0)
	s_barrier
	s_and_saveexec_b64 s[8:9], s[4:5]
	s_cbranch_execz .LBB0_781
	ds_read2st64_b32 v[36:37], v111 offset1:1
	ds_read2st64_b32 v[38:39], v111 offset0:16 offset1:17
	ds_read2st64_b32 v[40:41], v111 offset0:32 offset1:33
	ds_read2st64_b32 v[42:43], v111 offset0:48 offset1:49
	ds_read2st64_b32 v[44:45], v111 offset0:64 offset1:65
	ds_read2st64_b32 v[46:47], v111 offset0:80 offset1:81
	ds_read2st64_b32 v[48:49], v111 offset0:96 offset1:97
	ds_read2st64_b32 v[50:51], v111 offset0:112 offset1:113
	ds_read2st64_b32 v[20:21], v111 offset0:2 offset1:3
	ds_read2st64_b32 v[18:19], v111 offset0:18 offset1:19
	ds_read2st64_b32 v[16:17], v111 offset0:34 offset1:35
	ds_read2st64_b32 v[14:15], v111 offset0:50 offset1:51
	ds_read2st64_b32 v[12:13], v111 offset0:66 offset1:67
	ds_read2st64_b32 v[10:11], v111 offset0:82 offset1:83
	ds_read2st64_b32 v[8:9], v111 offset0:98 offset1:99
	ds_read2st64_b32 v[6:7], v111 offset0:114 offset1:115
	ds_read2st64_b32 v[52:53], v111 offset0:4 offset1:5
	ds_read2st64_b32 v[54:55], v111 offset0:20 offset1:21
	ds_read2st64_b32 v[56:57], v111 offset0:36 offset1:37
	ds_read2st64_b32 v[58:59], v111 offset0:52 offset1:53
	ds_read2st64_b32 v[60:61], v111 offset0:68 offset1:69
	ds_read2st64_b32 v[62:63], v111 offset0:84 offset1:85
	ds_read2st64_b32 v[64:65], v111 offset0:100 offset1:101
	ds_read2st64_b32 v[66:67], v111 offset0:116 offset1:117
	s_waitcnt lgkmcnt(14)
	v_mov_b32_e32 v34, v36
	s_waitcnt lgkmcnt(7)
	v_mov_b32_e32 v35, v53
	v_pk_add_f32 v[34:35], v[34:35], 0 op_sel_hi:[1,0]
	v_mov_b32_e32 v68, v38
	s_waitcnt lgkmcnt(6)
	v_mov_b32_e32 v69, v55
	v_pk_add_f32 v[34:35], v[34:35], v[68:69]
	v_mov_b32_e32 v68, v40
	s_waitcnt lgkmcnt(5)
	v_mov_b32_e32 v69, v57
	v_pk_add_f32 v[34:35], v[34:35], v[68:69]
	v_mov_b32_e32 v68, v42
	s_waitcnt lgkmcnt(4)
	v_mov_b32_e32 v69, v59
	v_pk_add_f32 v[34:35], v[34:35], v[68:69]
	v_mov_b32_e32 v68, v44
	s_waitcnt lgkmcnt(3)
	v_mov_b32_e32 v69, v61
	v_pk_add_f32 v[34:35], v[34:35], v[68:69]
	v_mov_b32_e32 v68, v46
	s_waitcnt lgkmcnt(2)
	v_mov_b32_e32 v69, v63
	v_mov_b32_e32 v53, v37
	v_pk_add_f32 v[34:35], v[34:35], v[68:69]
	v_mov_b32_e32 v68, v48
	s_waitcnt lgkmcnt(1)
	v_mov_b32_e32 v69, v65
	v_pk_add_f32 v[36:37], v[52:53], 0 op_sel_hi:[1,0]
	v_mov_b32_e32 v55, v39
	v_pk_add_f32 v[34:35], v[34:35], v[68:69]
	v_mov_b32_e32 v68, v50
	s_waitcnt lgkmcnt(0)
	v_mov_b32_e32 v69, v67
	v_pk_add_f32 v[36:37], v[36:37], v[54:55]
	v_mov_b32_e32 v57, v41
	v_mov_b32_e32 v59, v43
	v_mov_b32_e32 v61, v45
	v_mov_b32_e32 v63, v47
	v_mov_b32_e32 v65, v49
	v_mov_b32_e32 v67, v51
	ds_read2st64_b32 v[38:39], v111 offset0:6 offset1:7
	ds_read2st64_b32 v[40:41], v111 offset0:22 offset1:23
	ds_read2st64_b32 v[42:43], v111 offset0:38 offset1:39
	ds_read2st64_b32 v[44:45], v111 offset0:54 offset1:55
	ds_read2st64_b32 v[46:47], v111 offset0:70 offset1:71
	ds_read2st64_b32 v[48:49], v111 offset0:86 offset1:87
	ds_read2st64_b32 v[50:51], v111 offset0:102 offset1:103
	ds_read2st64_b32 v[52:53], v111 offset0:118 offset1:119
	v_mov_b32_e32 v54, v20
	s_waitcnt lgkmcnt(7)
	v_mov_b32_e32 v55, v39
	v_pk_add_f32 v[36:37], v[36:37], v[56:57]
	v_pk_add_f32 v[54:55], v[54:55], 0 op_sel_hi:[1,0]
	v_mov_b32_e32 v56, v18
	s_waitcnt lgkmcnt(6)
	v_mov_b32_e32 v57, v41
	v_pk_add_f32 v[54:55], v[54:55], v[56:57]
	v_mov_b32_e32 v56, v16
	s_waitcnt lgkmcnt(5)
	v_mov_b32_e32 v57, v43
	v_pk_add_f32 v[54:55], v[54:55], v[56:57]
	v_mov_b32_e32 v56, v14
	s_waitcnt lgkmcnt(4)
	v_mov_b32_e32 v57, v45
	v_pk_add_f32 v[54:55], v[54:55], v[56:57]
	v_mov_b32_e32 v56, v12
	s_waitcnt lgkmcnt(3)
	v_mov_b32_e32 v57, v47
	v_pk_add_f32 v[54:55], v[54:55], v[56:57]
	v_mov_b32_e32 v56, v10
	s_waitcnt lgkmcnt(2)
	v_mov_b32_e32 v57, v49
	v_pk_add_f32 v[54:55], v[54:55], v[56:57]
	v_mov_b32_e32 v56, v8
	s_waitcnt lgkmcnt(1)
	v_mov_b32_e32 v57, v51
	v_pk_add_f32 v[34:35], v[34:35], v[68:69]
	v_pk_add_f32 v[54:55], v[54:55], v[56:57]
	v_mov_b32_e32 v56, v6
	s_waitcnt lgkmcnt(0)
	v_mov_b32_e32 v57, v53
	v_mov_b32_e32 v53, v7
	ds_read2st64_b32 v[102:103], v111 offset0:8 offset1:9
	ds_read2st64_b32 v[100:101], v111 offset0:24 offset1:25
	ds_read2st64_b32 v[68:69], v111 offset0:10 offset1:11
	ds_read2st64_b32 v[6:7], v111 offset0:12 offset1:13
	v_pk_add_f32 v[36:37], v[36:37], v[58:59]
	s_waitcnt lgkmcnt(3)
; __device__ __forceinline__ float bf2f(unsigned short b) { return __uint_as_float(((unsigned)b) << 16); }
; template <class Epi, class Pre>
; __device__ __forceinline__ void meta_gemm(const bf16_t* __restrict__ A, int lda, const bf16_t* __restrict__ Bt, int ldb, int N, int K, Epi& epi, Pre pre) {
;     ...
;           for (int j = 0; j < 4; ++j) { float s = 0.f;
; #pragma unroll
;             for (int w = 0; w < 8; ++w) s += part[(w * 16 + (bj * 2 + n) * 4 + j) * 64 + lane];
;             v[bj][n][j] = s; }
; __device__ __forceinline__ void up_phase(const bf16_t* cqkv, const bf16_t* wqb, const bf16_t* wkvb, EpiUp& epi) {
;     ...
;     auto preq = [&](int fr, int fq) { const bf16_t* p = cqkv + (size_t)(NREAL + fr) * 512 + fq * 64; float ss = 0.f;
; #pragma unroll
;       for (int c = 0; c < 8; ++c) { const u32x4 w = *(const u32x4*)(p + c * 8);
; #pragma unroll
;         for (int q = 0; q < 4; ++q) { const float a = bf2f(w[q] & 0xffff), b = bf2f(w[q] >> 16); ss += a * a + b * b; } }
	v_mov_b32_e32 v85, v103
	v_pk_add_f32 v[36:37], v[36:37], v[60:61]
	ds_read2st64_b32 v[98:99], v111 offset0:40 offset1:41
	v_pk_add_f32 v[36:37], v[36:37], v[62:63]
	s_waitcnt lgkmcnt(1)
	v_mov_b32_e32 v84, v6
	v_pk_add_f32 v[36:37], v[36:37], v[64:65]
	v_mov_b32_e32 v103, v7
	v_pk_add_f32 v[36:37], v[36:37], v[66:67]
	ds_read2st64_b32 v[66:67], v111 offset0:26 offset1:27
	ds_read2st64_b32 v[6:7], v111 offset0:28 offset1:29
	v_mov_b32_e32 v83, v101
	ds_read2st64_b32 v[96:97], v111 offset0:56 offset1:57
	ds_read2st64_b32 v[64:65], v111 offset0:42 offset1:43
	s_waitcnt lgkmcnt(4)
	v_mov_b32_e32 v81, v99
	s_waitcnt lgkmcnt(2)
	v_mov_b32_e32 v82, v6
	v_mov_b32_e32 v101, v7
	ds_read2st64_b32 v[6:7], v111 offset0:44 offset1:45
	ds_read2st64_b32 v[94:95], v111 offset0:72 offset1:73
	ds_read2st64_b32 v[62:63], v111 offset0:58 offset1:59
	s_waitcnt lgkmcnt(4)
	v_mov_b32_e32 v79, v97
	ds_read2st64_b32 v[92:93], v111 offset0:88 offset1:89
	ds_read2st64_b32 v[60:61], v111 offset0:74 offset1:75
	s_waitcnt lgkmcnt(4)
	v_mov_b32_e32 v80, v6
	v_mov_b32_e32 v99, v7
	ds_read2st64_b32 v[6:7], v111 offset0:60 offset1:61
	s_waitcnt lgkmcnt(4)
	v_mov_b32_e32 v77, v95
	ds_read2st64_b32 v[90:91], v111 offset0:104 offset1:105
	ds_read2st64_b32 v[58:59], v111 offset0:90 offset1:91
	v_pk_add_f32 v[86:87], v[54:55], v[56:57]
	s_waitcnt lgkmcnt(2)
	v_mov_b32_e32 v78, v6
	v_mov_b32_e32 v97, v7
	ds_read2st64_b32 v[6:7], v111 offset0:76 offset1:77
	v_mov_b32_e32 v75, v93
	ds_read2st64_b32 v[88:89], v111 offset0:120 offset1:121
	ds_read2st64_b32 v[56:57], v111 offset0:106 offset1:107
	ds_read2st64_b32 v[54:55], v111 offset0:122 offset1:123
	s_waitcnt lgkmcnt(3)
	v_mov_b32_e32 v76, v6
	v_mov_b32_e32 v95, v7
	ds_read2st64_b32 v[6:7], v111 offset0:92 offset1:93
	v_mov_b32_e32 v73, v91
	v_mov_b32_e32 v39, v21
	v_pk_add_f32 v[20:21], v[38:39], 0 op_sel_hi:[1,0]
	v_mov_b32_e32 v41, v19
	s_waitcnt lgkmcnt(0)
	v_mov_b32_e32 v74, v6
	v_mov_b32_e32 v93, v7
	ds_read2st64_b32 v[6:7], v111 offset0:108 offset1:109
	v_pk_add_f32 v[18:19], v[20:21], v[40:41]
	v_mov_b32_e32 v43, v17
	v_pk_add_f32 v[16:17], v[18:19], v[42:43]
	v_mov_b32_e32 v45, v15
	s_waitcnt lgkmcnt(0)
	v_mov_b32_e32 v72, v6
	v_mov_b32_e32 v91, v7
	ds_read2st64_b32 v[6:7], v111 offset0:124 offset1:125
	v_mov_b32_e32 v71, v89
	v_pk_add_f32 v[14:15], v[16:17], v[44:45]
	v_mov_b32_e32 v47, v13
	v_pk_add_f32 v[12:13], v[14:15], v[46:47]
	s_waitcnt lgkmcnt(0)
	v_mov_b32_e32 v70, v6
	v_mov_b32_e32 v89, v7
	ds_read2st64_b32 v[6:7], v111 offset0:14 offset1:15
	v_mov_b32_e32 v49, v11
	v_pk_add_f32 v[10:11], v[12:13], v[48:49]
	v_mov_b32_e32 v51, v9
	v_pk_add_f32 v[8:9], v[10:11], v[50:51]
	v_mov_b32_e32 v51, v67
	v_pk_add_f32 v[104:105], v[8:9], v[52:53]
	v_mov_b32_e32 v53, v69
	s_waitcnt lgkmcnt(0)
	v_mov_b32_e32 v52, v6
	v_mov_b32_e32 v69, v7
	ds_read2st64_b32 v[6:7], v111 offset0:30 offset1:31
	v_mov_b32_e32 v49, v65
	v_mov_b32_e32 v108, v34
	v_mov_b32_e32 v109, v37
	v_mov_b32_e32 v106, v36
	s_waitcnt lgkmcnt(0)
	v_mov_b32_e32 v50, v6
	v_mov_b32_e32 v67, v7
	ds_read2st64_b32 v[6:7], v111 offset0:46 offset1:47
	v_mov_b32_e32 v47, v63
	v_mov_b32_e32 v107, v35
	s_mov_b64 s[10:11], -1
	s_cmpk_gt_i32 s13, 0x2ff
	s_waitcnt lgkmcnt(0)
	v_mov_b32_e32 v48, v6
	v_mov_b32_e32 v65, v7
	ds_read2st64_b32 v[6:7], v111 offset0:62 offset1:63
	v_mov_b32_e32 v45, v61
	s_waitcnt lgkmcnt(0)
	v_mov_b32_e32 v46, v6
	v_mov_b32_e32 v63, v7
	ds_read2st64_b32 v[6:7], v111 offset0:78 offset1:79
	v_mov_b32_e32 v43, v59
	s_waitcnt lgkmcnt(0)
	v_mov_b32_e32 v44, v6
	v_mov_b32_e32 v61, v7
	ds_read2st64_b32 v[6:7], v111 offset0:94 offset1:95
	v_mov_b32_e32 v41, v57
	s_waitcnt lgkmcnt(0)
	v_mov_b32_e32 v42, v6
	v_mov_b32_e32 v59, v7
	ds_read2st64_b32 v[6:7], v111 offset0:110 offset1:111
	v_mov_b32_e32 v39, v55
	s_waitcnt lgkmcnt(0)
	v_mov_b32_e32 v40, v6
	v_mov_b32_e32 v57, v7
	ds_read2st64_b32 v[6:7], v111 offset0:126 offset1:127
	s_waitcnt lgkmcnt(0)
	v_mov_b32_e32 v38, v6
	v_mov_b32_e32 v55, v7
	global_load_dwordx4 v[6:9], v[28:29], off offset:48
	global_load_dwordx4 v[10:13], v[28:29], off offset:32
	global_load_dwordx4 v[14:17], v[28:29], off offset:16
	global_load_dwordx4 v[18:21], v[28:29], off
	s_waitcnt vmcnt(0)
	v_lshlrev_b32_e32 v114, 16, v18
	v_and_b32_e32 v18, 0xffff0000, v18
	v_mul_f32_e32 v18, v18, v18
	v_fmac_f32_e32 v18, v114, v114
	v_lshlrev_b32_e32 v114, 16, v19
	v_and_b32_e32 v19, 0xffff0000, v19
	v_mul_f32_e32 v19, v19, v19
	v_fmac_f32_e32 v19, v114, v114
	v_add_f32_e32 v18, v18, v19
	v_lshlrev_b32_e32 v19, 16, v20
	v_and_b32_e32 v20, 0xffff0000, v20
	v_mul_f32_e32 v20, v20, v20
	v_fmac_f32_e32 v20, v19, v19
	v_add_f32_e32 v18, v20, v18
	v_and_b32_e32 v20, 0xffff0000, v21
	v_lshlrev_b32_e32 v19, 16, v21
	v_mul_f32_e32 v20, v20, v20
	v_fmac_f32_e32 v20, v19, v19
	v_lshlrev_b32_e32 v19, 16, v14
	v_and_b32_e32 v14, 0xffff0000, v14
	v_mul_f32_e32 v14, v14, v14
	v_add_f32_e32 v18, v20, v18
	v_fmac_f32_e32 v14, v19, v19
	v_add_f32_e32 v14, v14, v18
	v_lshlrev_b32_e32 v18, 16, v15
	v_and_b32_e32 v15, 0xffff0000, v15
	v_mul_f32_e32 v15, v15, v15
	v_fmac_f32_e32 v15, v18, v18
	v_add_f32_e32 v14, v15, v14
	v_lshlrev_b32_e32 v15, 16, v16
	v_and_b32_e32 v16, 0xffff0000, v16
	v_mul_f32_e32 v16, v16, v16
	v_fmac_f32_e32 v16, v15, v15
	v_add_f32_e32 v14, v16, v14
	v_and_b32_e32 v16, 0xffff0000, v17
	v_lshlrev_b32_e32 v15, 16, v17
	v_mul_f32_e32 v16, v16, v16
	v_fmac_f32_e32 v16, v15, v15
	v_lshlrev_b32_e32 v15, 16, v10
	v_and_b32_e32 v10, 0xffff0000, v10
	v_mul_f32_e32 v10, v10, v10
	v_add_f32_e32 v14, v16, v14
	v_fmac_f32_e32 v10, v15, v15
	v_add_f32_e32 v10, v10, v14
	v_lshlrev_b32_e32 v14, 16, v11
	v_and_b32_e32 v11, 0xffff0000, v11
	v_mul_f32_e32 v11, v11, v11
	v_fmac_f32_e32 v11, v14, v14
	v_add_f32_e32 v10, v11, v10
	v_lshlrev_b32_e32 v11, 16, v12
	v_and_b32_e32 v12, 0xffff0000, v12
	v_mul_f32_e32 v12, v12, v12
	v_fmac_f32_e32 v12, v11, v11
	v_add_f32_e32 v10, v12, v10
	v_and_b32_e32 v12, 0xffff0000, v13
	v_lshlrev_b32_e32 v11, 16, v13
	v_mul_f32_e32 v12, v12, v12
	v_fmac_f32_e32 v12, v11, v11
	v_lshlrev_b32_e32 v11, 16, v6
	v_and_b32_e32 v6, 0xffff0000, v6
	v_mul_f32_e32 v6, v6, v6
	v_add_f32_e32 v10, v12, v10
	v_fmac_f32_e32 v6, v11, v11
	v_add_f32_e32 v6, v6, v10
	v_lshlrev_b32_e32 v10, 16, v7
	v_and_b32_e32 v7, 0xffff0000, v7
	v_mul_f32_e32 v7, v7, v7
	v_fmac_f32_e32 v7, v10, v10
	v_add_f32_e32 v6, v7, v6
	v_lshlrev_b32_e32 v7, 16, v8
	v_and_b32_e32 v8, 0xffff0000, v8
	v_mul_f32_e32 v8, v8, v8
	v_fmac_f32_e32 v8, v7, v7
	v_add_f32_e32 v6, v8, v6
	v_and_b32_e32 v8, 0xffff0000, v9
	v_lshlrev_b32_e32 v7, 16, v9
	v_mul_f32_e32 v8, v8, v8
	v_fmac_f32_e32 v8, v7, v7
	v_add_f32_e32 v114, v8, v6
	global_load_dwordx4 v[6:9], v[28:29], off offset:112
	global_load_dwordx4 v[10:13], v[28:29], off offset:96
	global_load_dwordx4 v[14:17], v[28:29], off offset:80
	global_load_dwordx4 v[18:21], v[28:29], off offset:64
	s_waitcnt vmcnt(0)
; __device__ __forceinline__ float bf2f(unsigned short b) { return __uint_as_float(((unsigned)b) << 16); }
; __device__ __forceinline__ unsigned short f2bf(float f) { return (unsigned short)(cvt_pk_bf16(f, f) & 0xffffu); }
; __device__ __forceinline__ void store8bf(bf16_t* p, f32x4 v0, f32x4 v1) { u32x4 w; w.x = cvt_pk_bf16(v0[0], v0[1]); w.y = cvt_pk_bf16(v0[2], v0[3]); w.z = cvt_pk_bf16(v1[0], v1[1]); w.w = cvt_pk_bf16(v1[2], v1[3]); *(u32x4*)p = w; }
; template <int M> __device__ __forceinline__ float shx(float v) { return __builtin_bit_cast(float, __builtin_amdgcn_ds_swizzle(__builtin_bit_cast(int, v), (M << 10) | 0x1f)); }
; __device__ __forceinline__ float sum32(float v) { return v + xhalf(v); }
;   __device__ __forceinline__ void group(int row, int c32, int fq, f32x4 v0, f32x4 v1) const {
;     ...
;     } else {
;       const int cc = c32 - 768, h = cc >> 7, part = (cc & 127) >> 5;
;       if (part < 2) store8bf(ka + ((size_t)(b * 6 + h) * E + e) * 96 + part * 32 + fq * 8, v0 * rs, v1 * rs);
;       else { bf16_t* p = vta + ((size_t)(b * 6 + h) * 64 + (part - 2) * 32 + fq * 4) * E + e;
; #pragma unroll
;         for (int j = 0; j < 4; ++j) { p[(size_t)j * E] = f2bf(v0[j] * rs); p[(size_t)(j + 16) * E] = f2bf(v1[j] * rs); } }
; __device__ __forceinline__ void up_phase(const bf16_t* cqkv, const bf16_t* wqb, const bf16_t* wkvb, EpiUp& epi) {
;     ...
;         for (int q = 0; q < 4; ++q) { const float a = bf2f(w[q] & 0xffff), b = bf2f(w[q] >> 16); ss += a * a + b * b; } }
;       ss += shx<16>(ss); ss = sum32(ss); epi.rs_direct = rsqrtf(ss * (1.0f / 256.0f) + 1e-6f); };
	v_lshlrev_b32_e32 v115, 16, v18
	v_and_b32_e32 v18, 0xffff0000, v18
	v_mul_f32_e32 v18, v18, v18
	v_fmac_f32_e32 v18, v115, v115
	v_add_f32_e32 v18, v18, v114
	v_lshlrev_b32_e32 v114, 16, v19
	v_and_b32_e32 v19, 0xffff0000, v19
	v_mul_f32_e32 v19, v19, v19
	v_fmac_f32_e32 v19, v114, v114
	v_add_f32_e32 v18, v19, v18
	v_lshlrev_b32_e32 v19, 16, v20
	v_and_b32_e32 v20, 0xffff0000, v20
	v_mul_f32_e32 v20, v20, v20
	v_fmac_f32_e32 v20, v19, v19
	v_add_f32_e32 v18, v20, v18
	v_and_b32_e32 v20, 0xffff0000, v21
	v_lshlrev_b32_e32 v19, 16, v21
	v_mul_f32_e32 v20, v20, v20
	v_fmac_f32_e32 v20, v19, v19
	v_lshlrev_b32_e32 v19, 16, v14
	v_and_b32_e32 v14, 0xffff0000, v14
	v_mul_f32_e32 v14, v14, v14
	v_add_f32_e32 v18, v20, v18
	v_fmac_f32_e32 v14, v19, v19
	v_add_f32_e32 v14, v14, v18
	v_lshlrev_b32_e32 v18, 16, v15
	v_and_b32_e32 v15, 0xffff0000, v15
	v_mul_f32_e32 v15, v15, v15
	v_fmac_f32_e32 v15, v18, v18
	v_add_f32_e32 v14, v15, v14
	v_lshlrev_b32_e32 v15, 16, v16
	v_and_b32_e32 v16, 0xffff0000, v16
	v_mul_f32_e32 v16, v16, v16
	v_fmac_f32_e32 v16, v15, v15
	v_add_f32_e32 v14, v16, v14
	v_and_b32_e32 v16, 0xffff0000, v17
	v_lshlrev_b32_e32 v15, 16, v17
	v_mul_f32_e32 v16, v16, v16
	v_fmac_f32_e32 v16, v15, v15
	v_add_f32_e32 v16, v16, v14
	v_lshlrev_b32_e32 v15, 16, v11
	v_lshlrev_b32_e32 v14, 16, v10
	v_and_b32_e32 v11, 0xffff0000, v11
	v_and_b32_e32 v10, 0xffff0000, v10
	v_pk_mul_f32 v[10:11], v[10:11], v[10:11]
	s_nop 0
	v_pk_fma_f32 v[10:11], v[14:15], v[14:15], v[10:11]
	s_nop 0
	v_add_f32_e32 v10, v10, v16
	v_add_f32_e32 v14, v11, v10
	v_lshlrev_b32_e32 v11, 16, v13
	v_lshlrev_b32_e32 v10, 16, v12
	v_and_b32_e32 v13, 0xffff0000, v13
	v_and_b32_e32 v12, 0xffff0000, v12
	v_pk_mul_f32 v[12:13], v[12:13], v[12:13]
	s_nop 0
	v_pk_fma_f32 v[10:11], v[10:11], v[10:11], v[12:13]
	s_nop 0
	v_add_f32_e32 v10, v10, v14
	v_add_f32_e32 v12, v11, v10
	v_lshlrev_b32_e32 v11, 16, v7
	v_lshlrev_b32_e32 v10, 16, v6
	v_and_b32_e32 v7, 0xffff0000, v7
	v_and_b32_e32 v6, 0xffff0000, v6
	v_pk_mul_f32 v[6:7], v[6:7], v[6:7]
	s_nop 0
	v_pk_fma_f32 v[6:7], v[10:11], v[10:11], v[6:7]
	s_nop 0
	v_add_f32_e32 v6, v6, v12
	v_add_f32_e32 v10, v7, v6
	v_lshlrev_b32_e32 v7, 16, v9
	v_lshlrev_b32_e32 v6, 16, v8
	v_and_b32_e32 v9, 0xffff0000, v9
	v_and_b32_e32 v8, 0xffff0000, v8
	v_pk_mul_f32 v[8:9], v[8:9], v[8:9]
	s_nop 0
	v_pk_fma_f32 v[6:7], v[6:7], v[6:7], v[8:9]
	s_nop 0
	v_add_f32_e32 v6, v6, v10
	v_add_f32_e32 v6, v7, v6
	ds_swizzle_b32 v7, v6 offset:swizzle(SWAP,16)
	s_waitcnt lgkmcnt(0)
	v_add_f32_e32 v6, v6, v7
	v_mov_b32_e32 v7, v210
	s_nop 0
	v_lshlrev_b32_e32 v7, 2, v7
	v_xor_b32_e32 v7, 0x80, v7
	ds_bpermute_b32 v7, v7, v6
	s_waitcnt lgkmcnt(0)
	v_add_f32_e32 v6, v6, v7
	v_fmamk_f32 v6, v6, 0x3b800000, v154
	v_cmp_gt_f32_e32 vcc, s46, v6
	v_mul_f32_e32 v7, 0x4b800000, v6
	s_nop 0
	v_cndmask_b32_e32 v6, v6, v7, vcc
	v_rsq_f32_e32 v6, v6
	s_nop 0
	v_mul_f32_e32 v7, 0x45800000, v6
	v_cndmask_b32_e32 v6, v6, v7, vcc
	s_cbranch_scc0 .LBB0_789
	s_add_i32 s10, s14, 0xfffffd00
	s_lshr_b32 s10, s10, 7
	s_and_b32 s15, s12, 3
	v_add_u32_e32 v8, s10, v112
	s_cmp_gt_u32 s15, 1
	v_ashrrev_i32_e32 v9, 31, v8
	s_mov_b64 s[10:11], -1
	s_cbranch_scc0 .LBB0_786
	s_lshl_b32 s10, s15, 5
	v_lshlrev_b64 v[10:11], 6, v[8:9]
	s_sub_i32 s90, s10, 64
	v_lshl_add_u64 v[10:11], v[10:11], 0, s[90:91]
	v_or_b32_e32 v7, v10, v26
	v_mad_u64_u32 v[12:13], s[10:11], v7, s95, v[30:31]
	v_mul_f32_e32 v7, v34, v6
	v_mad_i32_i24 v13, v11, s95, v13
	v_cvt_pk_bf16_f32 v7, v7, s0
	s_mov_b32 s10, 0x40000
	global_store_short v[12:13], v7, off sc1
	v_mul_f32_e32 v7, v36, v6
	v_add_co_u32_e32 v10, vcc, s10, v12
	v_cvt_pk_bf16_f32 v7, v7, s0
	s_nop 0
	v_addc_co_u32_e32 v11, vcc, 0, v13, vcc
	s_movk_i32 s10, 0x4000
	global_store_short v[10:11], v7, off offset:2048 sc1
	v_mul_f32_e32 v7, v37, v6
	v_add_co_u32_e32 v10, vcc, s10, v12
	v_cvt_pk_bf16_f32 v7, v7, s0
	s_nop 0
	v_addc_co_u32_e32 v11, vcc, 0, v13, vcc
	s_mov_b32 s10, 0x44000
	global_store_short v[10:11], v7, off offset:128 sc1
	v_mul_f32_e32 v7, v35, v6
	v_add_co_u32_e32 v10, vcc, s10, v12
	v_cvt_pk_bf16_f32 v7, v7, s0
	s_nop 0
	v_addc_co_u32_e32 v11, vcc, 0, v13, vcc
	s_mov_b32 s10, 0x8000
	global_store_short v[10:11], v7, off offset:2176 sc1
	v_mul_f32_e32 v7, v86, v6
	v_add_co_u32_e32 v10, vcc, s10, v12
	v_cvt_pk_bf16_f32 v7, v7, s0
	s_nop 0
	v_addc_co_u32_e32 v11, vcc, 0, v13, vcc
	s_mov_b32 s10, 0x48000
	global_store_short v[10:11], v7, off offset:256 sc1
	v_mul_f32_e32 v7, v104, v6
	v_add_co_u32_e32 v10, vcc, s10, v12
	v_cvt_pk_bf16_f32 v7, v7, s0
	s_nop 0
	v_addc_co_u32_e32 v11, vcc, 0, v13, vcc
	global_store_short v[10:11], v7, off offset:2304 sc1
	v_mul_f32_e32 v7, v105, v6
	v_add_co_u32_e32 v10, vcc, 0xc000, v12
	v_cvt_pk_bf16_f32 v7, v7, s0
	s_nop 0
	v_addc_co_u32_e32 v11, vcc, 0, v13, vcc
	global_store_short v[10:11], v7, off offset:384 sc1
	v_mul_f32_e32 v7, v87, v6
	v_add_co_u32_e32 v10, vcc, 0x4c000, v12
	v_cvt_pk_bf16_f32 v7, v7, s0
	s_nop 0
	v_addc_co_u32_e32 v11, vcc, 0, v13, vcc
	global_store_short v[10:11], v7, off offset:2432 sc1
	s_mov_b64 s[10:11], 0
.LBB0_786:
	s_andn2_b64 vcc, exec, s[10:11]
	s_cbranch_vccnz .LBB0_788
	s_movk_i32 s10, 0x2040
	v_mad_i64_i32 v[8:9], s[10:11], v8, s10, v[24:25]
	v_readlane_b32 s10, v254, 4
	v_readlane_b32 s11, v254, 5
	s_lshl_b32 s90, s15, 6
	v_mov_b32_e32 v14, v104
	v_mov_b64_e32 v[10:11], s[10:11]
	v_mad_u64_u32 v[10:11], s[10:11], v8, s47, v[10:11]
	v_mad_i32_i24 v11, v9, s47, v11
	v_lshl_add_u64 v[8:9], v[10:11], 0, s[90:91]
	v_lshlrev_b32_e32 v10, 1, v0
	v_mov_b32_e32 v11, v1
	v_lshl_add_u64 v[12:13], v[8:9], 0, v[10:11]
	v_mov_b32_e32 v8, v86
	v_mov_b32_e32 v9, v105
	v_mov_b32_e32 v15, v87
	v_pk_mul_f32 v[10:11], v[8:9], v[6:7] op_sel_hi:[1,0]
	v_pk_mul_f32 v[8:9], v[108:109], v[6:7] op_sel_hi:[1,0]
	v_pk_mul_f32 v[14:15], v[14:15], v[6:7] op_sel_hi:[1,0]
	v_pk_mul_f32 v[16:17], v[106:107], v[6:7] op_sel_hi:[1,0]
	v_cvt_pk_bf16_f32 v8, v8, v9
	v_cvt_pk_bf16_f32 v9, v10, v11
	v_cvt_pk_bf16_f32 v10, v16, v17
	v_cvt_pk_bf16_f32 v11, v14, v15
	global_store_dwordx4 v[12:13], v[8:11], off sc1

; __device__ __forceinline__ void store4bf(bf16_t* p, f32x4 v) { u32x2 w; w.x = cvt_pk_bf16(v[0], v[1]); w.y = cvt_pk_bf16(v[2], v[3]); *(u32x2*)p = w; }
; __device__ __forceinline__ void store8bf(bf16_t* p, f32x4 v0, f32x4 v1) { u32x4 w; w.x = cvt_pk_bf16(v0[0], v0[1]); w.y = cvt_pk_bf16(v0[2], v0[3]); w.z = cvt_pk_bf16(v1[0], v1[1]); w.w = cvt_pk_bf16(v1[2], v1[3]); *(u32x4*)p = w; }
;   __device__ __forceinline__ void group(int row, int c32, int fq, f32x4 v0, f32x4 v1) const {
;     ...
;     if (c32 < 768) {
;       if (c32 >= 576) return;
;       const int h = c32 / 96, part = (c32 - h * 96) >> 5; const float sc = rs * QSC_A;
;       bf16_t* p = qa + ((size_t)(b * 6 + h) * E + e) * 96 + part * 32 + fq * 4;
;       if (part < 2) store8bf(qa + ((size_t)(b * 6 + h) * E + e) * 96 + part * 32 + fq * 8, v0 * sc, v1 * sc);
;       else { const float2* rp = rope + pos_of_e(e) * 16 + fq * 4; f32x4 o0, o1;
; #pragma unroll
;         for (int j = 0; j < 4; ++j) { const float2 cs = rp[j]; o0[j] = (v0[j] * cs.x - v1[j] * cs.y) * sc; o1[j] = (v1[j] * cs.x + v0[j] * cs.y) * sc; }
;         store4bf(p, o0); store4bf(p + 16, o1); }
.LBB0_789:
	s_andn2_b64 vcc, exec, s[10:11]
	s_cbranch_vccnz .LBB0_795
	s_cmpk_gt_i32 s13, 0x23f
	s_cbranch_scc1 .LBB0_795
	s_mul_hi_i32 s10, s13, 0x2aaaaaab
	s_lshr_b32 s11, s10, 31
	s_ashr_i32 s10, s10, 4
	s_add_i32 s11, s10, s11
	s_mul_i32 s10, s11, 0xffffffa0
	v_add_u32_e32 v7, s11, v112
	s_movk_i32 s11, 0x2040
	v_mad_i64_i32 v[10:11], s[16:17], v7, s11, v[24:25]
	v_readlane_b32 s16, v254, 24
	v_readlane_b32 s17, v254, 25
	s_add_i32 s10, s10, s13
	s_ashr_i32 s11, s10, 31
	v_mov_b64_e32 v[12:13], s[16:17]
	v_mad_u64_u32 v[12:13], s[16:17], v10, s47, v[12:13]
	v_mad_i32_i24 v13, v11, s47, v13
	v_mul_f32_e32 v8, 0x3e16c740, v6
	v_lshl_add_u64 v[10:11], s[10:11], 1, v[12:13]
	s_cmp_gt_i32 s10, 63
	s_mov_b64 s[10:11], -1
	s_cbranch_scc0 .LBB0_793
	global_load_dwordx4 v[16:19], v[32:33], off offset:16
	global_load_dwordx4 v[114:117], v[32:33], off
	v_lshlrev_b32_e32 v12, 1, v26
	v_mov_b32_e32 v13, v1
	v_lshl_add_u64 v[12:13], v[10:11], 0, v[12:13]
	s_mov_b64 s[10:11], 0
	s_waitcnt vmcnt(1)
	v_mov_b32_e32 v20, v17
	s_waitcnt vmcnt(0)
	v_mov_b32_e32 v118, v114
	v_mov_b32_e32 v119, v117
	v_mov_b32_e32 v14, v115
	v_mov_b32_e32 v15, v116
	v_pk_mul_f32 v[118:119], v[36:37], v[118:119]
	v_mov_b32_e32 v120, v115
	v_pk_fma_f32 v[14:15], v[34:35], v[14:15], v[118:119]
	v_mov_b32_e32 v118, v36
	v_mov_b32_e32 v119, v35
	v_mov_b32_e32 v121, v117
	v_mov_b32_e32 v35, v37
	v_mov_b32_e32 v36, v16
	v_mov_b32_e32 v37, v19
	v_mov_b32_e32 v21, v18
	v_pk_mul_f32 v[118:119], v[118:119], v[120:121]
	v_mov_b32_e32 v115, v116
	v_pk_mul_f32 v[36:37], v[104:105], v[36:37]
	v_pk_fma_f32 v[34:35], v[34:35], v[114:115], v[118:119] neg_lo:[0,0,1] neg_hi:[0,0,1]
	v_pk_fma_f32 v[20:21], v[86:87], v[20:21], v[36:37]
	v_mov_b32_e32 v36, v104
	v_mov_b32_e32 v37, v87
	v_mov_b32_e32 v114, v17
	v_mov_b32_e32 v115, v19
	v_pk_mul_f32 v[36:37], v[36:37], v[114:115]
	v_mov_b32_e32 v114, v86
	v_mov_b32_e32 v115, v105
	v_mov_b32_e32 v17, v18
	v_pk_fma_f32 v[16:17], v[114:115], v[16:17], v[36:37] neg_lo:[0,0,1] neg_hi:[0,0,1]
	v_pk_mul_f32 v[14:15], v[8:9], v[14:15] op_sel_hi:[0,1]
	v_pk_mul_f32 v[34:35], v[8:9], v[34:35] op_sel_hi:[0,1]
	v_pk_mul_f32 v[20:21], v[8:9], v[20:21] op_sel_hi:[0,1]
	v_pk_mul_f32 v[16:17], v[8:9], v[16:17] op_sel_hi:[0,1]
	v_cvt_pk_bf16_f32 v18, v34, v35
	v_cvt_pk_bf16_f32 v19, v16, v17
	v_cvt_pk_bf16_f32 v14, v14, v15
	v_cvt_pk_bf16_f32 v15, v20, v21
	global_store_dwordx2 v[12:13], v[18:19], off sc1
	global_store_dwordx2 v[12:13], v[14:15], off offset:32 sc1
.LBB0_793:
	s_andn2_b64 vcc, exec, s[10:11]
	s_cbranch_vccnz .LBB0_795
	v_lshlrev_b32_e32 v12, 1, v0
	v_mov_b32_e32 v13, v1
	v_lshl_add_u64 v[12:13], v[10:11], 0, v[12:13]
	v_mov_b32_e32 v10, v86
	v_mov_b32_e32 v11, v105
	v_mov_b32_e32 v105, v87
	v_pk_mul_f32 v[10:11], v[10:11], v[8:9] op_sel_hi:[1,0]
	v_pk_mul_f32 v[14:15], v[108:109], v[8:9] op_sel_hi:[1,0]
	v_pk_mul_f32 v[16:17], v[104:105], v[8:9] op_sel_hi:[1,0]
	v_pk_mul_f32 v[18:19], v[106:107], v[8:9] op_sel_hi:[1,0]
	v_cvt_pk_bf16_f32 v8, v14, v15
	v_cvt_pk_bf16_f32 v9, v10, v11
	v_cvt_pk_bf16_f32 v10, v18, v19
	v_cvt_pk_bf16_f32 v11, v16, v17
	global_store_dwordx4 v[12:13], v[8:11], off sc1
; __device__ __forceinline__ unsigned short f2bf(float f) { return (unsigned short)(cvt_pk_bf16(f, f) & 0xffffu); }
; __device__ __forceinline__ void store8bf(bf16_t* p, f32x4 v0, f32x4 v1) { u32x4 w; w.x = cvt_pk_bf16(v0[0], v0[1]); w.y = cvt_pk_bf16(v0[2], v0[3]); w.z = cvt_pk_bf16(v1[0], v1[1]); w.w = cvt_pk_bf16(v1[2], v1[3]); *(u32x4*)p = w; }
;   __device__ __forceinline__ void group(int row, int c32, int fq, f32x4 v0, f32x4 v1) const {
;     ...
;     } else {
;       const int cc = c32 - 768, h = cc >> 7, part = (cc & 127) >> 5;
;       if (part < 2) store8bf(ka + ((size_t)(b * 6 + h) * E + e) * 96 + part * 32 + fq * 8, v0 * rs, v1 * rs);
;       else { bf16_t* p = vta + ((size_t)(b * 6 + h) * 64 + (part - 2) * 32 + fq * 4) * E + e;
; #pragma unroll
;         for (int j = 0; j < 4; ++j) { p[(size_t)j * E] = f2bf(v0[j] * rs); p[(size_t)(j + 16) * E] = f2bf(v1[j] * rs); } }
; template <class Epi, class Pre>
; __device__ __forceinline__ void meta_gemm(const bf16_t* __restrict__ A, int lda, const bf16_t* __restrict__ Bt, int ldb, int N, int K, Epi& epi, Pre pre) {
;     ...
;           for (int j = 0; j < 4; ++j) { float s = 0.f;
; #pragma unroll
;             for (int w = 0; w < 8; ++w) s += part[(w * 16 + (bj * 2 + n) * 4 + j) * 64 + lane];
;             v[bj][n][j] = s; }
.LBB0_795:
	s_nop 1
	v_pk_add_f32 v[8:9], v[102:103], 0 op_sel_hi:[1,0]
	v_pk_add_f32 v[10:11], v[52:53], 0 op_sel_hi:[1,0]
	v_pk_add_f32 v[8:9], v[8:9], v[100:101]
	v_pk_add_f32 v[10:11], v[10:11], v[50:51]
	v_pk_add_f32 v[8:9], v[8:9], v[98:99]
	v_pk_add_f32 v[10:11], v[10:11], v[48:49]
	v_pk_add_f32 v[8:9], v[8:9], v[96:97]
	v_pk_add_f32 v[10:11], v[10:11], v[46:47]
	v_pk_add_f32 v[8:9], v[8:9], v[94:95]
	v_pk_add_f32 v[10:11], v[10:11], v[44:45]
	v_pk_add_f32 v[8:9], v[8:9], v[92:93]
	v_pk_add_f32 v[10:11], v[10:11], v[42:43]
	v_pk_add_f32 v[8:9], v[8:9], v[90:91]
	v_pk_add_f32 v[10:11], v[10:11], v[40:41]
	v_pk_add_f32 v[16:17], v[8:9], v[88:89]
	v_pk_add_f32 v[8:9], v[84:85], 0 op_sel_hi:[1,0]
	v_pk_add_f32 v[10:11], v[10:11], v[38:39]
	v_pk_add_f32 v[8:9], v[8:9], v[82:83]
	v_mov_b32_e32 v14, v16
	v_pk_add_f32 v[8:9], v[8:9], v[80:81]
	v_mov_b32_e32 v13, v17
	v_pk_add_f32 v[8:9], v[8:9], v[78:79]
	s_cmpk_gt_i32 s13, 0x27f
	v_pk_add_f32 v[8:9], v[8:9], v[76:77]
	s_mov_b64 s[10:11], -1
	v_pk_add_f32 v[8:9], v[8:9], v[74:75]
	s_nop 0
	v_pk_add_f32 v[8:9], v[8:9], v[72:73]
	s_nop 0
	v_pk_add_f32 v[18:19], v[8:9], v[70:71]
	v_pk_add_f32 v[8:9], v[68:69], 0 op_sel_hi:[1,0]
	v_mov_b32_e32 v15, v19
	v_pk_add_f32 v[8:9], v[8:9], v[66:67]
	v_mov_b32_e32 v12, v18
	v_pk_add_f32 v[8:9], v[8:9], v[64:65]
	s_nop 0
	v_pk_add_f32 v[8:9], v[8:9], v[62:63]
	s_nop 0
	v_pk_add_f32 v[8:9], v[8:9], v[60:61]
	s_nop 0
	v_pk_add_f32 v[8:9], v[8:9], v[58:59]
	s_nop 0
	v_pk_add_f32 v[8:9], v[8:9], v[56:57]
	s_nop 0
	v_pk_add_f32 v[8:9], v[8:9], v[54:55]
	s_cbranch_scc0 .LBB0_801
	s_addk_i32 s14, 0xfd80
	s_lshr_b32 s10, s14, 7
	s_and_b32 s14, s12, 3
	v_add_u32_e32 v20, s10, v112
	s_cmp_gt_u32 s14, 1
	v_ashrrev_i32_e32 v21, 31, v20
	s_mov_b64 s[10:11], -1
	s_cbranch_scc0 .LBB0_798
	s_lshl_b32 s10, s14, 5
	v_lshlrev_b64 v[34:35], 6, v[20:21]
	s_sub_i32 s90, s10, 64
	v_lshl_add_u64 v[34:35], v[34:35], 0, s[90:91]
	v_or_b32_e32 v7, v34, v26
	v_mad_u64_u32 v[36:37], s[10:11], v7, s95, v[30:31]
	v_mul_f32_e32 v7, v16, v6
	v_mad_i32_i24 v37, v35, s95, v37
	v_cvt_pk_bf16_f32 v7, v7, s0
	s_mov_b32 s10, 0x40000
	global_store_short v[36:37], v7, off sc1
	v_mul_f32_e32 v7, v18, v6
	v_add_co_u32_e32 v34, vcc, s10, v36
	v_cvt_pk_bf16_f32 v7, v7, s0
	s_nop 0
	v_addc_co_u32_e32 v35, vcc, 0, v37, vcc
	s_movk_i32 s10, 0x4000
	global_store_short v[34:35], v7, off offset:2048 sc1
	v_mul_f32_e32 v7, v19, v6
	v_add_co_u32_e32 v34, vcc, s10, v36
	v_cvt_pk_bf16_f32 v7, v7, s0
	s_nop 0
	v_addc_co_u32_e32 v35, vcc, 0, v37, vcc
	s_mov_b32 s10, 0x44000
	global_store_short v[34:35], v7, off offset:128 sc1
	v_mul_f32_e32 v7, v17, v6
	v_add_co_u32_e32 v34, vcc, s10, v36
	v_cvt_pk_bf16_f32 v7, v7, s0
	s_nop 0
	v_addc_co_u32_e32 v35, vcc, 0, v37, vcc
	s_mov_b32 s10, 0x8000
	global_store_short v[34:35], v7, off offset:2176 sc1
	v_mul_f32_e32 v7, v8, v6
	v_add_co_u32_e32 v34, vcc, s10, v36
	v_cvt_pk_bf16_f32 v7, v7, s0
	s_nop 0
	v_addc_co_u32_e32 v35, vcc, 0, v37, vcc
	s_mov_b32 s10, 0x48000
	global_store_short v[34:35], v7, off offset:256 sc1
	v_mul_f32_e32 v7, v10, v6
	v_add_co_u32_e32 v34, vcc, s10, v36
	v_cvt_pk_bf16_f32 v7, v7, s0
	s_nop 0
	v_addc_co_u32_e32 v35, vcc, 0, v37, vcc
	global_store_short v[34:35], v7, off offset:2304 sc1
	v_mul_f32_e32 v7, v11, v6
	v_add_co_u32_e32 v34, vcc, 0xc000, v36
	v_cvt_pk_bf16_f32 v7, v7, s0
	s_nop 0
	v_addc_co_u32_e32 v35, vcc, 0, v37, vcc
	global_store_short v[34:35], v7, off offset:384 sc1
	v_mul_f32_e32 v7, v9, v6
	v_add_co_u32_e32 v34, vcc, 0x4c000, v36
	v_cvt_pk_bf16_f32 v7, v7, s0
	s_nop 0
	v_addc_co_u32_e32 v35, vcc, 0, v37, vcc
	global_store_short v[34:35], v7, off offset:2432 sc1
	s_mov_b64 s[10:11], 0
.LBB0_798:
	s_andn2_b64 vcc, exec, s[10:11]
	s_cbranch_vccnz .LBB0_800
	s_movk_i32 s10, 0x2040
	v_mad_i64_i32 v[20:21], s[10:11], v20, s10, v[24:25]
	v_readlane_b32 s10, v254, 4
	v_readlane_b32 s11, v254, 5
	s_lshl_b32 s90, s14, 6
	v_mov_b32_e32 v38, v10
	v_mov_b64_e32 v[34:35], s[10:11]
	v_mad_u64_u32 v[34:35], s[10:11], v20, s47, v[34:35]
	v_mad_i32_i24 v35, v21, s47, v35
	v_lshl_add_u64 v[20:21], v[34:35], 0, s[90:91]
	v_lshlrev_b32_e32 v34, 1, v0
	v_mov_b32_e32 v35, v1
	v_lshl_add_u64 v[20:21], v[20:21], 0, v[34:35]
	v_mov_b32_e32 v34, v8
	v_mov_b32_e32 v35, v11
	v_mov_b32_e32 v39, v9
	v_pk_mul_f32 v[36:37], v[34:35], v[6:7] op_sel_hi:[1,0]
	v_pk_mul_f32 v[34:35], v[14:15], v[6:7] op_sel_hi:[1,0]
	v_pk_mul_f32 v[38:39], v[38:39], v[6:7] op_sel_hi:[1,0]
	v_pk_mul_f32 v[40:41], v[12:13], v[6:7] op_sel_hi:[1,0]
	v_cvt_pk_bf16_f32 v34, v34, v35
	v_cvt_pk_bf16_f32 v35, v36, v37
	v_cvt_pk_bf16_f32 v36, v40, v41
	v_cvt_pk_bf16_f32 v37, v38, v39
	global_store_dwordx4 v[20:21], v[34:37], off sc1

; __device__ __forceinline__ void store4bf(bf16_t* p, f32x4 v) { u32x2 w; w.x = cvt_pk_bf16(v[0], v[1]); w.y = cvt_pk_bf16(v[2], v[3]); *(u32x2*)p = w; }
; __device__ __forceinline__ void store8bf(bf16_t* p, f32x4 v0, f32x4 v1) { u32x4 w; w.x = cvt_pk_bf16(v0[0], v0[1]); w.y = cvt_pk_bf16(v0[2], v0[3]); w.z = cvt_pk_bf16(v1[0], v1[1]); w.w = cvt_pk_bf16(v1[2], v1[3]); *(u32x4*)p = w; }
;   __device__ __forceinline__ void group(int row, int c32, int fq, f32x4 v0, f32x4 v1) const {
;     ...
;     if (c32 < 768) {
;       if (c32 >= 576) return;
;       const int h = c32 / 96, part = (c32 - h * 96) >> 5; const float sc = rs * QSC_A;
;       bf16_t* p = qa + ((size_t)(b * 6 + h) * E + e) * 96 + part * 32 + fq * 4;
;       if (part < 2) store8bf(qa + ((size_t)(b * 6 + h) * E + e) * 96 + part * 32 + fq * 8, v0 * sc, v1 * sc);
;       else { const float2* rp = rope + pos_of_e(e) * 16 + fq * 4; f32x4 o0, o1;
; #pragma unroll
;         for (int j = 0; j < 4; ++j) { const float2 cs = rp[j]; o0[j] = (v0[j] * cs.x - v1[j] * cs.y) * sc; o1[j] = (v1[j] * cs.x + v0[j] * cs.y) * sc; }
;         store4bf(p, o0); store4bf(p + 16, o1); }
.LBB0_801:
	s_andn2_b64 vcc, exec, s[10:11]
	s_cbranch_vccnz .LBB0_781
	s_cmpk_gt_i32 s13, 0x1bf
	s_cbranch_scc1 .LBB0_781
	s_bitset1_b32 s13, 7
	s_mul_hi_i32 s10, s13, 0x2aaaaaab
	s_lshr_b32 s11, s10, 31
	s_ashr_i32 s10, s10, 4
	s_add_i32 s11, s10, s11
	s_mul_i32 s10, s11, 0xffffffa0
	v_add_u32_e32 v7, s11, v112
	s_movk_i32 s11, 0x2040
	v_mad_i64_i32 v[20:21], s[14:15], v7, s11, v[24:25]
	v_readlane_b32 s14, v254, 24
	v_readlane_b32 s15, v254, 25
	s_add_i32 s10, s10, s13
	s_ashr_i32 s11, s10, 31
	v_mov_b64_e32 v[34:35], s[14:15]
	v_mad_u64_u32 v[34:35], s[14:15], v20, s47, v[34:35]
	v_mad_i32_i24 v35, v21, s47, v35
	v_mul_f32_e32 v6, 0x3e16c740, v6
	v_lshl_add_u64 v[20:21], s[10:11], 1, v[34:35]
	s_cmp_gt_i32 s10, 63
	s_mov_b64 s[10:11], -1
	s_cbranch_scc0 .LBB0_805
	global_load_dwordx4 v[38:41], v[32:33], off offset:16
	global_load_dwordx4 v[42:45], v[32:33], off
	v_lshlrev_b32_e32 v34, 1, v26
	v_mov_b32_e32 v35, v1
	v_lshl_add_u64 v[34:35], v[20:21], 0, v[34:35]
	s_mov_b64 s[10:11], 0
	s_waitcnt vmcnt(1)
	v_mov_b32_e32 v46, v39
	s_waitcnt vmcnt(0)
	v_mov_b32_e32 v48, v42
	v_mov_b32_e32 v49, v45
	v_mov_b32_e32 v36, v43
	v_mov_b32_e32 v37, v44
	v_pk_mul_f32 v[48:49], v[18:19], v[48:49]
	v_mov_b32_e32 v50, v43
	v_pk_fma_f32 v[36:37], v[16:17], v[36:37], v[48:49]
	v_mov_b32_e32 v48, v18
	v_mov_b32_e32 v49, v17
	v_mov_b32_e32 v51, v45
	v_pk_mul_f32 v[48:49], v[48:49], v[50:51]
	v_mov_b32_e32 v17, v19
	v_mov_b32_e32 v43, v44
	v_pk_fma_f32 v[16:17], v[16:17], v[42:43], v[48:49] neg_lo:[0,0,1] neg_hi:[0,0,1]
	v_mov_b32_e32 v42, v10
	v_mov_b32_e32 v43, v9
	v_mov_b32_e32 v44, v39
	v_mov_b32_e32 v45, v41
	v_mov_b32_e32 v18, v38
	v_mov_b32_e32 v19, v41
	v_pk_mul_f32 v[42:43], v[42:43], v[44:45]
	v_mov_b32_e32 v44, v8
	v_mov_b32_e32 v45, v11
	v_mov_b32_e32 v39, v40
	v_mov_b32_e32 v47, v40
	v_pk_mul_f32 v[18:19], v[10:11], v[18:19]
	v_pk_fma_f32 v[38:39], v[44:45], v[38:39], v[42:43] neg_lo:[0,0,1] neg_hi:[0,0,1]
	v_pk_mul_f32 v[16:17], v[6:7], v[16:17] op_sel_hi:[0,1]
	v_pk_fma_f32 v[18:19], v[8:9], v[46:47], v[18:19]
	v_pk_mul_f32 v[38:39], v[6:7], v[38:39] op_sel_hi:[0,1]
	v_pk_mul_f32 v[36:37], v[6:7], v[36:37] op_sel_hi:[0,1]
	v_pk_mul_f32 v[18:19], v[6:7], v[18:19] op_sel_hi:[0,1]
	v_cvt_pk_bf16_f32 v16, v16, v17
	v_cvt_pk_bf16_f32 v17, v38, v39
	global_store_dwordx2 v[34:35], v[16:17], off sc1
	v_cvt_pk_bf16_f32 v16, v36, v37
	v_cvt_pk_bf16_f32 v17, v18, v19
	global_store_dwordx2 v[34:35], v[16:17], off offset:32 sc1
.LBB0_805:
	s_andn2_b64 vcc, exec, s[10:11]
	s_cbranch_vccnz .LBB0_781
	v_mov_b32_e32 v18, v8
	v_mov_b32_e32 v19, v11
	v_mov_b32_e32 v11, v9
	v_lshlrev_b32_e32 v16, 1, v0
	v_mov_b32_e32 v17, v1
	v_pk_mul_f32 v[18:19], v[18:19], v[6:7] op_sel_hi:[1,0]
	v_pk_mul_f32 v[14:15], v[14:15], v[6:7] op_sel_hi:[1,0]
	v_pk_mul_f32 v[10:11], v[10:11], v[6:7] op_sel_hi:[1,0]
	v_pk_mul_f32 v[8:9], v[12:13], v[6:7] op_sel_hi:[1,0]
	v_lshl_add_u64 v[16:17], v[20:21], 0, v[16:17]
	v_cvt_pk_bf16_f32 v6, v14, v15
	v_cvt_pk_bf16_f32 v7, v18, v19
	v_cvt_pk_bf16_f32 v8, v8, v9
	v_cvt_pk_bf16_f32 v9, v10, v11
	global_store_dwordx4 v[16:17], v[6:9], off sc1
	s_branch .LBB0_781

; template <class Epi, class Pre>
; __device__ __forceinline__ void meta_gemm(const bf16_t* __restrict__ A, int lda, const bf16_t* __restrict__ Bt, int ldb, int N, int K, Epi& epi, Pre pre) {
;     ...
;     const bf16_t* ap = A + (size_t)(NREAL + fr) * lda + wid * ks + fq * 8;
;     const bf16_t* bp = Bt + (size_t)(cb + fr) * ldb + wid * ks + fq * 8;
; #pragma unroll 4
;     for (int k0 = 0; k0 < ks; k0 += 32) {
;       const bf16x8 a = *(const bf16x8*)(ap + k0);
; #pragma unroll
;       for (int bj = 0; bj < 2; ++bj)
; #pragma unroll
;         for (int n = 0; n < 2; ++n) { const bf16x8 b = *(const bf16x8*)(bp + (size_t)(bj * 128 + n * 16) * ldb + k0); acc[bj][n] = __builtin_amdgcn_mfma_f32_16x16x32_bf16(b, a, acc[bj][n], 0, 0, 0); }
;     }
; #pragma unroll
;     for (int bj = 0; bj < 2; ++bj)
; #pragma unroll
;       for (int n = 0; n < 2; ++n)
; #pragma unroll
;         for (int j = 0; j < 4; ++j) part[(wid * 16 + (bj * 2 + n) * 4 + j) * 64 + lane] = acc[bj][n][j];
;     __syncthreads();
;     if (wid < 4) {
;       f32x4 v[2][2];
; #pragma unroll
;       for (int bj = 0; bj < 2; ++bj)
; #pragma unroll
;         for (int n = 0; n < 2; ++n)
; #pragma unroll
;           for (int j = 0; j < 4; ++j) { float s = 0.f;
; #pragma unroll
;             for (int w = 0; w < 8; ++w) s += part[(w * 16 + (bj * 2 + n) * 4 + j) * 64 + lane];
.LBB0_810:
	s_and_b32 s4, s1, 0x60
	s_and_b32 s10, s0, 0xffffff00
	s_or_b32 s9, s10, s4
	v_or_b32_e32 v6, s9, v110
	v_ashrrev_i32_e32 v7, 31, v6
	v_lshlrev_b64 v[6:7], 9, v[6:7]
	v_lshl_add_u64 v[18:19], v[22:23], 0, v[6:7]
	v_add_co_u32_e32 v10, vcc, 0x2000, v18
	s_mov_b32 s4, 0x10000
	s_nop 0
	v_addc_co_u32_e32 v11, vcc, 0, v19, vcc
	global_load_dwordx4 v[6:9], v[18:19], off
	v_add_co_u32_e32 v14, vcc, s4, v18
	global_load_dwordx4 v[10:13], v[10:11], off
	s_nop 0
	v_addc_co_u32_e32 v15, vcc, 0, v19, vcc
	v_add_co_u32_e32 v18, vcc, 0x12000, v18
	global_load_dwordx4 v[14:17], v[14:15], off
	s_nop 0
	v_addc_co_u32_e32 v19, vcc, 0, v19, vcc
	global_load_dwordx4 v[18:21], v[18:19], off
	s_waitcnt vmcnt(3)
	v_mfma_f32_16x16x32_bf16 v[6:9], v[6:9], v[2:5], 0
	s_waitcnt vmcnt(2)
	v_mfma_f32_16x16x32_bf16 v[10:13], v[10:13], v[2:5], 0
	s_waitcnt vmcnt(1)
	v_mfma_f32_16x16x32_bf16 v[14:17], v[14:17], v[2:5], 0
	s_waitcnt vmcnt(0)
	v_mfma_f32_16x16x32_bf16 v[18:21], v[18:21], v[2:5], 0
	s_nop 1
	ds_write2st64_b32 v113, v6, v7 offset1:1
	ds_write2st64_b32 v113, v8, v9 offset0:2 offset1:3
	ds_write2st64_b32 v113, v10, v11 offset0:4 offset1:5
	ds_write2st64_b32 v113, v12, v13 offset0:6 offset1:7
	ds_write2st64_b32 v113, v14, v15 offset0:8 offset1:9
	ds_write2st64_b32 v113, v16, v17 offset0:10 offset1:11
	ds_write2st64_b32 v113, v18, v19 offset0:12 offset1:13
	ds_write2st64_b32 v113, v20, v21 offset0:14 offset1:15
	s_waitcnt lgkmcnt(0)
	s_barrier
	s_and_saveexec_b64 s[4:5], s[2:3]
	s_cbranch_execz .LBB0_809
	ds_read2st64_b32 v[36:37], v111 offset1:1
	ds_read2st64_b32 v[38:39], v111 offset0:16 offset1:17
	ds_read2st64_b32 v[40:41], v111 offset0:32 offset1:33
	ds_read2st64_b32 v[42:43], v111 offset0:48 offset1:49
	ds_read2st64_b32 v[44:45], v111 offset0:64 offset1:65
	ds_read2st64_b32 v[46:47], v111 offset0:80 offset1:81
	ds_read2st64_b32 v[48:49], v111 offset0:96 offset1:97
	ds_read2st64_b32 v[50:51], v111 offset0:112 offset1:113
	ds_read2st64_b32 v[20:21], v111 offset0:2 offset1:3
	ds_read2st64_b32 v[18:19], v111 offset0:18 offset1:19
	ds_read2st64_b32 v[16:17], v111 offset0:34 offset1:35
	ds_read2st64_b32 v[14:15], v111 offset0:50 offset1:51
	ds_read2st64_b32 v[12:13], v111 offset0:66 offset1:67
	ds_read2st64_b32 v[10:11], v111 offset0:82 offset1:83
	ds_read2st64_b32 v[8:9], v111 offset0:98 offset1:99
	ds_read2st64_b32 v[6:7], v111 offset0:114 offset1:115
	ds_read2st64_b32 v[52:53], v111 offset0:4 offset1:5
	ds_read2st64_b32 v[54:55], v111 offset0:20 offset1:21
	ds_read2st64_b32 v[56:57], v111 offset0:36 offset1:37
	ds_read2st64_b32 v[58:59], v111 offset0:52 offset1:53
	ds_read2st64_b32 v[60:61], v111 offset0:68 offset1:69
	ds_read2st64_b32 v[62:63], v111 offset0:84 offset1:85
	ds_read2st64_b32 v[64:65], v111 offset0:100 offset1:101
	ds_read2st64_b32 v[66:67], v111 offset0:116 offset1:117
	s_waitcnt lgkmcnt(14)
	v_mov_b32_e32 v34, v36
	s_waitcnt lgkmcnt(7)
	v_mov_b32_e32 v35, v53
	v_pk_add_f32 v[34:35], v[34:35], 0 op_sel_hi:[1,0]
	v_mov_b32_e32 v68, v38
	s_waitcnt lgkmcnt(6)
	v_mov_b32_e32 v69, v55
	v_pk_add_f32 v[34:35], v[34:35], v[68:69]
	v_mov_b32_e32 v68, v40
	s_waitcnt lgkmcnt(5)
	v_mov_b32_e32 v69, v57
	v_pk_add_f32 v[34:35], v[34:35], v[68:69]
	v_mov_b32_e32 v68, v42
	s_waitcnt lgkmcnt(4)
	v_mov_b32_e32 v69, v59
	v_pk_add_f32 v[34:35], v[34:35], v[68:69]
	v_mov_b32_e32 v68, v44
	s_waitcnt lgkmcnt(3)
	v_mov_b32_e32 v69, v61
	v_pk_add_f32 v[34:35], v[34:35], v[68:69]
	v_mov_b32_e32 v68, v46
	s_waitcnt lgkmcnt(2)
	v_mov_b32_e32 v69, v63
	v_mov_b32_e32 v53, v37
	v_pk_add_f32 v[34:35], v[34:35], v[68:69]
	v_mov_b32_e32 v68, v48
	s_waitcnt lgkmcnt(1)
	v_mov_b32_e32 v69, v65
	v_pk_add_f32 v[36:37], v[52:53], 0 op_sel_hi:[1,0]
	v_mov_b32_e32 v55, v39
	v_pk_add_f32 v[34:35], v[34:35], v[68:69]
	v_mov_b32_e32 v68, v50
	s_waitcnt lgkmcnt(0)
	v_mov_b32_e32 v69, v67
	v_pk_add_f32 v[36:37], v[36:37], v[54:55]
	v_mov_b32_e32 v57, v41
	v_mov_b32_e32 v59, v43
	v_mov_b32_e32 v61, v45
	v_mov_b32_e32 v63, v47
	v_mov_b32_e32 v65, v49
	v_mov_b32_e32 v67, v51
	ds_read2st64_b32 v[38:39], v111 offset0:6 offset1:7
	ds_read2st64_b32 v[40:41], v111 offset0:22 offset1:23
	ds_read2st64_b32 v[42:43], v111 offset0:38 offset1:39
	ds_read2st64_b32 v[44:45], v111 offset0:54 offset1:55
	ds_read2st64_b32 v[46:47], v111 offset0:70 offset1:71
	ds_read2st64_b32 v[48:49], v111 offset0:86 offset1:87
	ds_read2st64_b32 v[50:51], v111 offset0:102 offset1:103
	ds_read2st64_b32 v[52:53], v111 offset0:118 offset1:119
	v_mov_b32_e32 v54, v20
	s_waitcnt lgkmcnt(7)
	v_mov_b32_e32 v55, v39
	v_pk_add_f32 v[36:37], v[36:37], v[56:57]
	v_pk_add_f32 v[54:55], v[54:55], 0 op_sel_hi:[1,0]
	v_mov_b32_e32 v56, v18
	s_waitcnt lgkmcnt(6)
	v_mov_b32_e32 v57, v41
	v_pk_add_f32 v[54:55], v[54:55], v[56:57]
	v_mov_b32_e32 v56, v16
	s_waitcnt lgkmcnt(5)
	v_mov_b32_e32 v57, v43
	v_pk_add_f32 v[54:55], v[54:55], v[56:57]
	v_mov_b32_e32 v56, v14
	s_waitcnt lgkmcnt(4)
	v_mov_b32_e32 v57, v45
	v_pk_add_f32 v[54:55], v[54:55], v[56:57]
	v_mov_b32_e32 v56, v12
	s_waitcnt lgkmcnt(3)
	v_mov_b32_e32 v57, v47
	v_pk_add_f32 v[54:55], v[54:55], v[56:57]
	v_mov_b32_e32 v56, v10
	s_waitcnt lgkmcnt(2)
	v_mov_b32_e32 v57, v49
	v_pk_add_f32 v[54:55], v[54:55], v[56:57]
	v_mov_b32_e32 v56, v8
	s_waitcnt lgkmcnt(1)
	v_mov_b32_e32 v57, v51
	v_pk_add_f32 v[34:35], v[34:35], v[68:69]
	v_pk_add_f32 v[54:55], v[54:55], v[56:57]
	v_mov_b32_e32 v56, v6
	s_waitcnt lgkmcnt(0)
	v_mov_b32_e32 v57, v53
	v_mov_b32_e32 v53, v7
	ds_read2st64_b32 v[102:103], v111 offset0:8 offset1:9
	ds_read2st64_b32 v[100:101], v111 offset0:24 offset1:25
	ds_read2st64_b32 v[68:69], v111 offset0:10 offset1:11
	ds_read2st64_b32 v[6:7], v111 offset0:12 offset1:13
	v_pk_add_f32 v[36:37], v[36:37], v[58:59]
	s_waitcnt lgkmcnt(3)
; __device__ __forceinline__ float bf2f(unsigned short b) { return __uint_as_float(((unsigned)b) << 16); }
; template <class Epi, class Pre>
; __device__ __forceinline__ void meta_gemm(const bf16_t* __restrict__ A, int lda, const bf16_t* __restrict__ Bt, int ldb, int N, int K, Epi& epi, Pre pre) {
;     ...
;           for (int j = 0; j < 4; ++j) { float s = 0.f;
; #pragma unroll
;             for (int w = 0; w < 8; ++w) s += part[(w * 16 + (bj * 2 + n) * 4 + j) * 64 + lane];
;             v[bj][n][j] = s; }
; __device__ __forceinline__ void up_phase(const bf16_t* cqkv, const bf16_t* wqb, const bf16_t* wkvb, EpiUp& epi) {
;     ...
;     auto prekv = [&](int fr, int fq) { const bf16_t* p = cqkv + (size_t)(NREAL + fr) * 512 + 256 + fq * 32; float ss = 0.f;
; #pragma unroll
;       for (int c = 0; c < 4; ++c) { const u32x4 w = *(const u32x4*)(p + c * 8);
; #pragma unroll
;         for (int q = 0; q < 4; ++q) { const float a = bf2f(w[q] & 0xffff), b = bf2f(w[q] >> 16); ss += a * a + b * b; } }
	v_mov_b32_e32 v85, v103
	v_pk_add_f32 v[36:37], v[36:37], v[60:61]
	ds_read2st64_b32 v[98:99], v111 offset0:40 offset1:41
	v_pk_add_f32 v[36:37], v[36:37], v[62:63]
	s_waitcnt lgkmcnt(1)
	v_mov_b32_e32 v84, v6
	v_pk_add_f32 v[36:37], v[36:37], v[64:65]
	v_mov_b32_e32 v103, v7
	v_pk_add_f32 v[36:37], v[36:37], v[66:67]
	ds_read2st64_b32 v[66:67], v111 offset0:26 offset1:27
	ds_read2st64_b32 v[6:7], v111 offset0:28 offset1:29
	v_mov_b32_e32 v83, v101
	ds_read2st64_b32 v[96:97], v111 offset0:56 offset1:57
	ds_read2st64_b32 v[64:65], v111 offset0:42 offset1:43
	s_waitcnt lgkmcnt(4)
	v_mov_b32_e32 v81, v99
	s_waitcnt lgkmcnt(2)
	v_mov_b32_e32 v82, v6
	v_mov_b32_e32 v101, v7
	ds_read2st64_b32 v[6:7], v111 offset0:44 offset1:45
	ds_read2st64_b32 v[94:95], v111 offset0:72 offset1:73
	ds_read2st64_b32 v[62:63], v111 offset0:58 offset1:59
	s_waitcnt lgkmcnt(4)
	v_mov_b32_e32 v79, v97
	ds_read2st64_b32 v[92:93], v111 offset0:88 offset1:89
	ds_read2st64_b32 v[60:61], v111 offset0:74 offset1:75
	s_waitcnt lgkmcnt(4)
	v_mov_b32_e32 v80, v6
	v_mov_b32_e32 v99, v7
	ds_read2st64_b32 v[6:7], v111 offset0:60 offset1:61
	s_waitcnt lgkmcnt(4)
	v_mov_b32_e32 v77, v95
	ds_read2st64_b32 v[90:91], v111 offset0:104 offset1:105
	ds_read2st64_b32 v[58:59], v111 offset0:90 offset1:91
	v_pk_add_f32 v[86:87], v[54:55], v[56:57]
	s_waitcnt lgkmcnt(2)
	v_mov_b32_e32 v78, v6
	v_mov_b32_e32 v97, v7
	ds_read2st64_b32 v[6:7], v111 offset0:76 offset1:77
	v_mov_b32_e32 v75, v93
	ds_read2st64_b32 v[88:89], v111 offset0:120 offset1:121
	ds_read2st64_b32 v[56:57], v111 offset0:106 offset1:107
	ds_read2st64_b32 v[54:55], v111 offset0:122 offset1:123
	s_waitcnt lgkmcnt(3)
	v_mov_b32_e32 v76, v6
	v_mov_b32_e32 v95, v7
	ds_read2st64_b32 v[6:7], v111 offset0:92 offset1:93
	v_mov_b32_e32 v73, v91
	v_mov_b32_e32 v39, v21
	v_pk_add_f32 v[20:21], v[38:39], 0 op_sel_hi:[1,0]
	v_mov_b32_e32 v41, v19
	s_waitcnt lgkmcnt(0)
	v_mov_b32_e32 v74, v6
	v_mov_b32_e32 v93, v7
	ds_read2st64_b32 v[6:7], v111 offset0:108 offset1:109
	v_pk_add_f32 v[18:19], v[20:21], v[40:41]
	v_mov_b32_e32 v43, v17
	v_pk_add_f32 v[16:17], v[18:19], v[42:43]
	v_mov_b32_e32 v45, v15
	s_waitcnt lgkmcnt(0)
	v_mov_b32_e32 v72, v6
	v_mov_b32_e32 v91, v7
	ds_read2st64_b32 v[6:7], v111 offset0:124 offset1:125
	v_mov_b32_e32 v71, v89
	v_pk_add_f32 v[14:15], v[16:17], v[44:45]
	v_mov_b32_e32 v47, v13
	v_pk_add_f32 v[12:13], v[14:15], v[46:47]
	s_waitcnt lgkmcnt(0)
	v_mov_b32_e32 v70, v6
	v_mov_b32_e32 v89, v7
	ds_read2st64_b32 v[6:7], v111 offset0:14 offset1:15
	v_mov_b32_e32 v49, v11
	v_pk_add_f32 v[10:11], v[12:13], v[48:49]
	v_mov_b32_e32 v51, v9
	v_pk_add_f32 v[8:9], v[10:11], v[50:51]
	v_mov_b32_e32 v51, v67
	v_pk_add_f32 v[104:105], v[8:9], v[52:53]
	v_mov_b32_e32 v53, v69
	s_waitcnt lgkmcnt(0)
	v_mov_b32_e32 v52, v6
	v_mov_b32_e32 v69, v7
	ds_read2st64_b32 v[6:7], v111 offset0:30 offset1:31
	v_mov_b32_e32 v49, v65
	v_mov_b32_e32 v108, v34
	v_mov_b32_e32 v109, v37
	v_mov_b32_e32 v106, v36
	s_waitcnt lgkmcnt(0)
	v_mov_b32_e32 v50, v6
	v_mov_b32_e32 v67, v7
	ds_read2st64_b32 v[6:7], v111 offset0:46 offset1:47
	v_mov_b32_e32 v47, v63
	v_mov_b32_e32 v107, v35
	s_mov_b64 s[6:7], -1
	s_cmp_gt_i32 s8, -1
	s_waitcnt lgkmcnt(0)
	v_mov_b32_e32 v48, v6
	v_mov_b32_e32 v65, v7
	ds_read2st64_b32 v[6:7], v111 offset0:62 offset1:63
	v_mov_b32_e32 v45, v61
	s_waitcnt lgkmcnt(0)
	v_mov_b32_e32 v46, v6
	v_mov_b32_e32 v63, v7
	ds_read2st64_b32 v[6:7], v111 offset0:78 offset1:79
	v_mov_b32_e32 v43, v59
	s_waitcnt lgkmcnt(0)
	v_mov_b32_e32 v44, v6
	v_mov_b32_e32 v61, v7
	ds_read2st64_b32 v[6:7], v111 offset0:94 offset1:95
	v_mov_b32_e32 v41, v57
	s_waitcnt lgkmcnt(0)
	v_mov_b32_e32 v42, v6
	v_mov_b32_e32 v59, v7
	ds_read2st64_b32 v[6:7], v111 offset0:110 offset1:111
	v_mov_b32_e32 v39, v55
	s_waitcnt lgkmcnt(0)
	v_mov_b32_e32 v40, v6
	v_mov_b32_e32 v57, v7
	ds_read2st64_b32 v[6:7], v111 offset0:126 offset1:127
	s_waitcnt lgkmcnt(0)
	v_mov_b32_e32 v38, v6
	v_mov_b32_e32 v55, v7
	global_load_dwordx4 v[6:9], v[28:29], off offset:48
	global_load_dwordx4 v[10:13], v[28:29], off offset:32
	global_load_dwordx4 v[14:17], v[28:29], off offset:16
	global_load_dwordx4 v[18:21], v[28:29], off
	s_waitcnt vmcnt(0)
; __device__ __forceinline__ float bf2f(unsigned short b) { return __uint_as_float(((unsigned)b) << 16); }
; __device__ __forceinline__ unsigned short f2bf(float f) { return (unsigned short)(cvt_pk_bf16(f, f) & 0xffffu); }
; __device__ __forceinline__ void store8bf(bf16_t* p, f32x4 v0, f32x4 v1) { u32x4 w; w.x = cvt_pk_bf16(v0[0], v0[1]); w.y = cvt_pk_bf16(v0[2], v0[3]); w.z = cvt_pk_bf16(v1[0], v1[1]); w.w = cvt_pk_bf16(v1[2], v1[3]); *(u32x4*)p = w; }
; template <int M> __device__ __forceinline__ float shx(float v) { return __builtin_bit_cast(float, __builtin_amdgcn_ds_swizzle(__builtin_bit_cast(int, v), (M << 10) | 0x1f)); }
; __device__ __forceinline__ float sum32(float v) { return v + xhalf(v); }
;   __device__ __forceinline__ void group(int row, int c32, int fq, f32x4 v0, f32x4 v1) const {
;     ...
;     } else {
;       const int cc = c32 - 768, h = cc >> 7, part = (cc & 127) >> 5;
;       if (part < 2) store8bf(ka + ((size_t)(b * 6 + h) * E + e) * 96 + part * 32 + fq * 8, v0 * rs, v1 * rs);
;       else { bf16_t* p = vta + ((size_t)(b * 6 + h) * 64 + (part - 2) * 32 + fq * 4) * E + e;
; #pragma unroll
;         for (int j = 0; j < 4; ++j) { p[(size_t)j * E] = f2bf(v0[j] * rs); p[(size_t)(j + 16) * E] = f2bf(v1[j] * rs); } }
; __device__ __forceinline__ void up_phase(const bf16_t* cqkv, const bf16_t* wqb, const bf16_t* wkvb, EpiUp& epi) {
;     ...
;         for (int q = 0; q < 4; ++q) { const float a = bf2f(w[q] & 0xffff), b = bf2f(w[q] >> 16); ss += a * a + b * b; } }
;       ss += shx<16>(ss); ss = sum32(ss); epi.rs_direct = rsqrtf(ss * (1.0f / 128.0f) + 1e-6f); };
	v_lshlrev_b32_e32 v114, 16, v18
	v_and_b32_e32 v18, 0xffff0000, v18
	v_mul_f32_e32 v18, v18, v18
	v_fmac_f32_e32 v18, v114, v114
	v_lshlrev_b32_e32 v114, 16, v19
	v_and_b32_e32 v19, 0xffff0000, v19
	v_mul_f32_e32 v19, v19, v19
	v_fmac_f32_e32 v19, v114, v114
	v_add_f32_e32 v18, v18, v19
	v_lshlrev_b32_e32 v19, 16, v20
	v_and_b32_e32 v20, 0xffff0000, v20
	v_mul_f32_e32 v20, v20, v20
	v_fmac_f32_e32 v20, v19, v19
	v_add_f32_e32 v18, v20, v18
	v_and_b32_e32 v20, 0xffff0000, v21
	v_lshlrev_b32_e32 v19, 16, v21
	v_mul_f32_e32 v20, v20, v20
	v_fmac_f32_e32 v20, v19, v19
	v_lshlrev_b32_e32 v19, 16, v14
	v_and_b32_e32 v14, 0xffff0000, v14
	v_mul_f32_e32 v14, v14, v14
	v_add_f32_e32 v18, v20, v18
	v_fmac_f32_e32 v14, v19, v19
	v_add_f32_e32 v14, v14, v18
	v_lshlrev_b32_e32 v18, 16, v15
	v_and_b32_e32 v15, 0xffff0000, v15
	v_mul_f32_e32 v15, v15, v15
	v_fmac_f32_e32 v15, v18, v18
	v_add_f32_e32 v14, v15, v14
	v_lshlrev_b32_e32 v15, 16, v16
	v_and_b32_e32 v16, 0xffff0000, v16
	v_mul_f32_e32 v16, v16, v16
	v_fmac_f32_e32 v16, v15, v15
	v_add_f32_e32 v14, v16, v14
	v_and_b32_e32 v16, 0xffff0000, v17
	v_lshlrev_b32_e32 v15, 16, v17
	v_mul_f32_e32 v16, v16, v16
	v_fmac_f32_e32 v16, v15, v15
	v_add_f32_e32 v16, v16, v14
	v_lshlrev_b32_e32 v15, 16, v11
	v_lshlrev_b32_e32 v14, 16, v10
	v_and_b32_e32 v11, 0xffff0000, v11
	v_and_b32_e32 v10, 0xffff0000, v10
	v_pk_mul_f32 v[10:11], v[10:11], v[10:11]
	s_nop 0
	v_pk_fma_f32 v[10:11], v[14:15], v[14:15], v[10:11]
	s_nop 0
	v_add_f32_e32 v10, v10, v16
	v_add_f32_e32 v14, v11, v10
	v_lshlrev_b32_e32 v11, 16, v13
	v_lshlrev_b32_e32 v10, 16, v12
	v_and_b32_e32 v13, 0xffff0000, v13
	v_and_b32_e32 v12, 0xffff0000, v12
	v_pk_mul_f32 v[12:13], v[12:13], v[12:13]
	s_nop 0
	v_pk_fma_f32 v[10:11], v[10:11], v[10:11], v[12:13]
	s_nop 0
	v_add_f32_e32 v10, v10, v14
	v_add_f32_e32 v12, v11, v10
	v_lshlrev_b32_e32 v11, 16, v7
	v_lshlrev_b32_e32 v10, 16, v6
	v_and_b32_e32 v7, 0xffff0000, v7
	v_and_b32_e32 v6, 0xffff0000, v6
	v_pk_mul_f32 v[6:7], v[6:7], v[6:7]
	s_nop 0
	v_pk_fma_f32 v[6:7], v[10:11], v[10:11], v[6:7]
	s_nop 0
	v_add_f32_e32 v6, v6, v12
	v_add_f32_e32 v10, v7, v6
	v_lshlrev_b32_e32 v7, 16, v9
	v_lshlrev_b32_e32 v6, 16, v8
	v_and_b32_e32 v9, 0xffff0000, v9
	v_and_b32_e32 v8, 0xffff0000, v8
	v_pk_mul_f32 v[8:9], v[8:9], v[8:9]
	s_nop 0
	v_pk_fma_f32 v[6:7], v[6:7], v[6:7], v[8:9]
	s_nop 0
	v_add_f32_e32 v6, v6, v10
	v_add_f32_e32 v6, v7, v6
	ds_swizzle_b32 v7, v6 offset:swizzle(SWAP,16)
	s_waitcnt lgkmcnt(0)
	v_add_f32_e32 v6, v6, v7
	v_mov_b32_e32 v7, v210
	s_nop 0
	v_lshlrev_b32_e32 v7, 2, v7
	v_xor_b32_e32 v7, 0x80, v7
	ds_bpermute_b32 v7, v7, v6
	s_waitcnt lgkmcnt(0)
	v_add_f32_e32 v6, v6, v7
	v_fmamk_f32 v6, v6, 0x3c000000, v154
	v_cmp_gt_f32_e32 vcc, s46, v6
	v_mul_f32_e32 v7, 0x4b800000, v6
	s_nop 0
	v_cndmask_b32_e32 v6, v6, v7, vcc
	v_rsq_f32_e32 v6, v6
	s_nop 0
	v_mul_f32_e32 v7, 0x45800000, v6
	v_cndmask_b32_e32 v6, v6, v7, vcc
	s_cbranch_scc0 .LBB0_817
	s_lshr_b32 s6, s10, 7
	s_and_b32 s10, s8, 3
	v_add_u32_e32 v8, s6, v112
	s_cmp_gt_u32 s10, 1
	v_ashrrev_i32_e32 v9, 31, v8
	s_mov_b64 s[6:7], -1
	s_cbranch_scc0 .LBB0_814
	s_lshl_b32 s6, s10, 5
	v_lshlrev_b64 v[10:11], 6, v[8:9]
	s_sub_i32 s90, s6, 64
	v_lshl_add_u64 v[10:11], v[10:11], 0, s[90:91]
	v_or_b32_e32 v7, v10, v26
	v_mad_u64_u32 v[12:13], s[6:7], v7, s95, v[30:31]
	v_mul_f32_e32 v7, v34, v6
	v_mad_i32_i24 v13, v11, s95, v13
	v_cvt_pk_bf16_f32 v7, v7, s0
	s_mov_b32 s6, 0x40000
	global_store_short v[12:13], v7, off sc1
	v_mul_f32_e32 v7, v36, v6
	v_add_co_u32_e32 v10, vcc, s6, v12
	v_cvt_pk_bf16_f32 v7, v7, s0
	s_nop 0
	v_addc_co_u32_e32 v11, vcc, 0, v13, vcc
	s_movk_i32 s6, 0x4000
	global_store_short v[10:11], v7, off offset:2048 sc1
	v_mul_f32_e32 v7, v37, v6
	v_add_co_u32_e32 v10, vcc, s6, v12
	v_cvt_pk_bf16_f32 v7, v7, s0
	s_nop 0
	v_addc_co_u32_e32 v11, vcc, 0, v13, vcc
	s_mov_b32 s6, 0x44000
	global_store_short v[10:11], v7, off offset:128 sc1
	v_mul_f32_e32 v7, v35, v6
	v_add_co_u32_e32 v10, vcc, s6, v12
	v_cvt_pk_bf16_f32 v7, v7, s0
	s_nop 0
	v_addc_co_u32_e32 v11, vcc, 0, v13, vcc
	s_mov_b32 s6, 0x8000
	global_store_short v[10:11], v7, off offset:2176 sc1
	v_mul_f32_e32 v7, v86, v6
	v_add_co_u32_e32 v10, vcc, s6, v12
	v_cvt_pk_bf16_f32 v7, v7, s0
	s_nop 0
	v_addc_co_u32_e32 v11, vcc, 0, v13, vcc
	s_mov_b32 s6, 0x48000
	global_store_short v[10:11], v7, off offset:256 sc1
	v_mul_f32_e32 v7, v104, v6
	v_add_co_u32_e32 v10, vcc, s6, v12
	v_cvt_pk_bf16_f32 v7, v7, s0
	s_nop 0
	v_addc_co_u32_e32 v11, vcc, 0, v13, vcc
	global_store_short v[10:11], v7, off offset:2304 sc1
	v_mul_f32_e32 v7, v105, v6
	v_add_co_u32_e32 v10, vcc, 0xc000, v12
	v_cvt_pk_bf16_f32 v7, v7, s0
	s_nop 0
	v_addc_co_u32_e32 v11, vcc, 0, v13, vcc
	global_store_short v[10:11], v7, off offset:384 sc1
	v_mul_f32_e32 v7, v87, v6
	v_add_co_u32_e32 v10, vcc, 0x4c000, v12
	v_cvt_pk_bf16_f32 v7, v7, s0
	s_nop 0
	v_addc_co_u32_e32 v11, vcc, 0, v13, vcc
	global_store_short v[10:11], v7, off offset:2432 sc1
	s_mov_b64 s[6:7], 0
.LBB0_814:
	s_andn2_b64 vcc, exec, s[6:7]
	s_cbranch_vccnz .LBB0_816
	s_movk_i32 s6, 0x2040
	v_mad_i64_i32 v[8:9], s[6:7], v8, s6, v[24:25]
	v_readlane_b32 s6, v254, 4
	v_readlane_b32 s7, v254, 5
	s_lshl_b32 s90, s10, 6
	v_mov_b32_e32 v14, v104
	v_mov_b64_e32 v[10:11], s[6:7]
	v_mad_u64_u32 v[10:11], s[6:7], v8, s47, v[10:11]
	v_mad_i32_i24 v11, v9, s47, v11
	v_lshl_add_u64 v[8:9], v[10:11], 0, s[90:91]
	v_lshlrev_b32_e32 v10, 1, v0
	v_mov_b32_e32 v11, v1
	v_lshl_add_u64 v[12:13], v[8:9], 0, v[10:11]
	v_mov_b32_e32 v8, v86
	v_mov_b32_e32 v9, v105
	v_mov_b32_e32 v15, v87
	v_pk_mul_f32 v[10:11], v[8:9], v[6:7] op_sel_hi:[1,0]
	v_pk_mul_f32 v[8:9], v[108:109], v[6:7] op_sel_hi:[1,0]
	v_pk_mul_f32 v[14:15], v[14:15], v[6:7] op_sel_hi:[1,0]
	v_pk_mul_f32 v[16:17], v[106:107], v[6:7] op_sel_hi:[1,0]
	v_cvt_pk_bf16_f32 v8, v8, v9
	v_cvt_pk_bf16_f32 v9, v10, v11
	v_cvt_pk_bf16_f32 v10, v16, v17
	v_cvt_pk_bf16_f32 v11, v14, v15
	global_store_dwordx4 v[12:13], v[8:11], off sc1

; __device__ __forceinline__ void store4bf(bf16_t* p, f32x4 v) { u32x2 w; w.x = cvt_pk_bf16(v[0], v[1]); w.y = cvt_pk_bf16(v[2], v[3]); *(u32x2*)p = w; }
; __device__ __forceinline__ void store8bf(bf16_t* p, f32x4 v0, f32x4 v1) { u32x4 w; w.x = cvt_pk_bf16(v0[0], v0[1]); w.y = cvt_pk_bf16(v0[2], v0[3]); w.z = cvt_pk_bf16(v1[0], v1[1]); w.w = cvt_pk_bf16(v1[2], v1[3]); *(u32x4*)p = w; }
;   __device__ __forceinline__ void group(int row, int c32, int fq, f32x4 v0, f32x4 v1) const {
;     ...
;     if (c32 < 768) {
;       if (c32 >= 576) return;
;       const int h = c32 / 96, part = (c32 - h * 96) >> 5; const float sc = rs * QSC_A;
;       bf16_t* p = qa + ((size_t)(b * 6 + h) * E + e) * 96 + part * 32 + fq * 4;
;       if (part < 2) store8bf(qa + ((size_t)(b * 6 + h) * E + e) * 96 + part * 32 + fq * 8, v0 * sc, v1 * sc);
;       else { const float2* rp = rope + pos_of_e(e) * 16 + fq * 4; f32x4 o0, o1;
; #pragma unroll
;         for (int j = 0; j < 4; ++j) { const float2 cs = rp[j]; o0[j] = (v0[j] * cs.x - v1[j] * cs.y) * sc; o1[j] = (v1[j] * cs.x + v0[j] * cs.y) * sc; }
;         store4bf(p, o0); store4bf(p + 16, o1); }
.LBB0_817:
	s_andn2_b64 vcc, exec, s[6:7]
	s_cbranch_vccnz .LBB0_823
	s_cmpk_gt_i32 s9, 0xff3f
	s_cbranch_scc1 .LBB0_823
	s_add_i32 s6, s9, 0x300
	s_mul_hi_i32 s7, s6, 0x2aaaaaab
	s_lshr_b32 s10, s7, 31
	s_ashr_i32 s7, s7, 4
	s_add_i32 s7, s7, s10
	s_mul_i32 s10, s7, 0xffffffa0
	s_add_i32 s11, s10, s6
	v_add_u32_e32 v7, s7, v112
	s_movk_i32 s6, 0x2040
	v_mad_i64_i32 v[10:11], s[6:7], v7, s6, v[24:25]
	v_readlane_b32 s6, v254, 24
	v_readlane_b32 s7, v254, 25
	s_ashr_i32 s12, s9, 31
	v_mul_f32_e32 v8, 0x3e16c740, v6
	v_mov_b64_e32 v[12:13], s[6:7]
	v_mad_u64_u32 v[12:13], s[6:7], v10, s47, v[12:13]
	s_ashr_i32 s7, s10, 31
	s_add_u32 s6, s10, s9
	v_mad_i32_i24 v13, v11, s47, v13
	s_addc_u32 s7, s7, s12
	v_lshl_add_u64 v[10:11], s[6:7], 1, v[12:13]
	s_cmp_gt_i32 s11, 63
	s_mov_b64 s[6:7], -1
	s_cbranch_scc0 .LBB0_821
	global_load_dwordx4 v[16:19], v[32:33], off offset:16
	global_load_dwordx4 v[114:117], v[32:33], off
	v_lshlrev_b32_e32 v12, 1, v26
	v_mov_b32_e32 v13, v1
	v_lshl_add_u64 v[12:13], v[10:11], 0, v[12:13]
	s_mov_b64 s[6:7], 0
	s_waitcnt vmcnt(1)
	v_mov_b32_e32 v20, v17
	s_waitcnt vmcnt(0)
	v_mov_b32_e32 v118, v114
	v_mov_b32_e32 v119, v117
	v_mov_b32_e32 v14, v115
	v_mov_b32_e32 v15, v116
	v_pk_mul_f32 v[118:119], v[36:37], v[118:119]
	v_mov_b32_e32 v120, v115
	v_pk_fma_f32 v[14:15], v[34:35], v[14:15], v[118:119]
	v_mov_b32_e32 v118, v36
	v_mov_b32_e32 v119, v35
	v_mov_b32_e32 v121, v117
	v_mov_b32_e32 v35, v37
	v_mov_b32_e32 v36, v16
	v_mov_b32_e32 v37, v19
	v_mov_b32_e32 v21, v18
	v_pk_mul_f32 v[118:119], v[118:119], v[120:121]
	v_mov_b32_e32 v115, v116
	v_pk_mul_f32 v[36:37], v[104:105], v[36:37]
	v_pk_fma_f32 v[34:35], v[34:35], v[114:115], v[118:119] neg_lo:[0,0,1] neg_hi:[0,0,1]
	v_pk_fma_f32 v[20:21], v[86:87], v[20:21], v[36:37]
	v_mov_b32_e32 v36, v104
	v_mov_b32_e32 v37, v87
	v_mov_b32_e32 v114, v17
	v_mov_b32_e32 v115, v19
	v_pk_mul_f32 v[36:37], v[36:37], v[114:115]
	v_mov_b32_e32 v114, v86
	v_mov_b32_e32 v115, v105
	v_mov_b32_e32 v17, v18
	v_pk_fma_f32 v[16:17], v[114:115], v[16:17], v[36:37] neg_lo:[0,0,1] neg_hi:[0,0,1]
	v_pk_mul_f32 v[14:15], v[8:9], v[14:15] op_sel_hi:[0,1]
	v_pk_mul_f32 v[34:35], v[8:9], v[34:35] op_sel_hi:[0,1]
	v_pk_mul_f32 v[20:21], v[8:9], v[20:21] op_sel_hi:[0,1]
	v_pk_mul_f32 v[16:17], v[8:9], v[16:17] op_sel_hi:[0,1]
	v_cvt_pk_bf16_f32 v18, v34, v35
	v_cvt_pk_bf16_f32 v19, v16, v17
	v_cvt_pk_bf16_f32 v14, v14, v15
	v_cvt_pk_bf16_f32 v15, v20, v21
	global_store_dwordx2 v[12:13], v[18:19], off offset:1536 sc1
	global_store_dwordx2 v[12:13], v[14:15], off offset:1568 sc1
.LBB0_821:
	s_andn2_b64 vcc, exec, s[6:7]
	s_cbranch_vccnz .LBB0_823
	v_lshlrev_b32_e32 v12, 1, v0
	v_mov_b32_e32 v13, v1
	v_lshl_add_u64 v[12:13], v[10:11], 0, v[12:13]
	v_mov_b32_e32 v10, v86
	v_mov_b32_e32 v11, v105
	v_mov_b32_e32 v105, v87
	v_pk_mul_f32 v[10:11], v[10:11], v[8:9] op_sel_hi:[1,0]
	v_pk_mul_f32 v[14:15], v[108:109], v[8:9] op_sel_hi:[1,0]
	v_pk_mul_f32 v[16:17], v[104:105], v[8:9] op_sel_hi:[1,0]
	v_pk_mul_f32 v[18:19], v[106:107], v[8:9] op_sel_hi:[1,0]
	v_cvt_pk_bf16_f32 v8, v14, v15
	v_cvt_pk_bf16_f32 v9, v10, v11
	v_cvt_pk_bf16_f32 v10, v18, v19
	v_cvt_pk_bf16_f32 v11, v16, v17
	global_store_dwordx4 v[12:13], v[8:11], off offset:1536 sc1
; __device__ __forceinline__ unsigned short f2bf(float f) { return (unsigned short)(cvt_pk_bf16(f, f) & 0xffffu); }
; __device__ __forceinline__ void store8bf(bf16_t* p, f32x4 v0, f32x4 v1) { u32x4 w; w.x = cvt_pk_bf16(v0[0], v0[1]); w.y = cvt_pk_bf16(v0[2], v0[3]); w.z = cvt_pk_bf16(v1[0], v1[1]); w.w = cvt_pk_bf16(v1[2], v1[3]); *(u32x4*)p = w; }
;   __device__ __forceinline__ void group(int row, int c32, int fq, f32x4 v0, f32x4 v1) const {
;     ...
;     } else {
;       const int cc = c32 - 768, h = cc >> 7, part = (cc & 127) >> 5;
;       if (part < 2) store8bf(ka + ((size_t)(b * 6 + h) * E + e) * 96 + part * 32 + fq * 8, v0 * rs, v1 * rs);
;       else { bf16_t* p = vta + ((size_t)(b * 6 + h) * 64 + (part - 2) * 32 + fq * 4) * E + e;
; #pragma unroll
;         for (int j = 0; j < 4; ++j) { p[(size_t)j * E] = f2bf(v0[j] * rs); p[(size_t)(j + 16) * E] = f2bf(v1[j] * rs); } }
; template <class Epi, class Pre>
; __device__ __forceinline__ void meta_gemm(const bf16_t* __restrict__ A, int lda, const bf16_t* __restrict__ Bt, int ldb, int N, int K, Epi& epi, Pre pre) {
;     ...
;           for (int j = 0; j < 4; ++j) { float s = 0.f;
; #pragma unroll
;             for (int w = 0; w < 8; ++w) s += part[(w * 16 + (bj * 2 + n) * 4 + j) * 64 + lane];
;             v[bj][n][j] = s; }
.LBB0_823:
	s_nop 1
	v_pk_add_f32 v[8:9], v[102:103], 0 op_sel_hi:[1,0]
	v_pk_add_f32 v[10:11], v[52:53], 0 op_sel_hi:[1,0]
	v_pk_add_f32 v[8:9], v[8:9], v[100:101]
	v_pk_add_f32 v[10:11], v[10:11], v[50:51]
	v_pk_add_f32 v[8:9], v[8:9], v[98:99]
	v_pk_add_f32 v[10:11], v[10:11], v[48:49]
	v_pk_add_f32 v[8:9], v[8:9], v[96:97]
	v_pk_add_f32 v[10:11], v[10:11], v[46:47]
	v_pk_add_f32 v[8:9], v[8:9], v[94:95]
	v_pk_add_f32 v[10:11], v[10:11], v[44:45]
	v_pk_add_f32 v[8:9], v[8:9], v[92:93]
	v_pk_add_f32 v[10:11], v[10:11], v[42:43]
	v_pk_add_f32 v[8:9], v[8:9], v[90:91]
	v_pk_add_f32 v[10:11], v[10:11], v[40:41]
	v_pk_add_f32 v[16:17], v[8:9], v[88:89]
	v_pk_add_f32 v[8:9], v[84:85], 0 op_sel_hi:[1,0]
	v_pk_add_f32 v[10:11], v[10:11], v[38:39]
	v_pk_add_f32 v[8:9], v[8:9], v[82:83]
	v_mov_b32_e32 v14, v16
	v_pk_add_f32 v[8:9], v[8:9], v[80:81]
	v_mov_b32_e32 v13, v17
	v_pk_add_f32 v[8:9], v[8:9], v[78:79]
	s_cmpk_gt_i32 s9, 0xff7f
	v_pk_add_f32 v[8:9], v[8:9], v[76:77]
	s_mov_b64 s[6:7], -1
	v_pk_add_f32 v[8:9], v[8:9], v[74:75]
	s_nop 0
	v_pk_add_f32 v[8:9], v[8:9], v[72:73]
	s_nop 0
	v_pk_add_f32 v[18:19], v[8:9], v[70:71]
	v_pk_add_f32 v[8:9], v[68:69], 0 op_sel_hi:[1,0]
	v_mov_b32_e32 v15, v19
	v_pk_add_f32 v[8:9], v[8:9], v[66:67]
	v_mov_b32_e32 v12, v18
	v_pk_add_f32 v[8:9], v[8:9], v[64:65]
	s_nop 0
	v_pk_add_f32 v[8:9], v[8:9], v[62:63]
	s_nop 0
	v_pk_add_f32 v[8:9], v[8:9], v[60:61]
	s_nop 0
	v_pk_add_f32 v[8:9], v[8:9], v[58:59]
	s_nop 0
	v_pk_add_f32 v[8:9], v[8:9], v[56:57]
	s_nop 0
	v_pk_add_f32 v[8:9], v[8:9], v[54:55]
	s_cbranch_scc0 .LBB0_829
	s_lshr_b32 s6, s0, 7
	s_or_b32 s6, s6, 1
	s_and_b32 s10, s8, 3
	v_add_u32_e32 v20, s6, v112
	s_cmp_gt_u32 s10, 1
	v_ashrrev_i32_e32 v21, 31, v20
	s_mov_b64 s[6:7], -1
	s_cbranch_scc0 .LBB0_826
	s_lshl_b32 s6, s10, 5
	v_lshlrev_b64 v[34:35], 6, v[20:21]
	s_sub_i32 s90, s6, 64
	v_lshl_add_u64 v[34:35], v[34:35], 0, s[90:91]
	v_or_b32_e32 v7, v34, v26
	v_mad_u64_u32 v[36:37], s[6:7], v7, s95, v[30:31]
	v_mul_f32_e32 v7, v16, v6
	v_mad_i32_i24 v37, v35, s95, v37
	v_cvt_pk_bf16_f32 v7, v7, s0
	s_mov_b32 s6, 0x40000
	global_store_short v[36:37], v7, off sc1
	v_mul_f32_e32 v7, v18, v6
	v_add_co_u32_e32 v34, vcc, s6, v36
	v_cvt_pk_bf16_f32 v7, v7, s0
	s_nop 0
	v_addc_co_u32_e32 v35, vcc, 0, v37, vcc
	s_movk_i32 s6, 0x4000
	global_store_short v[34:35], v7, off offset:2048 sc1
	v_mul_f32_e32 v7, v19, v6
	v_add_co_u32_e32 v34, vcc, s6, v36
	v_cvt_pk_bf16_f32 v7, v7, s0
	s_nop 0
	v_addc_co_u32_e32 v35, vcc, 0, v37, vcc
	s_mov_b32 s6, 0x44000
	global_store_short v[34:35], v7, off offset:128 sc1
	v_mul_f32_e32 v7, v17, v6
	v_add_co_u32_e32 v34, vcc, s6, v36
	v_cvt_pk_bf16_f32 v7, v7, s0
	s_nop 0
	v_addc_co_u32_e32 v35, vcc, 0, v37, vcc
	s_mov_b32 s6, 0x8000
	global_store_short v[34:35], v7, off offset:2176 sc1
	v_mul_f32_e32 v7, v8, v6
	v_add_co_u32_e32 v34, vcc, s6, v36
	v_cvt_pk_bf16_f32 v7, v7, s0
	s_nop 0
	v_addc_co_u32_e32 v35, vcc, 0, v37, vcc
	s_mov_b32 s6, 0x48000
	global_store_short v[34:35], v7, off offset:256 sc1
	v_mul_f32_e32 v7, v10, v6
	v_add_co_u32_e32 v34, vcc, s6, v36
	v_cvt_pk_bf16_f32 v7, v7, s0
	s_nop 0
	v_addc_co_u32_e32 v35, vcc, 0, v37, vcc
	global_store_short v[34:35], v7, off offset:2304 sc1
	v_mul_f32_e32 v7, v11, v6
	v_add_co_u32_e32 v34, vcc, 0xc000, v36
	v_cvt_pk_bf16_f32 v7, v7, s0
	s_nop 0
	v_addc_co_u32_e32 v35, vcc, 0, v37, vcc
	global_store_short v[34:35], v7, off offset:384 sc1
	v_mul_f32_e32 v7, v9, v6
	v_add_co_u32_e32 v34, vcc, 0x4c000, v36
	v_cvt_pk_bf16_f32 v7, v7, s0
	s_nop 0
	v_addc_co_u32_e32 v35, vcc, 0, v37, vcc
	global_store_short v[34:35], v7, off offset:2432 sc1
	s_mov_b64 s[6:7], 0
.LBB0_826:
	s_andn2_b64 vcc, exec, s[6:7]
	s_cbranch_vccnz .LBB0_828
	s_movk_i32 s6, 0x2040
	v_mad_i64_i32 v[20:21], s[6:7], v20, s6, v[24:25]
	v_readlane_b32 s6, v254, 4
	v_readlane_b32 s7, v254, 5
	s_lshl_b32 s90, s10, 6
	v_mov_b32_e32 v38, v10
	v_mov_b64_e32 v[34:35], s[6:7]
	v_mad_u64_u32 v[34:35], s[6:7], v20, s47, v[34:35]
	v_mad_i32_i24 v35, v21, s47, v35
	v_lshl_add_u64 v[20:21], v[34:35], 0, s[90:91]
	v_lshlrev_b32_e32 v34, 1, v0
	v_mov_b32_e32 v35, v1
	v_lshl_add_u64 v[20:21], v[20:21], 0, v[34:35]
	v_mov_b32_e32 v34, v8
	v_mov_b32_e32 v35, v11
	v_mov_b32_e32 v39, v9
	v_pk_mul_f32 v[36:37], v[34:35], v[6:7] op_sel_hi:[1,0]
	v_pk_mul_f32 v[34:35], v[14:15], v[6:7] op_sel_hi:[1,0]
	v_pk_mul_f32 v[38:39], v[38:39], v[6:7] op_sel_hi:[1,0]
	v_pk_mul_f32 v[40:41], v[12:13], v[6:7] op_sel_hi:[1,0]
	v_cvt_pk_bf16_f32 v34, v34, v35
	v_cvt_pk_bf16_f32 v35, v36, v37
	v_cvt_pk_bf16_f32 v36, v40, v41
	v_cvt_pk_bf16_f32 v37, v38, v39
	global_store_dwordx4 v[20:21], v[34:37], off sc1

; __device__ __forceinline__ void store4bf(bf16_t* p, f32x4 v) { u32x2 w; w.x = cvt_pk_bf16(v[0], v[1]); w.y = cvt_pk_bf16(v[2], v[3]); *(u32x2*)p = w; }
; __device__ __forceinline__ void store8bf(bf16_t* p, f32x4 v0, f32x4 v1) { u32x4 w; w.x = cvt_pk_bf16(v0[0], v0[1]); w.y = cvt_pk_bf16(v0[2], v0[3]); w.z = cvt_pk_bf16(v1[0], v1[1]); w.w = cvt_pk_bf16(v1[2], v1[3]); *(u32x4*)p = w; }
;   __device__ __forceinline__ void group(int row, int c32, int fq, f32x4 v0, f32x4 v1) const {
;     ...
;     if (c32 < 768) {
;       if (c32 >= 576) return;
;       const int h = c32 / 96, part = (c32 - h * 96) >> 5; const float sc = rs * QSC_A;
;       bf16_t* p = qa + ((size_t)(b * 6 + h) * E + e) * 96 + part * 32 + fq * 4;
;       if (part < 2) store8bf(qa + ((size_t)(b * 6 + h) * E + e) * 96 + part * 32 + fq * 8, v0 * sc, v1 * sc);
;       else { const float2* rp = rope + pos_of_e(e) * 16 + fq * 4; f32x4 o0, o1;
; #pragma unroll
;         for (int j = 0; j < 4; ++j) { const float2 cs = rp[j]; o0[j] = (v0[j] * cs.x - v1[j] * cs.y) * sc; o1[j] = (v1[j] * cs.x + v0[j] * cs.y) * sc; }
;         store4bf(p, o0); store4bf(p + 16, o1); }
.LBB0_829:
	s_andn2_b64 vcc, exec, s[6:7]
	s_cbranch_vccnz .LBB0_809
	s_cmp_gt_u32 s9, 0xfffffebf
	s_cbranch_scc1 .LBB0_809
	s_add_i32 s6, s9, 0x380
	s_mul_hi_i32 s7, s6, 0x2aaaaaab
	s_lshr_b32 s10, s7, 31
	s_ashr_i32 s7, s7, 4
	s_add_i32 s7, s7, s10
	s_mul_i32 s10, s7, 0xffffffa0
	s_add_i32 s11, s10, s6
	v_add_u32_e32 v7, s7, v112
	s_movk_i32 s6, 0x2040
	v_mad_i64_i32 v[20:21], s[6:7], v7, s6, v[24:25]
	v_readlane_b32 s6, v254, 24
	v_readlane_b32 s7, v254, 25
	s_ashr_i32 s12, s9, 31
	v_mul_f32_e32 v6, 0x3e16c740, v6
	v_mov_b64_e32 v[34:35], s[6:7]
	v_mad_u64_u32 v[34:35], s[6:7], v20, s47, v[34:35]
	s_ashr_i32 s7, s10, 31
	s_add_u32 s6, s10, s9
	v_mad_i32_i24 v35, v21, s47, v35
	s_addc_u32 s7, s7, s12
	v_lshl_add_u64 v[20:21], s[6:7], 1, v[34:35]
	s_cmp_gt_i32 s11, 63
	s_mov_b64 s[6:7], -1
	s_cbranch_scc0 .LBB0_833
	global_load_dwordx4 v[38:41], v[32:33], off offset:16
	global_load_dwordx4 v[42:45], v[32:33], off
	v_lshlrev_b32_e32 v34, 1, v26
	v_mov_b32_e32 v35, v1
	v_lshl_add_u64 v[34:35], v[20:21], 0, v[34:35]
	s_mov_b64 s[6:7], 0
	s_waitcnt vmcnt(1)
	v_mov_b32_e32 v46, v39
	s_waitcnt vmcnt(0)
	v_mov_b32_e32 v48, v42
	v_mov_b32_e32 v49, v45
	v_mov_b32_e32 v36, v43
	v_mov_b32_e32 v37, v44
	v_pk_mul_f32 v[48:49], v[18:19], v[48:49]
	v_mov_b32_e32 v50, v43
	v_pk_fma_f32 v[36:37], v[16:17], v[36:37], v[48:49]
	v_mov_b32_e32 v48, v18
	v_mov_b32_e32 v49, v17
	v_mov_b32_e32 v51, v45
	v_pk_mul_f32 v[48:49], v[48:49], v[50:51]
	v_mov_b32_e32 v17, v19
	v_mov_b32_e32 v43, v44
	v_pk_fma_f32 v[16:17], v[16:17], v[42:43], v[48:49] neg_lo:[0,0,1] neg_hi:[0,0,1]
	v_mov_b32_e32 v42, v10
	v_mov_b32_e32 v43, v9
	v_mov_b32_e32 v44, v39
	v_mov_b32_e32 v45, v41
	v_mov_b32_e32 v18, v38
	v_mov_b32_e32 v19, v41
	v_pk_mul_f32 v[42:43], v[42:43], v[44:45]
	v_mov_b32_e32 v44, v8
	v_mov_b32_e32 v45, v11
	v_mov_b32_e32 v39, v40
	v_mov_b32_e32 v47, v40
	v_pk_mul_f32 v[18:19], v[10:11], v[18:19]
	v_pk_fma_f32 v[38:39], v[44:45], v[38:39], v[42:43] neg_lo:[0,0,1] neg_hi:[0,0,1]
	v_pk_mul_f32 v[16:17], v[6:7], v[16:17] op_sel_hi:[0,1]
	v_pk_fma_f32 v[18:19], v[8:9], v[46:47], v[18:19]
	v_pk_mul_f32 v[38:39], v[6:7], v[38:39] op_sel_hi:[0,1]
	v_pk_mul_f32 v[36:37], v[6:7], v[36:37] op_sel_hi:[0,1]
	v_pk_mul_f32 v[18:19], v[6:7], v[18:19] op_sel_hi:[0,1]
	v_cvt_pk_bf16_f32 v16, v16, v17
	v_cvt_pk_bf16_f32 v17, v38, v39
	global_store_dwordx2 v[34:35], v[16:17], off offset:1792 sc1
	v_cvt_pk_bf16_f32 v16, v36, v37
	v_cvt_pk_bf16_f32 v17, v18, v19
	global_store_dwordx2 v[34:35], v[16:17], off offset:1824 sc1
.LBB0_833:
	s_andn2_b64 vcc, exec, s[6:7]
	s_cbranch_vccnz .LBB0_809
	v_mov_b32_e32 v18, v8
	v_mov_b32_e32 v19, v11
	v_mov_b32_e32 v11, v9
	v_lshlrev_b32_e32 v16, 1, v0
	v_mov_b32_e32 v17, v1
	v_pk_mul_f32 v[18:19], v[18:19], v[6:7] op_sel_hi:[1,0]
	v_pk_mul_f32 v[14:15], v[14:15], v[6:7] op_sel_hi:[1,0]
	v_pk_mul_f32 v[10:11], v[10:11], v[6:7] op_sel_hi:[1,0]
	v_pk_mul_f32 v[8:9], v[12:13], v[6:7] op_sel_hi:[1,0]
	v_lshl_add_u64 v[16:17], v[20:21], 0, v[16:17]
	v_cvt_pk_bf16_f32 v6, v14, v15
	v_cvt_pk_bf16_f32 v7, v18, v19
	v_cvt_pk_bf16_f32 v8, v8, v9
	v_cvt_pk_bf16_f32 v9, v10, v11
	global_store_dwordx4 v[16:17], v[6:9], off offset:1792 sc1
	s_branch .LBB0_809

; #define LAS __attribute__((address_space(3)))
; __device__ __forceinline__ void store4bf(bf16_t* p, f32x4 v) { u32x2 w; w.x = cvt_pk_bf16(v[0], v[1]); w.y = cvt_pk_bf16(v[2], v[3]); *(u32x2*)p = w; }
; __device__ __forceinline__ void store8bf(bf16_t* p, f32x4 v0, f32x4 v1) { u32x4 w; w.x = cvt_pk_bf16(v0[0], v0[1]); w.y = cvt_pk_bf16(v0[2], v0[3]); w.z = cvt_pk_bf16(v1[0], v1[1]); w.w = cvt_pk_bf16(v1[2], v1[3]); *(u32x4*)p = w; }
;   __device__ __forceinline__ void group(int row, int c32, int fq, f32x4 v0, f32x4 v1) const { e->group(row, c32 + sh, fq, v0, v1); }
;   __device__ __forceinline__ void group(int row, int c32, int fq, f32x4 v0, f32x4 v1) const {
;     int b, e; if (!row_be(row, b, e)) return;
;     const float rs = use_direct ? rs_direct : ((LAS const float*)(lds_raw + RS_OFF))[row - brow];
;     if (c32 < 768) {
;       if (c32 >= 576) return;
;       const int h = c32 / 96, part = (c32 - h * 96) >> 5; const float sc = rs * QSC_A;
;       bf16_t* p = qa + ((size_t)(b * 6 + h) * E + e) * 96 + part * 32 + fq * 4;
;       if (part < 2) store8bf(qa + ((size_t)(b * 6 + h) * E + e) * 96 + part * 32 + fq * 8, v0 * sc, v1 * sc);
;       else { const float2* rp = rope + pos_of_e(e) * 16 + fq * 4; f32x4 o0, o1;
; #pragma unroll
;         for (int j = 0; j < 4; ++j) { const float2 cs = rp[j]; o0[j] = (v0[j] * cs.x - v1[j] * cs.y) * sc; o1[j] = (v1[j] * cs.x + v0[j] * cs.y) * sc; }
;         store4bf(p, o0); store4bf(p + 16, o1); }
;     } else {
;       const int cc = c32 - 768, h = cc >> 7, part = (cc & 127) >> 5;
;       if (part < 2) store8bf(ka + ((size_t)(b * 6 + h) * E + e) * 96 + part * 32 + fq * 8, v0 * rs, v1 * rs);
.LBB0_945:
	s_or_b64 exec, exec, s[4:5]
	v_lshlrev_b32_e32 v10, 6, v131
	v_bfe_u32 v136, v134, 4, 2
	v_add_u32_e32 v145, s20, v10
	s_mov_b32 s0, 0x8000
	v_cmp_gt_i32_e64 s[6:7], 4, v135
	v_lshlrev_b32_e32 v0, 5, v132
	v_lshlrev_b32_e32 v131, 3, v136
	v_cmp_gt_i32_e32 vcc, s0, v145
	v_ashrrev_i32_e32 v147, 13, v145
	v_or_b32_e32 v146, v145, v130
	v_cmp_gt_u32_e64 s[4:5], 2, v132
	s_lshr_b32 s1, s8, 7
	s_and_saveexec_b64 s[8:9], s[4:5]
	s_xor_b64 s[12:13], exec, s[8:9]
	s_cbranch_execz .LBB0_971
	s_movk_i32 s0, 0x7fff
	v_cmp_lt_i32_e64 s[8:9], s0, v146
	s_and_saveexec_b64 s[16:17], s[8:9]
	s_xor_b64 s[8:9], exec, s[16:17]
	v_cmp_gt_u32_e64 s[14:15], s49, v145
	s_or_saveexec_b64 s[8:9], s[8:9]
	v_mov_b32_e32 v133, 0
	v_mov_b32_e32 v132, v130
	s_xor_b64 exec, exec, s[8:9]
	v_and_b32_e32 v10, 0x1fcf, v146
	v_add_u32_e32 v132, 64, v10
	v_mul_i32_i24_e32 v133, 6, v147
	s_or_b64 s[14:15], s[14:15], exec
	s_or_b64 exec, exec, s[8:9]
	s_and_saveexec_b64 s[8:9], s[14:15]
	s_cbranch_execz .LBB0_952
	v_subrev_u32_e32 v10, s20, v146
	v_add_u32_e32 v11, s1, v133
	v_mov_b32_e32 v133, v1
	s_movk_i32 s0, 0x2040
	v_lshl_add_u32 v10, v10, 2, 0
	v_mad_i64_i32 v[12:13], s[14:15], v11, s0, v[132:133]
	v_add_u32_e32 v10, 0x20000, v10
	v_readlane_b32 s14, v254, 4
	ds_read_b32 v10, v10
	v_readlane_b32 s15, v254, 5
	s_waitcnt lgkmcnt(0)
	v_pk_mul_f32 v[126:127], v[126:127], v[10:11] op_sel_hi:[1,0]
	v_mov_b64_e32 v[132:133], s[14:15]
	v_mad_u64_u32 v[132:133], s[14:15], v12, s47, v[132:133]
	v_mad_i32_i24 v133, v13, s47, v133
	v_lshlrev_b32_e32 v12, 1, v0
	v_mov_b32_e32 v13, v1
	v_lshl_add_u64 v[12:13], v[132:133], 0, v[12:13]
	v_lshlrev_b32_e32 v132, 1, v131
	v_mov_b32_e32 v133, v1
	v_lshl_add_u64 v[132:133], v[12:13], 0, v[132:133]
	v_pk_mul_f32 v[12:13], v[128:129], v[10:11] op_sel_hi:[1,0]
	v_pk_mul_f32 v[124:125], v[124:125], v[10:11] op_sel_hi:[1,0]
	v_pk_mul_f32 v[122:123], v[122:123], v[10:11] op_sel_hi:[1,0]
	v_cvt_pk_bf16_f32 v10, v126, v127
	v_cvt_pk_bf16_f32 v11, v12, v13
	v_cvt_pk_bf16_f32 v12, v122, v123
	v_cvt_pk_bf16_f32 v13, v124, v125
	global_store_dwordx4 v[132:133], v[10:13], off sc1
.LBB0_952:
	s_or_b64 exec, exec, s[8:9]
	v_or_b32_e32 v123, 16, v146
	s_movk_i32 s0, 0x7fff
	v_cmp_lt_i32_e64 s[8:9], s0, v123
	s_and_saveexec_b64 s[16:17], s[8:9]
	s_xor_b64 s[8:9], exec, s[16:17]
	v_cmp_gt_u32_e64 s[14:15], s49, v145
	s_or_saveexec_b64 s[8:9], s[8:9]
	v_mov_b32_e32 v124, 6
	v_mov_b32_e32 v122, v130
	s_xor_b64 exec, exec, s[8:9]
	v_and_b32_e32 v10, 0x1fdf, v123
	v_add_u32_e32 v122, 64, v10
	v_mul_i32_i24_e32 v124, 6, v147
	s_or_b64 s[14:15], s[14:15], exec
	s_or_b64 exec, exec, s[8:9]
	s_and_saveexec_b64 s[8:9], s[14:15]
	s_cbranch_execz .LBB0_958
	v_subrev_u32_e32 v10, s20, v123
	v_add_u32_e32 v11, s1, v124
	v_mov_b32_e32 v123, v1
	s_movk_i32 s0, 0x2040
	v_lshl_add_u32 v10, v10, 2, 0
	v_mad_i64_i32 v[12:13], s[14:15], v11, s0, v[122:123]
	v_add_u32_e32 v10, 0x20000, v10
	v_readlane_b32 s14, v254, 4
	ds_read_b32 v10, v10
	v_readlane_b32 s15, v254, 5
	s_waitcnt lgkmcnt(0)
	v_pk_mul_f32 v[118:119], v[118:119], v[10:11] op_sel_hi:[1,0]
	v_mov_b64_e32 v[122:123], s[14:15]
	v_mad_u64_u32 v[122:123], s[14:15], v12, s47, v[122:123]
	v_mad_i32_i24 v123, v13, s47, v123
	v_lshlrev_b32_e32 v12, 1, v0
	v_mov_b32_e32 v13, v1
	v_lshl_add_u64 v[12:13], v[122:123], 0, v[12:13]
	v_lshlrev_b32_e32 v122, 1, v131
	v_mov_b32_e32 v123, v1
	v_lshl_add_u64 v[122:123], v[12:13], 0, v[122:123]
	v_pk_mul_f32 v[12:13], v[120:121], v[10:11] op_sel_hi:[1,0]
	v_pk_mul_f32 v[116:117], v[116:117], v[10:11] op_sel_hi:[1,0]
	v_pk_mul_f32 v[114:115], v[114:115], v[10:11] op_sel_hi:[1,0]
	v_cvt_pk_bf16_f32 v10, v118, v119
	v_cvt_pk_bf16_f32 v11, v12, v13
	v_cvt_pk_bf16_f32 v12, v114, v115
	v_cvt_pk_bf16_f32 v13, v116, v117
	global_store_dwordx4 v[122:123], v[10:13], off sc1
; #define LAS __attribute__((address_space(3)))
; __device__ __forceinline__ void store4bf(bf16_t* p, f32x4 v) { u32x2 w; w.x = cvt_pk_bf16(v[0], v[1]); w.y = cvt_pk_bf16(v[2], v[3]); *(u32x2*)p = w; }
; __device__ __forceinline__ void store8bf(bf16_t* p, f32x4 v0, f32x4 v1) { u32x4 w; w.x = cvt_pk_bf16(v0[0], v0[1]); w.y = cvt_pk_bf16(v0[2], v0[3]); w.z = cvt_pk_bf16(v1[0], v1[1]); w.w = cvt_pk_bf16(v1[2], v1[3]); *(u32x4*)p = w; }
;   __device__ __forceinline__ void group(int row, int c32, int fq, f32x4 v0, f32x4 v1) const { e->group(row, c32 + sh, fq, v0, v1); }
;   __device__ __forceinline__ void group(int row, int c32, int fq, f32x4 v0, f32x4 v1) const {
;     int b, e; if (!row_be(row, b, e)) return;
;     const float rs = use_direct ? rs_direct : ((LAS const float*)(lds_raw + RS_OFF))[row - brow];
;     if (c32 < 768) {
;       if (c32 >= 576) return;
;       const int h = c32 / 96, part = (c32 - h * 96) >> 5; const float sc = rs * QSC_A;
;       bf16_t* p = qa + ((size_t)(b * 6 + h) * E + e) * 96 + part * 32 + fq * 4;
;       if (part < 2) store8bf(qa + ((size_t)(b * 6 + h) * E + e) * 96 + part * 32 + fq * 8, v0 * sc, v1 * sc);
;       else { const float2* rp = rope + pos_of_e(e) * 16 + fq * 4; f32x4 o0, o1;
; #pragma unroll
;         for (int j = 0; j < 4; ++j) { const float2 cs = rp[j]; o0[j] = (v0[j] * cs.x - v1[j] * cs.y) * sc; o1[j] = (v1[j] * cs.x + v0[j] * cs.y) * sc; }
;         store4bf(p, o0); store4bf(p + 16, o1); }
;     } else {
;       const int cc = c32 - 768, h = cc >> 7, part = (cc & 127) >> 5;
;       if (part < 2) store8bf(ka + ((size_t)(b * 6 + h) * E + e) * 96 + part * 32 + fq * 8, v0 * rs, v1 * rs);
.LBB0_958:
	s_or_b64 exec, exec, s[8:9]
	v_or_b32_e32 v115, 32, v146
	s_movk_i32 s0, 0x7fff
	v_cmp_lt_i32_e64 s[8:9], s0, v115
	s_and_saveexec_b64 s[16:17], s[8:9]
	s_xor_b64 s[8:9], exec, s[16:17]
	v_cmp_gt_u32_e64 s[14:15], s49, v145
	s_or_saveexec_b64 s[8:9], s[8:9]
	v_mov_b32_e32 v116, 12
	v_mov_b32_e32 v114, v130
	s_xor_b64 exec, exec, s[8:9]
	v_and_b32_e32 v10, 0x1fef, v115
	v_add_u32_e32 v114, 64, v10
	v_mul_i32_i24_e32 v116, 6, v147
	s_or_b64 s[14:15], s[14:15], exec
	s_or_b64 exec, exec, s[8:9]
	s_and_saveexec_b64 s[8:9], s[14:15]
	s_cbranch_execz .LBB0_964
	v_subrev_u32_e32 v10, s20, v115
	v_add_u32_e32 v11, s1, v116
	v_mov_b32_e32 v115, v1
	s_movk_i32 s0, 0x2040
	v_lshl_add_u32 v10, v10, 2, 0
	v_mad_i64_i32 v[12:13], s[14:15], v11, s0, v[114:115]
	v_add_u32_e32 v10, 0x20000, v10
	v_readlane_b32 s14, v254, 4
	ds_read_b32 v10, v10
	v_readlane_b32 s15, v254, 5
	s_waitcnt lgkmcnt(0)
	v_pk_mul_f32 v[110:111], v[110:111], v[10:11] op_sel_hi:[1,0]
	v_mov_b64_e32 v[114:115], s[14:15]
	v_mad_u64_u32 v[114:115], s[14:15], v12, s47, v[114:115]
	v_mad_i32_i24 v115, v13, s47, v115
	v_lshlrev_b32_e32 v12, 1, v0
	v_mov_b32_e32 v13, v1
	v_lshl_add_u64 v[12:13], v[114:115], 0, v[12:13]
	v_lshlrev_b32_e32 v114, 1, v131
	v_mov_b32_e32 v115, v1
	v_lshl_add_u64 v[114:115], v[12:13], 0, v[114:115]
	v_pk_mul_f32 v[12:13], v[112:113], v[10:11] op_sel_hi:[1,0]
	v_pk_mul_f32 v[108:109], v[108:109], v[10:11] op_sel_hi:[1,0]
	v_pk_mul_f32 v[106:107], v[106:107], v[10:11] op_sel_hi:[1,0]
	v_cvt_pk_bf16_f32 v10, v110, v111
	v_cvt_pk_bf16_f32 v11, v12, v13
	v_cvt_pk_bf16_f32 v12, v106, v107
	v_cvt_pk_bf16_f32 v13, v108, v109
	global_store_dwordx4 v[114:115], v[10:13], off sc1
.LBB0_964:
	s_or_b64 exec, exec, s[8:9]
	v_or_b32_e32 v107, 48, v146
	s_movk_i32 s0, 0x7fff
	v_cmp_lt_i32_e64 s[8:9], s0, v107
	s_and_saveexec_b64 s[16:17], s[8:9]
	s_xor_b64 s[8:9], exec, s[16:17]
	v_cmp_gt_u32_e64 s[14:15], s49, v145
	s_or_saveexec_b64 s[8:9], s[8:9]
	v_mov_b32_e32 v108, 18
	v_mov_b32_e32 v106, v130
	s_xor_b64 exec, exec, s[8:9]
	v_and_b32_e32 v10, 0x1fff, v107
	v_add_u32_e32 v106, 64, v10
	v_mul_i32_i24_e32 v108, 6, v147
	s_or_b64 s[14:15], s[14:15], exec
	s_or_b64 exec, exec, s[8:9]
	s_and_saveexec_b64 s[8:9], s[14:15]
	s_cbranch_execz .LBB0_970
	v_subrev_u32_e32 v10, s20, v107
	v_add_u32_e32 v11, s1, v108
	v_mov_b32_e32 v107, v1
	s_movk_i32 s0, 0x2040
	v_lshl_add_u32 v10, v10, 2, 0
	v_mad_i64_i32 v[12:13], s[14:15], v11, s0, v[106:107]
	v_add_u32_e32 v10, 0x20000, v10
	v_readlane_b32 s14, v254, 4
	ds_read_b32 v10, v10
	v_readlane_b32 s15, v254, 5
	s_waitcnt lgkmcnt(0)
	v_pk_mul_f32 v[102:103], v[102:103], v[10:11] op_sel_hi:[1,0]
	v_mov_b64_e32 v[106:107], s[14:15]
	v_mad_u64_u32 v[106:107], s[14:15], v12, s47, v[106:107]
	v_mad_i32_i24 v107, v13, s47, v107
	v_lshlrev_b32_e32 v12, 1, v0
	v_mov_b32_e32 v13, v1
	v_lshl_add_u64 v[12:13], v[106:107], 0, v[12:13]
	v_lshlrev_b32_e32 v106, 1, v131
	v_mov_b32_e32 v107, v1
	v_lshl_add_u64 v[106:107], v[12:13], 0, v[106:107]
	v_pk_mul_f32 v[12:13], v[104:105], v[10:11] op_sel_hi:[1,0]
	v_pk_mul_f32 v[100:101], v[100:101], v[10:11] op_sel_hi:[1,0]
	v_pk_mul_f32 v[98:99], v[98:99], v[10:11] op_sel_hi:[1,0]
	v_cvt_pk_bf16_f32 v10, v102, v103
	v_cvt_pk_bf16_f32 v11, v12, v13
	v_cvt_pk_bf16_f32 v12, v98, v99
	v_cvt_pk_bf16_f32 v13, v100, v101
	global_store_dwordx4 v[106:107], v[10:13], off sc1

; #define LAS __attribute__((address_space(3)))
; __device__ __forceinline__ unsigned short f2bf(float f) { return (unsigned short)(cvt_pk_bf16(f, f) & 0xffffu); }
;   __device__ __forceinline__ bool vt_info(int c32, int b, bf16_t*& base) const { return e->vt_info(c32 + sh, b, base); }
;     ...
;         const int c32 = bcol + wc * 32 + bj * HALF, row0 = brow + ai * HALF + wr * 64;
;         int b0, e0; row_be(row0, b0, e0); bf16_t* vbase;
;         if (epi.vt_info(c32, b0, vbase)) {
; #pragma unroll
;           for (int m = 0; m < 4; ++m) { const float sc = epi.row_scale(row0 + m * 16 + fr);
; #pragma unroll
;             for (int n = 0; n < 2; ++n)
; #pragma unroll
;               for (int j = 0; j < 4; ++j) *(LAS bf16_t*)(T + (n * 16 + fq * 4 + j) * 144 + (m * 16 + fr) * 2) = f2bf(acc[ai][bj][m][n][j] * sc); }
;           asm volatile("s_waitcnt lgkmcnt(0)" ::: "memory");
; #pragma unroll
;           for (int q = 0; q < 4; ++q) { const int ch = lane + 64 * q, d = ch >> 3, ec = ch & 7;
;             *(u32x4*)(vbase + (size_t)d * E + e0 + ec * 8) = *(LAS const u32x4*)(T + d * 144 + ec * 16); }
;           asm volatile("s_waitcnt lgkmcnt(0)" ::: "memory");
.LBB0_971:
	s_or_saveexec_b64 s[8:9], s[12:13]
	s_movk_i32 s0, 0x1200
	v_mul_lo_u32 v11, v135, s0
	v_cndmask_b32_e64 v12, v213, v211, s[6:7]
	v_and_b32_e32 v132, 0x1fc0, v145
	v_and_b32_e32 v10, 63, v134
	v_add3_u32 v11, 0, v11, v12
	v_and_b32_e32 v12, 7, v134
	v_add_u32_e32 v132, 64, v132
	v_lshl_add_u32 v13, v12, 4, v11
	v_lshlrev_b32_e32 v12, 3, v12
	v_cndmask_b32_e32 v132, 0, v132, vcc
	v_subrev_u32_e32 v133, s20, v146
	v_lshlrev_b32_e32 v135, 1, v130
	v_mul_u32_u24_e32 v137, 0x240, v136
	v_lshrrev_b32_e32 v10, 3, v10
	v_cndmask_b32_e32 v149, 0, v147, vcc
	v_subrev_u32_e32 v134, 64, v0
	v_lshlrev_b32_e32 v136, 1, v132
	v_lshl_add_u32 v148, v133, 2, 0
	v_add3_u32 v144, v11, v135, v137
	v_lshlrev_b32_e32 v132, 1, v12
	v_mad_u32_u24 v138, v10, s54, v13
	v_mul_u32_u24_e32 v139, 0x2040, v10
	s_xor_b64 exec, exec, s[8:9]
	s_cbranch_execz .LBB0_973
	v_mad_i32_i24 v10, v149, 6, s1
	v_ashrrev_i32_e32 v11, 31, v10
	v_readlane_b32 s6, v254, 26
	v_lshlrev_b64 v[10:11], 6, v[10:11]
	v_mov_b32_e32 v135, v1
	v_readlane_b32 s7, v254, 27
	v_lshl_add_u64 v[10:11], v[10:11], 0, v[134:135]
	v_add_u32_e32 v133, 0x20000, v148
	v_mov_b64_e32 v[12:13], s[6:7]
	v_mad_u64_u32 v[12:13], s[6:7], v10, s95, v[12:13]
	v_mad_i32_i24 v13, v11, s95, v13
	ds_read2_b32 v[10:11], v133 offset1:16
	v_mov_b32_e32 v137, v1
	s_waitcnt lgkmcnt(0)
	v_mul_f32_e32 v126, v126, v10
	v_cvt_pk_bf16_f32 v126, v126, s0
	ds_write_b16 v144, v126
	v_mul_f32_e32 v126, v127, v10
	v_mul_f32_e32 v122, v122, v10
	v_cvt_pk_bf16_f32 v126, v126, s0
	v_cvt_pk_bf16_f32 v122, v122, s0
	ds_write_b16 v144, v126 offset:144
	v_mul_f32_e32 v126, v128, v10
	ds_write_b16 v144, v122 offset:2304
	v_mul_f32_e32 v122, v123, v10
	v_cvt_pk_bf16_f32 v126, v126, s0
	v_cvt_pk_bf16_f32 v122, v122, s0
	ds_write_b16 v144, v126 offset:288
	v_mul_f32_e32 v126, v129, v10
	ds_write_b16 v144, v122 offset:2448
	v_mul_f32_e32 v122, v124, v10
	v_mul_f32_e32 v10, v125, v10
	v_cvt_pk_bf16_f32 v10, v10, s0
	ds_write_b16 v144, v10 offset:2736
	v_mul_f32_e32 v10, v118, v11
	v_cvt_pk_bf16_f32 v10, v10, s0
	ds_write_b16 v144, v10 offset:32
	v_mul_f32_e32 v10, v119, v11
	v_cvt_pk_bf16_f32 v10, v10, s0
	ds_write_b16 v144, v10 offset:176
	v_mul_f32_e32 v10, v120, v11
	v_cvt_pk_bf16_f32 v10, v10, s0
	ds_write_b16 v144, v10 offset:320
	v_mul_f32_e32 v10, v121, v11
	v_cvt_pk_bf16_f32 v10, v10, s0
	ds_write_b16 v144, v10 offset:464
	v_mul_f32_e32 v10, v114, v11
	v_cvt_pk_bf16_f32 v10, v10, s0
	ds_write_b16 v144, v10 offset:2336
	v_mul_f32_e32 v10, v115, v11
	v_cvt_pk_bf16_f32 v10, v10, s0
	ds_write_b16 v144, v10 offset:2480
	v_mul_f32_e32 v10, v116, v11
	v_cvt_pk_bf16_f32 v10, v10, s0
	ds_write_b16 v144, v10 offset:2624
	v_mul_f32_e32 v10, v117, v11
	v_cvt_pk_bf16_f32 v10, v10, s0
	ds_write_b16 v144, v10 offset:2768
	ds_read2_b32 v[10:11], v133 offset0:32 offset1:48
	v_cvt_pk_bf16_f32 v126, v126, s0
	v_cvt_pk_bf16_f32 v122, v122, s0
	ds_write_b16 v144, v126 offset:432
	ds_write_b16 v144, v122 offset:2592
	s_waitcnt lgkmcnt(0)
	v_mul_f32_e32 v110, v110, v10
	v_cvt_pk_bf16_f32 v110, v110, s0
	ds_write_b16 v144, v110 offset:64
	v_mul_f32_e32 v110, v111, v10
	v_mul_f32_e32 v106, v106, v10
	v_cvt_pk_bf16_f32 v110, v110, s0
	v_cvt_pk_bf16_f32 v106, v106, s0
	ds_write_b16 v144, v110 offset:208
	v_mul_f32_e32 v110, v112, v10
	ds_write_b16 v144, v106 offset:2368
	v_mul_f32_e32 v106, v107, v10
	v_cvt_pk_bf16_f32 v110, v110, s0
	v_cvt_pk_bf16_f32 v106, v106, s0
	ds_write_b16 v144, v110 offset:352
	v_mul_f32_e32 v110, v113, v10
	ds_write_b16 v144, v106 offset:2512
	v_mul_f32_e32 v106, v108, v10
	v_mul_f32_e32 v10, v109, v10
	v_cvt_pk_bf16_f32 v10, v10, s0
	ds_write_b16 v144, v10 offset:2800
	v_mul_f32_e32 v10, v102, v11
	v_cvt_pk_bf16_f32 v10, v10, s0
	ds_write_b16 v144, v10 offset:96
	v_mul_f32_e32 v10, v103, v11
	v_cvt_pk_bf16_f32 v10, v10, s0
	ds_write_b16 v144, v10 offset:240
	v_mul_f32_e32 v10, v104, v11
	v_cvt_pk_bf16_f32 v10, v10, s0
	ds_write_b16 v144, v10 offset:384
	v_mul_f32_e32 v10, v105, v11
	v_cvt_pk_bf16_f32 v10, v10, s0
	ds_write_b16 v144, v10 offset:528
	v_mul_f32_e32 v10, v98, v11
	v_cvt_pk_bf16_f32 v10, v10, s0
	ds_write_b16 v144, v10 offset:2400
	v_mul_f32_e32 v10, v99, v11
	v_cvt_pk_bf16_f32 v10, v10, s0
	ds_write_b16 v144, v10 offset:2544
	v_mul_f32_e32 v10, v100, v11
	v_cvt_pk_bf16_f32 v10, v10, s0
	ds_write_b16 v144, v10 offset:2688
	v_mul_f32_e32 v10, v101, v11
	v_cvt_pk_bf16_f32 v110, v110, s0
	v_cvt_pk_bf16_f32 v106, v106, s0
	v_cvt_pk_bf16_f32 v10, v10, s0
	ds_write_b16 v144, v110 offset:496
	ds_write_b16 v144, v106 offset:2656
	ds_write_b16 v144, v10 offset:2832
	s_waitcnt lgkmcnt(0)
	v_lshl_add_u64 v[10:11], v[12:13], 0, v[136:137]
	v_mov_b32_e32 v133, v1
	v_lshl_add_u64 v[98:99], v[10:11], 0, v[132:133]
	ds_read_b128 v[10:13], v138
	v_lshlrev_b32_e32 v100, 1, v139
	v_mov_b32_e32 v101, v1
	v_lshl_add_u64 v[98:99], v[98:99], 0, v[100:101]
	v_add_co_u32_e32 v100, vcc, 0x20000, v98
	s_waitcnt lgkmcnt(0)
	global_store_dwordx4 v[98:99], v[10:13], off sc1
	ds_read_b128 v[10:13], v138 offset:1152
	v_addc_co_u32_e32 v101, vcc, 0, v99, vcc
	s_waitcnt lgkmcnt(0)
	global_store_dwordx4 v[100:101], v[10:13], off offset:1024 sc1
	ds_read_b128 v[10:13], v138 offset:2304
	v_add_co_u32_e32 v100, vcc, 0x40000, v98
	s_nop 1
	v_addc_co_u32_e32 v101, vcc, 0, v99, vcc
	s_waitcnt lgkmcnt(0)
	global_store_dwordx4 v[100:101], v[10:13], off offset:2048 sc1
	ds_read_b128 v[10:13], v138 offset:3456
	v_add_co_u32_e32 v98, vcc, 0x60000, v98
	s_nop 1
	v_addc_co_u32_e32 v99, vcc, 0, v99, vcc
	s_waitcnt lgkmcnt(0)
	global_store_dwordx4 v[98:99], v[10:13], off offset:3072 sc1
	s_waitcnt lgkmcnt(0)
; #define LAS __attribute__((address_space(3)))
; __device__ __forceinline__ void store4bf(bf16_t* p, f32x4 v) { u32x2 w; w.x = cvt_pk_bf16(v[0], v[1]); w.y = cvt_pk_bf16(v[2], v[3]); *(u32x2*)p = w; }
; __device__ __forceinline__ void store8bf(bf16_t* p, f32x4 v0, f32x4 v1) { u32x4 w; w.x = cvt_pk_bf16(v0[0], v0[1]); w.y = cvt_pk_bf16(v0[2], v0[3]); w.z = cvt_pk_bf16(v1[0], v1[1]); w.w = cvt_pk_bf16(v1[2], v1[3]); *(u32x4*)p = w; }
;   __device__ __forceinline__ void group(int row, int c32, int fq, f32x4 v0, f32x4 v1) const { e->group(row, c32 + sh, fq, v0, v1); }
;   __device__ __forceinline__ void group(int row, int c32, int fq, f32x4 v0, f32x4 v1) const {
;     int b, e; if (!row_be(row, b, e)) return;
;     const float rs = use_direct ? rs_direct : ((LAS const float*)(lds_raw + RS_OFF))[row - brow];
;     if (c32 < 768) {
;       if (c32 >= 576) return;
;       const int h = c32 / 96, part = (c32 - h * 96) >> 5; const float sc = rs * QSC_A;
;       bf16_t* p = qa + ((size_t)(b * 6 + h) * E + e) * 96 + part * 32 + fq * 4;
;       if (part < 2) store8bf(qa + ((size_t)(b * 6 + h) * E + e) * 96 + part * 32 + fq * 8, v0 * sc, v1 * sc);
;       else { const float2* rp = rope + pos_of_e(e) * 16 + fq * 4; f32x4 o0, o1;
; #pragma unroll
;         for (int j = 0; j < 4; ++j) { const float2 cs = rp[j]; o0[j] = (v0[j] * cs.x - v1[j] * cs.y) * sc; o1[j] = (v1[j] * cs.x + v0[j] * cs.y) * sc; }
;         store4bf(p, o0); store4bf(p + 16, o1); }
;     } else {
;       const int cc = c32 - 768, h = cc >> 7, part = (cc & 127) >> 5;
;       if (part < 2) store8bf(ka + ((size_t)(b * 6 + h) * E + e) * 96 + part * 32 + fq * 8, v0 * rs, v1 * rs);
.LBB0_973:
	s_or_b64 exec, exec, s[8:9]
	s_lshr_b32 s0, s10, 7
	s_and_saveexec_b64 s[6:7], s[4:5]
	s_xor_b64 s[6:7], exec, s[6:7]
	s_cbranch_execz .LBB0_999
	s_movk_i32 s8, 0x7fff
	v_cmp_lt_i32_e32 vcc, s8, v146
	s_and_saveexec_b64 s[8:9], vcc
	s_xor_b64 s[8:9], exec, s[8:9]
	v_cmp_gt_u32_e64 s[10:11], s49, v145
	s_or_saveexec_b64 s[8:9], s[8:9]
	v_mov_b32_e32 v99, 0
	v_mul_i32_i24_e32 v100, 6, v147
	v_mov_b32_e32 v98, v130
	s_xor_b64 exec, exec, s[8:9]
	v_and_b32_e32 v10, 0x1fcf, v146
	v_add_u32_e32 v98, 64, v10
	v_mul_i32_i24_e32 v99, 6, v147
	s_or_b64 s[10:11], s[10:11], exec
	s_or_b64 exec, exec, s[8:9]
	s_and_saveexec_b64 s[8:9], s[10:11]
	s_cbranch_execz .LBB0_980
	v_add_u32_e32 v11, s0, v99
	v_mov_b32_e32 v99, v1
	s_movk_i32 s10, 0x2040
	v_mad_i64_i32 v[12:13], s[10:11], v11, s10, v[98:99]
	v_add_u32_e32 v10, 0x20000, v148
	v_readlane_b32 s10, v254, 4
	ds_read_b32 v10, v10
	v_readlane_b32 s11, v254, 5
	s_waitcnt lgkmcnt(0)
	v_pk_mul_f32 v[94:95], v[94:95], v[10:11] op_sel_hi:[1,0]
	v_mov_b64_e32 v[98:99], s[10:11]
	v_mad_u64_u32 v[98:99], s[10:11], v12, s47, v[98:99]
	v_mad_i32_i24 v99, v13, s47, v99
	v_lshlrev_b32_e32 v12, 1, v0
	v_mov_b32_e32 v13, v1
	v_lshl_add_u64 v[12:13], v[98:99], 0, v[12:13]
	v_lshlrev_b32_e32 v98, 1, v131
	v_mov_b32_e32 v99, v1
	v_lshl_add_u64 v[98:99], v[12:13], 0, v[98:99]
	v_pk_mul_f32 v[12:13], v[96:97], v[10:11] op_sel_hi:[1,0]
	v_pk_mul_f32 v[92:93], v[92:93], v[10:11] op_sel_hi:[1,0]
	v_pk_mul_f32 v[90:91], v[90:91], v[10:11] op_sel_hi:[1,0]
	v_cvt_pk_bf16_f32 v10, v94, v95
	v_cvt_pk_bf16_f32 v11, v12, v13
	v_cvt_pk_bf16_f32 v12, v90, v91
	v_cvt_pk_bf16_f32 v13, v92, v93
	global_store_dwordx4 v[98:99], v[10:13], off sc1
.LBB0_980:
	s_or_b64 exec, exec, s[8:9]
	v_or_b32_e32 v91, 16, v146
	s_movk_i32 s8, 0x7fff
	v_cmp_lt_i32_e32 vcc, s8, v91
	s_and_saveexec_b64 s[8:9], vcc
	s_xor_b64 s[8:9], exec, s[8:9]
	v_cmp_gt_u32_e64 s[10:11], s49, v145
	s_or_saveexec_b64 s[8:9], s[8:9]
	v_mov_b32_e32 v92, 6
	v_mov_b32_e32 v90, v130
	s_xor_b64 exec, exec, s[8:9]
	v_and_b32_e32 v10, 0x1fdf, v91
	v_add_u32_e32 v90, 64, v10
	v_mul_i32_i24_e32 v92, 6, v147
	s_or_b64 s[10:11], s[10:11], exec
	s_or_b64 exec, exec, s[8:9]
	s_and_saveexec_b64 s[8:9], s[10:11]
	s_cbranch_execz .LBB0_986
	v_subrev_u32_e32 v10, s20, v91
	v_add_u32_e32 v11, s0, v92
	v_mov_b32_e32 v91, v1
	s_movk_i32 s10, 0x2040
	v_lshl_add_u32 v10, v10, 2, 0
	v_mad_i64_i32 v[12:13], s[10:11], v11, s10, v[90:91]
	v_add_u32_e32 v10, 0x20000, v10
	v_readlane_b32 s10, v254, 4
	ds_read_b32 v10, v10
	v_readlane_b32 s11, v254, 5
	s_waitcnt lgkmcnt(0)
	v_pk_mul_f32 v[86:87], v[86:87], v[10:11] op_sel_hi:[1,0]
	v_mov_b64_e32 v[90:91], s[10:11]
	v_mad_u64_u32 v[90:91], s[10:11], v12, s47, v[90:91]
	v_mad_i32_i24 v91, v13, s47, v91
	v_lshlrev_b32_e32 v12, 1, v0
	v_mov_b32_e32 v13, v1
	v_lshl_add_u64 v[12:13], v[90:91], 0, v[12:13]
	v_lshlrev_b32_e32 v90, 1, v131
	v_mov_b32_e32 v91, v1
	v_lshl_add_u64 v[90:91], v[12:13], 0, v[90:91]
	v_pk_mul_f32 v[12:13], v[88:89], v[10:11] op_sel_hi:[1,0]
	v_pk_mul_f32 v[84:85], v[84:85], v[10:11] op_sel_hi:[1,0]
	v_pk_mul_f32 v[82:83], v[82:83], v[10:11] op_sel_hi:[1,0]
	v_cvt_pk_bf16_f32 v10, v86, v87
	v_cvt_pk_bf16_f32 v11, v12, v13
	v_cvt_pk_bf16_f32 v12, v82, v83
	v_cvt_pk_bf16_f32 v13, v84, v85
	global_store_dwordx4 v[90:91], v[10:13], off sc1
.LBB0_986:
	s_or_b64 exec, exec, s[8:9]
	v_or_b32_e32 v83, 32, v146
	s_movk_i32 s8, 0x7fff
	v_cmp_lt_i32_e32 vcc, s8, v83
	s_and_saveexec_b64 s[8:9], vcc
	s_xor_b64 s[8:9], exec, s[8:9]
	v_cmp_gt_u32_e64 s[10:11], s49, v145
	s_or_saveexec_b64 s[8:9], s[8:9]
	v_mov_b32_e32 v84, 12
	v_mov_b32_e32 v82, v130
	s_xor_b64 exec, exec, s[8:9]
	v_and_b32_e32 v10, 0x1fef, v83
	v_add_u32_e32 v82, 64, v10
	v_mul_i32_i24_e32 v84, 6, v147
	s_or_b64 s[10:11], s[10:11], exec
	s_or_b64 exec, exec, s[8:9]
	s_and_saveexec_b64 s[8:9], s[10:11]
	s_cbranch_execz .LBB0_992
	v_subrev_u32_e32 v10, s20, v83
	v_add_u32_e32 v11, s0, v84
	v_mov_b32_e32 v83, v1
	s_movk_i32 s10, 0x2040
	v_lshl_add_u32 v10, v10, 2, 0
	v_mad_i64_i32 v[12:13], s[10:11], v11, s10, v[82:83]
	v_add_u32_e32 v10, 0x20000, v10
	v_readlane_b32 s10, v254, 4
	ds_read_b32 v10, v10
	v_readlane_b32 s11, v254, 5
	s_waitcnt lgkmcnt(0)
	v_pk_mul_f32 v[78:79], v[78:79], v[10:11] op_sel_hi:[1,0]
	v_mov_b64_e32 v[82:83], s[10:11]
	v_mad_u64_u32 v[82:83], s[10:11], v12, s47, v[82:83]
	v_mad_i32_i24 v83, v13, s47, v83
	v_lshlrev_b32_e32 v12, 1, v0
	v_mov_b32_e32 v13, v1
	v_lshl_add_u64 v[12:13], v[82:83], 0, v[12:13]
	v_lshlrev_b32_e32 v82, 1, v131
	v_mov_b32_e32 v83, v1
	v_lshl_add_u64 v[82:83], v[12:13], 0, v[82:83]
	v_pk_mul_f32 v[12:13], v[80:81], v[10:11] op_sel_hi:[1,0]
	v_pk_mul_f32 v[76:77], v[76:77], v[10:11] op_sel_hi:[1,0]
	v_pk_mul_f32 v[74:75], v[74:75], v[10:11] op_sel_hi:[1,0]
	v_cvt_pk_bf16_f32 v10, v78, v79
	v_cvt_pk_bf16_f32 v11, v12, v13
	v_cvt_pk_bf16_f32 v12, v74, v75
	v_cvt_pk_bf16_f32 v13, v76, v77
	global_store_dwordx4 v[82:83], v[10:13], off sc1
.LBB0_992:
	s_or_b64 exec, exec, s[8:9]
	v_or_b32_e32 v75, 48, v146
	s_movk_i32 s8, 0x7fff
	v_cmp_lt_i32_e32 vcc, s8, v75
	s_and_saveexec_b64 s[8:9], vcc
	s_xor_b64 s[8:9], exec, s[8:9]
	v_cmp_gt_u32_e64 s[10:11], s49, v145
	s_or_saveexec_b64 s[8:9], s[8:9]
	v_mov_b32_e32 v76, 18
	v_mov_b32_e32 v74, v130
	s_xor_b64 exec, exec, s[8:9]
	v_and_b32_e32 v10, 0x1fff, v75
	v_add_u32_e32 v74, 64, v10
	s_or_b64 s[10:11], s[10:11], exec
	v_mov_b32_e32 v76, v100
	s_or_b64 exec, exec, s[8:9]
	s_and_saveexec_b64 s[8:9], s[10:11]
	s_cbranch_execz .LBB0_998
	v_subrev_u32_e32 v10, s20, v75
	v_add_u32_e32 v11, s0, v76
	v_mov_b32_e32 v75, v1
	s_movk_i32 s10, 0x2040
	v_lshl_add_u32 v10, v10, 2, 0
	v_mad_i64_i32 v[12:13], s[10:11], v11, s10, v[74:75]
	v_add_u32_e32 v10, 0x20000, v10
	v_readlane_b32 s10, v254, 4
	ds_read_b32 v10, v10
	v_readlane_b32 s11, v254, 5
	s_waitcnt lgkmcnt(0)
	v_pk_mul_f32 v[70:71], v[70:71], v[10:11] op_sel_hi:[1,0]
	v_mov_b64_e32 v[74:75], s[10:11]
	v_mad_u64_u32 v[74:75], s[10:11], v12, s47, v[74:75]
	v_mad_i32_i24 v75, v13, s47, v75
	v_lshlrev_b32_e32 v12, 1, v0
	v_mov_b32_e32 v13, v1
	v_lshl_add_u64 v[12:13], v[74:75], 0, v[12:13]
	v_lshlrev_b32_e32 v74, 1, v131
	v_mov_b32_e32 v75, v1
	v_lshl_add_u64 v[74:75], v[12:13], 0, v[74:75]
	v_pk_mul_f32 v[12:13], v[72:73], v[10:11] op_sel_hi:[1,0]
	v_pk_mul_f32 v[68:69], v[68:69], v[10:11] op_sel_hi:[1,0]
	v_pk_mul_f32 v[66:67], v[66:67], v[10:11] op_sel_hi:[1,0]
	v_cvt_pk_bf16_f32 v10, v70, v71
	v_cvt_pk_bf16_f32 v11, v12, v13
	v_cvt_pk_bf16_f32 v12, v66, v67
	v_cvt_pk_bf16_f32 v13, v68, v69
	global_store_dwordx4 v[74:75], v[10:13], off sc1

; #define LAS __attribute__((address_space(3)))
; __device__ __forceinline__ unsigned short f2bf(float f) { return (unsigned short)(cvt_pk_bf16(f, f) & 0xffffu); }
; __device__ __forceinline__ void store8bf(bf16_t* p, f32x4 v0, f32x4 v1) { u32x4 w; w.x = cvt_pk_bf16(v0[0], v0[1]); w.y = cvt_pk_bf16(v0[2], v0[3]); w.z = cvt_pk_bf16(v1[0], v1[1]); w.w = cvt_pk_bf16(v1[2], v1[3]); *(u32x4*)p = w; }
;     ...
;           for (int m = 0; m < 4; ++m) { const float sc = epi.row_scale(row0 + m * 16 + fr);
; #pragma unroll
;             for (int n = 0; n < 2; ++n)
; #pragma unroll
;               for (int j = 0; j < 4; ++j) *(LAS bf16_t*)(T + (n * 16 + fq * 4 + j) * 144 + (m * 16 + fr) * 2) = f2bf(acc[ai][bj][m][n][j] * sc); }
;           asm volatile("s_waitcnt lgkmcnt(0)" ::: "memory");
; #pragma unroll
;           for (int q = 0; q < 4; ++q) { const int ch = lane + 64 * q, d = ch >> 3, ec = ch & 7;
;             *(u32x4*)(vbase + (size_t)d * E + e0 + ec * 8) = *(LAS const u32x4*)(T + d * 144 + ec * 16); }
;           asm volatile("s_waitcnt lgkmcnt(0)" ::: "memory");
;   __device__ __forceinline__ void group(int row, int c32, int fq, f32x4 v0, f32x4 v1) const {
;     ...
;       const int cc = c32 - 768, h = cc >> 7, part = (cc & 127) >> 5;
;       if (part < 2) store8bf(ka + ((size_t)(b * 6 + h) * E + e) * 96 + part * 32 + fq * 8, v0 * rs, v1 * rs);
.LBB0_999:
	s_andn2_saveexec_b64 s[6:7], s[6:7]
	s_cbranch_execz .LBB0_1001
	v_mad_i32_i24 v10, v149, 6, s0
	v_ashrrev_i32_e32 v11, 31, v10
	v_readlane_b32 s8, v254, 26
	v_lshlrev_b64 v[10:11], 6, v[10:11]
	v_mov_b32_e32 v135, v1
	v_readlane_b32 s9, v254, 27
	v_lshl_add_u64 v[10:11], v[10:11], 0, v[134:135]
	v_add_u32_e32 v98, 0x20000, v148
	v_mov_b64_e32 v[12:13], s[8:9]
	v_mad_u64_u32 v[12:13], s[8:9], v10, s95, v[12:13]
	v_mad_i32_i24 v13, v11, s95, v13
	ds_read2_b32 v[10:11], v98 offset1:16
	v_mov_b32_e32 v137, v1
	v_mov_b32_e32 v133, v1
	s_waitcnt lgkmcnt(0)
	v_mul_f32_e32 v94, v94, v10
	v_cvt_pk_bf16_f32 v94, v94, s0
	ds_write_b16 v144, v94
	v_mul_f32_e32 v94, v95, v10
	v_mul_f32_e32 v90, v90, v10
	v_cvt_pk_bf16_f32 v94, v94, s0
	v_cvt_pk_bf16_f32 v90, v90, s0
	ds_write_b16 v144, v94 offset:144
	v_mul_f32_e32 v94, v96, v10
	ds_write_b16 v144, v90 offset:2304
	v_mul_f32_e32 v90, v91, v10
	v_cvt_pk_bf16_f32 v94, v94, s0
	v_cvt_pk_bf16_f32 v90, v90, s0
	ds_write_b16 v144, v94 offset:288
	v_mul_f32_e32 v94, v97, v10
	ds_write_b16 v144, v90 offset:2448
	v_mul_f32_e32 v90, v92, v10
	v_mul_f32_e32 v10, v93, v10
	v_cvt_pk_bf16_f32 v10, v10, s0
	ds_write_b16 v144, v10 offset:2736
	v_mul_f32_e32 v10, v86, v11
	v_cvt_pk_bf16_f32 v10, v10, s0
	ds_write_b16 v144, v10 offset:32
	v_mul_f32_e32 v10, v87, v11
	v_cvt_pk_bf16_f32 v10, v10, s0
	ds_write_b16 v144, v10 offset:176
	v_mul_f32_e32 v10, v88, v11
	v_cvt_pk_bf16_f32 v10, v10, s0
	ds_write_b16 v144, v10 offset:320
	v_mul_f32_e32 v10, v89, v11
	v_cvt_pk_bf16_f32 v10, v10, s0
	ds_write_b16 v144, v10 offset:464
	v_mul_f32_e32 v10, v82, v11
	v_cvt_pk_bf16_f32 v10, v10, s0
	ds_write_b16 v144, v10 offset:2336
	v_mul_f32_e32 v10, v83, v11
	v_cvt_pk_bf16_f32 v10, v10, s0
	ds_write_b16 v144, v10 offset:2480
	v_mul_f32_e32 v10, v84, v11
	v_cvt_pk_bf16_f32 v10, v10, s0
	ds_write_b16 v144, v10 offset:2624
	v_mul_f32_e32 v10, v85, v11
	v_cvt_pk_bf16_f32 v10, v10, s0
	ds_write_b16 v144, v10 offset:2768
	ds_read2_b32 v[10:11], v98 offset0:32 offset1:48
	v_cvt_pk_bf16_f32 v94, v94, s0
	v_cvt_pk_bf16_f32 v90, v90, s0
	ds_write_b16 v144, v94 offset:432
	ds_write_b16 v144, v90 offset:2592
	s_waitcnt lgkmcnt(0)
	v_mul_f32_e32 v78, v78, v10
	v_cvt_pk_bf16_f32 v78, v78, s0
	ds_write_b16 v144, v78 offset:64
	v_mul_f32_e32 v78, v79, v10
	v_mul_f32_e32 v74, v74, v10
	v_cvt_pk_bf16_f32 v78, v78, s0
	v_cvt_pk_bf16_f32 v74, v74, s0
	ds_write_b16 v144, v78 offset:208
	v_mul_f32_e32 v78, v80, v10
	ds_write_b16 v144, v74 offset:2368
	v_mul_f32_e32 v74, v75, v10
	v_cvt_pk_bf16_f32 v78, v78, s0
	v_cvt_pk_bf16_f32 v74, v74, s0
	ds_write_b16 v144, v78 offset:352
	v_mul_f32_e32 v78, v81, v10
	ds_write_b16 v144, v74 offset:2512
	v_mul_f32_e32 v74, v76, v10
	v_mul_f32_e32 v10, v77, v10
	v_cvt_pk_bf16_f32 v10, v10, s0
	ds_write_b16 v144, v10 offset:2800
	v_mul_f32_e32 v10, v70, v11
	v_cvt_pk_bf16_f32 v10, v10, s0
	ds_write_b16 v144, v10 offset:96
	v_mul_f32_e32 v10, v71, v11
	v_cvt_pk_bf16_f32 v10, v10, s0
	ds_write_b16 v144, v10 offset:240
	v_mul_f32_e32 v10, v72, v11
	v_cvt_pk_bf16_f32 v10, v10, s0
	ds_write_b16 v144, v10 offset:384
	v_mul_f32_e32 v10, v73, v11
	v_cvt_pk_bf16_f32 v10, v10, s0
	ds_write_b16 v144, v10 offset:528
	v_mul_f32_e32 v10, v66, v11
	v_cvt_pk_bf16_f32 v10, v10, s0
	ds_write_b16 v144, v10 offset:2400
	v_mul_f32_e32 v10, v67, v11
	v_cvt_pk_bf16_f32 v10, v10, s0
	ds_write_b16 v144, v10 offset:2544
	v_mul_f32_e32 v10, v68, v11
	v_cvt_pk_bf16_f32 v10, v10, s0
	ds_write_b16 v144, v10 offset:2688
	v_mul_f32_e32 v10, v69, v11
	v_cvt_pk_bf16_f32 v78, v78, s0
	v_cvt_pk_bf16_f32 v74, v74, s0
	v_cvt_pk_bf16_f32 v10, v10, s0
	ds_write_b16 v144, v78 offset:496
	ds_write_b16 v144, v74 offset:2656
	ds_write_b16 v144, v10 offset:2832
	s_waitcnt lgkmcnt(0)
	v_lshl_add_u64 v[10:11], v[12:13], 0, v[136:137]
	v_lshl_add_u64 v[66:67], v[10:11], 0, v[132:133]
	ds_read_b128 v[10:13], v138
	v_lshlrev_b32_e32 v68, 1, v139
	v_mov_b32_e32 v69, v1
	v_lshl_add_u64 v[66:67], v[66:67], 0, v[68:69]
	v_add_co_u32_e32 v68, vcc, 0x20000, v66
	s_waitcnt lgkmcnt(0)
	global_store_dwordx4 v[66:67], v[10:13], off sc1
	ds_read_b128 v[10:13], v138 offset:1152
	v_addc_co_u32_e32 v69, vcc, 0, v67, vcc
	s_waitcnt lgkmcnt(0)
	global_store_dwordx4 v[68:69], v[10:13], off offset:1024 sc1
	ds_read_b128 v[10:13], v138 offset:2304
	v_add_co_u32_e32 v68, vcc, 0x40000, v66
	s_nop 1
	v_addc_co_u32_e32 v69, vcc, 0, v67, vcc
	s_waitcnt lgkmcnt(0)
	global_store_dwordx4 v[68:69], v[10:13], off offset:2048 sc1
	ds_read_b128 v[10:13], v138 offset:3456
	v_add_co_u32_e32 v66, vcc, 0x60000, v66
	s_nop 1
	v_addc_co_u32_e32 v67, vcc, 0, v67, vcc
	s_waitcnt lgkmcnt(0)
	global_store_dwordx4 v[66:67], v[10:13], off offset:3072 sc1
	s_waitcnt lgkmcnt(0)
.LBB0_1001:
	s_or_b64 exec, exec, s[6:7]
	v_add_u32_e32 v68, 0x80, v145
	s_mov_b32 s6, 0x8000
	v_cmp_gt_i32_e32 vcc, s6, v68
	v_ashrrev_i32_e32 v70, 13, v68
	v_or_b32_e32 v69, v68, v130
	s_and_saveexec_b64 s[6:7], s[4:5]
	s_xor_b64 s[8:9], exec, s[6:7]
	s_cbranch_execz .LBB0_1023
	s_movk_i32 s6, 0x7fff
	v_cmp_lt_i32_e64 s[6:7], s6, v69
	s_and_saveexec_b64 s[12:13], s[6:7]
	s_xor_b64 s[6:7], exec, s[12:13]
	v_cmp_gt_u32_e64 s[10:11], s49, v68
	s_or_saveexec_b64 s[6:7], s[6:7]
	v_mov_b32_e32 v67, 0
	v_mov_b32_e32 v66, v130
	s_xor_b64 exec, exec, s[6:7]
	v_and_b32_e32 v10, 0x1fcf, v69
	v_add_u32_e32 v66, 64, v10
	v_mul_i32_i24_e32 v67, 6, v70
	s_or_b64 s[10:11], s[10:11], exec
	s_or_b64 exec, exec, s[6:7]
	s_and_saveexec_b64 s[6:7], s[10:11]
	s_cbranch_execz .LBB0_1008
	v_subrev_u32_e32 v10, s20, v69
	v_add_u32_e32 v11, s1, v67
	v_mov_b32_e32 v67, v1
	s_movk_i32 s10, 0x2040
	v_lshl_add_u32 v10, v10, 2, 0
	v_mad_i64_i32 v[12:13], s[10:11], v11, s10, v[66:67]
	v_add_u32_e32 v10, 0x20000, v10
	v_readlane_b32 s10, v254, 4
	ds_read_b32 v10, v10
	v_readlane_b32 s11, v254, 5
	s_waitcnt lgkmcnt(0)
	v_pk_mul_f32 v[62:63], v[62:63], v[10:11] op_sel_hi:[1,0]
	v_mov_b64_e32 v[66:67], s[10:11]
	v_mad_u64_u32 v[66:67], s[10:11], v12, s47, v[66:67]
	v_mad_i32_i24 v67, v13, s47, v67
	v_lshlrev_b32_e32 v12, 1, v0
	v_mov_b32_e32 v13, v1
	v_lshl_add_u64 v[12:13], v[66:67], 0, v[12:13]
	v_lshlrev_b32_e32 v66, 1, v131
	v_mov_b32_e32 v67, v1
	v_lshl_add_u64 v[66:67], v[12:13], 0, v[66:67]
	v_pk_mul_f32 v[12:13], v[64:65], v[10:11] op_sel_hi:[1,0]
	v_pk_mul_f32 v[60:61], v[60:61], v[10:11] op_sel_hi:[1,0]
	v_pk_mul_f32 v[58:59], v[58:59], v[10:11] op_sel_hi:[1,0]
	v_cvt_pk_bf16_f32 v10, v62, v63
	v_cvt_pk_bf16_f32 v11, v12, v13
	v_cvt_pk_bf16_f32 v12, v58, v59
	v_cvt_pk_bf16_f32 v13, v60, v61
	global_store_dwordx4 v[66:67], v[10:13], off sc1

; #define LAS __attribute__((address_space(3)))
; __device__ __forceinline__ void store4bf(bf16_t* p, f32x4 v) { u32x2 w; w.x = cvt_pk_bf16(v[0], v[1]); w.y = cvt_pk_bf16(v[2], v[3]); *(u32x2*)p = w; }
; __device__ __forceinline__ void store8bf(bf16_t* p, f32x4 v0, f32x4 v1) { u32x4 w; w.x = cvt_pk_bf16(v0[0], v0[1]); w.y = cvt_pk_bf16(v0[2], v0[3]); w.z = cvt_pk_bf16(v1[0], v1[1]); w.w = cvt_pk_bf16(v1[2], v1[3]); *(u32x4*)p = w; }
;   __device__ __forceinline__ void group(int row, int c32, int fq, f32x4 v0, f32x4 v1) const {
;     int b, e; if (!row_be(row, b, e)) return;
;     const float rs = use_direct ? rs_direct : ((LAS const float*)(lds_raw + RS_OFF))[row - brow];
;     if (c32 < 768) {
;       if (c32 >= 576) return;
;       const int h = c32 / 96, part = (c32 - h * 96) >> 5; const float sc = rs * QSC_A;
;       bf16_t* p = qa + ((size_t)(b * 6 + h) * E + e) * 96 + part * 32 + fq * 4;
;       if (part < 2) store8bf(qa + ((size_t)(b * 6 + h) * E + e) * 96 + part * 32 + fq * 8, v0 * sc, v1 * sc);
;       else { const float2* rp = rope + pos_of_e(e) * 16 + fq * 4; f32x4 o0, o1;
; #pragma unroll
;         for (int j = 0; j < 4; ++j) { const float2 cs = rp[j]; o0[j] = (v0[j] * cs.x - v1[j] * cs.y) * sc; o1[j] = (v1[j] * cs.x + v0[j] * cs.y) * sc; }
;         store4bf(p, o0); store4bf(p + 16, o1); }
;     } else {
;       const int cc = c32 - 768, h = cc >> 7, part = (cc & 127) >> 5;
;       if (part < 2) store8bf(ka + ((size_t)(b * 6 + h) * E + e) * 96 + part * 32 + fq * 8, v0 * rs, v1 * rs);
.LBB0_1011:
	v_subrev_u32_e32 v10, s20, v59
	v_mad_i32_i24 v11, v60, 6, s1
	v_mov_b32_e32 v59, v1
	s_movk_i32 s10, 0x2040
	v_lshl_add_u32 v10, v10, 2, 0
	v_mad_i64_i32 v[12:13], s[10:11], v11, s10, v[58:59]
	v_add_u32_e32 v10, 0x20000, v10
	v_readlane_b32 s10, v254, 4
	ds_read_b32 v10, v10
	v_readlane_b32 s11, v254, 5
	s_waitcnt lgkmcnt(0)
	v_pk_mul_f32 v[54:55], v[54:55], v[10:11] op_sel_hi:[1,0]
	v_mov_b64_e32 v[58:59], s[10:11]
	v_mad_u64_u32 v[58:59], s[10:11], v12, s47, v[58:59]
	v_mad_i32_i24 v59, v13, s47, v59
	v_lshlrev_b32_e32 v12, 1, v0
	v_mov_b32_e32 v13, v1
	v_lshl_add_u64 v[12:13], v[58:59], 0, v[12:13]
	v_lshlrev_b32_e32 v58, 1, v131
	v_mov_b32_e32 v59, v1
	v_lshl_add_u64 v[58:59], v[12:13], 0, v[58:59]
	v_pk_mul_f32 v[12:13], v[56:57], v[10:11] op_sel_hi:[1,0]
	v_pk_mul_f32 v[52:53], v[52:53], v[10:11] op_sel_hi:[1,0]
	v_pk_mul_f32 v[50:51], v[50:51], v[10:11] op_sel_hi:[1,0]
	v_cvt_pk_bf16_f32 v10, v54, v55
	v_cvt_pk_bf16_f32 v11, v12, v13
	v_cvt_pk_bf16_f32 v12, v50, v51
	v_cvt_pk_bf16_f32 v13, v52, v53
	global_store_dwordx4 v[58:59], v[10:13], off sc1

; #define LAS __attribute__((address_space(3)))
; __device__ __forceinline__ void store4bf(bf16_t* p, f32x4 v) { u32x2 w; w.x = cvt_pk_bf16(v[0], v[1]); w.y = cvt_pk_bf16(v[2], v[3]); *(u32x2*)p = w; }
; __device__ __forceinline__ void store8bf(bf16_t* p, f32x4 v0, f32x4 v1) { u32x4 w; w.x = cvt_pk_bf16(v0[0], v0[1]); w.y = cvt_pk_bf16(v0[2], v0[3]); w.z = cvt_pk_bf16(v1[0], v1[1]); w.w = cvt_pk_bf16(v1[2], v1[3]); *(u32x4*)p = w; }
;   __device__ __forceinline__ void group(int row, int c32, int fq, f32x4 v0, f32x4 v1) const {
;     int b, e; if (!row_be(row, b, e)) return;
;     const float rs = use_direct ? rs_direct : ((LAS const float*)(lds_raw + RS_OFF))[row - brow];
;     if (c32 < 768) {
;       if (c32 >= 576) return;
;       const int h = c32 / 96, part = (c32 - h * 96) >> 5; const float sc = rs * QSC_A;
;       bf16_t* p = qa + ((size_t)(b * 6 + h) * E + e) * 96 + part * 32 + fq * 4;
;       if (part < 2) store8bf(qa + ((size_t)(b * 6 + h) * E + e) * 96 + part * 32 + fq * 8, v0 * sc, v1 * sc);
;       else { const float2* rp = rope + pos_of_e(e) * 16 + fq * 4; f32x4 o0, o1;
; #pragma unroll
;         for (int j = 0; j < 4; ++j) { const float2 cs = rp[j]; o0[j] = (v0[j] * cs.x - v1[j] * cs.y) * sc; o1[j] = (v1[j] * cs.x + v0[j] * cs.y) * sc; }
;         store4bf(p, o0); store4bf(p + 16, o1); }
;     } else {
;       const int cc = c32 - 768, h = cc >> 7, part = (cc & 127) >> 5;
;       if (part < 2) store8bf(ka + ((size_t)(b * 6 + h) * E + e) * 96 + part * 32 + fq * 8, v0 * rs, v1 * rs);
.LBB0_1015:
	v_subrev_u32_e32 v10, s20, v51
	v_mad_i32_i24 v11, v52, 6, s1
	v_mov_b32_e32 v51, v1
	s_movk_i32 s10, 0x2040
	v_lshl_add_u32 v10, v10, 2, 0
	v_mad_i64_i32 v[12:13], s[10:11], v11, s10, v[50:51]
	v_add_u32_e32 v10, 0x20000, v10
	v_readlane_b32 s10, v254, 4
	ds_read_b32 v10, v10
	v_readlane_b32 s11, v254, 5
	s_waitcnt lgkmcnt(0)
	v_pk_mul_f32 v[46:47], v[46:47], v[10:11] op_sel_hi:[1,0]
	v_mov_b64_e32 v[50:51], s[10:11]
	v_mad_u64_u32 v[50:51], s[10:11], v12, s47, v[50:51]
	v_mad_i32_i24 v51, v13, s47, v51
	v_lshlrev_b32_e32 v12, 1, v0
	v_mov_b32_e32 v13, v1
	v_lshl_add_u64 v[12:13], v[50:51], 0, v[12:13]
	v_lshlrev_b32_e32 v50, 1, v131
	v_mov_b32_e32 v51, v1
	v_lshl_add_u64 v[50:51], v[12:13], 0, v[50:51]
	v_pk_mul_f32 v[12:13], v[48:49], v[10:11] op_sel_hi:[1,0]
	v_pk_mul_f32 v[44:45], v[44:45], v[10:11] op_sel_hi:[1,0]
	v_pk_mul_f32 v[42:43], v[42:43], v[10:11] op_sel_hi:[1,0]
	v_cvt_pk_bf16_f32 v10, v46, v47
	v_cvt_pk_bf16_f32 v11, v12, v13
	v_cvt_pk_bf16_f32 v12, v42, v43
	v_cvt_pk_bf16_f32 v13, v44, v45
	global_store_dwordx4 v[50:51], v[10:13], off sc1
.LBB0_1016:
	s_or_b64 exec, exec, s[6:7]
	v_or_b32_e32 v43, 48, v69
	s_movk_i32 s6, 0x7fff
	v_cmp_lt_i32_e64 s[6:7], s6, v43
	s_and_saveexec_b64 s[12:13], s[6:7]
	s_xor_b64 s[6:7], exec, s[12:13]
	v_cmp_gt_u32_e64 s[10:11], s49, v68
	s_or_saveexec_b64 s[6:7], s[6:7]
	v_mov_b32_e32 v44, 18
	v_mov_b32_e32 v42, v130
	s_xor_b64 exec, exec, s[6:7]
	v_and_b32_e32 v10, 0x1fff, v43
	v_add_u32_e32 v42, 64, v10
	v_mul_i32_i24_e32 v44, 6, v70
	s_or_b64 s[10:11], s[10:11], exec
	s_or_b64 exec, exec, s[6:7]
	s_and_saveexec_b64 s[6:7], s[10:11]
	s_cbranch_execz .LBB0_1022
	v_subrev_u32_e32 v10, s20, v43
	v_add_u32_e32 v11, s1, v44
	v_mov_b32_e32 v43, v1
	s_movk_i32 s10, 0x2040
	v_lshl_add_u32 v10, v10, 2, 0
	v_mad_i64_i32 v[12:13], s[10:11], v11, s10, v[42:43]
	v_add_u32_e32 v10, 0x20000, v10
	v_readlane_b32 s10, v254, 4
	ds_read_b32 v10, v10
	v_readlane_b32 s11, v254, 5
	s_waitcnt lgkmcnt(0)
	v_pk_mul_f32 v[38:39], v[38:39], v[10:11] op_sel_hi:[1,0]
	v_mov_b64_e32 v[42:43], s[10:11]
	v_mad_u64_u32 v[42:43], s[10:11], v12, s47, v[42:43]
	v_mad_i32_i24 v43, v13, s47, v43
	v_lshlrev_b32_e32 v12, 1, v0
	v_mov_b32_e32 v13, v1
	v_lshl_add_u64 v[12:13], v[42:43], 0, v[12:13]
	v_lshlrev_b32_e32 v42, 1, v131
	v_mov_b32_e32 v43, v1
	v_lshl_add_u64 v[42:43], v[12:13], 0, v[42:43]
	v_pk_mul_f32 v[12:13], v[40:41], v[10:11] op_sel_hi:[1,0]
	v_pk_mul_f32 v[36:37], v[36:37], v[10:11] op_sel_hi:[1,0]
	v_pk_mul_f32 v[34:35], v[34:35], v[10:11] op_sel_hi:[1,0]
	v_cvt_pk_bf16_f32 v10, v38, v39
	v_cvt_pk_bf16_f32 v11, v12, v13
	v_cvt_pk_bf16_f32 v12, v34, v35
	v_cvt_pk_bf16_f32 v13, v36, v37
	global_store_dwordx4 v[42:43], v[10:13], off sc1

; #define LAS __attribute__((address_space(3)))
; __device__ __forceinline__ unsigned short f2bf(float f) { return (unsigned short)(cvt_pk_bf16(f, f) & 0xffffu); }
;   __device__ __forceinline__ bool vt_info(int c32, int b, bf16_t*& base) const { return e->vt_info(c32 + sh, b, base); }
;     ...
;         const int c32 = bcol + wc * 32 + bj * HALF, row0 = brow + ai * HALF + wr * 64;
;         int b0, e0; row_be(row0, b0, e0); bf16_t* vbase;
;         if (epi.vt_info(c32, b0, vbase)) {
; #pragma unroll
;           for (int m = 0; m < 4; ++m) { const float sc = epi.row_scale(row0 + m * 16 + fr);
; #pragma unroll
;             for (int n = 0; n < 2; ++n)
; #pragma unroll
;               for (int j = 0; j < 4; ++j) *(LAS bf16_t*)(T + (n * 16 + fq * 4 + j) * 144 + (m * 16 + fr) * 2) = f2bf(acc[ai][bj][m][n][j] * sc); }
;           asm volatile("s_waitcnt lgkmcnt(0)" ::: "memory");
; #pragma unroll
;           for (int q = 0; q < 4; ++q) { const int ch = lane + 64 * q, d = ch >> 3, ec = ch & 7;
;             *(u32x4*)(vbase + (size_t)d * E + e0 + ec * 8) = *(LAS const u32x4*)(T + d * 144 + ec * 16); }
;           asm volatile("s_waitcnt lgkmcnt(0)" ::: "memory");
.LBB0_1023:
	s_or_saveexec_b64 s[6:7], s[8:9]
	v_and_b32_e32 v10, 0x1fc0, v68
	v_add_u32_e32 v10, 64, v10
	v_cndmask_b32_e32 v10, 0, v10, vcc
	v_subrev_u32_e32 v11, s20, v69
	v_cndmask_b32_e32 v72, 0, v70, vcc
	v_lshlrev_b32_e32 v66, 1, v10
	v_lshl_add_u32 v71, v11, 2, 0
	s_xor_b64 exec, exec, s[6:7]
	s_cbranch_execz .LBB0_1153
	v_mad_i32_i24 v10, v72, 6, s1
	v_ashrrev_i32_e32 v11, 31, v10
	v_readlane_b32 s8, v254, 26
	v_lshlrev_b64 v[10:11], 6, v[10:11]
	v_mov_b32_e32 v135, v1
	v_readlane_b32 s9, v254, 27
	v_lshl_add_u64 v[10:11], v[10:11], 0, v[134:135]
	v_add_u32_e32 v67, 0x20000, v71
	v_mov_b64_e32 v[12:13], s[8:9]
	v_mad_u64_u32 v[12:13], s[8:9], v10, s95, v[12:13]
	v_mad_i32_i24 v13, v11, s95, v13
	ds_read2_b32 v[10:11], v67 offset1:16
	v_mov_b32_e32 v133, v1
	s_waitcnt lgkmcnt(0)
	v_mul_f32_e32 v62, v62, v10
	v_cvt_pk_bf16_f32 v62, v62, s0
	ds_write_b16 v144, v62
	v_mul_f32_e32 v62, v63, v10
	v_mul_f32_e32 v58, v58, v10
	v_cvt_pk_bf16_f32 v62, v62, s0
	v_cvt_pk_bf16_f32 v58, v58, s0
	ds_write_b16 v144, v62 offset:144
	v_mul_f32_e32 v62, v64, v10
	ds_write_b16 v144, v58 offset:2304
	v_mul_f32_e32 v58, v59, v10
	v_cvt_pk_bf16_f32 v62, v62, s0
	v_cvt_pk_bf16_f32 v58, v58, s0
	ds_write_b16 v144, v62 offset:288
	v_mul_f32_e32 v62, v65, v10
	ds_write_b16 v144, v58 offset:2448
	v_mul_f32_e32 v58, v60, v10
	v_mul_f32_e32 v10, v61, v10
	v_cvt_pk_bf16_f32 v10, v10, s0
	ds_write_b16 v144, v10 offset:2736
	v_mul_f32_e32 v10, v54, v11
	v_cvt_pk_bf16_f32 v10, v10, s0
	ds_write_b16 v144, v10 offset:32
	v_mul_f32_e32 v10, v55, v11
	v_cvt_pk_bf16_f32 v10, v10, s0
	ds_write_b16 v144, v10 offset:176
	v_mul_f32_e32 v10, v56, v11
	v_cvt_pk_bf16_f32 v10, v10, s0
	ds_write_b16 v144, v10 offset:320
	v_mul_f32_e32 v10, v57, v11
	v_cvt_pk_bf16_f32 v10, v10, s0
	ds_write_b16 v144, v10 offset:464
	v_mul_f32_e32 v10, v50, v11
	v_cvt_pk_bf16_f32 v10, v10, s0
	ds_write_b16 v144, v10 offset:2336
	v_mul_f32_e32 v10, v51, v11
	v_cvt_pk_bf16_f32 v10, v10, s0
	ds_write_b16 v144, v10 offset:2480
	v_mul_f32_e32 v10, v52, v11
	v_cvt_pk_bf16_f32 v10, v10, s0
	ds_write_b16 v144, v10 offset:2624
	v_mul_f32_e32 v10, v53, v11
	v_cvt_pk_bf16_f32 v10, v10, s0
	ds_write_b16 v144, v10 offset:2768
	ds_read2_b32 v[10:11], v67 offset0:32 offset1:48
	v_cvt_pk_bf16_f32 v62, v62, s0
	v_cvt_pk_bf16_f32 v58, v58, s0
	ds_write_b16 v144, v62 offset:432
	ds_write_b16 v144, v58 offset:2592
	s_waitcnt lgkmcnt(0)
	v_mul_f32_e32 v46, v46, v10
	v_cvt_pk_bf16_f32 v46, v46, s0
	ds_write_b16 v144, v46 offset:64
	v_mul_f32_e32 v46, v47, v10
	v_mul_f32_e32 v42, v42, v10
	v_cvt_pk_bf16_f32 v46, v46, s0
	v_cvt_pk_bf16_f32 v42, v42, s0
	ds_write_b16 v144, v46 offset:208
	v_mul_f32_e32 v46, v48, v10
	ds_write_b16 v144, v42 offset:2368
	v_mul_f32_e32 v42, v43, v10
	v_cvt_pk_bf16_f32 v46, v46, s0
	v_cvt_pk_bf16_f32 v42, v42, s0
	ds_write_b16 v144, v46 offset:352
	v_mul_f32_e32 v46, v49, v10
	ds_write_b16 v144, v42 offset:2512
	v_mul_f32_e32 v42, v44, v10
	v_mul_f32_e32 v10, v45, v10
	v_cvt_pk_bf16_f32 v10, v10, s0
	ds_write_b16 v144, v10 offset:2800
	v_mul_f32_e32 v10, v38, v11
	v_cvt_pk_bf16_f32 v10, v10, s0
	ds_write_b16 v144, v10 offset:96
	v_mul_f32_e32 v10, v39, v11
	v_cvt_pk_bf16_f32 v10, v10, s0
	ds_write_b16 v144, v10 offset:240
	v_mul_f32_e32 v10, v40, v11
	v_cvt_pk_bf16_f32 v10, v10, s0
	ds_write_b16 v144, v10 offset:384
	v_mul_f32_e32 v10, v41, v11
	v_cvt_pk_bf16_f32 v10, v10, s0
	ds_write_b16 v144, v10 offset:528
	v_mul_f32_e32 v10, v34, v11
	v_cvt_pk_bf16_f32 v10, v10, s0
	ds_write_b16 v144, v10 offset:2400
	v_mul_f32_e32 v10, v35, v11
	v_cvt_pk_bf16_f32 v10, v10, s0
	ds_write_b16 v144, v10 offset:2544
	v_mul_f32_e32 v10, v36, v11
	v_cvt_pk_bf16_f32 v10, v10, s0
	ds_write_b16 v144, v10 offset:2688
	v_mul_f32_e32 v10, v37, v11
	v_cvt_pk_bf16_f32 v46, v46, s0
	v_cvt_pk_bf16_f32 v42, v42, s0
	v_cvt_pk_bf16_f32 v10, v10, s0
	ds_write_b16 v144, v46 offset:496
	ds_write_b16 v144, v42 offset:2656
	ds_write_b16 v144, v10 offset:2832
	v_mov_b32_e32 v67, v1
	s_waitcnt lgkmcnt(0)
	v_lshl_add_u64 v[10:11], v[12:13], 0, v[66:67]
	v_lshl_add_u64 v[34:35], v[10:11], 0, v[132:133]
	ds_read_b128 v[10:13], v138
	v_lshlrev_b32_e32 v36, 1, v139
	v_mov_b32_e32 v37, v1
	v_lshl_add_u64 v[34:35], v[34:35], 0, v[36:37]
	v_add_co_u32_e32 v36, vcc, 0x20000, v34
	s_waitcnt lgkmcnt(0)
	global_store_dwordx4 v[34:35], v[10:13], off sc1
	ds_read_b128 v[10:13], v138 offset:1152
	v_addc_co_u32_e32 v37, vcc, 0, v35, vcc
	s_waitcnt lgkmcnt(0)
	global_store_dwordx4 v[36:37], v[10:13], off offset:1024 sc1
	ds_read_b128 v[10:13], v138 offset:2304
	v_add_co_u32_e32 v36, vcc, 0x40000, v34
	s_nop 1
	v_addc_co_u32_e32 v37, vcc, 0, v35, vcc
	s_waitcnt lgkmcnt(0)
	global_store_dwordx4 v[36:37], v[10:13], off offset:2048 sc1
	ds_read_b128 v[10:13], v138 offset:3456
	v_add_co_u32_e32 v34, vcc, 0x60000, v34
	s_nop 1
	v_addc_co_u32_e32 v35, vcc, 0, v35, vcc
	s_waitcnt lgkmcnt(0)
	global_store_dwordx4 v[34:35], v[10:13], off offset:3072 sc1
	s_waitcnt lgkmcnt(0)
	s_or_b64 exec, exec, s[6:7]
	s_and_saveexec_b64 s[6:7], s[4:5]
	s_xor_b64 s[4:5], exec, s[6:7]
	s_cbranch_execnz .LBB0_1154

; #define LAS __attribute__((address_space(3)))
; __device__ __forceinline__ unsigned short f2bf(float f) { return (unsigned short)(cvt_pk_bf16(f, f) & 0xffffu); }
;   __device__ __forceinline__ bool vt_info(int c32, int b, bf16_t*& base) const { return e->vt_info(c32 + sh, b, base); }
;     ...
;         const int c32 = bcol + wc * 32 + bj * HALF, row0 = brow + ai * HALF + wr * 64;
;         int b0, e0; row_be(row0, b0, e0); bf16_t* vbase;
;         if (epi.vt_info(c32, b0, vbase)) {
; #pragma unroll
;           for (int m = 0; m < 4; ++m) { const float sc = epi.row_scale(row0 + m * 16 + fr);
; #pragma unroll
;             for (int n = 0; n < 2; ++n)
; #pragma unroll
;               for (int j = 0; j < 4; ++j) *(LAS bf16_t*)(T + (n * 16 + fq * 4 + j) * 144 + (m * 16 + fr) * 2) = f2bf(acc[ai][bj][m][n][j] * sc); }
;           asm volatile("s_waitcnt lgkmcnt(0)" ::: "memory");
; #pragma unroll
;           for (int q = 0; q < 4; ++q) { const int ch = lane + 64 * q, d = ch >> 3, ec = ch & 7;
;             *(u32x4*)(vbase + (size_t)d * E + e0 + ec * 8) = *(LAS const u32x4*)(T + d * 144 + ec * 16); }
;           asm volatile("s_waitcnt lgkmcnt(0)" ::: "memory");
.LBB0_1026:
	v_mad_i32_i24 v10, v72, 6, s0
	v_ashrrev_i32_e32 v11, 31, v10
	v_readlane_b32 s0, v254, 26
	v_lshlrev_b64 v[10:11], 6, v[10:11]
	v_mov_b32_e32 v135, v1
	v_readlane_b32 s1, v254, 27
	v_lshl_add_u64 v[10:11], v[10:11], 0, v[134:135]
	v_add_u32_e32 v0, 0x20000, v71
	v_mov_b64_e32 v[12:13], s[0:1]
	v_mad_u64_u32 v[12:13], s[0:1], v10, s95, v[12:13]
	v_mad_i32_i24 v13, v11, s95, v13
	ds_read2_b32 v[10:11], v0 offset1:16
	v_mov_b32_e32 v67, v1
	v_mov_b32_e32 v133, v1
	s_waitcnt lgkmcnt(0)
	v_mul_f32_e32 v30, v30, v10
	v_cvt_pk_bf16_f32 v30, v30, s0
	ds_write_b16 v144, v30
	v_mul_f32_e32 v30, v31, v10
	v_mul_f32_e32 v26, v26, v10
	v_cvt_pk_bf16_f32 v30, v30, s0
	v_cvt_pk_bf16_f32 v26, v26, s0
	ds_write_b16 v144, v30 offset:144
	v_mul_f32_e32 v30, v32, v10
	ds_write_b16 v144, v26 offset:2304
	v_mul_f32_e32 v26, v27, v10
	v_cvt_pk_bf16_f32 v30, v30, s0
	v_cvt_pk_bf16_f32 v26, v26, s0
	ds_write_b16 v144, v30 offset:288
	v_mul_f32_e32 v30, v33, v10
	ds_write_b16 v144, v26 offset:2448
	v_mul_f32_e32 v26, v28, v10
	v_mul_f32_e32 v10, v29, v10
	v_cvt_pk_bf16_f32 v10, v10, s0
	ds_write_b16 v144, v10 offset:2736
	v_mul_f32_e32 v10, v22, v11
	v_cvt_pk_bf16_f32 v10, v10, s0
	ds_write_b16 v144, v10 offset:32
	v_mul_f32_e32 v10, v23, v11
	v_cvt_pk_bf16_f32 v10, v10, s0
	ds_write_b16 v144, v10 offset:176
	v_mul_f32_e32 v10, v24, v11
	v_cvt_pk_bf16_f32 v10, v10, s0
	ds_write_b16 v144, v10 offset:320
	v_mul_f32_e32 v10, v25, v11
	v_cvt_pk_bf16_f32 v10, v10, s0
	ds_write_b16 v144, v10 offset:464
	v_mul_f32_e32 v10, v18, v11
	v_cvt_pk_bf16_f32 v10, v10, s0
	ds_write_b16 v144, v10 offset:2336
	v_mul_f32_e32 v10, v19, v11
	v_cvt_pk_bf16_f32 v10, v10, s0
	ds_write_b16 v144, v10 offset:2480
	v_mul_f32_e32 v10, v20, v11
	v_cvt_pk_bf16_f32 v10, v10, s0
	ds_write_b16 v144, v10 offset:2624
	v_mul_f32_e32 v10, v21, v11
	v_cvt_pk_bf16_f32 v10, v10, s0
	ds_write_b16 v144, v10 offset:2768
	ds_read2_b32 v[10:11], v0 offset0:32 offset1:48
	v_cvt_pk_bf16_f32 v30, v30, s0
	v_cvt_pk_bf16_f32 v26, v26, s0
	ds_write_b16 v144, v30 offset:432
	ds_write_b16 v144, v26 offset:2592
	s_waitcnt lgkmcnt(0)
	v_mul_f32_e32 v0, v14, v10
	v_cvt_pk_bf16_f32 v0, v0, s0
	ds_write_b16 v144, v0 offset:64
	v_mul_f32_e32 v0, v15, v10
	v_cvt_pk_bf16_f32 v0, v0, s0
	ds_write_b16 v144, v0 offset:208
	v_mul_f32_e32 v0, v16, v10
	v_cvt_pk_bf16_f32 v0, v0, s0
	ds_write_b16 v144, v0 offset:352
	v_mul_f32_e32 v0, v17, v10
	v_cvt_pk_bf16_f32 v0, v0, s0
	ds_write_b16 v144, v0 offset:496
	v_mul_f32_e32 v0, v150, v10
	v_cvt_pk_bf16_f32 v0, v0, s0
	ds_write_b16 v144, v0 offset:2368
	v_mul_f32_e32 v0, v151, v10
	v_cvt_pk_bf16_f32 v0, v0, s0
	ds_write_b16 v144, v0 offset:2512
	v_mul_f32_e32 v0, v152, v10
	v_cvt_pk_bf16_f32 v0, v0, s0
	ds_write_b16 v144, v0 offset:2656
	v_mul_f32_e32 v0, v153, v10
	v_cvt_pk_bf16_f32 v0, v0, s0
	ds_write_b16 v144, v0 offset:2800
	v_mul_f32_e32 v0, v6, v11
	v_cvt_pk_bf16_f32 v0, v0, s0
	ds_write_b16 v144, v0 offset:96
	v_mul_f32_e32 v0, v7, v11
	v_cvt_pk_bf16_f32 v0, v0, s0
	ds_write_b16 v144, v0 offset:240
	v_mul_f32_e32 v0, v8, v11
	v_cvt_pk_bf16_f32 v0, v0, s0
	ds_write_b16 v144, v0 offset:384
	v_mul_f32_e32 v0, v9, v11
	v_cvt_pk_bf16_f32 v0, v0, s0
	ds_write_b16 v144, v0 offset:528
	v_mul_f32_e32 v0, v2, v11
	v_cvt_pk_bf16_f32 v0, v0, s0
	ds_write_b16 v144, v0 offset:2400
	v_mul_f32_e32 v0, v3, v11
	v_cvt_pk_bf16_f32 v0, v0, s0
	ds_write_b16 v144, v0 offset:2544
	v_mul_f32_e32 v0, v4, v11
	v_cvt_pk_bf16_f32 v0, v0, s0
	ds_write_b16 v144, v0 offset:2688
	v_mul_f32_e32 v0, v5, v11
	v_cvt_pk_bf16_f32 v0, v0, s0
	ds_write_b16 v144, v0 offset:2832
	s_waitcnt lgkmcnt(0)
	v_lshl_add_u64 v[2:3], v[12:13], 0, v[66:67]
	v_lshl_add_u64 v[6:7], v[2:3], 0, v[132:133]
	ds_read_b128 v[2:5], v138
	v_lshlrev_b32_e32 v8, 1, v139
	v_mov_b32_e32 v9, v1
	v_lshl_add_u64 v[6:7], v[6:7], 0, v[8:9]
	v_add_co_u32_e32 v8, vcc, 0x20000, v6
	s_waitcnt lgkmcnt(0)
	global_store_dwordx4 v[6:7], v[2:5], off sc1
	ds_read_b128 v[2:5], v138 offset:1152
	v_addc_co_u32_e32 v9, vcc, 0, v7, vcc
	s_waitcnt lgkmcnt(0)
	global_store_dwordx4 v[8:9], v[2:5], off offset:1024 sc1
	ds_read_b128 v[2:5], v138 offset:2304
	v_add_co_u32_e32 v8, vcc, 0x40000, v6
	s_nop 1
	v_addc_co_u32_e32 v9, vcc, 0, v7, vcc
	s_waitcnt lgkmcnt(0)
	global_store_dwordx4 v[8:9], v[2:5], off offset:2048 sc1
	ds_read_b128 v[2:5], v138 offset:3456
	v_add_co_u32_e32 v6, vcc, 0x60000, v6
	s_nop 1
	v_addc_co_u32_e32 v7, vcc, 0, v7, vcc
	s_waitcnt lgkmcnt(0)
	global_store_dwordx4 v[6:7], v[2:5], off offset:3072 sc1
	s_waitcnt lgkmcnt(0)

; #define LAS __attribute__((address_space(3)))
; __device__ __forceinline__ void store4bf(bf16_t* p, f32x4 v) { u32x2 w; w.x = cvt_pk_bf16(v[0], v[1]); w.y = cvt_pk_bf16(v[2], v[3]); *(u32x2*)p = w; }
; __device__ __forceinline__ void store8bf(bf16_t* p, f32x4 v0, f32x4 v1) { u32x4 w; w.x = cvt_pk_bf16(v0[0], v0[1]); w.y = cvt_pk_bf16(v0[2], v0[3]); w.z = cvt_pk_bf16(v1[0], v1[1]); w.w = cvt_pk_bf16(v1[2], v1[3]); *(u32x4*)p = w; }
;   __device__ __forceinline__ void group(int row, int c32, int fq, f32x4 v0, f32x4 v1) const { e->group(row, c32 + sh, fq, v0, v1); }
;   __device__ __forceinline__ void group(int row, int c32, int fq, f32x4 v0, f32x4 v1) const {
;     int b, e; if (!row_be(row, b, e)) return;
;     const float rs = use_direct ? rs_direct : ((LAS const float*)(lds_raw + RS_OFF))[row - brow];
;     if (c32 < 768) {
;       if (c32 >= 576) return;
;       const int h = c32 / 96, part = (c32 - h * 96) >> 5; const float sc = rs * QSC_A;
;       bf16_t* p = qa + ((size_t)(b * 6 + h) * E + e) * 96 + part * 32 + fq * 4;
;       if (part < 2) store8bf(qa + ((size_t)(b * 6 + h) * E + e) * 96 + part * 32 + fq * 8, v0 * sc, v1 * sc);
;       else { const float2* rp = rope + pos_of_e(e) * 16 + fq * 4; f32x4 o0, o1;
; #pragma unroll
;         for (int j = 0; j < 4; ++j) { const float2 cs = rp[j]; o0[j] = (v0[j] * cs.x - v1[j] * cs.y) * sc; o1[j] = (v1[j] * cs.x + v0[j] * cs.y) * sc; }
;         store4bf(p, o0); store4bf(p + 16, o1); }
.LBB0_1033:
	s_or_b64 exec, exec, s[4:5]
	v_lshlrev_b32_e32 v133, 6, v132
	v_lshl_or_b32 v132, v0, 5, s90
	v_add_u32_e32 v145, s20, v133
	s_movk_i32 s0, 0x23f
	v_or_b32_e32 v149, v145, v130
	v_cmp_lt_u32_e32 vcc, s0, v132
	s_movk_i32 s0, 0x7fff
	v_cmp_lt_i32_e64 s[6:7], s0, v149
	s_and_saveexec_b64 s[0:1], s[6:7]
	s_xor_b64 s[8:9], exec, s[0:1]
	v_cmp_lt_u32_e64 s[4:5], s50, v145
	s_or_b64 s[4:5], s[4:5], vcc
	s_or_saveexec_b64 s[8:9], s[8:9]
	v_ashrrev_i32_e32 v147, 13, v145
	v_and_b32_e32 v134, 0x1fcf, v149
	v_mov_b32_e32 v136, 0
	v_add_u32_e32 v133, 64, v134
	v_mul_i32_i24_e32 v146, 6, v147
	v_mov_b32_e32 v0, v130
	s_xor_b64 exec, exec, s[8:9]
	s_andn2_b64 s[0:1], s[4:5], exec
	s_and_b64 s[4:5], vcc, exec
	v_add_u32_e32 v0, 64, v134
	v_mul_i32_i24_e32 v136, 6, v147
	s_or_b64 s[4:5], s[0:1], s[4:5]
	s_or_b64 exec, exec, s[8:9]
	v_bfe_u32 v131, v131, 4, 2
	v_lshlrev_b32_e32 v137, 2, v131
	v_lshlrev_b32_e32 v144, 3, v131
	v_mul_hi_u32 v131, v132, s55
	s_xor_b64 s[0:1], s[4:5], -1
	v_lshrrev_b32_e32 v131, 4, v131
	s_movk_i32 s4, 0xffa0
	v_mad_u64_u32 v[134:135], s[4:5], v131, s4, v[132:133]
	v_subrev_u32_e32 v138, s20, v149
	v_ashrrev_i32_e32 v135, 31, v134
	v_cmp_lt_i32_e64 s[8:9], 63, v134
	v_lshl_add_u32 v148, v138, 2, 0
	s_and_saveexec_b64 s[10:11], s[0:1]
	s_cbranch_execz .LBB0_1042
	v_add_u32_e32 v138, 0x20000, v148
	v_readlane_b32 s0, v254, 24
	ds_read_b32 v152, v138
	v_readlane_b32 s1, v254, 25
	v_add_u32_e32 v136, v136, v131
	s_nop 0
	v_mov_b64_e32 v[138:139], s[0:1]
	s_movk_i32 s0, 0x2040
	v_mad_i64_i32 v[150:151], s[0:1], v136, s0, v[0:1]
	v_mad_u64_u32 v[138:139], s[0:1], v150, s47, v[138:139]
	v_mad_i32_i24 v139, v151, s47, v139
	s_waitcnt lgkmcnt(0)
	v_mul_f32_e32 v136, 0x3e16c740, v152
	v_lshl_add_u64 v[138:139], v[134:135], 1, v[138:139]
	s_and_saveexec_b64 s[0:1], s[8:9]
	s_xor_b64 s[12:13], exec, s[0:1]
	s_cbranch_execz .LBB0_1040
	v_lshlrev_b32_e32 v150, 1, v137
	v_mov_b32_e32 v151, v1
	v_cmp_lt_u32_e64 s[4:5], 63, v0
	v_lshlrev_b32_e32 v0, 4, v0
	v_lshl_add_u64 v[138:139], v[138:139], 0, v[150:151]
	v_add_u32_e32 v150, 0xfffffd00, v0
	v_readlane_b32 s0, v253, 40
	v_cndmask_b32_e64 v150, v0, v150, s[4:5]
	v_readlane_b32 s1, v253, 41
	v_lshlrev_b32_e32 v152, 3, v137
	v_mov_b32_e32 v153, v1
	v_lshl_add_u64 v[150:151], v[150:151], 3, s[0:1]
	v_lshl_add_u64 v[158:159], v[150:151], 0, v[152:153]
	global_load_dwordx4 v[150:153], v[158:159], off offset:16
	s_nop 0
	global_load_dwordx4 v[158:161], v[158:159], off
	s_waitcnt vmcnt(0)
	v_mov_b32_e32 v163, v160
	v_mov_b32_e32 v160, v159
	v_mov_b32_e32 v162, v158
	v_pk_mul_f32 v[158:159], v[122:123], v[160:161]
	s_nop 0
	v_pk_fma_f32 v[158:159], v[126:127], v[162:163], v[158:159]
	v_pk_mul_f32 v[126:127], v[126:127], v[160:161]
	v_pk_mul_f32 v[158:159], v[136:137], v[158:159] op_sel_hi:[0,1]
	v_pk_fma_f32 v[122:123], v[122:123], v[162:163], v[126:127] neg_lo:[0,0,1] neg_hi:[0,0,1]
	v_mov_b32_e32 v127, v152
	v_mov_b32_e32 v152, v151
	v_mov_b32_e32 v126, v150
	v_pk_mul_f32 v[150:151], v[124:125], v[152:153]
	v_pk_mul_f32 v[122:123], v[136:137], v[122:123] op_sel_hi:[0,1]
	v_pk_fma_f32 v[150:151], v[128:129], v[126:127], v[150:151]
	v_pk_mul_f32 v[128:129], v[128:129], v[152:153]
	v_pk_mul_f32 v[150:151], v[136:137], v[150:151] op_sel_hi:[0,1]
	v_pk_fma_f32 v[124:125], v[124:125], v[126:127], v[128:129] neg_lo:[0,0,1] neg_hi:[0,0,1]
	v_cvt_pk_bf16_f32 v122, v122, v123
	v_pk_mul_f32 v[124:125], v[136:137], v[124:125] op_sel_hi:[0,1]
	v_cvt_pk_bf16_f32 v123, v124, v125
	global_store_dwordx2 v[138:139], v[122:123], off sc1
	v_cvt_pk_bf16_f32 v122, v158, v159
	v_cvt_pk_bf16_f32 v123, v150, v151
	global_store_dwordx2 v[138:139], v[122:123], off offset:32 sc1
.LBB0_1040:
	s_andn2_saveexec_b64 s[0:1], s[12:13]
	s_cbranch_execz .LBB0_1042
	v_lshlrev_b32_e32 v150, 1, v144
	v_mov_b32_e32 v151, v1
	v_pk_mul_f32 v[124:125], v[124:125], v[136:137] op_sel_hi:[1,0]
	v_pk_mul_f32 v[122:123], v[122:123], v[136:137] op_sel_hi:[1,0]
	v_pk_mul_f32 v[128:129], v[128:129], v[136:137] op_sel_hi:[1,0]
	v_pk_mul_f32 v[126:127], v[126:127], v[136:137] op_sel_hi:[1,0]
	v_lshl_add_u64 v[138:139], v[138:139], 0, v[150:151]
	v_cvt_pk_bf16_f32 v122, v122, v123
	v_cvt_pk_bf16_f32 v123, v124, v125
	v_cvt_pk_bf16_f32 v124, v126, v127
	v_cvt_pk_bf16_f32 v125, v128, v129
	global_store_dwordx4 v[138:139], v[122:125], off sc1
; #define LAS __attribute__((address_space(3)))
; __device__ __forceinline__ void store4bf(bf16_t* p, f32x4 v) { u32x2 w; w.x = cvt_pk_bf16(v[0], v[1]); w.y = cvt_pk_bf16(v[2], v[3]); *(u32x2*)p = w; }
; __device__ __forceinline__ void store8bf(bf16_t* p, f32x4 v0, f32x4 v1) { u32x4 w; w.x = cvt_pk_bf16(v0[0], v0[1]); w.y = cvt_pk_bf16(v0[2], v0[3]); w.z = cvt_pk_bf16(v1[0], v1[1]); w.w = cvt_pk_bf16(v1[2], v1[3]); *(u32x4*)p = w; }
;   __device__ __forceinline__ void group(int row, int c32, int fq, f32x4 v0, f32x4 v1) const { e->group(row, c32 + sh, fq, v0, v1); }
;   __device__ __forceinline__ void group(int row, int c32, int fq, f32x4 v0, f32x4 v1) const {
;     int b, e; if (!row_be(row, b, e)) return;
;     const float rs = use_direct ? rs_direct : ((LAS const float*)(lds_raw + RS_OFF))[row - brow];
;     if (c32 < 768) {
;       if (c32 >= 576) return;
;       const int h = c32 / 96, part = (c32 - h * 96) >> 5; const float sc = rs * QSC_A;
;       bf16_t* p = qa + ((size_t)(b * 6 + h) * E + e) * 96 + part * 32 + fq * 4;
;       if (part < 2) store8bf(qa + ((size_t)(b * 6 + h) * E + e) * 96 + part * 32 + fq * 8, v0 * sc, v1 * sc);
;       else { const float2* rp = rope + pos_of_e(e) * 16 + fq * 4; f32x4 o0, o1;
; #pragma unroll
;         for (int j = 0; j < 4; ++j) { const float2 cs = rp[j]; o0[j] = (v0[j] * cs.x - v1[j] * cs.y) * sc; o1[j] = (v1[j] * cs.x + v0[j] * cs.y) * sc; }
;         store4bf(p, o0); store4bf(p + 16, o1); }
.LBB0_1042:
	s_or_b64 exec, exec, s[10:11]
	s_nop 0
	v_or_b32_e32 v122, 16, v149
	s_movk_i32 s0, 0x7fff
	v_cmp_lt_i32_e64 s[14:15], s0, v122
	s_and_saveexec_b64 s[0:1], s[14:15]
	s_xor_b64 s[10:11], exec, s[0:1]
	v_cmp_lt_u32_e64 s[4:5], s50, v145
	s_or_b64 s[4:5], s[4:5], vcc
	s_or_saveexec_b64 s[10:11], s[10:11]
	v_and_b32_e32 v125, 0x1fdf, v122
	v_mov_b32_e32 v124, 6
	v_add_u32_e32 v123, 64, v125
	v_mov_b32_e32 v0, v130
	s_xor_b64 exec, exec, s[10:11]
	s_andn2_b64 s[0:1], s[4:5], exec
	s_and_b64 s[4:5], vcc, exec
	v_add_u32_e32 v0, 64, v125
	v_mul_i32_i24_e32 v124, 6, v147
	s_or_b64 s[4:5], s[0:1], s[4:5]
	s_or_b64 exec, exec, s[10:11]
	v_subrev_u32_e32 v122, s20, v122
	s_xor_b64 s[0:1], s[4:5], -1
	v_lshl_add_u32 v126, v122, 2, 0
	s_and_saveexec_b64 s[10:11], s[0:1]
	s_cbranch_execz .LBB0_1051
	v_add_u32_e32 v122, 0x20000, v126
	v_readlane_b32 s0, v254, 24
	ds_read_b32 v122, v122
	v_readlane_b32 s1, v254, 25
	v_add_u32_e32 v127, v124, v131
	s_waitcnt lgkmcnt(0)
	v_mul_f32_e32 v122, 0x3e16c740, v122
	v_mov_b64_e32 v[124:125], s[0:1]
	s_movk_i32 s0, 0x2040
	v_mad_i64_i32 v[128:129], s[0:1], v127, s0, v[0:1]
	v_mad_u64_u32 v[124:125], s[0:1], v128, s47, v[124:125]
	v_mad_i32_i24 v125, v129, s47, v125
	v_lshl_add_u64 v[124:125], v[134:135], 1, v[124:125]
	s_and_saveexec_b64 s[0:1], s[8:9]
	s_xor_b64 s[12:13], exec, s[0:1]
	s_cbranch_execz .LBB0_1049
	v_cmp_lt_u32_e64 s[4:5], 63, v0
	v_lshlrev_b32_e32 v0, 4, v0
	v_lshlrev_b32_e32 v128, 1, v137
	v_mov_b32_e32 v129, v1
	v_add_u32_e32 v127, 0xfffffd00, v0
	v_readlane_b32 s0, v253, 40
	v_lshl_add_u64 v[124:125], v[124:125], 0, v[128:129]
	v_cndmask_b32_e64 v128, v0, v127, s[4:5]
	v_readlane_b32 s1, v253, 41
	v_lshlrev_b32_e32 v138, 3, v137
	v_mov_b32_e32 v139, v1
	v_lshl_add_u64 v[128:129], v[128:129], 3, s[0:1]
	v_lshl_add_u64 v[128:129], v[128:129], 0, v[138:139]
	global_load_dwordx4 v[150:153], v[128:129], off offset:16
	global_load_dwordx4 v[158:161], v[128:129], off
	s_waitcnt vmcnt(0)
	v_mov_b32_e32 v129, v160
	v_mov_b32_e32 v160, v159
	v_mov_b32_e32 v128, v158
	v_pk_mul_f32 v[138:139], v[114:115], v[160:161]
	s_nop 0
	v_pk_fma_f32 v[138:139], v[118:119], v[128:129], v[138:139]
	v_pk_mul_f32 v[118:119], v[118:119], v[160:161]
	v_pk_mul_f32 v[138:139], v[122:123], v[138:139] op_sel_hi:[0,1]
	v_pk_fma_f32 v[114:115], v[114:115], v[128:129], v[118:119] neg_lo:[0,0,1] neg_hi:[0,0,1]
	v_mov_b32_e32 v119, v152
	v_mov_b32_e32 v152, v151
	v_mov_b32_e32 v118, v150
	v_pk_mul_f32 v[128:129], v[116:117], v[152:153]
	v_pk_mul_f32 v[114:115], v[122:123], v[114:115] op_sel_hi:[0,1]
	v_pk_fma_f32 v[128:129], v[120:121], v[118:119], v[128:129]
	v_pk_mul_f32 v[120:121], v[120:121], v[152:153]
	v_pk_mul_f32 v[128:129], v[122:123], v[128:129] op_sel_hi:[0,1]
	v_pk_fma_f32 v[116:117], v[116:117], v[118:119], v[120:121] neg_lo:[0,0,1] neg_hi:[0,0,1]
	v_cvt_pk_bf16_f32 v114, v114, v115
	v_pk_mul_f32 v[116:117], v[122:123], v[116:117] op_sel_hi:[0,1]
	v_cvt_pk_bf16_f32 v115, v116, v117
	global_store_dwordx2 v[124:125], v[114:115], off sc1
	v_cvt_pk_bf16_f32 v114, v138, v139
	v_cvt_pk_bf16_f32 v115, v128, v129
	global_store_dwordx2 v[124:125], v[114:115], off offset:32 sc1
.LBB0_1049:
	s_andn2_saveexec_b64 s[0:1], s[12:13]
	s_cbranch_execz .LBB0_1051
	v_lshlrev_b32_e32 v128, 1, v144
	v_mov_b32_e32 v129, v1
	v_pk_mul_f32 v[116:117], v[116:117], v[122:123] op_sel_hi:[1,0]
	v_pk_mul_f32 v[114:115], v[114:115], v[122:123] op_sel_hi:[1,0]
	v_pk_mul_f32 v[120:121], v[120:121], v[122:123] op_sel_hi:[1,0]
	v_pk_mul_f32 v[118:119], v[118:119], v[122:123] op_sel_hi:[1,0]
	v_lshl_add_u64 v[124:125], v[124:125], 0, v[128:129]
	v_cvt_pk_bf16_f32 v114, v114, v115
	v_cvt_pk_bf16_f32 v115, v116, v117
	v_cvt_pk_bf16_f32 v116, v118, v119
	v_cvt_pk_bf16_f32 v117, v120, v121
	global_store_dwordx4 v[124:125], v[114:117], off sc1
.LBB0_1051:
	s_or_b64 exec, exec, s[10:11]
	s_nop 0
	v_or_b32_e32 v114, 32, v149
	s_movk_i32 s0, 0x7fff
	v_cmp_lt_i32_e64 s[12:13], s0, v114
	s_and_saveexec_b64 s[0:1], s[12:13]
	s_xor_b64 s[10:11], exec, s[0:1]
	v_cmp_lt_u32_e64 s[4:5], s50, v145
	s_or_b64 s[4:5], s[4:5], vcc
	s_or_saveexec_b64 s[10:11], s[10:11]
	v_and_b32_e32 v117, 0x1fef, v114
	v_mov_b32_e32 v116, 12
	v_add_u32_e32 v115, 64, v117
	v_mov_b32_e32 v0, v130
	s_xor_b64 exec, exec, s[10:11]
	s_andn2_b64 s[0:1], s[4:5], exec
	s_and_b64 s[4:5], vcc, exec
	v_add_u32_e32 v0, 64, v117
	v_mul_i32_i24_e32 v116, 6, v147
	s_or_b64 s[4:5], s[0:1], s[4:5]
	s_or_b64 exec, exec, s[10:11]
	v_subrev_u32_e32 v114, s20, v114
	s_xor_b64 s[0:1], s[4:5], -1
	v_lshl_add_u32 v118, v114, 2, 0
	s_and_saveexec_b64 s[10:11], s[0:1]
	s_cbranch_execz .LBB0_1060
	v_add_u32_e32 v114, 0x20000, v118
	v_readlane_b32 s0, v254, 24
	ds_read_b32 v114, v114
	v_readlane_b32 s1, v254, 25
	v_add_u32_e32 v119, v116, v131
	s_waitcnt lgkmcnt(0)
	v_mul_f32_e32 v114, 0x3e16c740, v114
	v_mov_b64_e32 v[116:117], s[0:1]
	s_movk_i32 s0, 0x2040
	v_mad_i64_i32 v[120:121], s[0:1], v119, s0, v[0:1]
	v_mad_u64_u32 v[116:117], s[0:1], v120, s47, v[116:117]
	v_mad_i32_i24 v117, v121, s47, v117
	v_lshl_add_u64 v[116:117], v[134:135], 1, v[116:117]
	s_and_saveexec_b64 s[0:1], s[8:9]
	s_xor_b64 s[16:17], exec, s[0:1]
	s_cbranch_execz .LBB0_1058
	v_cmp_lt_u32_e64 s[4:5], 63, v0
	v_lshlrev_b32_e32 v0, 4, v0
	v_lshlrev_b32_e32 v120, 1, v137
	v_mov_b32_e32 v121, v1
	v_add_u32_e32 v119, 0xfffffd00, v0
	v_readlane_b32 s0, v253, 40
	v_lshl_add_u64 v[116:117], v[116:117], 0, v[120:121]
	v_cndmask_b32_e64 v120, v0, v119, s[4:5]
	v_readlane_b32 s1, v253, 41
	v_lshlrev_b32_e32 v124, 3, v137
	v_mov_b32_e32 v125, v1
	v_lshl_add_u64 v[120:121], v[120:121], 3, s[0:1]
	v_lshl_add_u64 v[120:121], v[120:121], 0, v[124:125]
	global_load_dwordx4 v[150:153], v[120:121], off offset:16
	global_load_dwordx4 v[158:161], v[120:121], off
	s_waitcnt vmcnt(0)
	v_mov_b32_e32 v121, v160
	v_mov_b32_e32 v160, v159
	v_mov_b32_e32 v120, v158
	v_pk_mul_f32 v[124:125], v[106:107], v[160:161]
	s_nop 0
	v_pk_fma_f32 v[124:125], v[110:111], v[120:121], v[124:125]
	v_pk_mul_f32 v[110:111], v[110:111], v[160:161]
	v_pk_mul_f32 v[124:125], v[114:115], v[124:125] op_sel_hi:[0,1]
	v_pk_fma_f32 v[106:107], v[106:107], v[120:121], v[110:111] neg_lo:[0,0,1] neg_hi:[0,0,1]
	v_mov_b32_e32 v111, v152
	v_mov_b32_e32 v152, v151
	v_mov_b32_e32 v110, v150
	v_pk_mul_f32 v[120:121], v[108:109], v[152:153]
	v_pk_mul_f32 v[106:107], v[114:115], v[106:107] op_sel_hi:[0,1]
	v_pk_fma_f32 v[120:121], v[112:113], v[110:111], v[120:121]
	v_pk_mul_f32 v[112:113], v[112:113], v[152:153]
	v_pk_mul_f32 v[120:121], v[114:115], v[120:121] op_sel_hi:[0,1]
	v_pk_fma_f32 v[108:109], v[108:109], v[110:111], v[112:113] neg_lo:[0,0,1] neg_hi:[0,0,1]
	v_cvt_pk_bf16_f32 v106, v106, v107
	v_pk_mul_f32 v[108:109], v[114:115], v[108:109] op_sel_hi:[0,1]
	v_cvt_pk_bf16_f32 v107, v108, v109
	global_store_dwordx2 v[116:117], v[106:107], off sc1
	v_cvt_pk_bf16_f32 v106, v124, v125
	v_cvt_pk_bf16_f32 v107, v120, v121
	global_store_dwordx2 v[116:117], v[106:107], off offset:32 sc1
; #define LAS __attribute__((address_space(3)))
; __device__ __forceinline__ void store4bf(bf16_t* p, f32x4 v) { u32x2 w; w.x = cvt_pk_bf16(v[0], v[1]); w.y = cvt_pk_bf16(v[2], v[3]); *(u32x2*)p = w; }
; __device__ __forceinline__ void store8bf(bf16_t* p, f32x4 v0, f32x4 v1) { u32x4 w; w.x = cvt_pk_bf16(v0[0], v0[1]); w.y = cvt_pk_bf16(v0[2], v0[3]); w.z = cvt_pk_bf16(v1[0], v1[1]); w.w = cvt_pk_bf16(v1[2], v1[3]); *(u32x4*)p = w; }
;   __device__ __forceinline__ void group(int row, int c32, int fq, f32x4 v0, f32x4 v1) const { e->group(row, c32 + sh, fq, v0, v1); }
;   __device__ __forceinline__ void group(int row, int c32, int fq, f32x4 v0, f32x4 v1) const {
;     int b, e; if (!row_be(row, b, e)) return;
;     const float rs = use_direct ? rs_direct : ((LAS const float*)(lds_raw + RS_OFF))[row - brow];
;     if (c32 < 768) {
;       if (c32 >= 576) return;
;       const int h = c32 / 96, part = (c32 - h * 96) >> 5; const float sc = rs * QSC_A;
;       bf16_t* p = qa + ((size_t)(b * 6 + h) * E + e) * 96 + part * 32 + fq * 4;
;       if (part < 2) store8bf(qa + ((size_t)(b * 6 + h) * E + e) * 96 + part * 32 + fq * 8, v0 * sc, v1 * sc);
;       else { const float2* rp = rope + pos_of_e(e) * 16 + fq * 4; f32x4 o0, o1;
; #pragma unroll
;         for (int j = 0; j < 4; ++j) { const float2 cs = rp[j]; o0[j] = (v0[j] * cs.x - v1[j] * cs.y) * sc; o1[j] = (v1[j] * cs.x + v0[j] * cs.y) * sc; }
;         store4bf(p, o0); store4bf(p + 16, o1); }
.LBB0_1058:
	s_andn2_saveexec_b64 s[0:1], s[16:17]
	s_cbranch_execz .LBB0_1060
	v_lshlrev_b32_e32 v120, 1, v144
	v_mov_b32_e32 v121, v1
	v_pk_mul_f32 v[108:109], v[108:109], v[114:115] op_sel_hi:[1,0]
	v_pk_mul_f32 v[106:107], v[106:107], v[114:115] op_sel_hi:[1,0]
	v_pk_mul_f32 v[112:113], v[112:113], v[114:115] op_sel_hi:[1,0]
	v_pk_mul_f32 v[110:111], v[110:111], v[114:115] op_sel_hi:[1,0]
	v_lshl_add_u64 v[116:117], v[116:117], 0, v[120:121]
	v_cvt_pk_bf16_f32 v106, v106, v107
	v_cvt_pk_bf16_f32 v107, v108, v109
	v_cvt_pk_bf16_f32 v108, v110, v111
	v_cvt_pk_bf16_f32 v109, v112, v113
	global_store_dwordx4 v[116:117], v[106:109], off sc1
.LBB0_1060:
	s_or_b64 exec, exec, s[10:11]
	s_nop 0
	v_or_b32_e32 v106, 48, v149
	s_movk_i32 s0, 0x7fff
	v_cmp_lt_i32_e64 s[10:11], s0, v106
	s_and_saveexec_b64 s[0:1], s[10:11]
	s_xor_b64 s[16:17], exec, s[0:1]
	v_cmp_lt_u32_e64 s[4:5], s50, v145
	s_or_b64 s[4:5], s[4:5], vcc
	s_or_saveexec_b64 s[16:17], s[16:17]
	v_and_b32_e32 v109, 0x1fff, v106
	v_mov_b32_e32 v108, 18
	v_add_u32_e32 v107, 64, v109
	v_mov_b32_e32 v0, v130
	s_xor_b64 exec, exec, s[16:17]
	s_andn2_b64 s[0:1], s[4:5], exec
	s_and_b64 s[4:5], vcc, exec
	v_add_u32_e32 v0, 64, v109
	v_mul_i32_i24_e32 v108, 6, v147
	s_or_b64 s[4:5], s[0:1], s[4:5]
	s_or_b64 exec, exec, s[16:17]
	v_subrev_u32_e32 v106, s20, v106
	s_xor_b64 s[0:1], s[4:5], -1
	v_lshl_add_u32 v110, v106, 2, 0
	s_and_saveexec_b64 s[16:17], s[0:1]
	s_cbranch_execz .LBB0_1069
	v_add_u32_e32 v106, 0x20000, v110
	v_readlane_b32 s0, v254, 24
	ds_read_b32 v106, v106
	v_readlane_b32 s1, v254, 25
	v_add_u32_e32 v111, v108, v131
	s_waitcnt lgkmcnt(0)
	v_mul_f32_e32 v106, 0x3e16c740, v106
	v_mov_b64_e32 v[108:109], s[0:1]
	s_movk_i32 s0, 0x2040
	v_mad_i64_i32 v[112:113], s[0:1], v111, s0, v[0:1]
	v_mad_u64_u32 v[108:109], s[0:1], v112, s47, v[108:109]
	v_mad_i32_i24 v109, v113, s47, v109
	v_lshl_add_u64 v[108:109], v[134:135], 1, v[108:109]
	s_and_saveexec_b64 s[0:1], s[8:9]
	s_xor_b64 s[18:19], exec, s[0:1]
	s_cbranch_execz .LBB0_1067
	v_cmp_lt_u32_e64 s[4:5], 63, v0
	v_lshlrev_b32_e32 v0, 4, v0
	v_lshlrev_b32_e32 v112, 1, v137
	v_mov_b32_e32 v113, v1
	v_add_u32_e32 v111, 0xfffffd00, v0
	v_readlane_b32 s0, v253, 40
	v_lshl_add_u64 v[108:109], v[108:109], 0, v[112:113]
	v_cndmask_b32_e64 v112, v0, v111, s[4:5]
	v_readlane_b32 s1, v253, 41
	v_lshlrev_b32_e32 v116, 3, v137
	v_mov_b32_e32 v117, v1
	v_lshl_add_u64 v[112:113], v[112:113], 3, s[0:1]
	v_lshl_add_u64 v[112:113], v[112:113], 0, v[116:117]
	global_load_dwordx4 v[150:153], v[112:113], off offset:16
	global_load_dwordx4 v[158:161], v[112:113], off
	s_waitcnt vmcnt(0)
	v_mov_b32_e32 v113, v160
	v_mov_b32_e32 v160, v159
	v_mov_b32_e32 v112, v158
	v_pk_mul_f32 v[116:117], v[98:99], v[160:161]
	s_nop 0
	v_pk_fma_f32 v[116:117], v[102:103], v[112:113], v[116:117]
	v_pk_mul_f32 v[102:103], v[102:103], v[160:161]
	v_pk_mul_f32 v[116:117], v[106:107], v[116:117] op_sel_hi:[0,1]
	v_pk_fma_f32 v[98:99], v[98:99], v[112:113], v[102:103] neg_lo:[0,0,1] neg_hi:[0,0,1]
	v_mov_b32_e32 v103, v152
	v_mov_b32_e32 v152, v151
	v_mov_b32_e32 v102, v150
	v_pk_mul_f32 v[112:113], v[100:101], v[152:153]
	v_pk_mul_f32 v[98:99], v[106:107], v[98:99] op_sel_hi:[0,1]
	v_pk_fma_f32 v[112:113], v[104:105], v[102:103], v[112:113]
	v_pk_mul_f32 v[104:105], v[104:105], v[152:153]
	v_pk_mul_f32 v[112:113], v[106:107], v[112:113] op_sel_hi:[0,1]
	v_pk_fma_f32 v[100:101], v[100:101], v[102:103], v[104:105] neg_lo:[0,0,1] neg_hi:[0,0,1]
	v_cvt_pk_bf16_f32 v98, v98, v99
	v_pk_mul_f32 v[100:101], v[106:107], v[100:101] op_sel_hi:[0,1]
	v_cvt_pk_bf16_f32 v99, v100, v101
	global_store_dwordx2 v[108:109], v[98:99], off sc1
	v_cvt_pk_bf16_f32 v98, v116, v117
	v_cvt_pk_bf16_f32 v99, v112, v113
	global_store_dwordx2 v[108:109], v[98:99], off offset:32 sc1
.LBB0_1067:
	s_andn2_saveexec_b64 s[0:1], s[18:19]
	s_cbranch_execz .LBB0_1069
	v_lshlrev_b32_e32 v112, 1, v144
	v_mov_b32_e32 v113, v1
	v_pk_mul_f32 v[100:101], v[100:101], v[106:107] op_sel_hi:[1,0]
	v_pk_mul_f32 v[98:99], v[98:99], v[106:107] op_sel_hi:[1,0]
	v_pk_mul_f32 v[104:105], v[104:105], v[106:107] op_sel_hi:[1,0]
	v_pk_mul_f32 v[102:103], v[102:103], v[106:107] op_sel_hi:[1,0]
	v_lshl_add_u64 v[108:109], v[108:109], 0, v[112:113]
	v_cvt_pk_bf16_f32 v98, v98, v99
	v_cvt_pk_bf16_f32 v99, v100, v101
	v_cvt_pk_bf16_f32 v100, v102, v103
	v_cvt_pk_bf16_f32 v101, v104, v105
	global_store_dwordx4 v[108:109], v[98:101], off sc1
; #define LAS __attribute__((address_space(3)))
; __device__ __forceinline__ void store4bf(bf16_t* p, f32x4 v) { u32x2 w; w.x = cvt_pk_bf16(v[0], v[1]); w.y = cvt_pk_bf16(v[2], v[3]); *(u32x2*)p = w; }
; __device__ __forceinline__ void store8bf(bf16_t* p, f32x4 v0, f32x4 v1) { u32x4 w; w.x = cvt_pk_bf16(v0[0], v0[1]); w.y = cvt_pk_bf16(v0[2], v0[3]); w.z = cvt_pk_bf16(v1[0], v1[1]); w.w = cvt_pk_bf16(v1[2], v1[3]); *(u32x4*)p = w; }
;   __device__ __forceinline__ void group(int row, int c32, int fq, f32x4 v0, f32x4 v1) const { e->group(row, c32 + sh, fq, v0, v1); }
;   __device__ __forceinline__ void group(int row, int c32, int fq, f32x4 v0, f32x4 v1) const {
;     int b, e; if (!row_be(row, b, e)) return;
;     const float rs = use_direct ? rs_direct : ((LAS const float*)(lds_raw + RS_OFF))[row - brow];
;     if (c32 < 768) {
;       if (c32 >= 576) return;
;       const int h = c32 / 96, part = (c32 - h * 96) >> 5; const float sc = rs * QSC_A;
;       bf16_t* p = qa + ((size_t)(b * 6 + h) * E + e) * 96 + part * 32 + fq * 4;
;       if (part < 2) store8bf(qa + ((size_t)(b * 6 + h) * E + e) * 96 + part * 32 + fq * 8, v0 * sc, v1 * sc);
;       else { const float2* rp = rope + pos_of_e(e) * 16 + fq * 4; f32x4 o0, o1;
; #pragma unroll
;         for (int j = 0; j < 4; ++j) { const float2 cs = rp[j]; o0[j] = (v0[j] * cs.x - v1[j] * cs.y) * sc; o1[j] = (v1[j] * cs.x + v0[j] * cs.y) * sc; }
;         store4bf(p, o0); store4bf(p + 16, o1); }
.LBB0_1069:
	s_or_b64 exec, exec, s[16:17]
	s_movk_i32 s0, 0x1bf
	v_cmp_lt_u32_e64 s[4:5], s0, v132
	s_and_saveexec_b64 s[0:1], s[6:7]
	s_xor_b64 s[18:19], exec, s[0:1]
	v_cmp_lt_u32_e64 s[6:7], s50, v145
	s_or_b64 s[16:17], s[6:7], s[4:5]
	s_or_saveexec_b64 s[6:7], s[18:19]
	v_mov_b32_e32 v100, 0
	v_mov_b32_e32 v0, v130
	s_xor_b64 exec, exec, s[6:7]
	s_andn2_b64 s[0:1], s[16:17], exec
	s_and_b64 s[16:17], s[4:5], exec
	v_mul_i32_i24_e32 v100, 6, v147
	s_or_b64 s[16:17], s[0:1], s[16:17]
	v_mov_b32_e32 v0, v133
	s_or_b64 exec, exec, s[6:7]
	v_or_b32_e32 v99, 0x80, v132
	v_mul_hi_u32 v98, v99, s55
	v_lshrrev_b32_e32 v101, 4, v98
	s_movk_i32 s6, 0xffa0
	v_mul_lo_u32 v98, v101, s6
	v_add_u32_e32 v99, v98, v99
	s_xor_b64 s[0:1], s[16:17], -1
	v_cmp_lt_i32_e64 s[6:7], 63, v99
	v_ashrrev_i32_e32 v99, 31, v98
	s_and_saveexec_b64 s[18:19], s[0:1]
	s_cbranch_execz .LBB0_1078
	v_add_u32_e32 v102, 0x20000, v148
	v_readlane_b32 s0, v254, 24
	ds_read_b32 v106, v102
	v_readlane_b32 s1, v254, 25
	v_add_u32_e32 v100, v100, v101
	v_mov_b32_e32 v133, v1
	v_mov_b64_e32 v[102:103], s[0:1]
	s_movk_i32 s0, 0x2040
	v_mad_i64_i32 v[104:105], s[0:1], v100, s0, v[0:1]
	v_mad_u64_u32 v[102:103], s[0:1], v104, s47, v[102:103]
	v_mad_i32_i24 v103, v105, s47, v103
	v_lshl_add_u64 v[104:105], v[98:99], 0, v[132:133]
	s_waitcnt lgkmcnt(0)
	v_mul_f32_e32 v100, 0x3e16c740, v106
	v_lshl_add_u64 v[102:103], v[104:105], 1, v[102:103]
	s_and_saveexec_b64 s[0:1], s[6:7]
	s_xor_b64 s[24:25], exec, s[0:1]
	s_cbranch_execz .LBB0_1076
	v_lshlrev_b32_e32 v104, 1, v137
	v_mov_b32_e32 v105, v1
	v_cmp_lt_u32_e64 s[16:17], 63, v0
	v_lshlrev_b32_e32 v0, 4, v0
	v_lshl_add_u64 v[108:109], v[102:103], 0, v[104:105]
	v_add_u32_e32 v102, 0xfffffd00, v0
	v_readlane_b32 s0, v253, 40
	v_cndmask_b32_e64 v102, v0, v102, s[16:17]
	v_mov_b32_e32 v103, v1
	v_readlane_b32 s1, v253, 41
	v_lshlrev_b32_e32 v104, 3, v137
	s_nop 0
	v_lshl_add_u64 v[102:103], v[102:103], 3, s[0:1]
	v_lshl_add_u64 v[112:113], v[102:103], 0, v[104:105]
	global_load_dwordx4 v[102:105], v[112:113], off offset:16
	global_load_dwordx4 v[148:151], v[112:113], off
	s_waitcnt vmcnt(0)
	v_mov_b32_e32 v113, v150
	v_mov_b32_e32 v150, v149
	v_mov_b32_e32 v112, v148
	v_pk_mul_f32 v[116:117], v[90:91], v[150:151]
	s_nop 0
	v_pk_fma_f32 v[116:117], v[94:95], v[112:113], v[116:117]
	v_pk_mul_f32 v[94:95], v[94:95], v[150:151]
	v_pk_mul_f32 v[116:117], v[100:101], v[116:117] op_sel_hi:[0,1]
	v_pk_fma_f32 v[90:91], v[90:91], v[112:113], v[94:95] neg_lo:[0,0,1] neg_hi:[0,0,1]
	v_mov_b32_e32 v95, v104
	v_mov_b32_e32 v104, v103
	v_mov_b32_e32 v94, v102
	v_pk_mul_f32 v[102:103], v[92:93], v[104:105]
	v_pk_mul_f32 v[90:91], v[100:101], v[90:91] op_sel_hi:[0,1]
	v_pk_fma_f32 v[102:103], v[96:97], v[94:95], v[102:103]
	v_pk_mul_f32 v[96:97], v[96:97], v[104:105]
	v_pk_mul_f32 v[102:103], v[100:101], v[102:103] op_sel_hi:[0,1]
	v_pk_fma_f32 v[92:93], v[92:93], v[94:95], v[96:97] neg_lo:[0,0,1] neg_hi:[0,0,1]
	v_cvt_pk_bf16_f32 v90, v90, v91
	v_pk_mul_f32 v[92:93], v[100:101], v[92:93] op_sel_hi:[0,1]
	v_cvt_pk_bf16_f32 v91, v92, v93
	global_store_dwordx2 v[108:109], v[90:91], off offset:256 sc1
	v_cvt_pk_bf16_f32 v90, v116, v117
	v_cvt_pk_bf16_f32 v91, v102, v103
	global_store_dwordx2 v[108:109], v[90:91], off offset:288 sc1
.LBB0_1076:
	s_andn2_saveexec_b64 s[0:1], s[24:25]
	s_cbranch_execz .LBB0_1078
	v_lshlrev_b32_e32 v104, 1, v144
	v_mov_b32_e32 v105, v1
	v_pk_mul_f32 v[92:93], v[92:93], v[100:101] op_sel_hi:[1,0]
	v_pk_mul_f32 v[90:91], v[90:91], v[100:101] op_sel_hi:[1,0]
	v_pk_mul_f32 v[96:97], v[96:97], v[100:101] op_sel_hi:[1,0]
	v_pk_mul_f32 v[94:95], v[94:95], v[100:101] op_sel_hi:[1,0]
	v_lshl_add_u64 v[102:103], v[102:103], 0, v[104:105]
	v_cvt_pk_bf16_f32 v90, v90, v91
	v_cvt_pk_bf16_f32 v91, v92, v93
	v_cvt_pk_bf16_f32 v92, v94, v95
	v_cvt_pk_bf16_f32 v93, v96, v97
	global_store_dwordx4 v[102:103], v[90:93], off offset:256 sc1
.LBB0_1078:
	s_or_b64 exec, exec, s[18:19]
	s_and_saveexec_b64 s[0:1], s[14:15]
	s_xor_b64 s[18:19], exec, s[0:1]
	v_cmp_lt_u32_e64 s[14:15], s50, v145
	s_or_b64 s[16:17], s[14:15], s[4:5]
	s_or_saveexec_b64 s[14:15], s[18:19]
	v_mov_b32_e32 v90, 6
	v_mov_b32_e32 v0, v130
	s_xor_b64 exec, exec, s[14:15]
	s_andn2_b64 s[0:1], s[16:17], exec
	s_and_b64 s[16:17], s[4:5], exec
	v_mul_i32_i24_e32 v90, 6, v147
	s_or_b64 s[16:17], s[0:1], s[16:17]
	v_mov_b32_e32 v0, v123
	s_or_b64 exec, exec, s[14:15]
	s_xor_b64 s[0:1], s[16:17], -1
	s_and_saveexec_b64 s[16:17], s[0:1]
	s_cbranch_execz .LBB0_1087
	v_add_u32_e32 v91, 0x20000, v126
	v_readlane_b32 s0, v254, 24
	ds_read_b32 v91, v91
	v_readlane_b32 s1, v254, 25
	v_add_u32_e32 v90, v90, v101
	v_mov_b32_e32 v133, v1
	v_mov_b64_e32 v[92:93], s[0:1]
	s_movk_i32 s0, 0x2040
	v_mad_i64_i32 v[94:95], s[0:1], v90, s0, v[0:1]
	v_mad_u64_u32 v[92:93], s[0:1], v94, s47, v[92:93]
	v_mad_i32_i24 v93, v95, s47, v93
	v_lshl_add_u64 v[94:95], v[98:99], 0, v[132:133]
	s_waitcnt lgkmcnt(0)
	v_mul_f32_e32 v90, 0x3e16c740, v91
	v_lshl_add_u64 v[92:93], v[94:95], 1, v[92:93]
	s_and_saveexec_b64 s[0:1], s[6:7]
	s_xor_b64 s[18:19], exec, s[0:1]
	s_cbranch_execz .LBB0_1085
	v_cmp_lt_u32_e64 s[14:15], 63, v0
	v_lshlrev_b32_e32 v0, 4, v0
	v_lshlrev_b32_e32 v94, 1, v137
	v_mov_b32_e32 v95, v1
	v_add_u32_e32 v91, 0xfffffd00, v0
	v_readlane_b32 s0, v253, 40
	v_lshl_add_u64 v[96:97], v[92:93], 0, v[94:95]
	v_cndmask_b32_e64 v92, v0, v91, s[14:15]
	v_mov_b32_e32 v93, v1
	v_readlane_b32 s1, v253, 41
	v_lshlrev_b32_e32 v94, 3, v137
	s_nop 0
	v_lshl_add_u64 v[92:93], v[92:93], 3, s[0:1]
	v_lshl_add_u64 v[102:103], v[92:93], 0, v[94:95]
	global_load_dwordx4 v[92:95], v[102:103], off offset:16
	s_nop 0
	global_load_dwordx4 v[102:105], v[102:103], off
	s_waitcnt vmcnt(0)
	v_mov_b32_e32 v109, v104
	v_mov_b32_e32 v104, v103
	v_mov_b32_e32 v108, v102
	v_pk_mul_f32 v[102:103], v[82:83], v[104:105]
	s_nop 0
	v_pk_fma_f32 v[102:103], v[86:87], v[108:109], v[102:103]
	v_pk_mul_f32 v[86:87], v[86:87], v[104:105]
	v_pk_mul_f32 v[102:103], v[90:91], v[102:103] op_sel_hi:[0,1]
	v_pk_fma_f32 v[82:83], v[82:83], v[108:109], v[86:87] neg_lo:[0,0,1] neg_hi:[0,0,1]
	v_mov_b32_e32 v87, v94
	v_mov_b32_e32 v94, v93
	v_mov_b32_e32 v86, v92
	v_pk_mul_f32 v[92:93], v[84:85], v[94:95]
	v_pk_mul_f32 v[82:83], v[90:91], v[82:83] op_sel_hi:[0,1]
	v_pk_fma_f32 v[92:93], v[88:89], v[86:87], v[92:93]
	v_pk_mul_f32 v[88:89], v[88:89], v[94:95]
	v_pk_mul_f32 v[92:93], v[90:91], v[92:93] op_sel_hi:[0,1]
	v_pk_fma_f32 v[84:85], v[84:85], v[86:87], v[88:89] neg_lo:[0,0,1] neg_hi:[0,0,1]
	v_cvt_pk_bf16_f32 v82, v82, v83
	v_pk_mul_f32 v[84:85], v[90:91], v[84:85] op_sel_hi:[0,1]
	v_cvt_pk_bf16_f32 v83, v84, v85
	global_store_dwordx2 v[96:97], v[82:83], off offset:256 sc1
	v_cvt_pk_bf16_f32 v82, v102, v103
	v_cvt_pk_bf16_f32 v83, v92, v93
	global_store_dwordx2 v[96:97], v[82:83], off offset:288 sc1
; #define LAS __attribute__((address_space(3)))
; __device__ __forceinline__ void store4bf(bf16_t* p, f32x4 v) { u32x2 w; w.x = cvt_pk_bf16(v[0], v[1]); w.y = cvt_pk_bf16(v[2], v[3]); *(u32x2*)p = w; }
; __device__ __forceinline__ void store8bf(bf16_t* p, f32x4 v0, f32x4 v1) { u32x4 w; w.x = cvt_pk_bf16(v0[0], v0[1]); w.y = cvt_pk_bf16(v0[2], v0[3]); w.z = cvt_pk_bf16(v1[0], v1[1]); w.w = cvt_pk_bf16(v1[2], v1[3]); *(u32x4*)p = w; }
;   __device__ __forceinline__ void group(int row, int c32, int fq, f32x4 v0, f32x4 v1) const { e->group(row, c32 + sh, fq, v0, v1); }
;   __device__ __forceinline__ void group(int row, int c32, int fq, f32x4 v0, f32x4 v1) const {
;     int b, e; if (!row_be(row, b, e)) return;
;     const float rs = use_direct ? rs_direct : ((LAS const float*)(lds_raw + RS_OFF))[row - brow];
;     if (c32 < 768) {
;       if (c32 >= 576) return;
;       const int h = c32 / 96, part = (c32 - h * 96) >> 5; const float sc = rs * QSC_A;
;       bf16_t* p = qa + ((size_t)(b * 6 + h) * E + e) * 96 + part * 32 + fq * 4;
;       if (part < 2) store8bf(qa + ((size_t)(b * 6 + h) * E + e) * 96 + part * 32 + fq * 8, v0 * sc, v1 * sc);
;       else { const float2* rp = rope + pos_of_e(e) * 16 + fq * 4; f32x4 o0, o1;
; #pragma unroll
;         for (int j = 0; j < 4; ++j) { const float2 cs = rp[j]; o0[j] = (v0[j] * cs.x - v1[j] * cs.y) * sc; o1[j] = (v1[j] * cs.x + v0[j] * cs.y) * sc; }
;         store4bf(p, o0); store4bf(p + 16, o1); }
.LBB0_1085:
	s_andn2_saveexec_b64 s[0:1], s[18:19]
	s_cbranch_execz .LBB0_1087
	v_lshlrev_b32_e32 v94, 1, v144
	v_mov_b32_e32 v95, v1
	v_pk_mul_f32 v[84:85], v[84:85], v[90:91] op_sel_hi:[1,0]
	v_pk_mul_f32 v[82:83], v[82:83], v[90:91] op_sel_hi:[1,0]
	v_pk_mul_f32 v[88:89], v[88:89], v[90:91] op_sel_hi:[1,0]
	v_pk_mul_f32 v[86:87], v[86:87], v[90:91] op_sel_hi:[1,0]
	v_lshl_add_u64 v[92:93], v[92:93], 0, v[94:95]
	v_cvt_pk_bf16_f32 v82, v82, v83
	v_cvt_pk_bf16_f32 v83, v84, v85
	v_cvt_pk_bf16_f32 v84, v86, v87
	v_cvt_pk_bf16_f32 v85, v88, v89
	global_store_dwordx4 v[92:93], v[82:85], off offset:256 sc1
.LBB0_1087:
	s_or_b64 exec, exec, s[16:17]
	s_and_saveexec_b64 s[0:1], s[12:13]
	s_xor_b64 s[16:17], exec, s[0:1]
	v_cmp_lt_u32_e64 s[12:13], s50, v145
	s_or_b64 s[14:15], s[12:13], s[4:5]
	s_or_saveexec_b64 s[12:13], s[16:17]
	v_mov_b32_e32 v82, 12
	v_mov_b32_e32 v0, v130
	s_xor_b64 exec, exec, s[12:13]
	s_andn2_b64 s[0:1], s[14:15], exec
	s_and_b64 s[14:15], s[4:5], exec
	v_mul_i32_i24_e32 v82, 6, v147
	s_or_b64 s[14:15], s[0:1], s[14:15]
	v_mov_b32_e32 v0, v115
	s_or_b64 exec, exec, s[12:13]
	s_xor_b64 s[0:1], s[14:15], -1
	s_and_saveexec_b64 s[14:15], s[0:1]
	s_cbranch_execz .LBB0_1096
	v_add_u32_e32 v83, 0x20000, v118
	v_readlane_b32 s0, v254, 24
	ds_read_b32 v83, v83
	v_readlane_b32 s1, v254, 25
	v_add_u32_e32 v82, v82, v101
	v_mov_b32_e32 v133, v1
	v_mov_b64_e32 v[84:85], s[0:1]
	s_movk_i32 s0, 0x2040
	v_mad_i64_i32 v[86:87], s[0:1], v82, s0, v[0:1]
	v_mad_u64_u32 v[84:85], s[0:1], v86, s47, v[84:85]
	v_mad_i32_i24 v85, v87, s47, v85
	v_lshl_add_u64 v[86:87], v[98:99], 0, v[132:133]
	s_waitcnt lgkmcnt(0)
	v_mul_f32_e32 v82, 0x3e16c740, v83
	v_lshl_add_u64 v[84:85], v[86:87], 1, v[84:85]
	s_and_saveexec_b64 s[0:1], s[6:7]
	s_xor_b64 s[16:17], exec, s[0:1]
	s_cbranch_execz .LBB0_1094
	v_cmp_lt_u32_e64 s[12:13], 63, v0
	v_lshlrev_b32_e32 v0, 4, v0
	v_lshlrev_b32_e32 v86, 1, v137
	v_mov_b32_e32 v87, v1
	v_add_u32_e32 v83, 0xfffffd00, v0
	v_readlane_b32 s0, v253, 40
	v_lshl_add_u64 v[92:93], v[84:85], 0, v[86:87]
	v_cndmask_b32_e64 v84, v0, v83, s[12:13]
	v_mov_b32_e32 v85, v1
	v_readlane_b32 s1, v253, 41
	v_lshlrev_b32_e32 v86, 3, v137
	s_nop 0
	v_lshl_add_u64 v[84:85], v[84:85], 3, s[0:1]
	v_lshl_add_u64 v[88:89], v[84:85], 0, v[86:87]
	global_load_dwordx4 v[84:87], v[88:89], off offset:16
	s_nop 0
	global_load_dwordx4 v[88:91], v[88:89], off
	s_waitcnt vmcnt(0)
	v_mov_b32_e32 v95, v90
	v_mov_b32_e32 v90, v89
	v_mov_b32_e32 v94, v88
	v_pk_mul_f32 v[88:89], v[74:75], v[90:91]
	s_nop 0
	v_pk_fma_f32 v[88:89], v[78:79], v[94:95], v[88:89]
	v_pk_mul_f32 v[78:79], v[78:79], v[90:91]
	v_pk_mul_f32 v[88:89], v[82:83], v[88:89] op_sel_hi:[0,1]
	v_pk_fma_f32 v[74:75], v[74:75], v[94:95], v[78:79] neg_lo:[0,0,1] neg_hi:[0,0,1]
	v_mov_b32_e32 v79, v86
	v_mov_b32_e32 v86, v85
	v_mov_b32_e32 v78, v84
	v_pk_mul_f32 v[84:85], v[76:77], v[86:87]
	v_pk_mul_f32 v[74:75], v[82:83], v[74:75] op_sel_hi:[0,1]
	v_pk_fma_f32 v[84:85], v[80:81], v[78:79], v[84:85]
	v_pk_mul_f32 v[80:81], v[80:81], v[86:87]
	v_pk_mul_f32 v[84:85], v[82:83], v[84:85] op_sel_hi:[0,1]
	v_pk_fma_f32 v[76:77], v[76:77], v[78:79], v[80:81] neg_lo:[0,0,1] neg_hi:[0,0,1]
	v_cvt_pk_bf16_f32 v74, v74, v75
	v_pk_mul_f32 v[76:77], v[82:83], v[76:77] op_sel_hi:[0,1]
	v_cvt_pk_bf16_f32 v75, v76, v77
	global_store_dwordx2 v[92:93], v[74:75], off offset:256 sc1
	v_cvt_pk_bf16_f32 v74, v88, v89
	v_cvt_pk_bf16_f32 v75, v84, v85
	global_store_dwordx2 v[92:93], v[74:75], off offset:288 sc1
.LBB0_1094:
	s_andn2_saveexec_b64 s[0:1], s[16:17]
	s_cbranch_execz .LBB0_1096
	v_lshlrev_b32_e32 v86, 1, v144
	v_mov_b32_e32 v87, v1
	v_pk_mul_f32 v[76:77], v[76:77], v[82:83] op_sel_hi:[1,0]
	v_pk_mul_f32 v[74:75], v[74:75], v[82:83] op_sel_hi:[1,0]
	v_pk_mul_f32 v[80:81], v[80:81], v[82:83] op_sel_hi:[1,0]
	v_pk_mul_f32 v[78:79], v[78:79], v[82:83] op_sel_hi:[1,0]
	v_lshl_add_u64 v[84:85], v[84:85], 0, v[86:87]
	v_cvt_pk_bf16_f32 v74, v74, v75
	v_cvt_pk_bf16_f32 v75, v76, v77
	v_cvt_pk_bf16_f32 v76, v78, v79
	v_cvt_pk_bf16_f32 v77, v80, v81
	global_store_dwordx4 v[84:85], v[74:77], off offset:256 sc1
.LBB0_1096:
	s_or_b64 exec, exec, s[14:15]
	s_and_saveexec_b64 s[0:1], s[10:11]
	s_xor_b64 s[14:15], exec, s[0:1]
	v_cmp_lt_u32_e64 s[10:11], s50, v145
	s_or_b64 s[12:13], s[10:11], s[4:5]
	s_or_saveexec_b64 s[10:11], s[14:15]
	v_mov_b32_e32 v74, 18
	v_mov_b32_e32 v0, v130
	s_xor_b64 exec, exec, s[10:11]
	s_andn2_b64 s[0:1], s[12:13], exec
	s_and_b64 s[12:13], s[4:5], exec
	s_or_b64 s[12:13], s[0:1], s[12:13]
	v_mov_b32_e32 v74, v146
	v_mov_b32_e32 v0, v107
	s_or_b64 exec, exec, s[10:11]
	s_xor_b64 s[0:1], s[12:13], -1
	s_and_saveexec_b64 s[12:13], s[0:1]
	s_cbranch_execz .LBB0_1105
	v_add_u32_e32 v75, 0x20000, v110
	v_readlane_b32 s0, v254, 24
	ds_read_b32 v75, v75
	v_readlane_b32 s1, v254, 25
	v_add_u32_e32 v74, v74, v101
	v_mov_b32_e32 v133, v1
	v_mov_b64_e32 v[76:77], s[0:1]
	s_movk_i32 s0, 0x2040
	v_mad_i64_i32 v[78:79], s[0:1], v74, s0, v[0:1]
	v_mad_u64_u32 v[76:77], s[0:1], v78, s47, v[76:77]
	v_mad_i32_i24 v77, v79, s47, v77
	v_lshl_add_u64 v[78:79], v[98:99], 0, v[132:133]
	s_waitcnt lgkmcnt(0)
	v_mul_f32_e32 v74, 0x3e16c740, v75
	v_lshl_add_u64 v[76:77], v[78:79], 1, v[76:77]
	s_and_saveexec_b64 s[0:1], s[6:7]
	s_xor_b64 s[14:15], exec, s[0:1]
	s_cbranch_execz .LBB0_1103
	v_cmp_lt_u32_e64 s[10:11], 63, v0
	v_lshlrev_b32_e32 v0, 4, v0
	v_lshlrev_b32_e32 v78, 1, v137
	v_mov_b32_e32 v79, v1
	v_add_u32_e32 v75, 0xfffffd00, v0
	v_readlane_b32 s0, v253, 40
	v_lshl_add_u64 v[84:85], v[76:77], 0, v[78:79]
	v_cndmask_b32_e64 v76, v0, v75, s[10:11]
	v_mov_b32_e32 v77, v1
	v_readlane_b32 s1, v253, 41
	v_lshlrev_b32_e32 v78, 3, v137
	s_nop 0
	v_lshl_add_u64 v[76:77], v[76:77], 3, s[0:1]
	v_lshl_add_u64 v[80:81], v[76:77], 0, v[78:79]
	global_load_dwordx4 v[76:79], v[80:81], off offset:16
	s_nop 0
	global_load_dwordx4 v[80:83], v[80:81], off
	s_waitcnt vmcnt(0)
	v_mov_b32_e32 v87, v82
	v_mov_b32_e32 v82, v81
	v_mov_b32_e32 v86, v80
	v_pk_mul_f32 v[80:81], v[66:67], v[82:83]
	s_nop 0
	v_pk_fma_f32 v[80:81], v[70:71], v[86:87], v[80:81]
	v_pk_mul_f32 v[70:71], v[70:71], v[82:83]
	v_pk_mul_f32 v[80:81], v[74:75], v[80:81] op_sel_hi:[0,1]
	v_pk_fma_f32 v[66:67], v[66:67], v[86:87], v[70:71] neg_lo:[0,0,1] neg_hi:[0,0,1]
	v_mov_b32_e32 v71, v78
	v_mov_b32_e32 v78, v77
	v_mov_b32_e32 v70, v76
	v_pk_mul_f32 v[76:77], v[68:69], v[78:79]
	v_pk_mul_f32 v[66:67], v[74:75], v[66:67] op_sel_hi:[0,1]
	v_pk_fma_f32 v[76:77], v[72:73], v[70:71], v[76:77]
	v_pk_mul_f32 v[72:73], v[72:73], v[78:79]
	v_pk_mul_f32 v[76:77], v[74:75], v[76:77] op_sel_hi:[0,1]
	v_pk_fma_f32 v[68:69], v[68:69], v[70:71], v[72:73] neg_lo:[0,0,1] neg_hi:[0,0,1]
	v_cvt_pk_bf16_f32 v66, v66, v67
	v_pk_mul_f32 v[68:69], v[74:75], v[68:69] op_sel_hi:[0,1]
	v_cvt_pk_bf16_f32 v67, v68, v69
	global_store_dwordx2 v[84:85], v[66:67], off offset:256 sc1
	v_cvt_pk_bf16_f32 v66, v80, v81
	v_cvt_pk_bf16_f32 v67, v76, v77
	global_store_dwordx2 v[84:85], v[66:67], off offset:288 sc1
; #define LAS __attribute__((address_space(3)))
; __device__ __forceinline__ void store4bf(bf16_t* p, f32x4 v) { u32x2 w; w.x = cvt_pk_bf16(v[0], v[1]); w.y = cvt_pk_bf16(v[2], v[3]); *(u32x2*)p = w; }
; __device__ __forceinline__ void store8bf(bf16_t* p, f32x4 v0, f32x4 v1) { u32x4 w; w.x = cvt_pk_bf16(v0[0], v0[1]); w.y = cvt_pk_bf16(v0[2], v0[3]); w.z = cvt_pk_bf16(v1[0], v1[1]); w.w = cvt_pk_bf16(v1[2], v1[3]); *(u32x4*)p = w; }
;   __device__ __forceinline__ void group(int row, int c32, int fq, f32x4 v0, f32x4 v1) const { e->group(row, c32 + sh, fq, v0, v1); }
;   __device__ __forceinline__ void group(int row, int c32, int fq, f32x4 v0, f32x4 v1) const {
;     int b, e; if (!row_be(row, b, e)) return;
;     const float rs = use_direct ? rs_direct : ((LAS const float*)(lds_raw + RS_OFF))[row - brow];
;     if (c32 < 768) {
;       if (c32 >= 576) return;
;       const int h = c32 / 96, part = (c32 - h * 96) >> 5; const float sc = rs * QSC_A;
;       bf16_t* p = qa + ((size_t)(b * 6 + h) * E + e) * 96 + part * 32 + fq * 4;
;       if (part < 2) store8bf(qa + ((size_t)(b * 6 + h) * E + e) * 96 + part * 32 + fq * 8, v0 * sc, v1 * sc);
;       else { const float2* rp = rope + pos_of_e(e) * 16 + fq * 4; f32x4 o0, o1;
; #pragma unroll
;         for (int j = 0; j < 4; ++j) { const float2 cs = rp[j]; o0[j] = (v0[j] * cs.x - v1[j] * cs.y) * sc; o1[j] = (v1[j] * cs.x + v0[j] * cs.y) * sc; }
;         store4bf(p, o0); store4bf(p + 16, o1); }
.LBB0_1103:
	s_andn2_saveexec_b64 s[0:1], s[14:15]
	s_cbranch_execz .LBB0_1105
	v_lshlrev_b32_e32 v78, 1, v144
	v_mov_b32_e32 v79, v1
	v_pk_mul_f32 v[68:69], v[68:69], v[74:75] op_sel_hi:[1,0]
	v_pk_mul_f32 v[66:67], v[66:67], v[74:75] op_sel_hi:[1,0]
	v_pk_mul_f32 v[72:73], v[72:73], v[74:75] op_sel_hi:[1,0]
	v_pk_mul_f32 v[70:71], v[70:71], v[74:75] op_sel_hi:[1,0]
	v_lshl_add_u64 v[76:77], v[76:77], 0, v[78:79]
	v_cvt_pk_bf16_f32 v66, v66, v67
	v_cvt_pk_bf16_f32 v67, v68, v69
	v_cvt_pk_bf16_f32 v68, v70, v71
	v_cvt_pk_bf16_f32 v69, v72, v73
	global_store_dwordx4 v[76:77], v[66:69], off offset:256 sc1
.LBB0_1105:
	s_or_b64 exec, exec, s[12:13]
	s_nop 0
	v_add_u32_e32 v67, 0x80, v145
	v_or_b32_e32 v73, v67, v130
	s_movk_i32 s0, 0x7fff
	v_cmp_lt_i32_e64 s[12:13], s0, v73
	s_and_saveexec_b64 s[0:1], s[12:13]
	s_xor_b64 s[14:15], exec, s[0:1]
	v_cmp_lt_u32_e64 s[10:11], s50, v67
	s_or_b64 s[10:11], s[10:11], vcc
	s_or_saveexec_b64 s[14:15], s[14:15]
	v_and_b32_e32 v68, 0x1fcf, v73
	v_mov_b32_e32 v66, 0
	v_ashrrev_i32_e32 v70, 13, v67
	v_add_u32_e32 v71, 64, v68
	v_mov_b32_e32 v0, v130
	s_xor_b64 exec, exec, s[14:15]
	v_ashrrev_i32_e32 v0, 13, v67
	v_add_u32_e32 v68, 64, v68
	s_andn2_b64 s[0:1], s[10:11], exec
	s_and_b64 s[10:11], vcc, exec
	v_mul_i32_i24_e32 v66, 6, v0
	s_or_b64 s[10:11], s[0:1], s[10:11]
	v_mov_b32_e32 v0, v68
	s_or_b64 exec, exec, s[14:15]
	v_subrev_u32_e32 v68, s20, v73
	s_xor_b64 s[0:1], s[10:11], -1
	v_lshl_add_u32 v72, v68, 2, 0
	s_and_saveexec_b64 s[14:15], s[0:1]
	s_cbranch_execz .LBB0_1114
	v_add_u32_e32 v68, 0x20000, v72
	v_readlane_b32 s0, v254, 24
	ds_read_b32 v76, v68
	v_readlane_b32 s1, v254, 25
	v_add_u32_e32 v66, v66, v131
	s_nop 0
	v_mov_b64_e32 v[68:69], s[0:1]
	s_movk_i32 s0, 0x2040
	v_mad_i64_i32 v[74:75], s[0:1], v66, s0, v[0:1]
	v_mad_u64_u32 v[68:69], s[0:1], v74, s47, v[68:69]
	v_mad_i32_i24 v69, v75, s47, v69
	s_waitcnt lgkmcnt(0)
	v_mul_f32_e32 v66, 0x3e16c740, v76
	v_lshl_add_u64 v[68:69], v[134:135], 1, v[68:69]
	s_and_saveexec_b64 s[0:1], s[8:9]
	s_xor_b64 s[16:17], exec, s[0:1]
	s_cbranch_execz .LBB0_1112
	v_lshlrev_b32_e32 v74, 1, v137
	v_mov_b32_e32 v75, v1
	v_cmp_lt_u32_e64 s[10:11], 63, v0
	v_lshlrev_b32_e32 v0, 4, v0
	v_lshl_add_u64 v[68:69], v[68:69], 0, v[74:75]
	v_add_u32_e32 v74, 0xfffffd00, v0
	v_readlane_b32 s0, v253, 40
	v_cndmask_b32_e64 v74, v0, v74, s[10:11]
	v_readlane_b32 s1, v253, 41
	v_lshlrev_b32_e32 v76, 3, v137
	v_mov_b32_e32 v77, v1
	v_lshl_add_u64 v[74:75], v[74:75], 3, s[0:1]
	v_lshl_add_u64 v[78:79], v[74:75], 0, v[76:77]
	global_load_dwordx4 v[74:77], v[78:79], off offset:16
	s_nop 0
	global_load_dwordx4 v[78:81], v[78:79], off
	s_waitcnt vmcnt(0)
	v_mov_b32_e32 v83, v80
	v_mov_b32_e32 v80, v79
	v_mov_b32_e32 v82, v78
	v_pk_mul_f32 v[78:79], v[58:59], v[80:81]
	s_nop 0
	v_pk_fma_f32 v[78:79], v[62:63], v[82:83], v[78:79]
	v_pk_mul_f32 v[62:63], v[62:63], v[80:81]
	v_pk_mul_f32 v[78:79], v[66:67], v[78:79] op_sel_hi:[0,1]
	v_pk_fma_f32 v[58:59], v[58:59], v[82:83], v[62:63] neg_lo:[0,0,1] neg_hi:[0,0,1]
	v_mov_b32_e32 v63, v76
	v_mov_b32_e32 v76, v75
	v_mov_b32_e32 v62, v74
	v_pk_mul_f32 v[74:75], v[60:61], v[76:77]
	v_pk_mul_f32 v[58:59], v[66:67], v[58:59] op_sel_hi:[0,1]
	v_pk_fma_f32 v[74:75], v[64:65], v[62:63], v[74:75]
	v_pk_mul_f32 v[64:65], v[64:65], v[76:77]
	v_pk_mul_f32 v[74:75], v[66:67], v[74:75] op_sel_hi:[0,1]
	v_pk_fma_f32 v[60:61], v[60:61], v[62:63], v[64:65] neg_lo:[0,0,1] neg_hi:[0,0,1]
	v_cvt_pk_bf16_f32 v58, v58, v59
	v_pk_mul_f32 v[60:61], v[66:67], v[60:61] op_sel_hi:[0,1]
	v_cvt_pk_bf16_f32 v59, v60, v61
	global_store_dwordx2 v[68:69], v[58:59], off sc1
	v_cvt_pk_bf16_f32 v58, v78, v79
	v_cvt_pk_bf16_f32 v59, v74, v75
	global_store_dwordx2 v[68:69], v[58:59], off offset:32 sc1
.LBB0_1112:
	s_andn2_saveexec_b64 s[0:1], s[16:17]
	s_cbranch_execz .LBB0_1114
	v_lshlrev_b32_e32 v74, 1, v144
	v_mov_b32_e32 v75, v1
	v_pk_mul_f32 v[60:61], v[60:61], v[66:67] op_sel_hi:[1,0]
	v_pk_mul_f32 v[58:59], v[58:59], v[66:67] op_sel_hi:[1,0]
	v_pk_mul_f32 v[64:65], v[64:65], v[66:67] op_sel_hi:[1,0]
	v_pk_mul_f32 v[62:63], v[62:63], v[66:67] op_sel_hi:[1,0]
	v_lshl_add_u64 v[68:69], v[68:69], 0, v[74:75]
	v_cvt_pk_bf16_f32 v58, v58, v59
	v_cvt_pk_bf16_f32 v59, v60, v61
	v_cvt_pk_bf16_f32 v60, v62, v63
	v_cvt_pk_bf16_f32 v61, v64, v65
	global_store_dwordx4 v[68:69], v[58:61], off sc1
; #define LAS __attribute__((address_space(3)))
; __device__ __forceinline__ void store4bf(bf16_t* p, f32x4 v) { u32x2 w; w.x = cvt_pk_bf16(v[0], v[1]); w.y = cvt_pk_bf16(v[2], v[3]); *(u32x2*)p = w; }
; __device__ __forceinline__ void store8bf(bf16_t* p, f32x4 v0, f32x4 v1) { u32x4 w; w.x = cvt_pk_bf16(v0[0], v0[1]); w.y = cvt_pk_bf16(v0[2], v0[3]); w.z = cvt_pk_bf16(v1[0], v1[1]); w.w = cvt_pk_bf16(v1[2], v1[3]); *(u32x4*)p = w; }
;   __device__ __forceinline__ void group(int row, int c32, int fq, f32x4 v0, f32x4 v1) const { e->group(row, c32 + sh, fq, v0, v1); }
;   __device__ __forceinline__ void group(int row, int c32, int fq, f32x4 v0, f32x4 v1) const {
;     int b, e; if (!row_be(row, b, e)) return;
;     const float rs = use_direct ? rs_direct : ((LAS const float*)(lds_raw + RS_OFF))[row - brow];
;     if (c32 < 768) {
;       if (c32 >= 576) return;
;       const int h = c32 / 96, part = (c32 - h * 96) >> 5; const float sc = rs * QSC_A;
;       bf16_t* p = qa + ((size_t)(b * 6 + h) * E + e) * 96 + part * 32 + fq * 4;
;       if (part < 2) store8bf(qa + ((size_t)(b * 6 + h) * E + e) * 96 + part * 32 + fq * 8, v0 * sc, v1 * sc);
;       else { const float2* rp = rope + pos_of_e(e) * 16 + fq * 4; f32x4 o0, o1;
; #pragma unroll
;         for (int j = 0; j < 4; ++j) { const float2 cs = rp[j]; o0[j] = (v0[j] * cs.x - v1[j] * cs.y) * sc; o1[j] = (v1[j] * cs.x + v0[j] * cs.y) * sc; }
;         store4bf(p, o0); store4bf(p + 16, o1); }
.LBB0_1114:
	s_or_b64 exec, exec, s[14:15]
	s_nop 0
	v_or_b32_e32 v60, 16, v73
	s_movk_i32 s0, 0x7fff
	v_cmp_lt_i32_e64 s[10:11], s0, v60
	v_bfe_u32 v59, v60, 4, 2
	s_and_saveexec_b64 s[0:1], s[10:11]
	s_xor_b64 s[16:17], exec, s[0:1]
	v_cmp_lt_u32_e64 s[14:15], s50, v67
	v_bfe_u32 v58, v60, 4, 2
	s_or_b64 s[14:15], s[14:15], vcc
	s_or_saveexec_b64 s[16:17], s[16:17]
	v_and_b32_e32 v61, 0x1fdf, v60
	v_add_u32_e32 v62, 64, v61
	v_mov_b32_e32 v0, v130
	s_xor_b64 exec, exec, s[16:17]
	s_andn2_b64 s[0:1], s[14:15], exec
	s_and_b64 s[14:15], vcc, exec
	v_ashrrev_i32_e32 v58, 13, v67
	v_add_u32_e32 v0, 64, v61
	s_or_b64 s[14:15], s[0:1], s[14:15]
	s_or_b64 exec, exec, s[16:17]
	v_subrev_u32_e32 v60, s20, v60
	s_xor_b64 s[0:1], s[14:15], -1
	v_lshl_add_u32 v63, v60, 2, 0
	s_and_saveexec_b64 s[16:17], s[0:1]
	s_cbranch_execz .LBB0_1123
	v_add_u32_e32 v60, 0x20000, v63
	v_readlane_b32 s0, v254, 24
	ds_read_b32 v66, v60
	v_readlane_b32 s1, v254, 25
	v_mad_i32_i24 v58, v58, 6, v131
	s_nop 0
	v_mov_b64_e32 v[60:61], s[0:1]
	s_movk_i32 s0, 0x2040
	v_mad_i64_i32 v[64:65], s[0:1], v58, s0, v[0:1]
	v_mad_u64_u32 v[60:61], s[0:1], v64, s47, v[60:61]
	v_mad_i32_i24 v61, v65, s47, v61
	s_waitcnt lgkmcnt(0)
	v_mul_f32_e32 v58, 0x3e16c740, v66
	v_lshl_add_u64 v[60:61], v[134:135], 1, v[60:61]
	s_and_saveexec_b64 s[0:1], s[8:9]
	s_xor_b64 s[18:19], exec, s[0:1]
	s_cbranch_execz .LBB0_1121
	v_lshlrev_b32_e32 v64, 1, v137
	v_mov_b32_e32 v65, v1
	v_cmp_lt_u32_e64 s[14:15], 63, v0
	v_lshlrev_b32_e32 v0, 4, v0
	v_lshl_add_u64 v[60:61], v[60:61], 0, v[64:65]
	v_add_u32_e32 v64, 0xfffffd00, v0
	v_readlane_b32 s0, v253, 40
	v_cndmask_b32_e64 v64, v0, v64, s[14:15]
	v_readlane_b32 s1, v253, 41
	v_lshlrev_b32_e32 v68, 3, v137
	v_mov_b32_e32 v69, v1
	v_lshl_add_u64 v[64:65], v[64:65], 3, s[0:1]
	v_lshl_add_u64 v[64:65], v[64:65], 0, v[68:69]
	global_load_dwordx4 v[74:77], v[64:65], off offset:16
	global_load_dwordx4 v[78:81], v[64:65], off
	s_waitcnt vmcnt(0)
	v_mov_b32_e32 v65, v80
	v_mov_b32_e32 v80, v79
	v_mov_b32_e32 v64, v78
	v_pk_mul_f32 v[68:69], v[50:51], v[80:81]
	s_nop 0
	v_pk_fma_f32 v[68:69], v[54:55], v[64:65], v[68:69]
	v_pk_mul_f32 v[54:55], v[54:55], v[80:81]
	v_pk_mul_f32 v[68:69], v[58:59], v[68:69] op_sel_hi:[0,1]
	v_pk_fma_f32 v[50:51], v[50:51], v[64:65], v[54:55] neg_lo:[0,0,1] neg_hi:[0,0,1]
	v_mov_b32_e32 v55, v76
	v_mov_b32_e32 v76, v75
	v_mov_b32_e32 v54, v74
	v_pk_mul_f32 v[64:65], v[52:53], v[76:77]
	v_pk_mul_f32 v[50:51], v[58:59], v[50:51] op_sel_hi:[0,1]
	v_pk_fma_f32 v[64:65], v[56:57], v[54:55], v[64:65]
	v_pk_mul_f32 v[56:57], v[56:57], v[76:77]
	v_pk_mul_f32 v[64:65], v[58:59], v[64:65] op_sel_hi:[0,1]
	v_pk_fma_f32 v[52:53], v[52:53], v[54:55], v[56:57] neg_lo:[0,0,1] neg_hi:[0,0,1]
	v_cvt_pk_bf16_f32 v50, v50, v51
	v_pk_mul_f32 v[52:53], v[58:59], v[52:53] op_sel_hi:[0,1]
	v_cvt_pk_bf16_f32 v51, v52, v53
	global_store_dwordx2 v[60:61], v[50:51], off sc1
	v_cvt_pk_bf16_f32 v50, v68, v69
	v_cvt_pk_bf16_f32 v51, v64, v65
	global_store_dwordx2 v[60:61], v[50:51], off offset:32 sc1
.LBB0_1121:
	s_andn2_saveexec_b64 s[0:1], s[18:19]
	s_cbranch_execz .LBB0_1123
	v_lshlrev_b32_e32 v64, 1, v144
	v_mov_b32_e32 v65, v1
	v_pk_mul_f32 v[52:53], v[52:53], v[58:59] op_sel_hi:[1,0]
	v_pk_mul_f32 v[50:51], v[50:51], v[58:59] op_sel_hi:[1,0]
	v_pk_mul_f32 v[56:57], v[56:57], v[58:59] op_sel_hi:[1,0]
	v_pk_mul_f32 v[54:55], v[54:55], v[58:59] op_sel_hi:[1,0]
	v_lshl_add_u64 v[60:61], v[60:61], 0, v[64:65]
	v_cvt_pk_bf16_f32 v50, v50, v51
	v_cvt_pk_bf16_f32 v51, v52, v53
	v_cvt_pk_bf16_f32 v52, v54, v55
	v_cvt_pk_bf16_f32 v53, v56, v57
	global_store_dwordx4 v[60:61], v[50:53], off sc1
.LBB0_1123:
	s_or_b64 exec, exec, s[16:17]
	s_nop 0
	v_or_b32_e32 v52, 32, v73
	s_movk_i32 s0, 0x7fff
	v_cmp_lt_i32_e64 s[14:15], s0, v52
	v_bfe_u32 v51, v52, 4, 2
	s_and_saveexec_b64 s[0:1], s[14:15]
	s_xor_b64 s[18:19], exec, s[0:1]
	v_cmp_lt_u32_e64 s[16:17], s50, v67
	v_bfe_u32 v50, v52, 4, 2
	s_or_b64 s[16:17], s[16:17], vcc
	s_or_saveexec_b64 s[18:19], s[18:19]
	v_and_b32_e32 v53, 0x1fef, v52
	v_add_u32_e32 v54, 64, v53
	v_mov_b32_e32 v0, v130
	s_xor_b64 exec, exec, s[18:19]
	s_andn2_b64 s[0:1], s[16:17], exec
	s_and_b64 s[16:17], vcc, exec
	v_ashrrev_i32_e32 v50, 13, v67
	v_add_u32_e32 v0, 64, v53
	s_or_b64 s[16:17], s[0:1], s[16:17]
	s_or_b64 exec, exec, s[18:19]
	v_subrev_u32_e32 v52, s20, v52
	s_xor_b64 s[0:1], s[16:17], -1
	v_lshl_add_u32 v55, v52, 2, 0
	s_and_saveexec_b64 s[18:19], s[0:1]
	s_cbranch_execz .LBB0_1132
	v_add_u32_e32 v52, 0x20000, v55
	v_readlane_b32 s0, v254, 24
	ds_read_b32 v58, v52
	v_readlane_b32 s1, v254, 25
	v_mad_i32_i24 v50, v50, 6, v131
	s_nop 0
	v_mov_b64_e32 v[52:53], s[0:1]
	s_movk_i32 s0, 0x2040
	v_mad_i64_i32 v[56:57], s[0:1], v50, s0, v[0:1]
	v_mad_u64_u32 v[52:53], s[0:1], v56, s47, v[52:53]
	v_mad_i32_i24 v53, v57, s47, v53
	s_waitcnt lgkmcnt(0)
	v_mul_f32_e32 v50, 0x3e16c740, v58
	v_lshl_add_u64 v[52:53], v[134:135], 1, v[52:53]
	s_and_saveexec_b64 s[0:1], s[8:9]
	s_xor_b64 s[24:25], exec, s[0:1]
	s_cbranch_execz .LBB0_1130
	v_lshlrev_b32_e32 v56, 1, v137
	v_mov_b32_e32 v57, v1
	v_cmp_lt_u32_e64 s[16:17], 63, v0
	v_lshlrev_b32_e32 v0, 4, v0
	v_lshl_add_u64 v[52:53], v[52:53], 0, v[56:57]
	v_add_u32_e32 v56, 0xfffffd00, v0
	v_readlane_b32 s0, v253, 40
	v_cndmask_b32_e64 v56, v0, v56, s[16:17]
	v_readlane_b32 s1, v253, 41
	v_lshlrev_b32_e32 v60, 3, v137
	v_mov_b32_e32 v61, v1
	v_lshl_add_u64 v[56:57], v[56:57], 3, s[0:1]
	v_lshl_add_u64 v[56:57], v[56:57], 0, v[60:61]
	global_load_dwordx4 v[74:77], v[56:57], off offset:16
	global_load_dwordx4 v[78:81], v[56:57], off
	s_waitcnt vmcnt(0)
	v_mov_b32_e32 v57, v80
	v_mov_b32_e32 v80, v79
	v_mov_b32_e32 v56, v78
	v_pk_mul_f32 v[60:61], v[42:43], v[80:81]
	s_nop 0
	v_pk_fma_f32 v[60:61], v[46:47], v[56:57], v[60:61]
	v_pk_mul_f32 v[46:47], v[46:47], v[80:81]
	v_pk_mul_f32 v[60:61], v[50:51], v[60:61] op_sel_hi:[0,1]
	v_pk_fma_f32 v[42:43], v[42:43], v[56:57], v[46:47] neg_lo:[0,0,1] neg_hi:[0,0,1]
	v_mov_b32_e32 v47, v76
	v_mov_b32_e32 v76, v75
	v_mov_b32_e32 v46, v74
	v_pk_mul_f32 v[56:57], v[44:45], v[76:77]
	v_pk_mul_f32 v[42:43], v[50:51], v[42:43] op_sel_hi:[0,1]
	v_pk_fma_f32 v[56:57], v[48:49], v[46:47], v[56:57]
	v_pk_mul_f32 v[48:49], v[48:49], v[76:77]
	v_pk_mul_f32 v[56:57], v[50:51], v[56:57] op_sel_hi:[0,1]
	v_pk_fma_f32 v[44:45], v[44:45], v[46:47], v[48:49] neg_lo:[0,0,1] neg_hi:[0,0,1]
	v_cvt_pk_bf16_f32 v42, v42, v43
	v_pk_mul_f32 v[44:45], v[50:51], v[44:45] op_sel_hi:[0,1]
	v_cvt_pk_bf16_f32 v43, v44, v45
	global_store_dwordx2 v[52:53], v[42:43], off sc1
	v_cvt_pk_bf16_f32 v42, v60, v61
	v_cvt_pk_bf16_f32 v43, v56, v57
	global_store_dwordx2 v[52:53], v[42:43], off offset:32 sc1
; #define LAS __attribute__((address_space(3)))
; __device__ __forceinline__ void store4bf(bf16_t* p, f32x4 v) { u32x2 w; w.x = cvt_pk_bf16(v[0], v[1]); w.y = cvt_pk_bf16(v[2], v[3]); *(u32x2*)p = w; }
; __device__ __forceinline__ void store8bf(bf16_t* p, f32x4 v0, f32x4 v1) { u32x4 w; w.x = cvt_pk_bf16(v0[0], v0[1]); w.y = cvt_pk_bf16(v0[2], v0[3]); w.z = cvt_pk_bf16(v1[0], v1[1]); w.w = cvt_pk_bf16(v1[2], v1[3]); *(u32x4*)p = w; }
;   __device__ __forceinline__ void group(int row, int c32, int fq, f32x4 v0, f32x4 v1) const { e->group(row, c32 + sh, fq, v0, v1); }
;   __device__ __forceinline__ void group(int row, int c32, int fq, f32x4 v0, f32x4 v1) const {
;     int b, e; if (!row_be(row, b, e)) return;
;     const float rs = use_direct ? rs_direct : ((LAS const float*)(lds_raw + RS_OFF))[row - brow];
;     if (c32 < 768) {
;       if (c32 >= 576) return;
;       const int h = c32 / 96, part = (c32 - h * 96) >> 5; const float sc = rs * QSC_A;
;       bf16_t* p = qa + ((size_t)(b * 6 + h) * E + e) * 96 + part * 32 + fq * 4;
;       if (part < 2) store8bf(qa + ((size_t)(b * 6 + h) * E + e) * 96 + part * 32 + fq * 8, v0 * sc, v1 * sc);
;       else { const float2* rp = rope + pos_of_e(e) * 16 + fq * 4; f32x4 o0, o1;
; #pragma unroll
;         for (int j = 0; j < 4; ++j) { const float2 cs = rp[j]; o0[j] = (v0[j] * cs.x - v1[j] * cs.y) * sc; o1[j] = (v1[j] * cs.x + v0[j] * cs.y) * sc; }
;         store4bf(p, o0); store4bf(p + 16, o1); }
.LBB0_1130:
	s_andn2_saveexec_b64 s[0:1], s[24:25]
	s_cbranch_execz .LBB0_1132
	v_lshlrev_b32_e32 v56, 1, v144
	v_mov_b32_e32 v57, v1
	v_pk_mul_f32 v[44:45], v[44:45], v[50:51] op_sel_hi:[1,0]
	v_pk_mul_f32 v[42:43], v[42:43], v[50:51] op_sel_hi:[1,0]
	v_pk_mul_f32 v[48:49], v[48:49], v[50:51] op_sel_hi:[1,0]
	v_pk_mul_f32 v[46:47], v[46:47], v[50:51] op_sel_hi:[1,0]
	v_lshl_add_u64 v[52:53], v[52:53], 0, v[56:57]
	v_cvt_pk_bf16_f32 v42, v42, v43
	v_cvt_pk_bf16_f32 v43, v44, v45
	v_cvt_pk_bf16_f32 v44, v46, v47
	v_cvt_pk_bf16_f32 v45, v48, v49
	global_store_dwordx4 v[52:53], v[42:45], off sc1
.LBB0_1132:
	s_or_b64 exec, exec, s[18:19]
	s_nop 0
	v_or_b32_e32 v42, 48, v73
	s_movk_i32 s0, 0x7fff
	v_cmp_lt_i32_e64 s[16:17], s0, v42
	s_and_saveexec_b64 s[0:1], s[16:17]
	s_xor_b64 s[24:25], exec, s[0:1]
	v_cmp_lt_u32_e64 s[18:19], s50, v67
	s_or_b64 s[18:19], s[18:19], vcc
	s_or_saveexec_b64 s[24:25], s[24:25]
	v_and_b32_e32 v45, 0x1fff, v42
	v_mov_b32_e32 v44, 18
	v_add_u32_e32 v43, 64, v45
	v_mov_b32_e32 v0, v130
	s_xor_b64 exec, exec, s[24:25]
	v_ashrrev_i32_e32 v0, 13, v67
	v_add_u32_e32 v45, 64, v45
	s_andn2_b64 s[0:1], s[18:19], exec
	s_and_b64 s[18:19], vcc, exec
	v_mul_i32_i24_e32 v44, 6, v0
	s_or_b64 s[18:19], s[0:1], s[18:19]
	v_mov_b32_e32 v0, v45
	s_or_b64 exec, exec, s[24:25]
	v_subrev_u32_e32 v42, s20, v42
	s_xor_b64 s[0:1], s[18:19], -1
	v_lshl_add_u32 v46, v42, 2, 0
	s_and_saveexec_b64 s[18:19], s[0:1]
	s_cbranch_execz .LBB0_1141
	v_add_u32_e32 v42, 0x20000, v46
	v_readlane_b32 s0, v254, 24
	ds_read_b32 v42, v42
	v_readlane_b32 s1, v254, 25
	v_add_u32_e32 v47, v44, v131
	s_waitcnt lgkmcnt(0)
	v_mul_f32_e32 v42, 0x3e16c740, v42
	v_mov_b64_e32 v[44:45], s[0:1]
	s_movk_i32 s0, 0x2040
	v_mad_i64_i32 v[48:49], s[0:1], v47, s0, v[0:1]
	v_mad_u64_u32 v[44:45], s[0:1], v48, s47, v[44:45]
	v_mad_i32_i24 v45, v49, s47, v45
	v_lshl_add_u64 v[44:45], v[134:135], 1, v[44:45]
	s_and_saveexec_b64 s[0:1], s[8:9]
	s_xor_b64 s[8:9], exec, s[0:1]
	s_cbranch_execz .LBB0_1139
	v_cmp_lt_u32_e32 vcc, 63, v0
	v_lshlrev_b32_e32 v0, 4, v0
	v_lshlrev_b32_e32 v48, 1, v137
	v_mov_b32_e32 v49, v1
	v_add_u32_e32 v47, 0xfffffd00, v0
	v_readlane_b32 s0, v253, 40
	v_lshl_add_u64 v[44:45], v[44:45], 0, v[48:49]
	v_cndmask_b32_e32 v48, v0, v47, vcc
	v_readlane_b32 s1, v253, 41
	v_lshlrev_b32_e32 v52, 3, v137
	v_mov_b32_e32 v53, v1
	v_lshl_add_u64 v[48:49], v[48:49], 3, s[0:1]
	v_lshl_add_u64 v[48:49], v[48:49], 0, v[52:53]
	global_load_dwordx4 v[74:77], v[48:49], off offset:16
	global_load_dwordx4 v[78:81], v[48:49], off
	s_waitcnt vmcnt(0)
	v_mov_b32_e32 v49, v80
	v_mov_b32_e32 v80, v79
	v_mov_b32_e32 v48, v78
	v_pk_mul_f32 v[52:53], v[34:35], v[80:81]
	s_nop 0
	v_pk_fma_f32 v[52:53], v[38:39], v[48:49], v[52:53]
	v_pk_mul_f32 v[38:39], v[38:39], v[80:81]
	v_pk_mul_f32 v[52:53], v[42:43], v[52:53] op_sel_hi:[0,1]
	v_pk_fma_f32 v[34:35], v[34:35], v[48:49], v[38:39] neg_lo:[0,0,1] neg_hi:[0,0,1]
	v_mov_b32_e32 v39, v76
	v_mov_b32_e32 v76, v75
	v_mov_b32_e32 v38, v74
	v_pk_mul_f32 v[48:49], v[36:37], v[76:77]
	v_pk_mul_f32 v[34:35], v[42:43], v[34:35] op_sel_hi:[0,1]
	v_pk_fma_f32 v[48:49], v[40:41], v[38:39], v[48:49]
	v_pk_mul_f32 v[40:41], v[40:41], v[76:77]
	v_pk_mul_f32 v[48:49], v[42:43], v[48:49] op_sel_hi:[0,1]
	v_pk_fma_f32 v[36:37], v[36:37], v[38:39], v[40:41] neg_lo:[0,0,1] neg_hi:[0,0,1]
	v_cvt_pk_bf16_f32 v34, v34, v35
	v_pk_mul_f32 v[36:37], v[42:43], v[36:37] op_sel_hi:[0,1]
	v_cvt_pk_bf16_f32 v35, v36, v37
	global_store_dwordx2 v[44:45], v[34:35], off sc1
	v_cvt_pk_bf16_f32 v34, v52, v53
	v_cvt_pk_bf16_f32 v35, v48, v49
	global_store_dwordx2 v[44:45], v[34:35], off offset:32 sc1
; #define LAS __attribute__((address_space(3)))
; __device__ __forceinline__ void store4bf(bf16_t* p, f32x4 v) { u32x2 w; w.x = cvt_pk_bf16(v[0], v[1]); w.y = cvt_pk_bf16(v[2], v[3]); *(u32x2*)p = w; }
; __device__ __forceinline__ void store8bf(bf16_t* p, f32x4 v0, f32x4 v1) { u32x4 w; w.x = cvt_pk_bf16(v0[0], v0[1]); w.y = cvt_pk_bf16(v0[2], v0[3]); w.z = cvt_pk_bf16(v1[0], v1[1]); w.w = cvt_pk_bf16(v1[2], v1[3]); *(u32x4*)p = w; }
;   __device__ __forceinline__ void group(int row, int c32, int fq, f32x4 v0, f32x4 v1) const { e->group(row, c32 + sh, fq, v0, v1); }
;   __device__ __forceinline__ void group(int row, int c32, int fq, f32x4 v0, f32x4 v1) const {
;     int b, e; if (!row_be(row, b, e)) return;
;     const float rs = use_direct ? rs_direct : ((LAS const float*)(lds_raw + RS_OFF))[row - brow];
;     if (c32 < 768) {
;       if (c32 >= 576) return;
;       const int h = c32 / 96, part = (c32 - h * 96) >> 5; const float sc = rs * QSC_A;
;       bf16_t* p = qa + ((size_t)(b * 6 + h) * E + e) * 96 + part * 32 + fq * 4;
;       if (part < 2) store8bf(qa + ((size_t)(b * 6 + h) * E + e) * 96 + part * 32 + fq * 8, v0 * sc, v1 * sc);
;       else { const float2* rp = rope + pos_of_e(e) * 16 + fq * 4; f32x4 o0, o1;
; #pragma unroll
;         for (int j = 0; j < 4; ++j) { const float2 cs = rp[j]; o0[j] = (v0[j] * cs.x - v1[j] * cs.y) * sc; o1[j] = (v1[j] * cs.x + v0[j] * cs.y) * sc; }
;         store4bf(p, o0); store4bf(p + 16, o1); }
.LBB0_1139:
	s_andn2_saveexec_b64 s[0:1], s[8:9]
	s_cbranch_execz .LBB0_1141
	v_lshlrev_b32_e32 v48, 1, v144
	v_mov_b32_e32 v49, v1
	v_pk_mul_f32 v[36:37], v[36:37], v[42:43] op_sel_hi:[1,0]
	v_pk_mul_f32 v[34:35], v[34:35], v[42:43] op_sel_hi:[1,0]
	v_pk_mul_f32 v[40:41], v[40:41], v[42:43] op_sel_hi:[1,0]
	v_pk_mul_f32 v[38:39], v[38:39], v[42:43] op_sel_hi:[1,0]
	v_lshl_add_u64 v[44:45], v[44:45], 0, v[48:49]
	v_cvt_pk_bf16_f32 v34, v34, v35
	v_cvt_pk_bf16_f32 v35, v36, v37
	v_cvt_pk_bf16_f32 v36, v38, v39
	v_cvt_pk_bf16_f32 v37, v40, v41
	global_store_dwordx4 v[44:45], v[34:37], off sc1
.LBB0_1141:
	s_or_b64 exec, exec, s[18:19]
	s_and_saveexec_b64 s[0:1], s[12:13]
	s_xor_b64 s[12:13], exec, s[0:1]
	v_cmp_lt_u32_e32 vcc, s50, v67
	s_or_b64 s[8:9], vcc, s[4:5]
	s_or_saveexec_b64 s[12:13], s[12:13]
	v_mov_b32_e32 v34, 0
	v_mov_b32_e32 v0, v130
	s_xor_b64 exec, exec, s[12:13]
	v_ashrrev_i32_e32 v0, 13, v67
	s_andn2_b64 s[0:1], s[8:9], exec
	s_and_b64 s[8:9], s[4:5], exec
	v_mul_i32_i24_e32 v34, 6, v0
	s_or_b64 s[8:9], s[0:1], s[8:9]
	v_mov_b32_e32 v0, v71
	s_or_b64 exec, exec, s[12:13]
	s_xor_b64 s[0:1], s[8:9], -1
	s_and_saveexec_b64 s[8:9], s[0:1]
	s_cbranch_execz .LBB0_1150
	v_add_u32_e32 v35, 0x20000, v72
	v_readlane_b32 s0, v254, 24
	ds_read_b32 v35, v35
	v_readlane_b32 s1, v254, 25
	v_add_u32_e32 v34, v34, v101
	v_mov_b32_e32 v133, v1
	v_mov_b64_e32 v[36:37], s[0:1]
	s_movk_i32 s0, 0x2040
	v_mad_i64_i32 v[38:39], s[0:1], v34, s0, v[0:1]
	v_mad_u64_u32 v[36:37], s[0:1], v38, s47, v[36:37]
	v_mad_i32_i24 v37, v39, s47, v37
	v_lshl_add_u64 v[38:39], v[98:99], 0, v[132:133]
	s_waitcnt lgkmcnt(0)
	v_mul_f32_e32 v34, 0x3e16c740, v35
	v_lshl_add_u64 v[36:37], v[38:39], 1, v[36:37]
	s_and_saveexec_b64 s[0:1], s[6:7]
	s_xor_b64 s[12:13], exec, s[0:1]
	s_cbranch_execz .LBB0_1148
	v_cmp_lt_u32_e32 vcc, 63, v0
	v_lshlrev_b32_e32 v0, 4, v0
	v_lshlrev_b32_e32 v38, 1, v137
	v_mov_b32_e32 v39, v1
	v_add_u32_e32 v35, 0xfffffd00, v0
	v_readlane_b32 s0, v253, 40
	v_lshl_add_u64 v[40:41], v[36:37], 0, v[38:39]
	v_cndmask_b32_e32 v36, v0, v35, vcc
	v_mov_b32_e32 v37, v1
	v_readlane_b32 s1, v253, 41
	v_lshlrev_b32_e32 v38, 3, v137
	s_nop 0
	v_lshl_add_u64 v[36:37], v[36:37], 3, s[0:1]
	v_lshl_add_u64 v[44:45], v[36:37], 0, v[38:39]
	global_load_dwordx4 v[36:39], v[44:45], off offset:16
	global_load_dwordx4 v[72:75], v[44:45], off
	s_waitcnt vmcnt(0)
	v_mov_b32_e32 v45, v74
	v_mov_b32_e32 v74, v73
	v_mov_b32_e32 v44, v72
	v_pk_mul_f32 v[48:49], v[26:27], v[74:75]
	s_nop 0
	v_pk_fma_f32 v[48:49], v[30:31], v[44:45], v[48:49]
	v_pk_mul_f32 v[30:31], v[30:31], v[74:75]
	v_pk_mul_f32 v[48:49], v[34:35], v[48:49] op_sel_hi:[0,1]
	v_pk_fma_f32 v[26:27], v[26:27], v[44:45], v[30:31] neg_lo:[0,0,1] neg_hi:[0,0,1]
	v_mov_b32_e32 v31, v38
	v_mov_b32_e32 v38, v37
	v_mov_b32_e32 v30, v36
	v_pk_mul_f32 v[36:37], v[28:29], v[38:39]
	v_pk_mul_f32 v[26:27], v[34:35], v[26:27] op_sel_hi:[0,1]
	v_pk_fma_f32 v[36:37], v[32:33], v[30:31], v[36:37]
	v_pk_mul_f32 v[32:33], v[32:33], v[38:39]
	v_pk_mul_f32 v[36:37], v[34:35], v[36:37] op_sel_hi:[0,1]
	v_pk_fma_f32 v[28:29], v[28:29], v[30:31], v[32:33] neg_lo:[0,0,1] neg_hi:[0,0,1]
	v_cvt_pk_bf16_f32 v26, v26, v27
	v_pk_mul_f32 v[28:29], v[34:35], v[28:29] op_sel_hi:[0,1]
	v_cvt_pk_bf16_f32 v27, v28, v29
	global_store_dwordx2 v[40:41], v[26:27], off offset:256 sc1
	v_cvt_pk_bf16_f32 v26, v48, v49
	v_cvt_pk_bf16_f32 v27, v36, v37
	global_store_dwordx2 v[40:41], v[26:27], off offset:288 sc1
.LBB0_1148:
	s_andn2_saveexec_b64 s[0:1], s[12:13]
	s_cbranch_execz .LBB0_1150
	v_lshlrev_b32_e32 v38, 1, v144
	v_mov_b32_e32 v39, v1
	v_pk_mul_f32 v[28:29], v[28:29], v[34:35] op_sel_hi:[1,0]
	v_pk_mul_f32 v[26:27], v[26:27], v[34:35] op_sel_hi:[1,0]
	v_pk_mul_f32 v[32:33], v[32:33], v[34:35] op_sel_hi:[1,0]
	v_pk_mul_f32 v[30:31], v[30:31], v[34:35] op_sel_hi:[1,0]
	v_lshl_add_u64 v[36:37], v[36:37], 0, v[38:39]
	v_cvt_pk_bf16_f32 v26, v26, v27
	v_cvt_pk_bf16_f32 v27, v28, v29
	v_cvt_pk_bf16_f32 v28, v30, v31
	v_cvt_pk_bf16_f32 v29, v32, v33
	global_store_dwordx4 v[36:37], v[26:29], off offset:256 sc1

; #define LAS __attribute__((address_space(3)))
; __device__ __forceinline__ void store4bf(bf16_t* p, f32x4 v) { u32x2 w; w.x = cvt_pk_bf16(v[0], v[1]); w.y = cvt_pk_bf16(v[2], v[3]); *(u32x2*)p = w; }
; __device__ __forceinline__ void store8bf(bf16_t* p, f32x4 v0, f32x4 v1) { u32x4 w; w.x = cvt_pk_bf16(v0[0], v0[1]); w.y = cvt_pk_bf16(v0[2], v0[3]); w.z = cvt_pk_bf16(v1[0], v1[1]); w.w = cvt_pk_bf16(v1[2], v1[3]); *(u32x4*)p = w; }
;   __device__ __forceinline__ void group(int row, int c32, int fq, f32x4 v0, f32x4 v1) const {
;     int b, e; if (!row_be(row, b, e)) return;
;     const float rs = use_direct ? rs_direct : ((LAS const float*)(lds_raw + RS_OFF))[row - brow];
;     if (c32 < 768) {
;       if (c32 >= 576) return;
;       const int h = c32 / 96, part = (c32 - h * 96) >> 5; const float sc = rs * QSC_A;
;       bf16_t* p = qa + ((size_t)(b * 6 + h) * E + e) * 96 + part * 32 + fq * 4;
;       if (part < 2) store8bf(qa + ((size_t)(b * 6 + h) * E + e) * 96 + part * 32 + fq * 8, v0 * sc, v1 * sc);
;       else { const float2* rp = rope + pos_of_e(e) * 16 + fq * 4; f32x4 o0, o1;
; #pragma unroll
;         for (int j = 0; j < 4; ++j) { const float2 cs = rp[j]; o0[j] = (v0[j] * cs.x - v1[j] * cs.y) * sc; o1[j] = (v1[j] * cs.x + v0[j] * cs.y) * sc; }
;         store4bf(p, o0); store4bf(p + 16, o1); }
;     } else {
;       const int cc = c32 - 768, h = cc >> 7, part = (cc & 127) >> 5;
;       if (part < 2) store8bf(ka + ((size_t)(b * 6 + h) * E + e) * 96 + part * 32 + fq * 8, v0 * rs, v1 * rs);
.LBB0_1154:
	s_movk_i32 s1, 0x7fff
	v_cmp_lt_i32_e32 vcc, s1, v69
	s_and_saveexec_b64 s[6:7], vcc
	s_xor_b64 s[6:7], exec, s[6:7]
	v_cmp_gt_u32_e64 s[8:9], s49, v68
	s_or_saveexec_b64 s[6:7], s[6:7]
	v_mov_b32_e32 v35, 0
	v_mul_i32_i24_e32 v40, 6, v70
	v_mov_b32_e32 v38, v130
	s_xor_b64 exec, exec, s[6:7]
	v_and_b32_e32 v10, 0x1fcf, v69
	v_add_u32_e32 v38, 64, v10
	v_mul_i32_i24_e32 v35, 6, v70
	s_or_b64 s[8:9], s[8:9], exec
	s_or_b64 exec, exec, s[6:7]
	v_lshlrev_b32_e32 v36, 1, v0
	v_lshlrev_b32_e32 v34, 1, v131
	s_and_saveexec_b64 s[6:7], s[8:9]
	s_cbranch_execz .LBB0_1160
	v_add_u32_e32 v10, s0, v35
	v_mov_b32_e32 v39, v1
	s_movk_i32 s1, 0x2040
	v_mad_i64_i32 v[10:11], s[8:9], v10, s1, v[38:39]
	v_add_u32_e32 v0, 0x20000, v71
	v_readlane_b32 s8, v254, 4
	ds_read_b32 v0, v0
	v_readlane_b32 s9, v254, 5
	v_mov_b32_e32 v37, v1
	v_mov_b32_e32 v35, v1
	v_mov_b64_e32 v[12:13], s[8:9]
	v_mad_u64_u32 v[12:13], s[8:9], v10, s47, v[12:13]
	v_mad_i32_i24 v13, v11, s47, v13
	v_lshl_add_u64 v[10:11], v[12:13], 0, v[36:37]
	v_lshl_add_u64 v[38:39], v[10:11], 0, v[34:35]
	s_waitcnt lgkmcnt(0)
	v_pk_mul_f32 v[12:13], v[32:33], v[0:1] op_sel_hi:[1,0]
	v_pk_mul_f32 v[10:11], v[30:31], v[0:1] op_sel_hi:[1,0]
	v_pk_mul_f32 v[28:29], v[28:29], v[0:1] op_sel_hi:[1,0]
	v_pk_mul_f32 v[26:27], v[26:27], v[0:1] op_sel_hi:[1,0]
	v_cvt_pk_bf16_f32 v10, v10, v11
	v_cvt_pk_bf16_f32 v11, v12, v13
	v_cvt_pk_bf16_f32 v12, v26, v27
	v_cvt_pk_bf16_f32 v13, v28, v29
	global_store_dwordx4 v[38:39], v[10:13], off sc1

; #define LAS __attribute__((address_space(3)))
; __device__ __forceinline__ void store4bf(bf16_t* p, f32x4 v) { u32x2 w; w.x = cvt_pk_bf16(v[0], v[1]); w.y = cvt_pk_bf16(v[2], v[3]); *(u32x2*)p = w; }
; __device__ __forceinline__ void store8bf(bf16_t* p, f32x4 v0, f32x4 v1) { u32x4 w; w.x = cvt_pk_bf16(v0[0], v0[1]); w.y = cvt_pk_bf16(v0[2], v0[3]); w.z = cvt_pk_bf16(v1[0], v1[1]); w.w = cvt_pk_bf16(v1[2], v1[3]); *(u32x4*)p = w; }
;   __device__ __forceinline__ void group(int row, int c32, int fq, f32x4 v0, f32x4 v1) const {
;     int b, e; if (!row_be(row, b, e)) return;
;     const float rs = use_direct ? rs_direct : ((LAS const float*)(lds_raw + RS_OFF))[row - brow];
;     if (c32 < 768) {
;       if (c32 >= 576) return;
;       const int h = c32 / 96, part = (c32 - h * 96) >> 5; const float sc = rs * QSC_A;
;       bf16_t* p = qa + ((size_t)(b * 6 + h) * E + e) * 96 + part * 32 + fq * 4;
;       if (part < 2) store8bf(qa + ((size_t)(b * 6 + h) * E + e) * 96 + part * 32 + fq * 8, v0 * sc, v1 * sc);
;       else { const float2* rp = rope + pos_of_e(e) * 16 + fq * 4; f32x4 o0, o1;
; #pragma unroll
;         for (int j = 0; j < 4; ++j) { const float2 cs = rp[j]; o0[j] = (v0[j] * cs.x - v1[j] * cs.y) * sc; o1[j] = (v1[j] * cs.x + v0[j] * cs.y) * sc; }
;         store4bf(p, o0); store4bf(p + 16, o1); }
;     } else {
;       const int cc = c32 - 768, h = cc >> 7, part = (cc & 127) >> 5;
;       if (part < 2) store8bf(ka + ((size_t)(b * 6 + h) * E + e) * 96 + part * 32 + fq * 8, v0 * rs, v1 * rs);
.LBB0_1163:
	v_subrev_u32_e32 v0, s20, v0
	v_mad_i32_i24 v10, v27, 6, s0
	v_mov_b32_e32 v27, v1
	s_movk_i32 s1, 0x2040
	v_lshl_add_u32 v0, v0, 2, 0
	v_mad_i64_i32 v[10:11], s[8:9], v10, s1, v[26:27]
	v_add_u32_e32 v0, 0x20000, v0
	v_readlane_b32 s8, v254, 4
	ds_read_b32 v0, v0
	v_readlane_b32 s9, v254, 5
	v_mov_b32_e32 v37, v1
	v_mov_b32_e32 v35, v1
	v_mov_b64_e32 v[12:13], s[8:9]
	v_mad_u64_u32 v[12:13], s[8:9], v10, s47, v[12:13]
	v_mad_i32_i24 v13, v11, s47, v13
	v_lshl_add_u64 v[10:11], v[12:13], 0, v[36:37]
	v_lshl_add_u64 v[26:27], v[10:11], 0, v[34:35]
	s_waitcnt lgkmcnt(0)
	v_pk_mul_f32 v[12:13], v[24:25], v[0:1] op_sel_hi:[1,0]
	v_pk_mul_f32 v[10:11], v[22:23], v[0:1] op_sel_hi:[1,0]
	v_pk_mul_f32 v[20:21], v[20:21], v[0:1] op_sel_hi:[1,0]
	v_pk_mul_f32 v[18:19], v[18:19], v[0:1] op_sel_hi:[1,0]
	v_cvt_pk_bf16_f32 v10, v10, v11
	v_cvt_pk_bf16_f32 v11, v12, v13
	v_cvt_pk_bf16_f32 v12, v18, v19
	v_cvt_pk_bf16_f32 v13, v20, v21
	global_store_dwordx4 v[26:27], v[10:13], off sc1

; #define LAS __attribute__((address_space(3)))
; __device__ __forceinline__ void store4bf(bf16_t* p, f32x4 v) { u32x2 w; w.x = cvt_pk_bf16(v[0], v[1]); w.y = cvt_pk_bf16(v[2], v[3]); *(u32x2*)p = w; }
; __device__ __forceinline__ void store8bf(bf16_t* p, f32x4 v0, f32x4 v1) { u32x4 w; w.x = cvt_pk_bf16(v0[0], v0[1]); w.y = cvt_pk_bf16(v0[2], v0[3]); w.z = cvt_pk_bf16(v1[0], v1[1]); w.w = cvt_pk_bf16(v1[2], v1[3]); *(u32x4*)p = w; }
;   __device__ __forceinline__ void group(int row, int c32, int fq, f32x4 v0, f32x4 v1) const {
;     int b, e; if (!row_be(row, b, e)) return;
;     const float rs = use_direct ? rs_direct : ((LAS const float*)(lds_raw + RS_OFF))[row - brow];
;     if (c32 < 768) {
;       if (c32 >= 576) return;
;       const int h = c32 / 96, part = (c32 - h * 96) >> 5; const float sc = rs * QSC_A;
;       bf16_t* p = qa + ((size_t)(b * 6 + h) * E + e) * 96 + part * 32 + fq * 4;
;       if (part < 2) store8bf(qa + ((size_t)(b * 6 + h) * E + e) * 96 + part * 32 + fq * 8, v0 * sc, v1 * sc);
;       else { const float2* rp = rope + pos_of_e(e) * 16 + fq * 4; f32x4 o0, o1;
; #pragma unroll
;         for (int j = 0; j < 4; ++j) { const float2 cs = rp[j]; o0[j] = (v0[j] * cs.x - v1[j] * cs.y) * sc; o1[j] = (v1[j] * cs.x + v0[j] * cs.y) * sc; }
;         store4bf(p, o0); store4bf(p + 16, o1); }
;     } else {
;       const int cc = c32 - 768, h = cc >> 7, part = (cc & 127) >> 5;
;       if (part < 2) store8bf(ka + ((size_t)(b * 6 + h) * E + e) * 96 + part * 32 + fq * 8, v0 * rs, v1 * rs);
.LBB0_1167:
	v_subrev_u32_e32 v0, s20, v0
	v_mad_i32_i24 v10, v70, 6, s0
	v_mov_b32_e32 v19, v1
	s_movk_i32 s1, 0x2040
	v_lshl_add_u32 v0, v0, 2, 0
	v_mad_i64_i32 v[10:11], s[8:9], v10, s1, v[18:19]
	v_add_u32_e32 v0, 0x20000, v0
	v_readlane_b32 s8, v254, 4
	ds_read_b32 v0, v0
	v_readlane_b32 s9, v254, 5
	v_mov_b32_e32 v37, v1
	v_mov_b32_e32 v35, v1
	v_mov_b64_e32 v[12:13], s[8:9]
	v_mad_u64_u32 v[12:13], s[8:9], v10, s47, v[12:13]
	v_mad_i32_i24 v13, v11, s47, v13
	v_lshl_add_u64 v[10:11], v[12:13], 0, v[36:37]
	v_lshl_add_u64 v[18:19], v[10:11], 0, v[34:35]
	s_waitcnt lgkmcnt(0)
	v_pk_mul_f32 v[12:13], v[16:17], v[0:1] op_sel_hi:[1,0]
	v_pk_mul_f32 v[10:11], v[14:15], v[0:1] op_sel_hi:[1,0]
	v_pk_mul_f32 v[14:15], v[152:153], v[0:1] op_sel_hi:[1,0]
	v_pk_mul_f32 v[16:17], v[150:151], v[0:1] op_sel_hi:[1,0]
	v_cvt_pk_bf16_f32 v10, v10, v11
	v_cvt_pk_bf16_f32 v11, v12, v13
	v_cvt_pk_bf16_f32 v12, v16, v17
	v_cvt_pk_bf16_f32 v13, v14, v15
	global_store_dwordx4 v[18:19], v[10:13], off sc1

; #define LAS __attribute__((address_space(3)))
; __device__ __forceinline__ void store4bf(bf16_t* p, f32x4 v) { u32x2 w; w.x = cvt_pk_bf16(v[0], v[1]); w.y = cvt_pk_bf16(v[2], v[3]); *(u32x2*)p = w; }
; __device__ __forceinline__ void store8bf(bf16_t* p, f32x4 v0, f32x4 v1) { u32x4 w; w.x = cvt_pk_bf16(v0[0], v0[1]); w.y = cvt_pk_bf16(v0[2], v0[3]); w.z = cvt_pk_bf16(v1[0], v1[1]); w.w = cvt_pk_bf16(v1[2], v1[3]); *(u32x4*)p = w; }
;   __device__ __forceinline__ void group(int row, int c32, int fq, f32x4 v0, f32x4 v1) const {
;     int b, e; if (!row_be(row, b, e)) return;
;     const float rs = use_direct ? rs_direct : ((LAS const float*)(lds_raw + RS_OFF))[row - brow];
;     if (c32 < 768) {
;       if (c32 >= 576) return;
;       const int h = c32 / 96, part = (c32 - h * 96) >> 5; const float sc = rs * QSC_A;
;       bf16_t* p = qa + ((size_t)(b * 6 + h) * E + e) * 96 + part * 32 + fq * 4;
;       if (part < 2) store8bf(qa + ((size_t)(b * 6 + h) * E + e) * 96 + part * 32 + fq * 8, v0 * sc, v1 * sc);
;       else { const float2* rp = rope + pos_of_e(e) * 16 + fq * 4; f32x4 o0, o1;
; #pragma unroll
;         for (int j = 0; j < 4; ++j) { const float2 cs = rp[j]; o0[j] = (v0[j] * cs.x - v1[j] * cs.y) * sc; o1[j] = (v1[j] * cs.x + v0[j] * cs.y) * sc; }
;         store4bf(p, o0); store4bf(p + 16, o1); }
;     } else {
;       const int cc = c32 - 768, h = cc >> 7, part = (cc & 127) >> 5;
;       if (part < 2) store8bf(ka + ((size_t)(b * 6 + h) * E + e) * 96 + part * 32 + fq * 8, v0 * rs, v1 * rs);
.LBB0_1171:
	v_subrev_u32_e32 v0, s20, v0
	v_lshl_add_u32 v0, v0, 2, 0
	v_add_u32_e32 v10, s0, v10
	v_mov_b32_e32 v131, v1
	s_movk_i32 s1, 0x2040
	v_add_u32_e32 v0, 0x20000, v0
	v_mad_i64_i32 v[10:11], s[8:9], v10, s1, v[130:131]
	ds_read_b32 v0, v0
	v_readlane_b32 s8, v254, 4
	v_readlane_b32 s9, v254, 5
	v_mov_b32_e32 v37, v1
	v_mov_b32_e32 v35, v1
	v_mov_b64_e32 v[12:13], s[8:9]
	v_mad_u64_u32 v[12:13], s[8:9], v10, s47, v[12:13]
	v_mad_i32_i24 v13, v11, s47, v13
	v_lshl_add_u64 v[10:11], v[12:13], 0, v[36:37]
	s_waitcnt lgkmcnt(0)
	v_pk_mul_f32 v[8:9], v[8:9], v[0:1] op_sel_hi:[1,0]
	v_pk_mul_f32 v[6:7], v[6:7], v[0:1] op_sel_hi:[1,0]
	v_pk_mul_f32 v[12:13], v[4:5], v[0:1] op_sel_hi:[1,0]
	v_pk_mul_f32 v[4:5], v[2:3], v[0:1] op_sel_hi:[1,0]
	v_lshl_add_u64 v[10:11], v[10:11], 0, v[34:35]
	v_cvt_pk_bf16_f32 v2, v6, v7
	v_cvt_pk_bf16_f32 v3, v8, v9
	v_cvt_pk_bf16_f32 v4, v4, v5
	v_cvt_pk_bf16_f32 v5, v12, v13
	global_store_dwordx4 v[10:11], v[2:5], off sc1

; #define LAS __attribute__((address_space(3)))
; __device__ __forceinline__ void store4bf(bf16_t* p, f32x4 v) { u32x2 w; w.x = cvt_pk_bf16(v[0], v[1]); w.y = cvt_pk_bf16(v[2], v[3]); *(u32x2*)p = w; }
; __device__ __forceinline__ void store8bf(bf16_t* p, f32x4 v0, f32x4 v1) { u32x4 w; w.x = cvt_pk_bf16(v0[0], v0[1]); w.y = cvt_pk_bf16(v0[2], v0[3]); w.z = cvt_pk_bf16(v1[0], v1[1]); w.w = cvt_pk_bf16(v1[2], v1[3]); *(u32x4*)p = w; }
;   __device__ __forceinline__ void group(int row, int c32, int fq, f32x4 v0, f32x4 v1) const { e->group(row, c32 + sh, fq, v0, v1); }
;   __device__ __forceinline__ void group(int row, int c32, int fq, f32x4 v0, f32x4 v1) const {
;     int b, e; if (!row_be(row, b, e)) return;
;     const float rs = use_direct ? rs_direct : ((LAS const float*)(lds_raw + RS_OFF))[row - brow];
;     if (c32 < 768) {
;       if (c32 >= 576) return;
;       const int h = c32 / 96, part = (c32 - h * 96) >> 5; const float sc = rs * QSC_A;
;       bf16_t* p = qa + ((size_t)(b * 6 + h) * E + e) * 96 + part * 32 + fq * 4;
;       if (part < 2) store8bf(qa + ((size_t)(b * 6 + h) * E + e) * 96 + part * 32 + fq * 8, v0 * sc, v1 * sc);
;       else { const float2* rp = rope + pos_of_e(e) * 16 + fq * 4; f32x4 o0, o1;
; #pragma unroll
;         for (int j = 0; j < 4; ++j) { const float2 cs = rp[j]; o0[j] = (v0[j] * cs.x - v1[j] * cs.y) * sc; o1[j] = (v1[j] * cs.x + v0[j] * cs.y) * sc; }
;         store4bf(p, o0); store4bf(p + 16, o1); }
.LBB0_1175:
	v_add_u32_e32 v26, 0x20000, v63
	v_readlane_b32 s0, v254, 24
	ds_read_b32 v26, v26
	v_readlane_b32 s1, v254, 25
	v_mad_i32_i24 v27, v59, 6, v101
	v_mov_b32_e32 v133, v1
	v_mov_b64_e32 v[28:29], s[0:1]
	s_movk_i32 s0, 0x2040
	v_mad_i64_i32 v[30:31], s[0:1], v27, s0, v[0:1]
	v_mad_u64_u32 v[28:29], s[0:1], v30, s47, v[28:29]
	v_mad_i32_i24 v29, v31, s47, v29
	v_lshl_add_u64 v[30:31], v[98:99], 0, v[132:133]
	s_waitcnt lgkmcnt(0)
	v_mul_f32_e32 v26, 0x3e16c740, v26
	v_lshl_add_u64 v[28:29], v[30:31], 1, v[28:29]
	s_and_saveexec_b64 s[0:1], s[6:7]
	s_xor_b64 s[10:11], exec, s[0:1]
	s_cbranch_execz .LBB0_1177
	v_cmp_lt_u32_e32 vcc, 63, v0
	v_lshlrev_b32_e32 v0, 4, v0
	v_lshlrev_b32_e32 v30, 1, v137
	v_mov_b32_e32 v31, v1
	v_add_u32_e32 v27, 0xfffffd00, v0
	v_readlane_b32 s0, v253, 40
	v_lshl_add_u64 v[36:37], v[28:29], 0, v[30:31]
	v_cndmask_b32_e32 v28, v0, v27, vcc
	v_mov_b32_e32 v29, v1
	v_readlane_b32 s1, v253, 41
	v_lshlrev_b32_e32 v30, 3, v137
	s_nop 0
	v_lshl_add_u64 v[28:29], v[28:29], 3, s[0:1]
	v_lshl_add_u64 v[32:33], v[28:29], 0, v[30:31]
	global_load_dwordx4 v[28:31], v[32:33], off offset:16
	s_nop 0
	global_load_dwordx4 v[32:35], v[32:33], off
	s_waitcnt vmcnt(0)
	v_mov_b32_e32 v39, v34
	v_mov_b32_e32 v34, v33
	v_mov_b32_e32 v38, v32
	v_pk_mul_f32 v[32:33], v[18:19], v[34:35]
	s_nop 0
	v_pk_fma_f32 v[32:33], v[22:23], v[38:39], v[32:33]
	v_pk_mul_f32 v[22:23], v[22:23], v[34:35]
	v_pk_mul_f32 v[32:33], v[26:27], v[32:33] op_sel_hi:[0,1]
	v_pk_fma_f32 v[18:19], v[18:19], v[38:39], v[22:23] neg_lo:[0,0,1] neg_hi:[0,0,1]
	v_mov_b32_e32 v23, v30
	v_mov_b32_e32 v30, v29
	v_mov_b32_e32 v22, v28
	v_pk_mul_f32 v[28:29], v[20:21], v[30:31]
	v_pk_mul_f32 v[18:19], v[26:27], v[18:19] op_sel_hi:[0,1]
	v_pk_fma_f32 v[28:29], v[24:25], v[22:23], v[28:29]
	v_pk_mul_f32 v[24:25], v[24:25], v[30:31]
	v_pk_mul_f32 v[28:29], v[26:27], v[28:29] op_sel_hi:[0,1]
	v_pk_fma_f32 v[20:21], v[20:21], v[22:23], v[24:25] neg_lo:[0,0,1] neg_hi:[0,0,1]
	v_cvt_pk_bf16_f32 v18, v18, v19
	v_pk_mul_f32 v[20:21], v[26:27], v[20:21] op_sel_hi:[0,1]
	v_cvt_pk_bf16_f32 v19, v20, v21
	global_store_dwordx2 v[36:37], v[18:19], off offset:256 sc1
	v_cvt_pk_bf16_f32 v18, v32, v33
	v_cvt_pk_bf16_f32 v19, v28, v29
	global_store_dwordx2 v[36:37], v[18:19], off offset:288 sc1
.LBB0_1177:
	s_andn2_saveexec_b64 s[0:1], s[10:11]
	s_cbranch_execz .LBB0_1179
	v_lshlrev_b32_e32 v30, 1, v144
	v_mov_b32_e32 v31, v1
	v_pk_mul_f32 v[20:21], v[20:21], v[26:27] op_sel_hi:[1,0]
	v_pk_mul_f32 v[18:19], v[18:19], v[26:27] op_sel_hi:[1,0]
	v_pk_mul_f32 v[24:25], v[24:25], v[26:27] op_sel_hi:[1,0]
	v_pk_mul_f32 v[22:23], v[22:23], v[26:27] op_sel_hi:[1,0]
	v_lshl_add_u64 v[28:29], v[28:29], 0, v[30:31]
	v_cvt_pk_bf16_f32 v18, v18, v19
	v_cvt_pk_bf16_f32 v19, v20, v21
	v_cvt_pk_bf16_f32 v20, v22, v23
	v_cvt_pk_bf16_f32 v21, v24, v25
	global_store_dwordx4 v[28:29], v[18:21], off offset:256 sc1

; #define LAS __attribute__((address_space(3)))
; __device__ __forceinline__ void store4bf(bf16_t* p, f32x4 v) { u32x2 w; w.x = cvt_pk_bf16(v[0], v[1]); w.y = cvt_pk_bf16(v[2], v[3]); *(u32x2*)p = w; }
; __device__ __forceinline__ void store8bf(bf16_t* p, f32x4 v0, f32x4 v1) { u32x4 w; w.x = cvt_pk_bf16(v0[0], v0[1]); w.y = cvt_pk_bf16(v0[2], v0[3]); w.z = cvt_pk_bf16(v1[0], v1[1]); w.w = cvt_pk_bf16(v1[2], v1[3]); *(u32x4*)p = w; }
;   __device__ __forceinline__ void group(int row, int c32, int fq, f32x4 v0, f32x4 v1) const { e->group(row, c32 + sh, fq, v0, v1); }
;   __device__ __forceinline__ void group(int row, int c32, int fq, f32x4 v0, f32x4 v1) const {
;     int b, e; if (!row_be(row, b, e)) return;
;     const float rs = use_direct ? rs_direct : ((LAS const float*)(lds_raw + RS_OFF))[row - brow];
;     if (c32 < 768) {
;       if (c32 >= 576) return;
;       const int h = c32 / 96, part = (c32 - h * 96) >> 5; const float sc = rs * QSC_A;
;       bf16_t* p = qa + ((size_t)(b * 6 + h) * E + e) * 96 + part * 32 + fq * 4;
;       if (part < 2) store8bf(qa + ((size_t)(b * 6 + h) * E + e) * 96 + part * 32 + fq * 8, v0 * sc, v1 * sc);
;       else { const float2* rp = rope + pos_of_e(e) * 16 + fq * 4; f32x4 o0, o1;
; #pragma unroll
;         for (int j = 0; j < 4; ++j) { const float2 cs = rp[j]; o0[j] = (v0[j] * cs.x - v1[j] * cs.y) * sc; o1[j] = (v1[j] * cs.x + v0[j] * cs.y) * sc; }
;         store4bf(p, o0); store4bf(p + 16, o1); }
.LBB0_1184:
	v_add_u32_e32 v18, 0x20000, v55
	v_readlane_b32 s0, v254, 24
	ds_read_b32 v18, v18
	v_readlane_b32 s1, v254, 25
	v_mad_i32_i24 v19, v51, 6, v101
	v_mov_b32_e32 v133, v1
	v_mov_b64_e32 v[20:21], s[0:1]
	s_movk_i32 s0, 0x2040
	v_mad_i64_i32 v[22:23], s[0:1], v19, s0, v[0:1]
	v_mad_u64_u32 v[20:21], s[0:1], v22, s47, v[20:21]
	v_mad_i32_i24 v21, v23, s47, v21
	v_lshl_add_u64 v[22:23], v[98:99], 0, v[132:133]
	s_waitcnt lgkmcnt(0)
	v_mul_f32_e32 v18, 0x3e16c740, v18
	v_lshl_add_u64 v[20:21], v[22:23], 1, v[20:21]
	s_and_saveexec_b64 s[0:1], s[6:7]
	s_xor_b64 s[10:11], exec, s[0:1]
	s_cbranch_execz .LBB0_1186
	v_cmp_lt_u32_e32 vcc, 63, v0
	v_lshlrev_b32_e32 v0, 4, v0
	v_lshlrev_b32_e32 v22, 1, v137
	v_mov_b32_e32 v23, v1
	v_add_u32_e32 v19, 0xfffffd00, v0
	v_readlane_b32 s0, v253, 40
	v_lshl_add_u64 v[28:29], v[20:21], 0, v[22:23]
	v_cndmask_b32_e32 v20, v0, v19, vcc
	v_mov_b32_e32 v21, v1
	v_readlane_b32 s1, v253, 41
	v_lshlrev_b32_e32 v22, 3, v137
	s_nop 0
	v_lshl_add_u64 v[20:21], v[20:21], 3, s[0:1]
	v_lshl_add_u64 v[24:25], v[20:21], 0, v[22:23]
	global_load_dwordx4 v[20:23], v[24:25], off offset:16
	s_nop 0
	global_load_dwordx4 v[24:27], v[24:25], off
	s_waitcnt vmcnt(0)
	v_mov_b32_e32 v31, v26
	v_mov_b32_e32 v26, v25
	v_mov_b32_e32 v30, v24
	v_pk_mul_f32 v[24:25], v[10:11], v[26:27]
	s_nop 0
	v_pk_fma_f32 v[24:25], v[14:15], v[30:31], v[24:25]
	v_pk_mul_f32 v[14:15], v[14:15], v[26:27]
	v_pk_mul_f32 v[24:25], v[18:19], v[24:25] op_sel_hi:[0,1]
	v_pk_fma_f32 v[10:11], v[10:11], v[30:31], v[14:15] neg_lo:[0,0,1] neg_hi:[0,0,1]
	v_mov_b32_e32 v15, v22
	v_mov_b32_e32 v22, v21
	v_mov_b32_e32 v14, v20
	v_pk_mul_f32 v[20:21], v[12:13], v[22:23]
	v_pk_mul_f32 v[10:11], v[18:19], v[10:11] op_sel_hi:[0,1]
	v_pk_fma_f32 v[20:21], v[16:17], v[14:15], v[20:21]
	v_pk_mul_f32 v[16:17], v[16:17], v[22:23]
	v_pk_mul_f32 v[20:21], v[18:19], v[20:21] op_sel_hi:[0,1]
	v_pk_fma_f32 v[12:13], v[12:13], v[14:15], v[16:17] neg_lo:[0,0,1] neg_hi:[0,0,1]
	v_cvt_pk_bf16_f32 v10, v10, v11
	v_pk_mul_f32 v[12:13], v[18:19], v[12:13] op_sel_hi:[0,1]
	v_cvt_pk_bf16_f32 v11, v12, v13
	global_store_dwordx2 v[28:29], v[10:11], off offset:256 sc1
	v_cvt_pk_bf16_f32 v10, v24, v25
	v_cvt_pk_bf16_f32 v11, v20, v21
	global_store_dwordx2 v[28:29], v[10:11], off offset:288 sc1
.LBB0_1186:
	s_andn2_saveexec_b64 s[0:1], s[10:11]
	s_cbranch_execz .LBB0_1188
	v_lshlrev_b32_e32 v22, 1, v144
	v_mov_b32_e32 v23, v1
	v_pk_mul_f32 v[12:13], v[12:13], v[18:19] op_sel_hi:[1,0]
	v_pk_mul_f32 v[10:11], v[10:11], v[18:19] op_sel_hi:[1,0]
	v_pk_mul_f32 v[16:17], v[16:17], v[18:19] op_sel_hi:[1,0]
	v_pk_mul_f32 v[14:15], v[14:15], v[18:19] op_sel_hi:[1,0]
	v_lshl_add_u64 v[20:21], v[20:21], 0, v[22:23]
	v_cvt_pk_bf16_f32 v10, v10, v11
	v_cvt_pk_bf16_f32 v11, v12, v13
	v_cvt_pk_bf16_f32 v12, v14, v15
	v_cvt_pk_bf16_f32 v13, v16, v17
	global_store_dwordx4 v[20:21], v[10:13], off offset:256 sc1

; #define LAS __attribute__((address_space(3)))
; __device__ __forceinline__ void store4bf(bf16_t* p, f32x4 v) { u32x2 w; w.x = cvt_pk_bf16(v[0], v[1]); w.y = cvt_pk_bf16(v[2], v[3]); *(u32x2*)p = w; }
; __device__ __forceinline__ void store8bf(bf16_t* p, f32x4 v0, f32x4 v1) { u32x4 w; w.x = cvt_pk_bf16(v0[0], v0[1]); w.y = cvt_pk_bf16(v0[2], v0[3]); w.z = cvt_pk_bf16(v1[0], v1[1]); w.w = cvt_pk_bf16(v1[2], v1[3]); *(u32x4*)p = w; }
;   __device__ __forceinline__ void group(int row, int c32, int fq, f32x4 v0, f32x4 v1) const { e->group(row, c32 + sh, fq, v0, v1); }
;   __device__ __forceinline__ void group(int row, int c32, int fq, f32x4 v0, f32x4 v1) const {
;     int b, e; if (!row_be(row, b, e)) return;
;     const float rs = use_direct ? rs_direct : ((LAS const float*)(lds_raw + RS_OFF))[row - brow];
;     if (c32 < 768) {
;       if (c32 >= 576) return;
;       const int h = c32 / 96, part = (c32 - h * 96) >> 5; const float sc = rs * QSC_A;
;       bf16_t* p = qa + ((size_t)(b * 6 + h) * E + e) * 96 + part * 32 + fq * 4;
;       if (part < 2) store8bf(qa + ((size_t)(b * 6 + h) * E + e) * 96 + part * 32 + fq * 8, v0 * sc, v1 * sc);
;       else { const float2* rp = rope + pos_of_e(e) * 16 + fq * 4; f32x4 o0, o1;
; #pragma unroll
;         for (int j = 0; j < 4; ++j) { const float2 cs = rp[j]; o0[j] = (v0[j] * cs.x - v1[j] * cs.y) * sc; o1[j] = (v1[j] * cs.x + v0[j] * cs.y) * sc; }
;         store4bf(p, o0); store4bf(p + 16, o1); }
.LBB0_1193:
	v_add_u32_e32 v10, 0x20000, v46
	ds_read_b32 v12, v10
	v_add_u32_e32 v0, v0, v101
	v_mov_b32_e32 v131, v1
	s_movk_i32 s0, 0x2040
	v_mad_i64_i32 v[10:11], s[0:1], v0, s0, v[130:131]
	v_readlane_b32 s0, v254, 24
	v_readlane_b32 s1, v254, 25
	s_waitcnt lgkmcnt(0)
	v_mul_f32_e32 v0, 0x3e16c740, v12
	v_mov_b32_e32 v133, v1
	v_mov_b64_e32 v[12:13], s[0:1]
	v_mad_u64_u32 v[12:13], s[0:1], v10, s47, v[12:13]
	v_mad_i32_i24 v13, v11, s47, v13
	v_lshl_add_u64 v[10:11], v[98:99], 0, v[132:133]
	v_lshl_add_u64 v[10:11], v[10:11], 1, v[12:13]
	s_and_saveexec_b64 s[0:1], s[6:7]
	s_xor_b64 s[6:7], exec, s[0:1]
	s_cbranch_execz .LBB0_1195
	v_lshlrev_b32_e32 v12, 1, v137
	v_mov_b32_e32 v13, v1
	v_lshl_add_u64 v[18:19], v[10:11], 0, v[12:13]
	v_lshlrev_b32_e32 v10, 4, v130
	v_cmp_lt_u32_e32 vcc, 63, v130
	v_add_u32_e32 v11, 0xfffffd00, v10
	v_readlane_b32 s0, v253, 40
	v_cndmask_b32_e32 v10, v10, v11, vcc
	v_mov_b32_e32 v11, v1
	v_readlane_b32 s1, v253, 41
	v_lshlrev_b32_e32 v12, 3, v137
	s_nop 0
	v_lshl_add_u64 v[10:11], v[10:11], 3, s[0:1]
	v_lshl_add_u64 v[14:15], v[10:11], 0, v[12:13]
	global_load_dwordx4 v[10:13], v[14:15], off offset:16
	s_nop 0
	global_load_dwordx4 v[14:17], v[14:15], off
	s_waitcnt vmcnt(0)
	v_mov_b32_e32 v21, v16
	v_mov_b32_e32 v16, v15
	v_mov_b32_e32 v20, v14
	v_pk_mul_f32 v[14:15], v[2:3], v[16:17]
	s_nop 0
	v_pk_fma_f32 v[14:15], v[6:7], v[20:21], v[14:15]
	v_pk_mul_f32 v[6:7], v[6:7], v[16:17]
	v_pk_mul_f32 v[14:15], v[0:1], v[14:15] op_sel_hi:[0,1]
	v_pk_fma_f32 v[2:3], v[2:3], v[20:21], v[6:7] neg_lo:[0,0,1] neg_hi:[0,0,1]
	v_mov_b32_e32 v7, v12
	v_mov_b32_e32 v12, v11
	v_mov_b32_e32 v6, v10
	v_pk_mul_f32 v[10:11], v[4:5], v[12:13]
	v_pk_mul_f32 v[2:3], v[0:1], v[2:3] op_sel_hi:[0,1]
	v_pk_fma_f32 v[10:11], v[8:9], v[6:7], v[10:11]
	v_pk_mul_f32 v[8:9], v[8:9], v[12:13]
	v_pk_mul_f32 v[10:11], v[0:1], v[10:11] op_sel_hi:[0,1]
	v_pk_fma_f32 v[4:5], v[4:5], v[6:7], v[8:9] neg_lo:[0,0,1] neg_hi:[0,0,1]
	v_cvt_pk_bf16_f32 v2, v2, v3
	v_pk_mul_f32 v[4:5], v[0:1], v[4:5] op_sel_hi:[0,1]
	v_cvt_pk_bf16_f32 v3, v4, v5
	global_store_dwordx2 v[18:19], v[2:3], off offset:256 sc1
	v_cvt_pk_bf16_f32 v2, v14, v15
	v_cvt_pk_bf16_f32 v3, v10, v11
	global_store_dwordx2 v[18:19], v[2:3], off offset:288 sc1
.LBB0_1195:
	s_andn2_saveexec_b64 s[0:1], s[6:7]
	s_cbranch_execz .LBB0_836
	v_lshlrev_b32_e32 v12, 1, v144
	v_mov_b32_e32 v13, v1
	v_pk_mul_f32 v[4:5], v[4:5], v[0:1] op_sel_hi:[1,0]
	v_pk_mul_f32 v[2:3], v[2:3], v[0:1] op_sel_hi:[1,0]
	v_pk_mul_f32 v[8:9], v[8:9], v[0:1] op_sel_hi:[1,0]
	v_pk_mul_f32 v[6:7], v[6:7], v[0:1] op_sel_hi:[1,0]
	v_lshl_add_u64 v[10:11], v[10:11], 0, v[12:13]
	v_cvt_pk_bf16_f32 v2, v2, v3
	v_cvt_pk_bf16_f32 v3, v4, v5
	v_cvt_pk_bf16_f32 v4, v6, v7
	v_cvt_pk_bf16_f32 v5, v8, v9
	global_store_dwordx4 v[10:11], v[2:5], off offset:256 sc1
	s_branch .LBB0_836
